# sc1 write-through also on QKV, attention, S5, SGU and P0 stores (outputs consumed by other XCDs)
# baseline (speedup 1.0000x reference)
.LBB0_16:
	s_or_b64 exec, exec, s[8:9]
	v_div_scale_f32 v153, s[8:9], v9, v9, s22
	v_rcp_f32_e32 v154, v153
	s_mul_hi_i32 s29, s27, 0x1600000
	s_mul_i32 s27, s27, 0x1600000
	s_add_u32 s8, s10, s27
	v_fma_f32 v155, -v153, v154, 1.0
	v_fmac_f32_e32 v154, v155, v154
	v_div_scale_f32 v155, vcc, s22, v9, s22
	v_mul_f32_e32 v156, v155, v154
	v_fma_f32 v157, -v153, v156, v155
	v_fmac_f32_e32 v156, v157, v154
	v_fma_f32 v153, -v153, v156, v155
	v_div_fmas_f32 v153, v153, v154, v156
	v_div_fixup_f32 v9, v153, v9, s22
	v_cndmask_b32_e64 v9, 0, v9, s[6:7]
	v_fmaak_f32 v26, v26, v9, 0x4b400000
	v_fmaak_f32 v27, v27, v9, 0x4b400000
	v_fmaak_f32 v28, v28, v9, 0x4b400000
	v_perm_b32 v26, v27, v26, s23
	v_fmaak_f32 v29, v29, v9, 0x4b400000
	v_perm_b32 v26, v28, v26, s24
	v_fmaak_f32 v27, v30, v9, 0x4b400000
	v_fmaak_f32 v28, v31, v9, 0x4b400000
	v_perm_b32 v26, v29, v26, s25
	v_fmaak_f32 v29, v32, v9, 0x4b400000
	v_perm_b32 v27, v28, v27, s23
	v_fmaak_f32 v30, v33, v9, 0x4b400000
	v_perm_b32 v27, v29, v27, s24
	v_perm_b32 v27, v30, v27, s25
	v_add_u32_e32 v28, 0x800, v11
	ds_write2_b32 v28, v26, v27 offset1:16
	v_fmaak_f32 v26, v34, v9, 0x4b400000
	v_fmaak_f32 v27, v35, v9, 0x4b400000
	v_fmaak_f32 v29, v36, v9, 0x4b400000
	v_perm_b32 v26, v27, v26, s23
	v_fmaak_f32 v30, v37, v9, 0x4b400000
	v_perm_b32 v26, v29, v26, s24
	v_fmaak_f32 v27, v38, v9, 0x4b400000
	v_fmaak_f32 v29, v39, v9, 0x4b400000
	v_perm_b32 v26, v30, v26, s25
	v_fmaak_f32 v30, v40, v9, 0x4b400000
	v_perm_b32 v27, v29, v27, s23
	v_fmaak_f32 v31, v41, v9, 0x4b400000
	v_perm_b32 v27, v30, v27, s24
	v_perm_b32 v27, v31, v27, s25
	ds_write2_b32 v28, v26, v27 offset0:32 offset1:48
	v_fmaak_f32 v26, v42, v9, 0x4b400000
	v_fmaak_f32 v27, v43, v9, 0x4b400000
	v_fmaak_f32 v29, v44, v9, 0x4b400000
	v_perm_b32 v26, v27, v26, s23
	v_fmaak_f32 v30, v45, v9, 0x4b400000
	v_perm_b32 v26, v29, v26, s24
	v_fmaak_f32 v27, v46, v9, 0x4b400000
	v_fmaak_f32 v29, v47, v9, 0x4b400000
	v_perm_b32 v26, v30, v26, s25
	v_fmaak_f32 v30, v48, v9, 0x4b400000
	v_perm_b32 v27, v29, v27, s23
	v_fmaak_f32 v31, v49, v9, 0x4b400000
	v_perm_b32 v27, v30, v27, s24
	v_perm_b32 v27, v31, v27, s25
	ds_write2_b32 v28, v26, v27 offset0:64 offset1:80
	v_fmaak_f32 v26, v50, v9, 0x4b400000
	v_fmaak_f32 v27, v51, v9, 0x4b400000
	v_fmaak_f32 v29, v52, v9, 0x4b400000
	v_perm_b32 v26, v27, v26, s23
	v_fmaak_f32 v30, v53, v9, 0x4b400000
	v_perm_b32 v26, v29, v26, s24
	v_fmaak_f32 v27, v54, v9, 0x4b400000
	v_fmaak_f32 v29, v55, v9, 0x4b400000
	v_perm_b32 v26, v30, v26, s25
	v_fmaak_f32 v30, v56, v9, 0x4b400000
	v_perm_b32 v27, v29, v27, s23
	v_fmaak_f32 v31, v57, v9, 0x4b400000
	v_perm_b32 v27, v30, v27, s24
	v_perm_b32 v27, v31, v27, s25
	ds_write2_b32 v28, v26, v27 offset0:96 offset1:112
	v_fmaak_f32 v26, v58, v9, 0x4b400000
	v_fmaak_f32 v27, v59, v9, 0x4b400000
	v_fmaak_f32 v29, v60, v9, 0x4b400000
	v_perm_b32 v26, v27, v26, s23
	v_fmaak_f32 v30, v61, v9, 0x4b400000
	v_perm_b32 v26, v29, v26, s24
	v_fmaak_f32 v27, v62, v9, 0x4b400000
	v_fmaak_f32 v29, v63, v9, 0x4b400000
	v_perm_b32 v26, v30, v26, s25
	v_fmaak_f32 v30, v64, v9, 0x4b400000
	v_perm_b32 v27, v29, v27, s23
	v_fmaak_f32 v31, v65, v9, 0x4b400000
	v_perm_b32 v27, v30, v27, s24
	v_perm_b32 v27, v31, v27, s25
	ds_write2_b32 v28, v26, v27 offset0:128 offset1:144
	v_fmaak_f32 v26, v66, v9, 0x4b400000
	v_fmaak_f32 v27, v67, v9, 0x4b400000
	v_fmaak_f32 v29, v68, v9, 0x4b400000
	v_perm_b32 v26, v27, v26, s23
	v_fmaak_f32 v30, v69, v9, 0x4b400000
	v_perm_b32 v26, v29, v26, s24
	v_fmaak_f32 v27, v70, v9, 0x4b400000
	v_fmaak_f32 v29, v71, v9, 0x4b400000
	v_perm_b32 v26, v30, v26, s25
	v_fmaak_f32 v30, v72, v9, 0x4b400000
	v_perm_b32 v27, v29, v27, s23
	v_fmaak_f32 v31, v73, v9, 0x4b400000
	v_perm_b32 v27, v30, v27, s24
	v_perm_b32 v27, v31, v27, s25
	ds_write2_b32 v28, v26, v27 offset0:160 offset1:176
	v_fmaak_f32 v26, v74, v9, 0x4b400000
	v_fmaak_f32 v27, v75, v9, 0x4b400000
	v_fmaak_f32 v29, v76, v9, 0x4b400000
	v_perm_b32 v26, v27, v26, s23
	v_fmaak_f32 v30, v77, v9, 0x4b400000
	v_perm_b32 v26, v29, v26, s24
	v_fmaak_f32 v27, v78, v9, 0x4b400000
	v_fmaak_f32 v29, v79, v9, 0x4b400000
	v_perm_b32 v26, v30, v26, s25
	v_fmaak_f32 v30, v80, v9, 0x4b400000
	v_perm_b32 v27, v29, v27, s23
	v_fmaak_f32 v31, v81, v9, 0x4b400000
	v_perm_b32 v27, v30, v27, s24
	v_perm_b32 v27, v31, v27, s25
	ds_write2_b32 v28, v26, v27 offset0:192 offset1:208
	v_fmaak_f32 v26, v82, v9, 0x4b400000
	v_fmaak_f32 v27, v83, v9, 0x4b400000
	v_fmaak_f32 v29, v84, v9, 0x4b400000
	v_perm_b32 v26, v27, v26, s23
	v_fmaak_f32 v30, v85, v9, 0x4b400000
	v_perm_b32 v26, v29, v26, s24
	v_fmaak_f32 v27, v86, v9, 0x4b400000
	v_fmaak_f32 v29, v87, v9, 0x4b400000
	v_perm_b32 v26, v30, v26, s25
	v_fmaak_f32 v30, v88, v9, 0x4b400000
	v_perm_b32 v27, v29, v27, s23
	v_fmaak_f32 v31, v89, v9, 0x4b400000
	v_perm_b32 v27, v30, v27, s24
	v_perm_b32 v27, v31, v27, s25
	ds_write2_b32 v28, v26, v27 offset0:224 offset1:240
	v_fmaak_f32 v26, v90, v9, 0x4b400000
	v_fmaak_f32 v27, v91, v9, 0x4b400000
	v_fmaak_f32 v28, v92, v9, 0x4b400000
	v_perm_b32 v26, v27, v26, s23
	v_fmaak_f32 v29, v93, v9, 0x4b400000
	v_perm_b32 v26, v28, v26, s24
	v_fmaak_f32 v27, v94, v9, 0x4b400000
	v_fmaak_f32 v28, v95, v9, 0x4b400000
	v_perm_b32 v26, v29, v26, s25
	v_fmaak_f32 v29, v96, v9, 0x4b400000
	v_perm_b32 v27, v28, v27, s23
	v_fmaak_f32 v30, v97, v9, 0x4b400000
	v_perm_b32 v27, v29, v27, s24
	v_perm_b32 v27, v30, v27, s25
	v_add_u32_e32 v28, 0xc00, v11
	ds_write2_b32 v28, v26, v27 offset1:16
	v_fmaak_f32 v26, v98, v9, 0x4b400000
	v_fmaak_f32 v27, v99, v9, 0x4b400000
	v_fmaak_f32 v29, v100, v9, 0x4b400000
	v_perm_b32 v26, v27, v26, s23
	v_fmaak_f32 v30, v101, v9, 0x4b400000
	v_perm_b32 v26, v29, v26, s24
	v_fmaak_f32 v27, v102, v9, 0x4b400000
	v_fmaak_f32 v29, v103, v9, 0x4b400000
	v_perm_b32 v26, v30, v26, s25
	v_fmaak_f32 v30, v104, v9, 0x4b400000
	v_perm_b32 v27, v29, v27, s23
	v_fmaak_f32 v31, v105, v9, 0x4b400000
	v_perm_b32 v27, v30, v27, s24
	v_perm_b32 v27, v31, v27, s25
	ds_write2_b32 v28, v26, v27 offset0:32 offset1:48
	v_fmaak_f32 v26, v106, v9, 0x4b400000
	v_fmaak_f32 v27, v107, v9, 0x4b400000
	v_fmaak_f32 v29, v108, v9, 0x4b400000
	v_perm_b32 v26, v27, v26, s23
	v_fmaak_f32 v30, v109, v9, 0x4b400000
	v_perm_b32 v26, v29, v26, s24
	v_fmaak_f32 v27, v110, v9, 0x4b400000
	v_fmaak_f32 v29, v111, v9, 0x4b400000
	v_perm_b32 v26, v30, v26, s25
	v_fmaak_f32 v30, v112, v9, 0x4b400000
	v_perm_b32 v27, v29, v27, s23
	v_fmaak_f32 v31, v113, v9, 0x4b400000
	v_perm_b32 v27, v30, v27, s24
	v_perm_b32 v27, v31, v27, s25
	ds_write2_b32 v28, v26, v27 offset0:64 offset1:80
	v_fmaak_f32 v26, v114, v9, 0x4b400000
	v_fmaak_f32 v27, v115, v9, 0x4b400000
	v_fmaak_f32 v29, v116, v9, 0x4b400000
	v_perm_b32 v26, v27, v26, s23
	v_fmaak_f32 v30, v117, v9, 0x4b400000
	v_perm_b32 v26, v29, v26, s24
	v_fmaak_f32 v27, v118, v9, 0x4b400000
	v_fmaak_f32 v29, v119, v9, 0x4b400000
	v_perm_b32 v26, v30, v26, s25
	v_fmaak_f32 v30, v120, v9, 0x4b400000
	v_perm_b32 v27, v29, v27, s23
	v_fmaak_f32 v31, v121, v9, 0x4b400000
	v_perm_b32 v27, v30, v27, s24
	v_perm_b32 v27, v31, v27, s25
	ds_write2_b32 v28, v26, v27 offset0:96 offset1:112
	v_fmaak_f32 v26, v122, v9, 0x4b400000
	v_fmaak_f32 v27, v123, v9, 0x4b400000
	v_fmaak_f32 v29, v124, v9, 0x4b400000
	v_perm_b32 v26, v27, v26, s23
	v_fmaak_f32 v30, v125, v9, 0x4b400000
	v_perm_b32 v26, v29, v26, s24
	v_fmaak_f32 v27, v126, v9, 0x4b400000
	v_fmaak_f32 v29, v127, v9, 0x4b400000
	v_perm_b32 v26, v30, v26, s25
	v_fmaak_f32 v30, v128, v9, 0x4b400000
	v_perm_b32 v27, v29, v27, s23
	v_fmaak_f32 v31, v129, v9, 0x4b400000
	v_perm_b32 v27, v30, v27, s24
	v_perm_b32 v27, v31, v27, s25
	ds_write2_b32 v28, v26, v27 offset0:128 offset1:144
	v_fmaak_f32 v26, v130, v9, 0x4b400000
	v_fmaak_f32 v27, v131, v9, 0x4b400000
	v_fmaak_f32 v29, v132, v9, 0x4b400000
	v_perm_b32 v26, v27, v26, s23
	v_fmaak_f32 v30, v133, v9, 0x4b400000
	v_perm_b32 v26, v29, v26, s24
	v_fmaak_f32 v27, v134, v9, 0x4b400000
	v_fmaak_f32 v29, v135, v9, 0x4b400000
	v_perm_b32 v26, v30, v26, s25
	v_fmaak_f32 v30, v136, v9, 0x4b400000
	v_perm_b32 v27, v29, v27, s23
	v_fmaak_f32 v31, v137, v9, 0x4b400000
	v_perm_b32 v27, v30, v27, s24
	v_perm_b32 v27, v31, v27, s25
	ds_write2_b32 v28, v26, v27 offset0:160 offset1:176
	v_fmaak_f32 v26, v138, v9, 0x4b400000
	v_fmaak_f32 v27, v139, v9, 0x4b400000
	v_fmaak_f32 v29, v140, v9, 0x4b400000
	v_perm_b32 v26, v27, v26, s23
	v_fmaak_f32 v30, v141, v9, 0x4b400000
	v_perm_b32 v26, v29, v26, s24
	v_fmaak_f32 v27, v142, v9, 0x4b400000
	v_fmaak_f32 v29, v143, v9, 0x4b400000
	v_perm_b32 v26, v30, v26, s25
	v_fmaak_f32 v30, v144, v9, 0x4b400000
	v_perm_b32 v27, v29, v27, s23
	v_fmaak_f32 v31, v145, v9, 0x4b400000
	v_perm_b32 v27, v30, v27, s24
	v_perm_b32 v27, v31, v27, s25
	ds_write2_b32 v28, v26, v27 offset0:192 offset1:208
	v_fmaak_f32 v26, v146, v9, 0x4b400000
	v_fmaak_f32 v27, v147, v9, 0x4b400000
	v_fmaak_f32 v29, v148, v9, 0x4b400000
	v_perm_b32 v26, v27, v26, s23
	v_fmaak_f32 v30, v149, v9, 0x4b400000
	v_perm_b32 v26, v29, v26, s24
	v_fmaak_f32 v27, v150, v9, 0x4b400000
	v_fmaak_f32 v29, v151, v9, 0x4b400000
	v_perm_b32 v26, v30, v26, s25
	v_fmaak_f32 v30, v152, v9, 0x4b400000
	v_fmaak_f32 v8, v8, v9, 0x4b400000
	v_perm_b32 v9, v29, v27, s23
	v_perm_b32 v9, v30, v9, s24
	v_perm_b32 v8, v8, v9, s25
	ds_write2_b32 v28, v26, v8 offset0:224 offset1:240
	v_add_u32_e32 v8, 0x800, v20
	s_waitcnt lgkmcnt(0)
	s_barrier
	v_add_u32_e32 v9, 0x808, v20
	ds_read2_b32 v[26:27], v8 offset1:1
	ds_read2_b32 v[28:29], v9 offset1:1
	v_or_b32_e32 v8, s28, v12
	v_ashrrev_i32_e32 v9, 31, v8
	s_addc_u32 s9, s11, s29
	v_lshlrev_b64 v[8:9], 11, v[8:9]
	v_lshl_add_u64 v[8:9], s[8:9], 0, v[8:9]
	v_lshl_add_u64 v[8:9], v[8:9], 0, v[4:5]
	v_add_u32_e32 v30, 0x800, v21
	v_add_u32_e32 v32, 0x808, v21
	ds_read2_b32 v[30:31], v30 offset1:1
	ds_read2_b32 v[32:33], v32 offset1:1
	s_waitcnt lgkmcnt(2)
	global_store_dwordx4 v[8:9], v[26:29], off sc1
	v_or_b32_e32 v8, s28, v13
	v_ashrrev_i32_e32 v9, 31, v8
	v_lshlrev_b64 v[8:9], 11, v[8:9]
	v_lshl_add_u64 v[8:9], s[8:9], 0, v[8:9]
	v_lshl_add_u64 v[8:9], v[8:9], 0, v[4:5]
	s_waitcnt lgkmcnt(0)
	global_store_dwordx4 v[8:9], v[30:33], off sc1
	v_add_u32_e32 v8, 0x4820, v20
	v_add_u32_e32 v9, 0x4828, v20
	ds_read2_b32 v[26:27], v8 offset1:1
	ds_read2_b32 v[28:29], v9 offset1:1
	v_or_b32_e32 v8, s28, v14
	v_ashrrev_i32_e32 v9, 31, v8
	v_lshlrev_b64 v[8:9], 11, v[8:9]
	v_lshl_add_u64 v[8:9], s[8:9], 0, v[8:9]
	v_lshl_add_u64 v[8:9], v[8:9], 0, v[4:5]
	v_add_u32_e32 v30, 0x800, v22
	v_add_u32_e32 v32, 0x808, v22
	ds_read2_b32 v[30:31], v30 offset1:1
	ds_read2_b32 v[32:33], v32 offset1:1
	s_waitcnt lgkmcnt(2)
	global_store_dwordx4 v[8:9], v[26:29], off sc1
	v_or_b32_e32 v8, s28, v15
	v_ashrrev_i32_e32 v9, 31, v8
	v_lshlrev_b64 v[8:9], 11, v[8:9]
	v_lshl_add_u64 v[8:9], s[8:9], 0, v[8:9]
	v_lshl_add_u64 v[8:9], v[8:9], 0, v[4:5]
	s_waitcnt lgkmcnt(0)
	global_store_dwordx4 v[8:9], v[30:33], off sc1
	v_add_u32_e32 v8, 0x8840, v20
	v_add_u32_e32 v9, 0x8848, v20
	ds_read2_b32 v[26:27], v8 offset1:1
	ds_read2_b32 v[28:29], v9 offset1:1
	v_or_b32_e32 v8, s28, v16
	v_ashrrev_i32_e32 v9, 31, v8
	v_lshlrev_b64 v[8:9], 11, v[8:9]
	v_lshl_add_u64 v[8:9], s[8:9], 0, v[8:9]
	v_lshl_add_u64 v[8:9], v[8:9], 0, v[4:5]
	v_add_u32_e32 v30, 0x800, v23
	v_add_u32_e32 v32, 0x808, v23
	ds_read2_b32 v[30:31], v30 offset1:1
	ds_read2_b32 v[32:33], v32 offset1:1
	s_waitcnt lgkmcnt(2)
	global_store_dwordx4 v[8:9], v[26:29], off sc1
	v_or_b32_e32 v8, s28, v17
	v_ashrrev_i32_e32 v9, 31, v8
	v_lshlrev_b64 v[8:9], 11, v[8:9]
	v_lshl_add_u64 v[8:9], s[8:9], 0, v[8:9]
	v_lshl_add_u64 v[8:9], v[8:9], 0, v[4:5]
	s_waitcnt lgkmcnt(0)
	global_store_dwordx4 v[8:9], v[30:33], off sc1
	v_add_u32_e32 v8, 0xc860, v20
	v_add_u32_e32 v9, 0xc868, v20
	ds_read2_b32 v[26:27], v8 offset1:1
	ds_read2_b32 v[28:29], v9 offset1:1
	v_or_b32_e32 v8, s28, v18
	v_ashrrev_i32_e32 v9, 31, v8
	v_lshlrev_b64 v[8:9], 11, v[8:9]
	v_lshl_add_u64 v[8:9], s[8:9], 0, v[8:9]
	v_lshl_add_u64 v[8:9], v[8:9], 0, v[4:5]
	v_add_u32_e32 v30, 0x800, v24
	v_add_u32_e32 v32, 0x808, v24
	ds_read2_b32 v[30:31], v30 offset1:1
	ds_read2_b32 v[32:33], v32 offset1:1
	s_waitcnt lgkmcnt(2)
	global_store_dwordx4 v[8:9], v[26:29], off sc1
	v_add_u32_e32 v8, s28, v19
	v_ashrrev_i32_e32 v9, 31, v8
	v_lshlrev_b64 v[8:9], 11, v[8:9]
	v_lshl_add_u64 v[8:9], s[8:9], 0, v[8:9]
	s_add_i32 s26, s26, s90
	s_add_i32 s14, s14, s15
	v_lshl_add_u64 v[8:9], v[8:9], 0, v[4:5]
	s_cmpk_lt_i32 s26, 0xb00
	s_waitcnt lgkmcnt(0)
	global_store_dwordx4 v[8:9], v[30:33], off sc1
	s_barrier
	s_cbranch_scc0 .LBB0_19

.LBB0_21:
	s_mul_hi_i32 s8, s7, 0x66666667
	s_lshr_b32 s9, s8, 31
	s_ashr_i32 s8, s8, 5
	s_add_i32 s8, s8, s9
	s_mul_i32 s9, s8, 0xfffff600
	s_lshl_b32 s8, s8, 6
	s_add_i32 s10, s4, s9
	v_or_b32_e32 v26, s8, v1
	s_ashr_i32 s11, s10, 31
	v_or_b32_e32 v28, 8, v26
	v_or_b32_e32 v30, 16, v26
	v_or_b32_e32 v31, 24, v26
	v_or_b32_e32 v34, 32, v26
	v_or_b32_e32 v35, 40, v26
	v_or_b32_e32 v38, 48, v26
	v_or_b32_e32 v39, 56, v26
	v_lshl_add_u64 v[24:25], s[10:11], 2, v[6:7]
	v_mad_i64_i32 v[26:27], s[12:13], v26, s6, v[24:25]
	v_mad_i64_i32 v[28:29], s[12:13], v28, s6, v[24:25]
	v_mad_i64_i32 v[32:33], s[12:13], v30, s6, v[24:25]
	v_mad_i64_i32 v[36:37], s[12:13], v31, s6, v[24:25]
	v_mad_i64_i32 v[40:41], s[12:13], v34, s6, v[24:25]
	v_mad_i64_i32 v[44:45], s[12:13], v35, s6, v[24:25]
	v_mad_i64_i32 v[48:49], s[12:13], v38, s6, v[24:25]
	v_mad_i64_i32 v[52:53], s[12:13], v39, s6, v[24:25]
	global_load_dwordx4 v[24:27], v[26:27], off nt
	s_nop 0
	global_load_dwordx4 v[28:31], v[28:29], off nt
	s_nop 0
	global_load_dwordx4 v[32:35], v[32:33], off nt
	s_nop 0
	global_load_dwordx4 v[36:39], v[36:37], off nt
	s_nop 0
	global_load_dwordx4 v[40:43], v[40:41], off nt
	s_nop 0
	global_load_dwordx4 v[44:47], v[44:45], off nt
	s_nop 0
	global_load_dwordx4 v[48:51], v[48:49], off nt
	s_nop 0
	global_load_dwordx4 v[52:55], v[52:53], off nt
	v_add_u32_e32 v58, s10, v1
	s_ashr_i32 s9, s8, 31
	v_ashrrev_i32_e32 v59, 31, v58
	v_lshl_add_u64 v[56:57], s[8:9], 1, v[8:9]
	v_lshlrev_b64 v[64:65], 12, v[58:59]
	v_add_u32_e32 v60, 8, v58
	v_lshl_add_u64 v[64:65], v[56:57], 0, v[64:65]
	v_ashrrev_i32_e32 v61, 31, v60
	v_lshlrev_b64 v[60:61], 12, v[60:61]
	v_add_u32_e32 v62, 16, v58
	v_lshl_add_u64 v[60:61], v[56:57], 0, v[60:61]
	v_ashrrev_i32_e32 v63, 31, v62
	v_lshlrev_b64 v[62:63], 12, v[62:63]
	v_lshl_add_u64 v[62:63], v[56:57], 0, v[62:63]
	s_add_i32 s7, s7, s28
	s_add_i32 s4, s4, s5
	s_cmpk_lt_i32 s7, 0xa00
	s_waitcnt vmcnt(7)
	ds_write2_b32 v11, v24, v25 offset1:1
	ds_write2_b32 v11, v26, v27 offset0:2 offset1:3
	s_waitcnt vmcnt(6)
	ds_write2_b32 v3, v28, v29 offset1:1
	ds_write2_b32 v5, v30, v31 offset1:1
	s_waitcnt vmcnt(5)
	ds_write2_b32 v12, v32, v33 offset1:1
	ds_write2_b32 v13, v34, v35 offset1:1
	s_waitcnt vmcnt(4)
	ds_write2_b32 v14, v36, v37 offset1:1
	ds_write2_b32 v15, v38, v39 offset1:1
	s_waitcnt vmcnt(3)
	ds_write2_b32 v16, v40, v41 offset1:1
	ds_write2_b32 v17, v42, v43 offset1:1
	s_waitcnt vmcnt(2)
	ds_write2_b32 v18, v44, v45 offset1:1
	ds_write2_b32 v19, v46, v47 offset1:1
	s_waitcnt vmcnt(1)
	ds_write2_b32 v20, v48, v49 offset1:1
	ds_write2_b32 v21, v50, v51 offset1:1
	s_waitcnt vmcnt(0)
	ds_write2_b32 v22, v52, v53 offset1:1
	ds_write2_b32 v23, v54, v55 offset1:1
	s_waitcnt lgkmcnt(0)
	ds_read2_b32 v[24:25], v10 offset1:33
	s_waitcnt lgkmcnt(0)
	v_cvt_pk_bf16_f32 v24, v24, v25
	ds_read2_b32 v[26:27], v10 offset0:66 offset1:99
	s_waitcnt lgkmcnt(0)
	v_cvt_pk_bf16_f32 v25, v26, v27
	ds_read2_b32 v[26:27], v10 offset0:132 offset1:165
	s_waitcnt lgkmcnt(0)
	v_cvt_pk_bf16_f32 v26, v26, v27
	ds_read2_b32 v[28:29], v10 offset0:198 offset1:231
	s_waitcnt lgkmcnt(0)
	v_cvt_pk_bf16_f32 v27, v28, v29
	ds_read2_b32 v[28:29], v10 offset0:8 offset1:41
	global_store_dwordx4 v[64:65], v[24:27], off sc1
	v_add_u32_e32 v30, 24, v58
	v_ashrrev_i32_e32 v31, 31, v30
	s_waitcnt lgkmcnt(0)
	v_cvt_pk_bf16_f32 v24, v28, v29
	ds_read2_b32 v[26:27], v10 offset0:74 offset1:107
	s_waitcnt lgkmcnt(0)
	v_cvt_pk_bf16_f32 v25, v26, v27
	ds_read2_b32 v[26:27], v10 offset0:140 offset1:173
	s_waitcnt lgkmcnt(0)
	v_cvt_pk_bf16_f32 v26, v26, v27
	ds_read2_b32 v[28:29], v10 offset0:206 offset1:239
	s_waitcnt lgkmcnt(0)
	v_cvt_pk_bf16_f32 v27, v28, v29
	ds_read2_b32 v[28:29], v10 offset0:16 offset1:49
	global_store_dwordx4 v[60:61], v[24:27], off sc1
	v_lshlrev_b64 v[30:31], 12, v[30:31]
	v_lshl_add_u64 v[30:31], v[56:57], 0, v[30:31]
	s_waitcnt lgkmcnt(0)
	v_cvt_pk_bf16_f32 v24, v28, v29
	ds_read2_b32 v[26:27], v10 offset0:82 offset1:115
	s_waitcnt lgkmcnt(0)
	v_cvt_pk_bf16_f32 v25, v26, v27
	ds_read2_b32 v[26:27], v10 offset0:148 offset1:181
	s_waitcnt lgkmcnt(0)
	v_cvt_pk_bf16_f32 v26, v26, v27
	ds_read2_b32 v[28:29], v10 offset0:214 offset1:247
	s_waitcnt lgkmcnt(0)
	v_cvt_pk_bf16_f32 v27, v28, v29
	ds_read2_b32 v[28:29], v10 offset0:24 offset1:57
	global_store_dwordx4 v[62:63], v[24:27], off sc1
	s_waitcnt lgkmcnt(0)
	s_nop 0
	v_cvt_pk_bf16_f32 v24, v28, v29
	ds_read2_b32 v[26:27], v10 offset0:90 offset1:123
	s_waitcnt lgkmcnt(0)
	v_cvt_pk_bf16_f32 v25, v26, v27
	ds_read2_b32 v[26:27], v10 offset0:156 offset1:189
	s_waitcnt lgkmcnt(0)
	v_cvt_pk_bf16_f32 v26, v26, v27
	ds_read2_b32 v[28:29], v10 offset0:222 offset1:255
	s_waitcnt lgkmcnt(0)
	v_cvt_pk_bf16_f32 v27, v28, v29
	global_store_dwordx4 v[30:31], v[24:27], off sc1
	s_waitcnt lgkmcnt(0)
	s_cbranch_scc1 .LBB0_21

.LBB0_24:
	s_ashr_i32 s6, s12, 31
	s_lshr_b32 s6, s6, 26
	s_add_i32 s6, s12, s6
	s_lshl_b32 s7, s6, 5
	s_and_b32 s8, s6, 0xffffffc0
	s_and_b32 s6, s7, 0xfffff800
	v_or_b32_e32 v24, s8, v1
	s_sub_i32 s6, s10, s6
	v_or_b32_e32 v26, 8, v24
	v_or_b32_e32 v28, 16, v24
	v_or_b32_e32 v30, 24, v24
	v_or_b32_e32 v32, 32, v24
	v_or_b32_e32 v34, 40, v24
	v_or_b32_e32 v36, 48, v24
	v_or_b32_e32 v38, 56, v24
	v_ashrrev_i32_e32 v25, 31, v24
	s_ashr_i32 s7, s6, 31
	v_ashrrev_i32_e32 v27, 31, v26
	v_ashrrev_i32_e32 v29, 31, v28
	v_ashrrev_i32_e32 v31, 31, v30
	v_ashrrev_i32_e32 v33, 31, v32
	v_ashrrev_i32_e32 v35, 31, v34
	v_ashrrev_i32_e32 v37, 31, v36
	v_ashrrev_i32_e32 v39, 31, v38
	v_lshlrev_b64 v[24:25], 13, v[24:25]
	v_lshl_add_u64 v[40:41], s[6:7], 2, v[6:7]
	v_lshlrev_b64 v[26:27], 13, v[26:27]
	v_lshlrev_b64 v[28:29], 13, v[28:29]
	v_lshlrev_b64 v[30:31], 13, v[30:31]
	v_lshlrev_b64 v[32:33], 13, v[32:33]
	v_lshlrev_b64 v[34:35], 13, v[34:35]
	v_lshlrev_b64 v[36:37], 13, v[36:37]
	v_lshlrev_b64 v[38:39], 13, v[38:39]
	v_lshl_add_u64 v[24:25], v[40:41], 0, v[24:25]
	v_lshl_add_u64 v[42:43], v[40:41], 0, v[26:27]
	v_lshl_add_u64 v[44:45], v[40:41], 0, v[28:29]
	v_lshl_add_u64 v[46:47], v[40:41], 0, v[30:31]
	v_lshl_add_u64 v[48:49], v[40:41], 0, v[32:33]
	v_lshl_add_u64 v[50:51], v[40:41], 0, v[34:35]
	v_lshl_add_u64 v[52:53], v[40:41], 0, v[36:37]
	v_lshl_add_u64 v[54:55], v[40:41], 0, v[38:39]
	global_load_dwordx4 v[24:27], v[24:25], off nt
	s_nop 0
	global_load_dwordx4 v[28:31], v[42:43], off nt
	global_load_dwordx4 v[32:35], v[44:45], off nt
	global_load_dwordx4 v[36:39], v[46:47], off nt
	s_nop 0
	global_load_dwordx4 v[40:43], v[48:49], off nt
	global_load_dwordx4 v[44:47], v[50:51], off nt
	s_nop 0
	global_load_dwordx4 v[48:51], v[52:53], off nt
	s_nop 0
	global_load_dwordx4 v[52:55], v[54:55], off nt
	v_add_u32_e32 v58, s6, v1
	s_ashr_i32 s9, s8, 31
	v_ashrrev_i32_e32 v59, 31, v58
	v_lshl_add_u64 v[56:57], s[8:9], 1, v[8:9]
	v_lshlrev_b64 v[64:65], 12, v[58:59]
	v_add_u32_e32 v60, 8, v58
	v_lshl_add_u64 v[64:65], v[56:57], 0, v[64:65]
	v_ashrrev_i32_e32 v61, 31, v60
	v_lshlrev_b64 v[60:61], 12, v[60:61]
	v_add_u32_e32 v62, 16, v58
	v_lshl_add_u64 v[60:61], v[56:57], 0, v[60:61]
	v_ashrrev_i32_e32 v63, 31, v62
	v_lshlrev_b64 v[62:63], 12, v[62:63]
	v_lshl_add_u64 v[62:63], v[56:57], 0, v[62:63]
	s_add_i32 s12, s12, s28
	s_add_i32 s10, s10, s11
	s_cmpk_lt_i32 s12, 0x800
	s_waitcnt vmcnt(7)
	ds_write2_b32 v11, v24, v25 offset1:1
	ds_write2_b32 v11, v26, v27 offset0:2 offset1:3
	s_waitcnt vmcnt(6)
	ds_write2_b32 v3, v28, v29 offset1:1
	ds_write2_b32 v5, v30, v31 offset1:1
	s_waitcnt vmcnt(5)
	ds_write2_b32 v12, v32, v33 offset1:1
	ds_write2_b32 v13, v34, v35 offset1:1
	s_waitcnt vmcnt(4)
	ds_write2_b32 v14, v36, v37 offset1:1
	ds_write2_b32 v15, v38, v39 offset1:1
	s_waitcnt vmcnt(3)
	ds_write2_b32 v16, v40, v41 offset1:1
	ds_write2_b32 v17, v42, v43 offset1:1
	s_waitcnt vmcnt(2)
	ds_write2_b32 v18, v44, v45 offset1:1
	ds_write2_b32 v19, v46, v47 offset1:1
	s_waitcnt vmcnt(1)
	ds_write2_b32 v20, v48, v49 offset1:1
	ds_write2_b32 v21, v50, v51 offset1:1
	s_waitcnt vmcnt(0)
	ds_write2_b32 v22, v52, v53 offset1:1
	ds_write2_b32 v23, v54, v55 offset1:1
	s_waitcnt lgkmcnt(0)
	ds_read2_b32 v[24:25], v10 offset1:33
	s_waitcnt lgkmcnt(0)
	v_cvt_pk_bf16_f32 v24, v24, v25
	ds_read2_b32 v[26:27], v10 offset0:66 offset1:99
	s_waitcnt lgkmcnt(0)
	v_cvt_pk_bf16_f32 v25, v26, v27
	ds_read2_b32 v[26:27], v10 offset0:132 offset1:165
	s_waitcnt lgkmcnt(0)
	v_cvt_pk_bf16_f32 v26, v26, v27
	ds_read2_b32 v[28:29], v10 offset0:198 offset1:231
	s_waitcnt lgkmcnt(0)
	v_cvt_pk_bf16_f32 v27, v28, v29
	ds_read2_b32 v[28:29], v10 offset0:8 offset1:41
	global_store_dwordx4 v[64:65], v[24:27], off sc1
	v_add_u32_e32 v30, 24, v58
	v_ashrrev_i32_e32 v31, 31, v30
	s_waitcnt lgkmcnt(0)
	v_cvt_pk_bf16_f32 v24, v28, v29
	ds_read2_b32 v[26:27], v10 offset0:74 offset1:107
	s_waitcnt lgkmcnt(0)
	v_cvt_pk_bf16_f32 v25, v26, v27
	ds_read2_b32 v[26:27], v10 offset0:140 offset1:173
	s_waitcnt lgkmcnt(0)
	v_cvt_pk_bf16_f32 v26, v26, v27
	ds_read2_b32 v[28:29], v10 offset0:206 offset1:239
	s_waitcnt lgkmcnt(0)
	v_cvt_pk_bf16_f32 v27, v28, v29
	ds_read2_b32 v[28:29], v10 offset0:16 offset1:49
	global_store_dwordx4 v[60:61], v[24:27], off sc1
	v_lshlrev_b64 v[30:31], 12, v[30:31]
	v_lshl_add_u64 v[30:31], v[56:57], 0, v[30:31]
	s_waitcnt lgkmcnt(0)
	v_cvt_pk_bf16_f32 v24, v28, v29
	ds_read2_b32 v[26:27], v10 offset0:82 offset1:115
	s_waitcnt lgkmcnt(0)
	v_cvt_pk_bf16_f32 v25, v26, v27
	ds_read2_b32 v[26:27], v10 offset0:148 offset1:181
	s_waitcnt lgkmcnt(0)
	v_cvt_pk_bf16_f32 v26, v26, v27
	ds_read2_b32 v[28:29], v10 offset0:214 offset1:247
	s_waitcnt lgkmcnt(0)
	v_cvt_pk_bf16_f32 v27, v28, v29
	ds_read2_b32 v[28:29], v10 offset0:24 offset1:57
	global_store_dwordx4 v[62:63], v[24:27], off sc1
	s_waitcnt lgkmcnt(0)
	s_nop 0
	v_cvt_pk_bf16_f32 v24, v28, v29
	ds_read2_b32 v[26:27], v10 offset0:90 offset1:123
	s_waitcnt lgkmcnt(0)
	v_cvt_pk_bf16_f32 v25, v26, v27
	ds_read2_b32 v[26:27], v10 offset0:156 offset1:189
	s_waitcnt lgkmcnt(0)
	v_cvt_pk_bf16_f32 v26, v26, v27
	ds_read2_b32 v[28:29], v10 offset0:222 offset1:255
	s_waitcnt lgkmcnt(0)
	v_cvt_pk_bf16_f32 v27, v28, v29
	global_store_dwordx4 v[30:31], v[24:27], off sc1
	s_waitcnt lgkmcnt(0)
	s_cbranch_scc1 .LBB0_24

.LBB0_27:
	s_ashr_i32 s6, s12, 31
	s_lshr_b32 s6, s6, 25
	s_add_i32 s6, s12, s6
	s_ashr_i32 s6, s6, 7
	s_lshl_b32 s8, s6, 6
	s_lshl_b32 s7, s6, 12
	v_or_b32_e32 v24, s8, v1
	s_sub_i32 s6, s10, s7
	v_or_b32_e32 v26, 8, v24
	v_or_b32_e32 v28, 16, v24
	v_or_b32_e32 v30, 24, v24
	v_or_b32_e32 v32, 32, v24
	v_or_b32_e32 v34, 40, v24
	v_or_b32_e32 v36, 48, v24
	v_or_b32_e32 v38, 56, v24
	s_ashr_i32 s7, s6, 31
	v_ashrrev_i32_e32 v25, 31, v24
	v_ashrrev_i32_e32 v27, 31, v26
	v_ashrrev_i32_e32 v29, 31, v28
	v_ashrrev_i32_e32 v31, 31, v30
	v_ashrrev_i32_e32 v33, 31, v32
	v_ashrrev_i32_e32 v35, 31, v34
	v_ashrrev_i32_e32 v37, 31, v36
	v_ashrrev_i32_e32 v39, 31, v38
	v_lshl_add_u64 v[40:41], s[6:7], 2, v[6:7]
	v_lshlrev_b64 v[24:25], 14, v[24:25]
	v_lshlrev_b64 v[42:43], 14, v[26:27]
	v_lshlrev_b64 v[28:29], 14, v[28:29]
	v_lshlrev_b64 v[30:31], 14, v[30:31]
	v_lshlrev_b64 v[32:33], 14, v[32:33]
	v_lshlrev_b64 v[34:35], 14, v[34:35]
	v_lshlrev_b64 v[36:37], 14, v[36:37]
	v_lshlrev_b64 v[38:39], 14, v[38:39]
	v_lshl_add_u64 v[24:25], v[40:41], 0, v[24:25]
	v_lshl_add_u64 v[42:43], v[40:41], 0, v[42:43]
	v_lshl_add_u64 v[44:45], v[40:41], 0, v[28:29]
	v_lshl_add_u64 v[46:47], v[40:41], 0, v[30:31]
	v_lshl_add_u64 v[48:49], v[40:41], 0, v[32:33]
	v_lshl_add_u64 v[50:51], v[40:41], 0, v[34:35]
	v_lshl_add_u64 v[52:53], v[40:41], 0, v[36:37]
	v_lshl_add_u64 v[54:55], v[40:41], 0, v[38:39]
	global_load_dwordx4 v[24:27], v[24:25], off nt
	s_nop 0
	global_load_dwordx4 v[28:31], v[42:43], off nt
	global_load_dwordx4 v[32:35], v[44:45], off nt
	global_load_dwordx4 v[36:39], v[46:47], off nt
	s_nop 0
	global_load_dwordx4 v[40:43], v[48:49], off nt
	global_load_dwordx4 v[44:47], v[50:51], off nt
	s_nop 0
	global_load_dwordx4 v[48:51], v[52:53], off nt
	s_nop 0
	global_load_dwordx4 v[52:55], v[54:55], off nt
	v_add_u32_e32 v58, s6, v1
	s_ashr_i32 s9, s8, 31
	v_ashrrev_i32_e32 v59, 31, v58
	v_lshl_add_u64 v[56:57], s[8:9], 1, v[8:9]
	v_lshlrev_b64 v[64:65], 12, v[58:59]
	v_add_u32_e32 v60, 8, v58
	v_lshl_add_u64 v[64:65], v[56:57], 0, v[64:65]
	v_ashrrev_i32_e32 v61, 31, v60
	v_lshlrev_b64 v[60:61], 12, v[60:61]
	v_add_u32_e32 v62, 16, v58
	v_lshl_add_u64 v[60:61], v[56:57], 0, v[60:61]
	v_ashrrev_i32_e32 v63, 31, v62
	v_lshlrev_b64 v[62:63], 12, v[62:63]
	v_lshl_add_u64 v[62:63], v[56:57], 0, v[62:63]
	s_add_i32 s12, s12, s28
	s_add_i32 s10, s10, s11
	s_cmpk_lt_i32 s12, 0x1000
	s_waitcnt vmcnt(7)
	ds_write2_b32 v11, v24, v25 offset1:1
	ds_write2_b32 v11, v26, v27 offset0:2 offset1:3
	s_waitcnt vmcnt(6)
	ds_write2_b32 v3, v28, v29 offset1:1
	ds_write2_b32 v5, v30, v31 offset1:1
	s_waitcnt vmcnt(5)
	ds_write2_b32 v12, v32, v33 offset1:1
	ds_write2_b32 v13, v34, v35 offset1:1
	s_waitcnt vmcnt(4)
	ds_write2_b32 v14, v36, v37 offset1:1
	ds_write2_b32 v15, v38, v39 offset1:1
	s_waitcnt vmcnt(3)
	ds_write2_b32 v16, v40, v41 offset1:1
	ds_write2_b32 v17, v42, v43 offset1:1
	s_waitcnt vmcnt(2)
	ds_write2_b32 v18, v44, v45 offset1:1
	ds_write2_b32 v19, v46, v47 offset1:1
	s_waitcnt vmcnt(1)
	ds_write2_b32 v20, v48, v49 offset1:1
	ds_write2_b32 v21, v50, v51 offset1:1
	s_waitcnt vmcnt(0)
	ds_write2_b32 v22, v52, v53 offset1:1
	ds_write2_b32 v23, v54, v55 offset1:1
	s_waitcnt lgkmcnt(0)
	ds_read2_b32 v[24:25], v10 offset1:33
	s_waitcnt lgkmcnt(0)
	v_cvt_pk_bf16_f32 v24, v24, v25
	ds_read2_b32 v[26:27], v10 offset0:66 offset1:99
	s_waitcnt lgkmcnt(0)
	v_cvt_pk_bf16_f32 v25, v26, v27
	ds_read2_b32 v[26:27], v10 offset0:132 offset1:165
	s_waitcnt lgkmcnt(0)
	v_cvt_pk_bf16_f32 v26, v26, v27
	ds_read2_b32 v[28:29], v10 offset0:198 offset1:231
	s_waitcnt lgkmcnt(0)
	v_cvt_pk_bf16_f32 v27, v28, v29
	ds_read2_b32 v[28:29], v10 offset0:8 offset1:41
	global_store_dwordx4 v[64:65], v[24:27], off sc1
	v_add_u32_e32 v30, 24, v58
	v_ashrrev_i32_e32 v31, 31, v30
	s_waitcnt lgkmcnt(0)
	v_cvt_pk_bf16_f32 v24, v28, v29
	ds_read2_b32 v[26:27], v10 offset0:74 offset1:107
	s_waitcnt lgkmcnt(0)
	v_cvt_pk_bf16_f32 v25, v26, v27
	ds_read2_b32 v[26:27], v10 offset0:140 offset1:173
	s_waitcnt lgkmcnt(0)
	v_cvt_pk_bf16_f32 v26, v26, v27
	ds_read2_b32 v[28:29], v10 offset0:206 offset1:239
	s_waitcnt lgkmcnt(0)
	v_cvt_pk_bf16_f32 v27, v28, v29
	ds_read2_b32 v[28:29], v10 offset0:16 offset1:49
	global_store_dwordx4 v[60:61], v[24:27], off sc1
	v_lshlrev_b64 v[30:31], 12, v[30:31]
	v_lshl_add_u64 v[30:31], v[56:57], 0, v[30:31]
	s_waitcnt lgkmcnt(0)
	v_cvt_pk_bf16_f32 v24, v28, v29
	ds_read2_b32 v[26:27], v10 offset0:82 offset1:115
	s_waitcnt lgkmcnt(0)
	v_cvt_pk_bf16_f32 v25, v26, v27
	ds_read2_b32 v[26:27], v10 offset0:148 offset1:181
	s_waitcnt lgkmcnt(0)
	v_cvt_pk_bf16_f32 v26, v26, v27
	ds_read2_b32 v[28:29], v10 offset0:214 offset1:247
	s_waitcnt lgkmcnt(0)
	v_cvt_pk_bf16_f32 v27, v28, v29
	ds_read2_b32 v[28:29], v10 offset0:24 offset1:57
	global_store_dwordx4 v[62:63], v[24:27], off sc1
	s_waitcnt lgkmcnt(0)
	s_nop 0
	v_cvt_pk_bf16_f32 v24, v28, v29
	ds_read2_b32 v[26:27], v10 offset0:90 offset1:123
	s_waitcnt lgkmcnt(0)
	v_cvt_pk_bf16_f32 v25, v26, v27
	ds_read2_b32 v[26:27], v10 offset0:156 offset1:189
	s_waitcnt lgkmcnt(0)
	v_cvt_pk_bf16_f32 v26, v26, v27
	ds_read2_b32 v[28:29], v10 offset0:222 offset1:255
	s_waitcnt lgkmcnt(0)
	v_cvt_pk_bf16_f32 v27, v28, v29
	global_store_dwordx4 v[30:31], v[24:27], off sc1
	s_waitcnt lgkmcnt(0)
	s_cbranch_scc1 .LBB0_27

.LBB0_30:
	s_ashr_i32 s4, s10, 31
	s_lshr_b32 s4, s4, 26
	s_add_i32 s4, s10, s4
	s_lshl_b32 s5, s4, 5
	s_and_b32 s6, s4, 0xffffffc0
	s_and_b32 s4, s5, 0xfffff800
	v_or_b32_e32 v22, s6, v1
	s_sub_i32 s4, s8, s4
	v_or_b32_e32 v24, 8, v22
	v_or_b32_e32 v26, 16, v22
	v_or_b32_e32 v28, 24, v22
	v_or_b32_e32 v30, 32, v22
	v_or_b32_e32 v32, 40, v22
	v_or_b32_e32 v34, 48, v22
	v_or_b32_e32 v36, 56, v22
	v_ashrrev_i32_e32 v23, 31, v22
	s_ashr_i32 s5, s4, 31
	v_ashrrev_i32_e32 v25, 31, v24
	v_ashrrev_i32_e32 v27, 31, v26
	v_ashrrev_i32_e32 v29, 31, v28
	v_ashrrev_i32_e32 v31, 31, v30
	v_ashrrev_i32_e32 v33, 31, v32
	v_ashrrev_i32_e32 v35, 31, v34
	v_ashrrev_i32_e32 v37, 31, v36
	v_lshlrev_b64 v[22:23], 13, v[22:23]
	v_lshl_add_u64 v[38:39], s[4:5], 2, v[6:7]
	v_lshlrev_b64 v[24:25], 13, v[24:25]
	v_lshlrev_b64 v[26:27], 13, v[26:27]
	v_lshlrev_b64 v[28:29], 13, v[28:29]
	v_lshlrev_b64 v[30:31], 13, v[30:31]
	v_lshlrev_b64 v[32:33], 13, v[32:33]
	v_lshlrev_b64 v[34:35], 13, v[34:35]
	v_lshlrev_b64 v[36:37], 13, v[36:37]
	v_lshl_add_u64 v[22:23], v[38:39], 0, v[22:23]
	v_lshl_add_u64 v[40:41], v[38:39], 0, v[24:25]
	v_lshl_add_u64 v[42:43], v[38:39], 0, v[26:27]
	v_lshl_add_u64 v[44:45], v[38:39], 0, v[28:29]
	v_lshl_add_u64 v[46:47], v[38:39], 0, v[30:31]
	v_lshl_add_u64 v[48:49], v[38:39], 0, v[32:33]
	v_lshl_add_u64 v[50:51], v[38:39], 0, v[34:35]
	v_lshl_add_u64 v[52:53], v[38:39], 0, v[36:37]
	global_load_dwordx4 v[22:25], v[22:23], off nt
	s_nop 0
	global_load_dwordx4 v[26:29], v[40:41], off nt
	global_load_dwordx4 v[30:33], v[42:43], off nt
	global_load_dwordx4 v[34:37], v[44:45], off nt
	s_nop 0
	global_load_dwordx4 v[38:41], v[46:47], off nt
	global_load_dwordx4 v[42:45], v[48:49], off nt
	s_nop 0
	global_load_dwordx4 v[46:49], v[50:51], off nt
	s_nop 0
	global_load_dwordx4 v[50:53], v[52:53], off nt
	v_add_u32_e32 v56, s4, v1
	s_ashr_i32 s7, s6, 31
	v_ashrrev_i32_e32 v57, 31, v56
	v_lshl_add_u64 v[54:55], s[6:7], 1, v[2:3]
	v_lshlrev_b64 v[62:63], 12, v[56:57]
	v_add_u32_e32 v58, 8, v56
	v_lshl_add_u64 v[62:63], v[54:55], 0, v[62:63]
	v_ashrrev_i32_e32 v59, 31, v58
	v_lshlrev_b64 v[58:59], 12, v[58:59]
	v_add_u32_e32 v60, 16, v56
	v_lshl_add_u64 v[58:59], v[54:55], 0, v[58:59]
	v_ashrrev_i32_e32 v61, 31, v60
	v_lshlrev_b64 v[60:61], 12, v[60:61]
	v_lshl_add_u64 v[60:61], v[54:55], 0, v[60:61]
	s_add_i32 s10, s10, s28
	s_add_i32 s8, s8, s9
	s_cmpk_lt_i32 s10, 0x800
	s_waitcnt vmcnt(7)
	ds_write2_b32 v11, v22, v23 offset1:1
	ds_write2_b32 v11, v24, v25 offset0:2 offset1:3
	s_waitcnt vmcnt(6)
	ds_write2_b32 v4, v26, v27 offset1:1
	ds_write2_b32 v5, v28, v29 offset1:1
	s_waitcnt vmcnt(5)
	ds_write2_b32 v8, v30, v31 offset1:1
	ds_write2_b32 v9, v32, v33 offset1:1
	s_waitcnt vmcnt(4)
	ds_write2_b32 v12, v34, v35 offset1:1
	ds_write2_b32 v13, v36, v37 offset1:1
	s_waitcnt vmcnt(3)
	ds_write2_b32 v14, v38, v39 offset1:1
	ds_write2_b32 v15, v40, v41 offset1:1
	s_waitcnt vmcnt(2)
	ds_write2_b32 v16, v42, v43 offset1:1
	ds_write2_b32 v17, v44, v45 offset1:1
	s_waitcnt vmcnt(1)
	ds_write2_b32 v18, v46, v47 offset1:1
	ds_write2_b32 v19, v48, v49 offset1:1
	s_waitcnt vmcnt(0)
	ds_write2_b32 v20, v50, v51 offset1:1
	ds_write2_b32 v21, v52, v53 offset1:1
	s_waitcnt lgkmcnt(0)
	ds_read2_b32 v[22:23], v10 offset1:33
	s_waitcnt lgkmcnt(0)
	v_cvt_pk_bf16_f32 v22, v22, v23
	ds_read2_b32 v[24:25], v10 offset0:66 offset1:99
	s_waitcnt lgkmcnt(0)
	v_cvt_pk_bf16_f32 v23, v24, v25
	ds_read2_b32 v[24:25], v10 offset0:132 offset1:165
	s_waitcnt lgkmcnt(0)
	v_cvt_pk_bf16_f32 v24, v24, v25
	ds_read2_b32 v[26:27], v10 offset0:198 offset1:231
	s_waitcnt lgkmcnt(0)
	v_cvt_pk_bf16_f32 v25, v26, v27
	ds_read2_b32 v[26:27], v10 offset0:8 offset1:41
	global_store_dwordx4 v[62:63], v[22:25], off sc1
	v_add_u32_e32 v28, 24, v56
	v_ashrrev_i32_e32 v29, 31, v28
	s_waitcnt lgkmcnt(0)
	v_cvt_pk_bf16_f32 v22, v26, v27
	ds_read2_b32 v[24:25], v10 offset0:74 offset1:107
	s_waitcnt lgkmcnt(0)
	v_cvt_pk_bf16_f32 v23, v24, v25
	ds_read2_b32 v[24:25], v10 offset0:140 offset1:173
	s_waitcnt lgkmcnt(0)
	v_cvt_pk_bf16_f32 v24, v24, v25
	ds_read2_b32 v[26:27], v10 offset0:206 offset1:239
	s_waitcnt lgkmcnt(0)
	v_cvt_pk_bf16_f32 v25, v26, v27
	ds_read2_b32 v[26:27], v10 offset0:16 offset1:49
	global_store_dwordx4 v[58:59], v[22:25], off sc1
	v_lshlrev_b64 v[28:29], 12, v[28:29]
	v_lshl_add_u64 v[28:29], v[54:55], 0, v[28:29]
	s_waitcnt lgkmcnt(0)
	v_cvt_pk_bf16_f32 v22, v26, v27
	ds_read2_b32 v[24:25], v10 offset0:82 offset1:115
	s_waitcnt lgkmcnt(0)
	v_cvt_pk_bf16_f32 v23, v24, v25
	ds_read2_b32 v[24:25], v10 offset0:148 offset1:181
	s_waitcnt lgkmcnt(0)
	v_cvt_pk_bf16_f32 v24, v24, v25
	ds_read2_b32 v[26:27], v10 offset0:214 offset1:247
	s_waitcnt lgkmcnt(0)
	v_cvt_pk_bf16_f32 v25, v26, v27
	ds_read2_b32 v[26:27], v10 offset0:24 offset1:57
	global_store_dwordx4 v[60:61], v[22:25], off sc1
	s_waitcnt lgkmcnt(0)
	s_nop 0
	v_cvt_pk_bf16_f32 v22, v26, v27
	ds_read2_b32 v[24:25], v10 offset0:90 offset1:123
	s_waitcnt lgkmcnt(0)
	v_cvt_pk_bf16_f32 v23, v24, v25
	ds_read2_b32 v[24:25], v10 offset0:156 offset1:189
	s_waitcnt lgkmcnt(0)
	v_cvt_pk_bf16_f32 v24, v24, v25
	ds_read2_b32 v[26:27], v10 offset0:222 offset1:255
	s_waitcnt lgkmcnt(0)
	v_cvt_pk_bf16_f32 v25, v26, v27
	global_store_dwordx4 v[28:29], v[22:25], off sc1
	s_waitcnt lgkmcnt(0)
	s_cbranch_scc1 .LBB0_30

.LBB0_41:
	s_or_b64 exec, exec, s[24:25]
	v_div_scale_f32 v72, s[24:25], s11, s11, v112
	v_rcp_f32_e32 v73, v72
	v_mov_b32_e32 v80, s11
	v_div_scale_f32 v80, vcc, s30, v80, s30
	v_fma_f32 v81, -v72, v73, 1.0
	v_fmac_f32_e32 v73, v81, v73
	v_mul_f32_e32 v81, v80, v73
	v_fma_f32 v98, -v72, v81, v80
	v_fmac_f32_e32 v81, v98, v73
	v_fma_f32 v72, -v72, v81, v80
	v_div_fmas_f32 v72, v72, v73, v81
	v_div_fixup_f32 v72, v72, s11, v112
	v_cndmask_b32_e64 v98, 0, v72, s[6:7]
	v_fmaak_f32 v72, v108, v98, 0x4b400000
	v_fmaak_f32 v73, v109, v98, 0x4b400000
	v_fmaak_f32 v80, v106, v98, 0x4b400000
	v_perm_b32 v72, v73, v72, s31
	v_fmaak_f32 v81, v107, v98, 0x4b400000
	v_perm_b32 v72, v80, v72, s34
	v_fmaak_f32 v73, v94, v98, 0x4b400000
	v_fmaak_f32 v80, v95, v98, 0x4b400000
	v_perm_b32 v72, v81, v72, s35
	v_fmaak_f32 v81, v96, v98, 0x4b400000
	v_perm_b32 v73, v80, v73, s31
	v_perm_b32 v73, v81, v73, s34
	v_lshl_add_u64 v[80:81], s[94:95], 0, v[100:101]
	v_fmaak_f32 v94, v97, v98, 0x4b400000
	v_add_co_u32_e32 v80, vcc, s36, v80
	v_perm_b32 v73, v94, v73, s35
	s_nop 0
	v_addc_co_u32_e32 v81, vcc, 0, v81, vcc
	global_store_dwordx2 v[80:81], v[72:73], off sc1
	v_fmaak_f32 v72, v90, v98, 0x4b400000
	v_fmaak_f32 v73, v91, v98, 0x4b400000
	v_perm_b32 v72, v73, v72, s31
	v_fmaak_f32 v73, v86, v98, 0x4b400000
	v_fmaak_f32 v86, v87, v98, 0x4b400000
	v_fmaak_f32 v90, v92, v98, 0x4b400000
	v_fmaak_f32 v87, v88, v98, 0x4b400000
	v_perm_b32 v73, v86, v73, s31
	v_fmaak_f32 v91, v93, v98, 0x4b400000
	v_perm_b32 v72, v90, v72, s34
	v_fmaak_f32 v88, v89, v98, 0x4b400000
	v_perm_b32 v73, v87, v73, s34
	v_perm_b32 v72, v91, v72, s35
	v_perm_b32 v73, v88, v73, s35
	global_store_dwordx2 v[80:81], v[72:73], off offset:512 sc1
	v_fmaak_f32 v72, v82, v98, 0x4b400000
	v_fmaak_f32 v73, v83, v98, 0x4b400000
	v_perm_b32 v72, v73, v72, s31
	v_fmaak_f32 v73, v76, v98, 0x4b400000
	v_fmaak_f32 v76, v77, v98, 0x4b400000
	v_fmaak_f32 v82, v84, v98, 0x4b400000
	v_fmaak_f32 v77, v78, v98, 0x4b400000
	v_perm_b32 v73, v76, v73, s31
	v_fmaak_f32 v83, v85, v98, 0x4b400000
	v_perm_b32 v72, v82, v72, s34
	v_fmaak_f32 v78, v79, v98, 0x4b400000
	v_perm_b32 v73, v77, v73, s34
	v_fmaak_f32 v66, v66, v98, 0x4b400000
	v_fmaak_f32 v67, v67, v98, 0x4b400000
	v_perm_b32 v72, v83, v72, s35
	v_perm_b32 v73, v78, v73, s35
	v_perm_b32 v66, v67, v66, s31
	v_fmaak_f32 v67, v68, v98, 0x4b400000
	v_fmaak_f32 v68, v69, v98, 0x4b400000
	global_store_dwordx2 v[80:81], v[72:73], off offset:1024 sc1
	v_fmaak_f32 v72, v74, v98, 0x4b400000
	v_fmaak_f32 v69, v70, v98, 0x4b400000
	v_perm_b32 v67, v68, v67, s31
	v_fmaak_f32 v73, v75, v98, 0x4b400000
	v_perm_b32 v66, v72, v66, s34
	v_fmaak_f32 v70, v71, v98, 0x4b400000
	v_perm_b32 v67, v69, v67, s34
	v_perm_b32 v66, v73, v66, s35
	v_perm_b32 v67, v70, v67, s35
	global_store_dwordx2 v[80:81], v[66:67], off offset:1536 sc1

.LBB0_45:
	v_lshl_add_u64 v[114:115], s[94:95], 0, v[102:103]
	v_add_co_u32_e32 v116, vcc, s29, v114
	v_cvt_pk_f16_f32 v106, v90, v91
	v_cvt_pk_f16_f32 v107, v92, v93
	v_cvt_pk_f16_f32 v108, v94, v95
	v_cvt_pk_f16_f32 v109, v96, v97
	v_addc_co_u32_e32 v117, vcc, 0, v115, vcc
	global_store_dwordx4 v[116:117], v[106:109], off offset:1024 sc1
	v_add_co_u32_e32 v114, vcc, 0x2f1e1000, v114
	s_nop 0
	v_cvt_pk_f16_f32 v106, v82, v83
	v_cvt_pk_f16_f32 v107, v84, v85
	v_cvt_pk_f16_f32 v108, v86, v87
	v_cvt_pk_f16_f32 v109, v88, v89
	global_store_dwordx4 v[116:117], v[106:109], off offset:2048 sc1
	v_addc_co_u32_e32 v115, vcc, 0, v115, vcc
	s_nop 0
	v_cvt_pk_f16_f32 v106, v74, v75
	v_cvt_pk_f16_f32 v107, v76, v77
	v_cvt_pk_f16_f32 v108, v78, v79
	v_cvt_pk_f16_f32 v109, v80, v81
	global_store_dwordx4 v[116:117], v[106:109], off offset:3072 sc1
	s_andn2_b64 vcc, exec, s[8:9]
	s_nop 0
	v_cvt_pk_f16_f32 v106, v66, v67
	v_cvt_pk_f16_f32 v107, v68, v69
	v_cvt_pk_f16_f32 v108, v70, v71
	v_cvt_pk_f16_f32 v109, v72, v73
	global_store_dwordx4 v[114:115], v[106:109], off sc1
	s_cbranch_vccnz .LBB0_42
	s_nop 0
	v_pk_mul_f32 v[106:107], v[92:93], v[92:93]
	v_pk_mul_f32 v[92:93], v[12:13], v[92:93]
	v_pk_fma_f32 v[106:107], v[90:91], v[90:91], v[106:107]
	v_pk_mul_f32 v[90:91], v[10:11], v[90:91]
	v_pk_fma_f32 v[106:107], v[94:95], v[94:95], v[106:107]
	s_nop 0
	v_pk_fma_f32 v[106:107], v[96:97], v[96:97], v[106:107]
	s_nop 0
	v_pk_fma_f32 v[106:107], v[82:83], v[82:83], v[106:107]
	v_pk_mul_f32 v[82:83], v[14:15], v[82:83]
	v_pk_fma_f32 v[106:107], v[84:85], v[84:85], v[106:107]
	s_nop 0
	v_pk_fma_f32 v[106:107], v[86:87], v[86:87], v[106:107]
	s_nop 0
	v_pk_fma_f32 v[106:107], v[88:89], v[88:89], v[106:107]
	s_nop 0
	v_pk_fma_f32 v[106:107], v[74:75], v[74:75], v[106:107]
	v_pk_mul_f32 v[74:75], v[18:19], v[74:75]
	v_pk_fma_f32 v[106:107], v[76:77], v[76:77], v[106:107]
	s_nop 0
	v_pk_fma_f32 v[106:107], v[78:79], v[78:79], v[106:107]
	s_nop 0
	v_pk_fma_f32 v[106:107], v[80:81], v[80:81], v[106:107]
	s_nop 0
	v_pk_fma_f32 v[106:107], v[66:67], v[66:67], v[106:107]
	v_pk_mul_f32 v[66:67], v[26:27], v[66:67]
	v_pk_fma_f32 v[106:107], v[68:69], v[68:69], v[106:107]
	v_pk_mul_f32 v[68:69], v[28:29], v[68:69]
	v_pk_fma_f32 v[106:107], v[70:71], v[70:71], v[106:107]
	s_nop 0
	v_pk_fma_f32 v[106:107], v[72:73], v[72:73], v[106:107]
	s_nop 0
	v_add_f32_e32 v98, v106, v107
	v_mov_b32_e32 v106, 0
	s_nop 0
	v_add_f32_dpp v98, v98, v98 quad_perm:[1,0,3,2] row_mask:0xf bank_mask:0xf bound_ctrl:1
	s_nop 1
	v_add_f32_dpp v98, v98, v98 quad_perm:[2,3,0,1] row_mask:0xf bank_mask:0xf bound_ctrl:1
	s_nop 1
	v_add_f32_dpp v98, v98, v98 row_half_mirror row_mask:0xf bank_mask:0xf bound_ctrl:1
	s_nop 1
	v_add_f32_dpp v98, v98, v98 row_mirror row_mask:0xf bank_mask:0xf bound_ctrl:1
	s_nop 1
	v_mov_b32_dpp v106, v98 row_bcast:15 row_mask:0xa bank_mask:0xf
	v_add_f32_e32 v98, v98, v106
	v_mov_b32_e32 v106, 0
	s_nop 1
	v_mov_b32_dpp v106, v98 row_bcast:31 row_mask:0xc bank_mask:0xf
	v_add_f32_e32 v98, v98, v106
	s_nop 0
	v_readlane_b32 s6, v98, 63
	s_nop 1
	v_fma_f32 v98, s6, v110, v1
	v_rsq_f32_e32 v98, v98
	s_nop 0
	v_pk_mul_f32 v[106:107], v[92:93], v[98:99] op_sel_hi:[1,0]
	v_pk_mul_f32 v[108:109], v[90:91], v[98:99] op_sel_hi:[1,0]
	v_max_f32_e64 v91, |v106|, |v107|
	v_max_f32_e64 v90, |v108|, |v109|
	v_max3_f32 v92, v90, 0, v91
	v_pk_mul_f32 v[90:91], v[2:3], v[94:95]
	v_pk_mul_f32 v[66:67], v[66:67], v[98:99] op_sel_hi:[1,0]
	v_pk_mul_f32 v[94:95], v[90:91], v[98:99] op_sel_hi:[1,0]
	v_pk_mul_f32 v[90:91], v[4:5], v[96:97]
	v_max_f32_e64 v93, |v94|, |v95|
	v_pk_mul_f32 v[96:97], v[90:91], v[98:99] op_sel_hi:[1,0]
	s_nop 0
	v_max_f32_e64 v90, |v96|, |v97|
	v_max3_f32 v113, v92, v93, v90
	v_pk_mul_f32 v[90:91], v[82:83], v[98:99] op_sel_hi:[1,0]
	v_pk_mul_f32 v[82:83], v[16:17], v[84:85]
	v_max_f32_e64 v114, |v90|, |v91|
	v_pk_mul_f32 v[92:93], v[82:83], v[98:99] op_sel_hi:[1,0]
	s_nop 0
	v_max_f32_e64 v82, |v92|, |v93|
	v_max3_f32 v84, v113, v114, v82
	v_pk_mul_f32 v[82:83], v[6:7], v[86:87]
	s_nop 0
	v_pk_mul_f32 v[86:87], v[82:83], v[98:99] op_sel_hi:[1,0]
	v_pk_mul_f32 v[82:83], v[8:9], v[88:89]
	v_max_f32_e64 v85, |v86|, |v87|
	v_pk_mul_f32 v[88:89], v[82:83], v[98:99] op_sel_hi:[1,0]
	s_nop 0
	v_max_f32_e64 v82, |v88|, |v89|
	v_max3_f32 v113, v84, v85, v82
	v_pk_mul_f32 v[82:83], v[74:75], v[98:99] op_sel_hi:[1,0]
	v_pk_mul_f32 v[74:75], v[20:21], v[76:77]
	v_max_f32_e64 v114, |v82|, |v83|
	v_pk_mul_f32 v[84:85], v[74:75], v[98:99] op_sel_hi:[1,0]
	s_nop 0
	v_max_f32_e64 v74, |v84|, |v85|
	v_max3_f32 v113, v113, v114, v74
	v_pk_mul_f32 v[74:75], v[22:23], v[78:79]
	s_nop 0
	v_pk_mul_f32 v[76:77], v[74:75], v[98:99] op_sel_hi:[1,0]
	v_pk_mul_f32 v[74:75], v[24:25], v[80:81]
	v_max_f32_e64 v114, |v76|, |v77|
	v_pk_mul_f32 v[78:79], v[74:75], v[98:99] op_sel_hi:[1,0]
	v_max_f32_e64 v81, |v66|, |v67|
	v_max_f32_e64 v74, |v78|, |v79|
	v_max3_f32 v80, v113, v114, v74
	v_pk_mul_f32 v[74:75], v[68:69], v[98:99] op_sel_hi:[1,0]
	s_nop 0
	v_max_f32_e64 v68, |v74|, |v75|
	v_max3_f32 v80, v80, v81, v68
	v_pk_mul_f32 v[68:69], v[30:31], v[70:71]
	v_pk_mul_f32 v[70:71], v[32:33], v[72:73]
	v_pk_mul_f32 v[68:69], v[68:69], v[98:99] op_sel_hi:[1,0]
	v_pk_mul_f32 v[70:71], v[70:71], v[98:99] op_sel_hi:[1,0]
	v_max_f32_e64 v81, |v68|, |v69|
	v_max_f32_e64 v72, |v70|, |v71|
	v_max3_f32 v72, v80, v81, v72
	v_mov_b32_e32 v73, 0
	s_nop 1
	v_mov_b32_dpp v73, v72 quad_perm:[1,0,3,2] row_mask:0xf bank_mask:0xf
	v_max_f32_e32 v73, v73, v73
	v_max_f32_e32 v72, v72, v73
	v_mov_b32_e32 v73, 0
	s_nop 1
	v_mov_b32_dpp v73, v72 quad_perm:[2,3,0,1] row_mask:0xf bank_mask:0xf
	v_max_f32_e32 v73, v73, v73
	v_max_f32_e32 v72, v72, v73
	v_mov_b32_e32 v73, 0
	s_nop 1
	v_mov_b32_dpp v73, v72 row_half_mirror row_mask:0xf bank_mask:0xf
	v_max_f32_e32 v73, v73, v73
	v_max_f32_e32 v72, v72, v73
	v_mov_b32_e32 v73, 0
	s_nop 1
	v_mov_b32_dpp v73, v72 row_mirror row_mask:0xf bank_mask:0xf
	v_max_f32_e32 v73, v73, v73
	v_max_f32_e32 v72, v72, v73
	v_mov_b32_e32 v73, 0
	s_nop 1
	v_mov_b32_dpp v73, v72 row_bcast:15 row_mask:0xa bank_mask:0xf
	v_max_f32_e32 v73, v73, v73
	v_max_f32_e32 v72, v72, v73
	v_mov_b32_e32 v73, 0
	s_nop 1
	v_mov_b32_dpp v73, v72 row_bcast:31 row_mask:0xc bank_mask:0xf
	v_max_f32_e32 v73, v73, v73
	v_max_f32_e32 v72, v72, v73
	s_nop 0
	v_readlane_b32 s11, v72, 63
	s_nop 1
	v_cmp_gt_f32_e64 s[6:7], s11, 0
	s_and_saveexec_b64 s[24:25], s[4:5]
	s_cbranch_execz .LBB0_41
	v_mul_f32_e32 v72, s11, v111
	s_add_u32 s40, s94, s37
	v_cndmask_b32_e64 v72, 1.0, v72, s[6:7]
	s_addc_u32 s41, s95, s38
	global_store_dword v99, v72, s[40:41]
	s_branch .LBB0_41

.LBB0_54:
	s_add_i32 s22, s28, s38
	s_cmpk_lt_i32 s22, 0x2020
	s_cselect_b64 s[24:25], -1, 0
	s_and_b64 s[8:9], s[24:25], exec
	s_cselect_b32 s23, s22, s38
	s_add_i32 s8, s38, 0xffffe000
	s_load_dwordx16 s[44:59], s[0:1], 0x0
	s_add_u32 s26, s10, s20
	s_addc_u32 s9, s11, s21
	s_cmpk_lt_i32 s38, 0x2000
	s_cselect_b32 s9, s9, 0
	s_cselect_b32 s8, s26, s8
	s_waitcnt lgkmcnt(0)
	s_cselect_b32 s26, s45, s47
	s_cselect_b32 s27, s44, s46
	s_lshl_b64 s[8:9], s[8:9], 13
	s_add_u32 s8, s27, s8
	s_addc_u32 s9, s26, s9
	global_load_dwordx4 v[56:59], v1, s[8:9]
	global_load_dwordx4 v[62:65], v1, s[8:9] offset:1024
	global_load_dwordx4 v[66:69], v1, s[8:9] offset:2048
	global_load_dwordx4 v[76:79], v1, s[8:9] offset:3072
	global_load_dwordx4 v[80:83], v34, s[8:9]
	global_load_dwordx4 v[84:87], v88, s[8:9]
	global_load_dwordx4 v[94:97], v89, s[8:9]
	s_ashr_i32 s26, s23, 31
	s_add_i32 s27, s23, 0xffffe000
	s_cmpk_lt_i32 s23, 0x2000
	global_load_dwordx4 v[98:101], v90, s[8:9]
	s_cselect_b32 s9, s26, 0
	s_cselect_b32 s8, s23, s27
	s_cselect_b32 s23, s45, s47
	s_cselect_b32 s26, s44, s46
	s_lshl_b64 s[8:9], s[8:9], 13
	s_add_u32 s8, s26, s8
	s_addc_u32 s9, s23, s9
	global_load_dwordx4 v[30:33], v1, s[8:9]
	global_load_dwordx4 v[26:29], v1, s[8:9] offset:1024
	global_load_dwordx4 v[22:25], v1, s[8:9] offset:2048
	global_load_dwordx4 v[18:21], v1, s[8:9] offset:3072
	global_load_dwordx4 v[14:17], v34, s[8:9]
	global_load_dwordx4 v[10:13], v88, s[8:9]
	global_load_dwordx4 v[6:9], v89, s[8:9]
	global_load_dwordx4 v[2:5], v90, s[8:9]
	v_lshl_add_u64 v[102:103], s[94:95], 0, v[50:51]
	v_add_co_u32_e32 v104, vcc, s31, v102
	s_waitcnt vmcnt(15)
	v_cvt_f16_f32_e32 v54, v56
	v_cvt_f16_f32_e32 v56, v57
	v_cvt_f16_f32_e32 v71, v59
	s_waitcnt vmcnt(14)
	v_cvt_f16_f32_e32 v72, v63
	v_cvt_f16_f32_e32 v60, v58
	v_cvt_f16_f32_e32 v62, v62
	v_cvt_f16_f32_e32 v73, v65
	s_waitcnt vmcnt(13)
	v_cvt_f16_f32_e32 v74, v67
	v_cvt_f16_f32_e32 v75, v69
	s_waitcnt vmcnt(12)
	v_cvt_f16_f32_e32 v77, v77
	v_cvt_f16_f32_e32 v79, v79
	s_waitcnt vmcnt(11)
	v_cvt_f16_f32_e32 v65, v80
	v_cvt_f16_f32_e32 v80, v81
	v_cvt_f16_f32_e32 v81, v83
	v_cvt_f16_f32_e32 v61, v64
	v_cvt_f16_f32_e32 v64, v66
	v_cvt_f16_f32_e32 v63, v68
	v_cvt_f16_f32_e32 v76, v76
	v_cvt_f16_f32_e32 v78, v78
	v_cvt_f16_f32_e32 v66, v82
	v_lshlrev_b32_e32 v55, 16, v56
	v_lshlrev_b32_e32 v57, 16, v71
	v_lshlrev_b32_e32 v69, 16, v72
	v_addc_co_u32_e32 v105, vcc, 0, v103, vcc
	s_waitcnt vmcnt(10)
	v_cvt_f16_f32_e32 v68, v84
	v_cvt_f16_f32_e32 v67, v86
	v_cvt_f16_f32_e32 v83, v87
	v_lshlrev_b32_e32 v70, 16, v73
	v_lshlrev_b32_e32 v86, 16, v74
	v_lshlrev_b32_e32 v87, 16, v75
	v_lshlrev_b32_e32 v93, 16, v77
	v_lshlrev_b32_e32 v107, 16, v79
	v_lshlrev_b32_e32 v108, 16, v80
	v_lshlrev_b32_e32 v109, 16, v81
	v_or_b32_e32 v58, v55, v54
	v_or_b32_e32 v59, v57, v60
	v_or_b32_e32 v84, v69, v62
	v_cvt_f16_f32_e32 v82, v85
	v_or_b32_e32 v85, v70, v61
	v_or_b32_e32 v86, v86, v64
	v_or_b32_e32 v87, v87, v63
	v_or_b32_e32 v106, v93, v76
	v_or_b32_e32 v107, v107, v78
	v_or_b32_e32 v108, v108, v65
	v_or_b32_e32 v109, v109, v66
	global_store_dwordx2 v[104:105], v[58:59], off offset:1024 sc1
	global_store_dwordx2 v[104:105], v[84:85], off offset:1536 sc1
	global_store_dwordx2 v[104:105], v[86:87], off offset:2048 sc1
	global_store_dwordx2 v[104:105], v[106:107], off offset:2560 sc1
	global_store_dwordx2 v[104:105], v[108:109], off offset:3072 sc1
	s_waitcnt vmcnt(14)
	v_cvt_f16_f32_e32 v84, v95
	v_cvt_f16_f32_e32 v69, v94
	v_cvt_f16_f32_e32 v85, v97
	v_cvt_f16_f32_e32 v70, v96
	v_lshlrev_b32_e32 v55, 16, v84
	v_or_b32_e32 v58, v55, v69
	v_lshlrev_b32_e32 v55, 16, v85
	v_add_co_u32_e32 v86, vcc, s34, v102
	v_or_b32_e32 v59, v55, v70
	s_nop 0
	v_addc_co_u32_e32 v87, vcc, 0, v103, vcc
	s_waitcnt vmcnt(13)
	v_cvt_f16_f32_e32 v55, v99
	global_store_dwordx2 v[86:87], v[58:59], off sc1
	v_cvt_f16_f32_e32 v57, v98
	v_cvt_f16_f32_e32 v59, v101
	v_cvt_f16_f32_e32 v58, v100
	v_lshlrev_b32_e32 v93, 16, v55
	v_lshlrev_b32_e32 v110, 16, v82
	v_lshlrev_b32_e32 v111, 16, v83
	v_or_b32_e32 v94, v93, v57
	v_lshlrev_b32_e32 v93, 16, v59
	v_or_b32_e32 v110, v110, v68
	v_or_b32_e32 v111, v111, v67
	v_or_b32_e32 v95, v93, v58
	s_and_b64 vcc, exec, s[6:7]
	global_store_dwordx2 v[104:105], v[110:111], off offset:3584 sc1
	global_store_dwordx2 v[86:87], v[94:95], off offset:512 sc1
	s_cbranch_vccnz .LBB0_58
	v_cvt_f32_f16_e32 v121, v85
	v_cvt_f32_f16_e32 v85, v56
	v_cvt_f32_f16_e32 v71, v71
	v_cvt_f32_f16_e32 v125, v83
	v_cvt_f32_f16_e32 v83, v72
	v_cvt_f32_f16_e32 v139, v73
	v_cvt_f32_f16_e32 v129, v81
	v_cvt_f32_f16_e32 v131, v76
	v_cvt_f32_f16_e32 v81, v74
	v_mul_f32_e32 v56, v85, v85
	v_cvt_f32_f16_e32 v137, v75
	v_fma_mix_f32 v130, v54, v54, v56 op_sel_hi:[1,1,0]
	v_mul_f32_e32 v56, v71, v71
	v_cvt_f32_f16_e32 v127, v80
	v_cvt_f32_f16_e32 v133, v77
	v_cvt_f32_f16_e32 v134, v78
	v_cvt_f32_f16_e32 v135, v79
	v_fma_mix_f32 v86, v60, v60, v56 op_sel_hi:[1,1,0]
	v_mul_f32_e32 v56, v83, v83
	v_mul_f32_e32 v80, v139, v139
	v_fma_mix_f32 v56, v62, v62, v56 op_sel_hi:[1,1,0]
	v_fma_mix_f32 v80, v61, v61, v80 op_sel_hi:[1,1,0]
	v_cvt_f32_f16_e32 v123, v82
	v_add_f32_e32 v102, v56, v80
	v_mul_f32_e32 v56, v81, v81
	v_mov_b32_e32 v87, v131
	v_fma_mix_f32 v104, v64, v64, v56 op_sel_hi:[1,1,0]
	v_mul_f32_e32 v56, v137, v137
	v_pk_add_f32 v[86:87], v[130:131], v[86:87]
	v_pk_mul_f32 v[108:109], v[130:131], v[130:131]
	v_cvt_f32_f16_e32 v119, v84
	v_fma_mix_f32 v106, v63, v63, v56 op_sel_hi:[1,1,0]
	v_mul_f32_e32 v103, v133, v133
	v_mul_f32_e32 v105, v134, v134
	v_mul_f32_e32 v107, v135, v135
	v_mov_b32_e32 v87, v109
	v_mul_f32_e32 v56, v127, v127
	v_mul_f32_e32 v80, v129, v129
	global_load_dwordx4 v[72:75], v[36:37], off
	global_load_dwordx4 v[76:79], v[36:37], off offset:1024
	global_load_dwordx4 v[94:97], v[36:37], off offset:2048
	global_load_dwordx4 v[98:101], v[36:37], off offset:3072
	v_pk_add_f32 v[86:87], v[86:87], v[102:103]
	v_pk_add_f32 v[102:103], v[104:105], v[106:107]
	v_fma_mix_f32 v56, v65, v65, v56 op_sel_hi:[1,1,0]
	v_fma_mix_f32 v80, v66, v66, v80 op_sel_hi:[1,1,0]
	v_cvt_f32_f16_e32 v57, v57
	v_pk_add_f32 v[86:87], v[86:87], v[102:103]
	v_add_f32_e32 v102, v56, v80
	v_mul_f32_e32 v56, v123, v123
	v_mul_f32_e32 v80, v125, v125
	v_fma_mix_f32 v56, v68, v68, v56 op_sel_hi:[1,1,0]
	v_fma_mix_f32 v80, v67, v67, v80 op_sel_hi:[1,1,0]
	v_cvt_f32_f16_e32 v55, v55
	v_cvt_f32_f16_e32 v58, v58
	v_cvt_f32_f16_e32 v59, v59
	v_add_f32_e32 v104, v56, v80
	v_mul_f32_e32 v56, v119, v119
	v_fma_mix_f32 v106, v69, v69, v56 op_sel_hi:[1,1,0]
	v_mul_f32_e32 v56, v121, v121
	v_pk_add_f32 v[86:87], v[86:87], v[86:87] op_sel:[0,1] op_sel_hi:[1,0]
	v_fma_mix_f32 v108, v70, v70, v56 op_sel_hi:[1,1,0]
	v_mov_b32_e32 v56, v86
	v_mov_b32_e32 v103, v57
	v_pk_add_f32 v[86:87], v[86:87], v[102:103]
	v_pk_mul_f32 v[102:103], v[56:57], v[56:57]
	v_mul_f32_e32 v105, v55, v55
	v_mul_f32_e32 v107, v58, v58
	v_mul_f32_e32 v109, v59, v59
	v_mov_b32_e32 v87, v103
	v_pk_add_f32 v[86:87], v[86:87], v[104:105]
	v_pk_add_f32 v[102:103], v[106:107], v[108:109]
	v_and_b32_e32 v80, 64, v92
	v_pk_add_f32 v[86:87], v[86:87], v[102:103]
	global_load_dwordx4 v[102:105], v[38:39], off
	global_load_dwordx4 v[106:109], v[40:41], off
	global_load_dwordx4 v[110:113], v[42:43], off
	global_load_dwordx4 v[114:117], v[44:45], off
	v_add_u32_e32 v82, 64, v80
	v_xor_b32_e32 v80, 1, v92
	v_cmp_lt_i32_e32 vcc, v80, v82
	v_add_f32_e32 v56, v86, v87
	v_cvt_f32_f16_e32 v122, v68
	v_cndmask_b32_e32 v80, v92, v80, vcc
	v_lshlrev_b32_e32 v93, 2, v80
	ds_bpermute_b32 v80, v93, v56
	v_xor_b32_e32 v68, 16, v92
	v_cvt_f32_f16_e32 v84, v54
	v_cvt_f32_f16_e32 v120, v70
	v_cvt_f32_f16_e32 v70, v60
	s_waitcnt lgkmcnt(0)
	v_add_f32_e32 v56, v56, v80
	v_xor_b32_e32 v80, 2, v92
	v_cmp_lt_i32_e32 vcc, v80, v82
	v_cvt_f32_f16_e32 v138, v61
	v_cvt_f32_f16_e32 v136, v63
	v_cndmask_b32_e32 v80, v92, v80, vcc
	v_lshlrev_b32_e32 v130, 2, v80
	ds_bpermute_b32 v80, v130, v56
	v_cvt_f32_f16_e32 v128, v66
	v_mov_b32_e32 v132, v131
	v_cvt_f32_f16_e32 v126, v65
	v_cvt_f32_f16_e32 v124, v67
	s_waitcnt lgkmcnt(0)
	v_add_f32_e32 v56, v56, v80
	v_xor_b32_e32 v80, 4, v92
	v_cmp_lt_i32_e32 vcc, v80, v82
	v_cvt_f32_f16_e32 v118, v69
	s_waitcnt vmcnt(7)
	v_pk_mul_f32 v[60:61], v[70:71], v[74:75]
	v_cndmask_b32_e32 v80, v92, v80, vcc
	v_lshlrev_b32_e32 v140, 2, v80
	ds_bpermute_b32 v80, v140, v56
	s_waitcnt lgkmcnt(0)
	v_add_f32_e32 v56, v56, v80
	v_xor_b32_e32 v80, 8, v92
	v_cmp_lt_i32_e32 vcc, v80, v82
	s_waitcnt vmcnt(0)
	v_pk_mul_f32 v[58:59], v[58:59], v[116:117]
	v_cndmask_b32_e32 v80, v92, v80, vcc
	v_lshlrev_b32_e32 v141, 2, v80
	ds_bpermute_b32 v80, v141, v56
	v_cmp_lt_i32_e32 vcc, v68, v82
	s_waitcnt lgkmcnt(0)
	v_add_f32_e32 v56, v56, v80
	v_cndmask_b32_e32 v68, v92, v68, vcc
	v_lshlrev_b32_e32 v142, 2, v68
	ds_bpermute_b32 v68, v142, v56
	v_cvt_f32_f16_e32 v80, v64
	v_xor_b32_e32 v64, 32, v92
	v_cmp_lt_i32_e32 vcc, v64, v82
	v_cvt_f32_f16_e32 v82, v62
	s_waitcnt lgkmcnt(0)
	v_add_f32_e32 v56, v56, v68
	v_cndmask_b32_e32 v64, v92, v64, vcc
	v_lshlrev_b32_e32 v143, 2, v64
	ds_bpermute_b32 v64, v143, v56
	v_pk_mul_f32 v[62:63], v[84:85], v[72:73]
	s_waitcnt lgkmcnt(0)
	v_add_f32_e32 v54, v56, v64
	v_fmamk_f32 v54, v54, 0x3a000000, v91
	v_rsq_f32_e32 v56, v54
	s_nop 0
	v_pk_mul_f32 v[84:85], v[60:61], v[56:57] op_sel_hi:[1,0]
	v_pk_mul_f32 v[60:61], v[138:139], v[78:79]
	v_pk_mul_f32 v[86:87], v[62:63], v[56:57] op_sel_hi:[1,0]
	v_pk_mul_f32 v[62:63], v[82:83], v[76:77]
	v_pk_mul_f32 v[78:79], v[60:61], v[56:57] op_sel_hi:[1,0]
	v_max_f32_e64 v54, |v84|, |v85|
	v_pk_mul_f32 v[82:83], v[62:63], v[56:57] op_sel_hi:[1,0]
	v_max_f32_e64 v60, |v78|, |v79|
	v_max3_f32 v54, |v86|, |v87|, v54
	v_max3_f32 v60, |v82|, |v83|, v60
	v_max3_f32 v54, v54, 0, v60
	v_pk_mul_f32 v[60:61], v[136:137], v[96:97]
	v_pk_mul_f32 v[62:63], v[80:81], v[94:95]
	v_pk_mul_f32 v[74:75], v[60:61], v[56:57] op_sel_hi:[1,0]
	v_pk_mul_f32 v[80:81], v[62:63], v[56:57] op_sel_hi:[1,0]
	v_max_f32_e64 v60, |v74|, |v75|
	v_max3_f32 v64, |v80|, |v81|, v60
	v_pk_mul_f32 v[60:61], v[134:135], v[100:101]
	v_pk_mul_f32 v[62:63], v[132:133], v[98:99]
	v_pk_mul_f32 v[70:71], v[60:61], v[56:57] op_sel_hi:[1,0]
	v_pk_mul_f32 v[76:77], v[62:63], v[56:57] op_sel_hi:[1,0]
	v_max_f32_e64 v60, |v70|, |v71|
	v_max3_f32 v60, |v76|, |v77|, v60
	v_max3_f32 v54, v54, v64, v60
	v_pk_mul_f32 v[60:61], v[128:129], v[104:105]
	v_pk_mul_f32 v[62:63], v[126:127], v[102:103]
	v_pk_mul_f32 v[66:67], v[60:61], v[56:57] op_sel_hi:[1,0]
	v_pk_mul_f32 v[72:73], v[62:63], v[56:57] op_sel_hi:[1,0]
	v_max_f32_e64 v60, |v66|, |v67|
	v_max3_f32 v94, |v72|, |v73|, v60
	v_pk_mul_f32 v[60:61], v[124:125], v[108:109]
	v_pk_mul_f32 v[64:65], v[122:123], v[106:107]
	v_pk_mul_f32 v[62:63], v[60:61], v[56:57] op_sel_hi:[1,0]
	v_pk_mul_f32 v[68:69], v[64:65], v[56:57] op_sel_hi:[1,0]
	v_max_f32_e64 v60, |v62|, |v63|
	v_max3_f32 v60, |v68|, |v69|, v60
	v_max3_f32 v96, v54, v94, v60
	v_pk_mul_f32 v[60:61], v[120:121], v[112:113]
	v_pk_mul_f32 v[64:65], v[118:119], v[110:111]
	v_pk_mul_f32 v[60:61], v[60:61], v[56:57] op_sel_hi:[1,0]
	v_pk_mul_f32 v[64:65], v[64:65], v[56:57] op_sel_hi:[1,0]
	v_max_f32_e64 v54, |v60|, |v61|
	v_max3_f32 v97, |v64|, |v65|, v54
	v_mov_b32_e32 v54, v57
	v_pk_mul_f32 v[94:95], v[54:55], v[114:115]
	v_pk_mul_f32 v[54:55], v[58:59], v[56:57] op_sel_hi:[1,0]
	v_pk_mul_f32 v[56:57], v[94:95], v[56:57] op_sel_hi:[1,0]
	v_max_f32_e64 v58, |v54|, |v55|
	v_max3_f32 v58, |v56|, |v57|, v58
	v_max3_f32 v58, v96, v97, v58
	ds_bpermute_b32 v59, v93, v58
	s_waitcnt lgkmcnt(0)
	v_max_f32_e32 v59, v59, v59
	v_max_f32_e32 v58, v58, v59
	ds_bpermute_b32 v59, v130, v58
	s_waitcnt lgkmcnt(0)
	v_max_f32_e32 v59, v59, v59
	v_max_f32_e32 v58, v58, v59
	ds_bpermute_b32 v59, v140, v58
	s_waitcnt lgkmcnt(0)
	v_max_f32_e32 v59, v59, v59
	v_max_f32_e32 v58, v58, v59
	ds_bpermute_b32 v59, v141, v58
	s_waitcnt lgkmcnt(0)
	v_max_f32_e32 v59, v59, v59
	v_max_f32_e32 v58, v58, v59
	ds_bpermute_b32 v59, v142, v58
	s_waitcnt lgkmcnt(0)
	v_max_f32_e32 v59, v59, v59
	v_max_f32_e32 v58, v58, v59
	ds_bpermute_b32 v59, v143, v58
	s_waitcnt lgkmcnt(0)
	v_max_f32_e32 v59, v59, v59
	v_max_f32_e32 v58, v58, v59
	v_cmp_lt_f32_e64 s[8:9], 0, v58
	s_and_saveexec_b64 s[26:27], s[4:5]
	s_cbranch_execz .LBB0_57
	v_mul_f32_e32 v59, 0x3c010204, v58
	s_add_u32 s40, s94, s29
	v_cndmask_b32_e64 v59, 1.0, v59, s[8:9]
	s_addc_u32 s41, s95, s30
	global_store_dword v35, v59, s[40:41]

.LBB0_58:
	s_andn2_b64 vcc, exec, s[24:25]
	s_cbranch_vccnz .LBB0_53
	s_waitcnt vmcnt(15)
	v_cvt_f16_f32_e32 v54, v31
	v_cvt_f16_f32_e32 v30, v30
	v_cvt_f16_f32_e32 v33, v33
	v_cvt_f16_f32_e32 v31, v32
	v_lshlrev_b32_e32 v32, 16, v54
	v_or_b32_e32 v56, v32, v30
	v_lshlrev_b32_e32 v32, 16, v33
	v_or_b32_e32 v57, v32, v31
	s_waitcnt vmcnt(14)
	v_cvt_f16_f32_e32 v32, v27
	v_cvt_f16_f32_e32 v27, v26
	v_cvt_f16_f32_e32 v29, v29
	s_ashr_i32 s23, s22, 31
	v_cvt_f16_f32_e32 v26, v28
	s_lshl_b64 s[8:9], s[22:23], 12
	v_lshl_add_u64 v[58:59], v[46:47], 0, s[8:9]
	v_lshlrev_b32_e32 v28, 16, v32
	global_store_dwordx2 v[58:59], v[56:57], off sc1
	v_or_b32_e32 v56, v28, v27
	v_lshlrev_b32_e32 v28, 16, v29
	v_or_b32_e32 v57, v28, v26
	s_waitcnt vmcnt(14)
	v_cvt_f16_f32_e32 v28, v23
	v_cvt_f16_f32_e32 v23, v22
	v_cvt_f16_f32_e32 v25, v25
	v_cvt_f16_f32_e32 v22, v24
	s_waitcnt vmcnt(13)
	v_cvt_f16_f32_e32 v19, v19
	v_cvt_f16_f32_e32 v18, v18
	v_cvt_f16_f32_e32 v21, v21
	v_lshlrev_b32_e32 v24, 16, v28
	v_cvt_f16_f32_e32 v20, v20
	global_store_dwordx2 v[58:59], v[56:57], off offset:512 sc1
	v_or_b32_e32 v56, v24, v23
	v_lshlrev_b32_e32 v24, 16, v25
	v_or_b32_e32 v57, v24, v22
	v_lshlrev_b32_e32 v24, 16, v19
	global_store_dwordx2 v[58:59], v[56:57], off offset:1024 sc1
	v_or_b32_e32 v56, v24, v18
	v_lshlrev_b32_e32 v24, 16, v21
	v_or_b32_e32 v57, v24, v20
	s_waitcnt vmcnt(14)
	v_cvt_f16_f32_e32 v24, v15
	v_cvt_f16_f32_e32 v14, v14
	v_cvt_f16_f32_e32 v17, v17
	v_cvt_f16_f32_e32 v15, v16
	v_lshlrev_b32_e32 v16, 16, v24
	global_store_dwordx2 v[58:59], v[56:57], off offset:1536 sc1
	v_or_b32_e32 v56, v16, v14
	v_lshlrev_b32_e32 v16, 16, v17
	v_or_b32_e32 v57, v16, v15
	s_waitcnt vmcnt(14)
	v_cvt_f16_f32_e32 v16, v11
	v_cvt_f16_f32_e32 v11, v10
	v_cvt_f16_f32_e32 v13, v13
	v_cvt_f16_f32_e32 v10, v12
	v_lshlrev_b32_e32 v12, 16, v16
	global_store_dwordx2 v[58:59], v[56:57], off offset:2048 sc1
	v_or_b32_e32 v56, v12, v11
	v_lshlrev_b32_e32 v12, 16, v13
	s_waitcnt vmcnt(14)
	v_cvt_f16_f32_e32 v55, v7
	v_cvt_f16_f32_e32 v9, v9
	v_or_b32_e32 v57, v12, v10
	v_cvt_f16_f32_e32 v12, v6
	v_cvt_f16_f32_e32 v8, v8
	v_lshlrev_b32_e32 v6, 16, v55
	v_lshlrev_b32_e32 v7, 16, v9
	v_or_b32_e32 v6, v6, v12
	v_or_b32_e32 v7, v7, v8
	s_waitcnt vmcnt(13)
	v_cvt_f16_f32_e32 v3, v3
	global_store_dwordx2 v[58:59], v[6:7], off offset:3072 sc1
	v_cvt_f16_f32_e32 v2, v2
	v_cvt_f16_f32_e32 v7, v5
	v_cvt_f16_f32_e32 v4, v4
	v_lshlrev_b32_e32 v5, 16, v3
	global_store_dwordx2 v[58:59], v[56:57], off offset:2560 sc1
	v_or_b32_e32 v56, v5, v2
	v_lshlrev_b32_e32 v5, 16, v7
	v_or_b32_e32 v57, v5, v4
	s_and_b64 vcc, exec, s[6:7]
	global_store_dwordx2 v[58:59], v[56:57], off offset:3584 sc1
	s_cbranch_vccnz .LBB0_53
	v_cvt_f32_f16_e32 v85, v55
	v_cvt_f32_f16_e32 v55, v54
	v_cvt_f32_f16_e32 v33, v33
	v_cvt_f32_f16_e32 v105, v32
	v_cvt_f32_f16_e32 v29, v29
	v_cvt_f32_f16_e32 v5, v2
	v_cvt_f32_f16_e32 v99, v18
	v_cvt_f32_f16_e32 v103, v28
	v_mul_f32_e32 v2, v55, v55
	v_cvt_f32_f16_e32 v25, v25
	v_fma_mix_f32 v98, v30, v30, v2 op_sel_hi:[1,1,0]
	v_mul_f32_e32 v2, v33, v33
	v_cvt_f32_f16_e32 v6, v4
	v_cvt_f32_f16_e32 v95, v24
	v_cvt_f32_f16_e32 v97, v17
	v_cvt_f32_f16_e32 v101, v19
	v_cvt_f32_f16_e32 v20, v20
	v_cvt_f32_f16_e32 v21, v21
	v_fma_mix_f32 v68, v31, v31, v2 op_sel_hi:[1,1,0]
	v_mul_f32_e32 v2, v105, v105
	v_mul_f32_e32 v4, v29, v29
	v_fma_mix_f32 v2, v27, v27, v2 op_sel_hi:[1,1,0]
	v_fma_mix_f32 v4, v26, v26, v4 op_sel_hi:[1,1,0]
	v_cvt_f32_f16_e32 v87, v16
	v_cvt_f32_f16_e32 v13, v13
	v_add_f32_e32 v70, v2, v4
	v_mul_f32_e32 v2, v103, v103
	v_mov_b32_e32 v69, v99
	v_fma_mix_f32 v72, v23, v23, v2 op_sel_hi:[1,1,0]
	v_mul_f32_e32 v2, v25, v25
	v_pk_add_f32 v[68:69], v[98:99], v[68:69]
	v_pk_mul_f32 v[76:77], v[98:99], v[98:99]
	global_load_dwordx4 v[16:19], v[36:37], off
	global_load_dwordx4 v[56:59], v[36:37], off offset:1024
	global_load_dwordx4 v[60:63], v[36:37], off offset:2048
	global_load_dwordx4 v[64:67], v[36:37], off offset:3072
	v_fma_mix_f32 v74, v22, v22, v2 op_sel_hi:[1,1,0]
	v_mul_f32_e32 v71, v101, v101
	v_mul_f32_e32 v73, v20, v20
	v_mul_f32_e32 v75, v21, v21
	v_mov_b32_e32 v69, v77
	v_mul_f32_e32 v2, v95, v95
	v_mul_f32_e32 v4, v97, v97
	v_cvt_f32_f16_e32 v9, v9
	v_pk_add_f32 v[68:69], v[68:69], v[70:71]
	v_pk_add_f32 v[70:71], v[72:73], v[74:75]
	v_fma_mix_f32 v2, v14, v14, v2 op_sel_hi:[1,1,0]
	v_fma_mix_f32 v4, v15, v15, v4 op_sel_hi:[1,1,0]
	v_cvt_f32_f16_e32 v3, v3
	v_cvt_f32_f16_e32 v7, v7
	v_pk_add_f32 v[68:69], v[68:69], v[70:71]
	v_add_f32_e32 v70, v2, v4
	v_mul_f32_e32 v2, v87, v87
	v_mul_f32_e32 v4, v13, v13
	v_fma_mix_f32 v2, v11, v11, v2 op_sel_hi:[1,1,0]
	v_fma_mix_f32 v4, v10, v10, v4 op_sel_hi:[1,1,0]
	v_pk_add_f32 v[68:69], v[68:69], v[68:69] op_sel:[0,1] op_sel_hi:[1,0]
	v_add_f32_e32 v72, v2, v4
	v_mul_f32_e32 v2, v85, v85
	v_mov_b32_e32 v4, v68
	v_mov_b32_e32 v71, v5
	v_fma_mix_f32 v74, v12, v12, v2 op_sel_hi:[1,1,0]
	v_mul_f32_e32 v2, v9, v9
	v_pk_add_f32 v[68:69], v[68:69], v[70:71]
	v_pk_mul_f32 v[70:71], v[4:5], v[4:5]
	v_fma_mix_f32 v76, v8, v8, v2 op_sel_hi:[1,1,0]
	v_mul_f32_e32 v73, v3, v3
	v_mul_f32_e32 v75, v6, v6
	v_mul_f32_e32 v77, v7, v7
	v_mov_b32_e32 v69, v71
	v_pk_add_f32 v[68:69], v[68:69], v[72:73]
	v_pk_add_f32 v[70:71], v[74:75], v[76:77]
	v_and_b32_e32 v4, 64, v92
	v_pk_add_f32 v[68:69], v[68:69], v[70:71]
	v_add_u32_e32 v4, 64, v4
	v_add_f32_e32 v2, v68, v69
	global_load_dwordx4 v[68:71], v[38:39], off
	global_load_dwordx4 v[72:75], v[40:41], off
	global_load_dwordx4 v[76:79], v[42:43], off
	global_load_dwordx4 v[80:83], v[44:45], off
	v_xor_b32_e32 v24, 1, v92
	v_cmp_lt_i32_e32 vcc, v24, v4
	v_cvt_f32_f16_e32 v86, v11
	v_xor_b32_e32 v11, 16, v92
	v_cndmask_b32_e32 v24, v92, v24, vcc
	v_lshlrev_b32_e32 v93, 2, v24
	ds_bpermute_b32 v24, v93, v2
	v_cvt_f32_f16_e32 v84, v12
	v_cvt_f32_f16_e32 v12, v10
	v_xor_b32_e32 v10, 32, v92
	v_cvt_f32_f16_e32 v32, v31
	s_waitcnt lgkmcnt(0)
	v_add_f32_e32 v2, v2, v24
	v_xor_b32_e32 v24, 2, v92
	v_cmp_lt_i32_e32 vcc, v24, v4
	v_cvt_f32_f16_e32 v54, v30
	v_cvt_f32_f16_e32 v28, v26
	v_cndmask_b32_e32 v24, v92, v24, vcc
	v_lshlrev_b32_e32 v98, 2, v24
	ds_bpermute_b32 v24, v98, v2
	v_cvt_f32_f16_e32 v104, v27
	v_cvt_f32_f16_e32 v94, v14
	v_cvt_f32_f16_e32 v96, v15
	v_cvt_f32_f16_e32 v102, v23
	s_waitcnt lgkmcnt(0)
	v_add_f32_e32 v2, v2, v24
	v_xor_b32_e32 v24, 4, v92
	v_cmp_lt_i32_e32 vcc, v24, v4
	v_mov_b32_e32 v100, v99
	v_cvt_f32_f16_e32 v8, v8
	v_cndmask_b32_e32 v24, v92, v24, vcc
	v_lshlrev_b32_e32 v106, 2, v24
	ds_bpermute_b32 v24, v106, v2
	s_waitcnt vmcnt(7)
	v_pk_mul_f32 v[14:15], v[54:55], v[16:17]
	s_waitcnt lgkmcnt(0)
	v_add_f32_e32 v2, v2, v24
	v_xor_b32_e32 v24, 8, v92
	v_cmp_lt_i32_e32 vcc, v24, v4
	s_waitcnt vmcnt(1)
	v_pk_mul_f32 v[8:9], v[8:9], v[78:79]
	v_cndmask_b32_e32 v24, v92, v24, vcc
	v_lshlrev_b32_e32 v107, 2, v24
	ds_bpermute_b32 v24, v107, v2
	v_cmp_lt_i32_e32 vcc, v11, v4
	s_waitcnt vmcnt(0)
	v_pk_mul_f32 v[6:7], v[6:7], v[82:83]
	s_waitcnt lgkmcnt(0)
	v_add_f32_e32 v2, v2, v24
	v_cndmask_b32_e32 v11, v92, v11, vcc
	v_lshlrev_b32_e32 v108, 2, v11
	ds_bpermute_b32 v11, v108, v2
	v_cmp_lt_i32_e32 vcc, v10, v4
	v_cvt_f32_f16_e32 v24, v22
	s_waitcnt lgkmcnt(0)
	v_add_f32_e32 v2, v2, v11
	v_cndmask_b32_e32 v4, v92, v10, vcc
	v_lshlrev_b32_e32 v109, 2, v4
	ds_bpermute_b32 v4, v109, v2
	v_pk_mul_f32 v[10:11], v[32:33], v[18:19]
	s_waitcnt lgkmcnt(0)
	v_add_f32_e32 v2, v2, v4
	v_fmamk_f32 v2, v2, 0x3a000000, v91
	v_rsq_f32_e32 v4, v2
	s_nop 0
	v_pk_mul_f32 v[30:31], v[10:11], v[4:5] op_sel_hi:[1,0]
	v_pk_mul_f32 v[10:11], v[28:29], v[58:59]
	v_pk_mul_f32 v[54:55], v[14:15], v[4:5] op_sel_hi:[1,0]
	v_pk_mul_f32 v[14:15], v[104:105], v[56:57]
	v_pk_mul_f32 v[26:27], v[10:11], v[4:5] op_sel_hi:[1,0]
	v_max_f32_e64 v2, |v30|, |v31|
	v_pk_mul_f32 v[32:33], v[14:15], v[4:5] op_sel_hi:[1,0]
	v_max_f32_e64 v10, |v26|, |v27|
	v_max3_f32 v2, |v54|, |v55|, v2
	v_max3_f32 v10, |v32|, |v33|, v10
	v_max3_f32 v2, v2, 0, v10
	v_pk_mul_f32 v[10:11], v[24:25], v[62:63]
	v_pk_mul_f32 v[14:15], v[102:103], v[60:61]
	v_pk_mul_f32 v[22:23], v[10:11], v[4:5] op_sel_hi:[1,0]
	v_pk_mul_f32 v[28:29], v[14:15], v[4:5] op_sel_hi:[1,0]
	v_max_f32_e64 v10, |v22|, |v23|
	v_max3_f32 v16, |v28|, |v29|, v10
	v_pk_mul_f32 v[10:11], v[20:21], v[66:67]
	v_pk_mul_f32 v[14:15], v[100:101], v[64:65]
	v_pk_mul_f32 v[18:19], v[10:11], v[4:5] op_sel_hi:[1,0]
	v_pk_mul_f32 v[24:25], v[14:15], v[4:5] op_sel_hi:[1,0]
	v_max_f32_e64 v10, |v18|, |v19|
	v_max3_f32 v10, |v24|, |v25|, v10
	v_max3_f32 v2, v2, v16, v10
	v_pk_mul_f32 v[10:11], v[96:97], v[70:71]
	v_pk_mul_f32 v[16:17], v[94:95], v[68:69]
	v_pk_mul_f32 v[14:15], v[10:11], v[4:5] op_sel_hi:[1,0]
	v_pk_mul_f32 v[20:21], v[16:17], v[4:5] op_sel_hi:[1,0]
	v_max_f32_e64 v10, |v14|, |v15|
	v_max3_f32 v56, |v20|, |v21|, v10
	v_pk_mul_f32 v[10:11], v[12:13], v[74:75]
	v_pk_mul_f32 v[12:13], v[86:87], v[72:73]
	v_pk_mul_f32 v[10:11], v[10:11], v[4:5] op_sel_hi:[1,0]
	v_pk_mul_f32 v[16:17], v[12:13], v[4:5] op_sel_hi:[1,0]
	v_max_f32_e64 v12, |v10|, |v11|
	v_max3_f32 v12, |v16|, |v17|, v12
	v_max3_f32 v58, v2, v56, v12
	v_pk_mul_f32 v[12:13], v[84:85], v[76:77]
	v_pk_mul_f32 v[8:9], v[8:9], v[4:5] op_sel_hi:[1,0]
	v_pk_mul_f32 v[12:13], v[12:13], v[4:5] op_sel_hi:[1,0]
	v_max_f32_e64 v2, |v8|, |v9|
	v_max3_f32 v59, |v12|, |v13|, v2
	v_mov_b32_e32 v2, v5
	v_pk_mul_f32 v[56:57], v[2:3], v[80:81]
	v_pk_mul_f32 v[2:3], v[6:7], v[4:5] op_sel_hi:[1,0]
	v_pk_mul_f32 v[4:5], v[56:57], v[4:5] op_sel_hi:[1,0]
	v_max_f32_e64 v6, |v2|, |v3|
	v_max3_f32 v6, |v4|, |v5|, v6
	v_max3_f32 v6, v58, v59, v6
	ds_bpermute_b32 v7, v93, v6
	s_waitcnt lgkmcnt(0)
	v_max_f32_e32 v7, v7, v7
	v_max_f32_e32 v6, v6, v7
	ds_bpermute_b32 v7, v98, v6
	s_waitcnt lgkmcnt(0)
	v_max_f32_e32 v7, v7, v7
	v_max_f32_e32 v6, v6, v7
	ds_bpermute_b32 v7, v106, v6
	s_waitcnt lgkmcnt(0)
	v_max_f32_e32 v7, v7, v7
	v_max_f32_e32 v6, v6, v7
	ds_bpermute_b32 v7, v107, v6
	s_waitcnt lgkmcnt(0)
	v_max_f32_e32 v7, v7, v7
	v_max_f32_e32 v6, v6, v7
	ds_bpermute_b32 v7, v108, v6
	s_waitcnt lgkmcnt(0)
	v_max_f32_e32 v7, v7, v7
	v_max_f32_e32 v6, v6, v7
	ds_bpermute_b32 v7, v109, v6
	s_waitcnt lgkmcnt(0)
	v_max_f32_e32 v7, v7, v7
	v_max_f32_e32 v6, v6, v7
	v_cmp_lt_f32_e64 s[8:9], 0, v6
	s_and_saveexec_b64 s[24:25], s[4:5]
	s_cbranch_execz .LBB0_52
	s_lshl_b64 s[26:27], s[22:23], 2
	v_mul_f32_e32 v7, 0x3c010204, v6
	s_add_u32 s26, s86, s26
	v_cndmask_b32_e64 v7, 1.0, v7, s[8:9]
	s_addc_u32 s27, s87, s27
	global_store_dword v35, v7, s[26:27]
	s_branch .LBB0_52

.LBB0_391:
	s_add_i32 s13, s66, -9
	s_cmp_eq_u32 s66, 8
	s_cselect_b32 s13, 0, s13
	s_cselect_b32 s15, s42, s44
	s_cselect_b32 s22, s43, s45
	s_cmp_lt_i32 s66, 8
	s_cselect_b32 s13, s66, s13
	s_cselect_b32 s22, s85, s22
	s_cselect_b32 s15, s84, s15
	v_lshl_add_u32 v148, s20, 8, v152
	v_lshl_or_b32 v160, s13, 8, v153
	v_mov_b32_e32 v146, s15
	v_mov_b32_e32 v147, s22
	v_ashrrev_i32_e32 v161, 31, v160
	v_ashrrev_i32_e32 v149, 31, v148
	s_cselect_b32 s13, 11, 8
	v_lshl_add_u64 v[146:147], v[160:161], 1, v[146:147]
	v_lshlrev_b64 v[160:161], s13, v[148:149]
	v_lshl_add_u64 v[160:161], v[160:161], 1, v[146:147]
	v_cvt_pk_bf16_f32 v126, v126, v127
	v_cvt_pk_bf16_f32 v127, v128, v129
	v_cvt_pk_bf16_f32 v128, v122, v123
	v_cvt_pk_bf16_f32 v129, v124, v125
	global_store_dwordx4 v[160:161], v[126:129], off sc1
	v_cvt_pk_bf16_f32 v114, v114, v115
	v_cvt_pk_bf16_f32 v115, v116, v117
	v_cvt_pk_bf16_f32 v116, v106, v107
	v_or_b32_e32 v106, 16, v148
	v_ashrrev_i32_e32 v107, 31, v106
	v_lshlrev_b64 v[106:107], s13, v[106:107]
	v_cvt_pk_bf16_f32 v117, v108, v109
	global_store_dwordx4 v[160:161], v[114:117], off offset:256 sc1
	s_andn2_b64 vcc, exec, s[4:5]
	s_mov_b64 s[4:5], -1
	v_lshl_add_u64 v[114:115], v[106:107], 1, v[146:147]
	v_cvt_pk_bf16_f32 v106, v118, v119
	v_cvt_pk_bf16_f32 v107, v120, v121
	v_cvt_pk_bf16_f32 v108, v110, v111
	v_cvt_pk_bf16_f32 v109, v112, v113
	global_store_dwordx4 v[114:115], v[106:109], off sc1
	v_cvt_pk_bf16_f32 v98, v98, v99
	v_cvt_pk_bf16_f32 v99, v100, v101
	v_cvt_pk_bf16_f32 v100, v90, v91
	v_or_b32_e32 v90, 32, v148
	v_ashrrev_i32_e32 v91, 31, v90
	v_lshlrev_b64 v[90:91], s13, v[90:91]
	v_cvt_pk_bf16_f32 v101, v92, v93
	global_store_dwordx4 v[114:115], v[98:101], off offset:256 sc1
	s_nop 1
	v_lshl_add_u64 v[98:99], v[90:91], 1, v[146:147]
	v_cvt_pk_bf16_f32 v90, v102, v103
	v_cvt_pk_bf16_f32 v91, v104, v105
	v_cvt_pk_bf16_f32 v92, v94, v95
	v_cvt_pk_bf16_f32 v93, v96, v97
	global_store_dwordx4 v[98:99], v[90:93], off sc1
	v_cvt_pk_bf16_f32 v82, v82, v83
	v_cvt_pk_bf16_f32 v83, v84, v85
	v_cvt_pk_bf16_f32 v84, v74, v75
	v_or_b32_e32 v74, 48, v148
	v_ashrrev_i32_e32 v75, 31, v74
	v_lshlrev_b64 v[74:75], s13, v[74:75]
	v_cvt_pk_bf16_f32 v85, v76, v77
	global_store_dwordx4 v[98:99], v[82:85], off offset:256 sc1
	s_nop 1
	v_lshl_add_u64 v[82:83], v[74:75], 1, v[146:147]
	v_cvt_pk_bf16_f32 v74, v86, v87
	v_cvt_pk_bf16_f32 v75, v88, v89
	v_cvt_pk_bf16_f32 v76, v78, v79
	v_cvt_pk_bf16_f32 v77, v80, v81
	global_store_dwordx4 v[82:83], v[74:77], off sc1
	v_cvt_pk_bf16_f32 v70, v70, v71
	v_cvt_pk_bf16_f32 v71, v72, v73
	v_cvt_pk_bf16_f32 v72, v66, v67
	v_add_u32_e32 v66, 0x80, v148
	v_ashrrev_i32_e32 v67, 31, v66
	v_lshlrev_b64 v[66:67], s13, v[66:67]
	v_lshl_add_u64 v[66:67], v[66:67], 1, v[146:147]
	v_cvt_pk_bf16_f32 v73, v68, v69
	global_store_dwordx4 v[82:83], v[70:73], off offset:256 sc1
	v_cvt_pk_bf16_f32 v62, v62, v63
	v_cvt_pk_bf16_f32 v63, v64, v65
	v_cvt_pk_bf16_f32 v64, v58, v59
	v_cvt_pk_bf16_f32 v65, v60, v61
	global_store_dwordx4 v[66:67], v[62:65], off sc1
	v_cvt_pk_bf16_f32 v50, v50, v51
	v_cvt_pk_bf16_f32 v51, v52, v53
	v_cvt_pk_bf16_f32 v52, v42, v43
	v_add_u32_e32 v42, 0x90, v148
	v_ashrrev_i32_e32 v43, 31, v42
	v_lshlrev_b64 v[42:43], s13, v[42:43]
	v_cvt_pk_bf16_f32 v53, v44, v45
	global_store_dwordx4 v[66:67], v[50:53], off offset:256 sc1
	s_nop 1
	v_lshl_add_u64 v[50:51], v[42:43], 1, v[146:147]
	v_cvt_pk_bf16_f32 v42, v54, v55
	v_cvt_pk_bf16_f32 v43, v56, v57
	v_cvt_pk_bf16_f32 v44, v46, v47
	v_cvt_pk_bf16_f32 v45, v48, v49
	global_store_dwordx4 v[50:51], v[42:45], off sc1
	v_cvt_pk_bf16_f32 v34, v34, v35
	v_cvt_pk_bf16_f32 v35, v36, v37
	v_cvt_pk_bf16_f32 v36, v26, v27
	v_add_u32_e32 v26, 0xa0, v148
	v_ashrrev_i32_e32 v27, 31, v26
	v_lshlrev_b64 v[26:27], s13, v[26:27]
	v_cvt_pk_bf16_f32 v37, v28, v29
	global_store_dwordx4 v[50:51], v[34:37], off offset:256 sc1
	s_nop 1
	v_lshl_add_u64 v[34:35], v[26:27], 1, v[146:147]
	v_cvt_pk_bf16_f32 v26, v38, v39
	v_cvt_pk_bf16_f32 v27, v40, v41
	v_cvt_pk_bf16_f32 v28, v30, v31
	v_cvt_pk_bf16_f32 v29, v32, v33
	global_store_dwordx4 v[34:35], v[26:29], off sc1
	v_cvt_pk_bf16_f32 v18, v18, v19
	v_cvt_pk_bf16_f32 v19, v20, v21
	v_cvt_pk_bf16_f32 v20, v10, v11
	v_add_u32_e32 v10, 0xb0, v148
	v_ashrrev_i32_e32 v11, 31, v10
	v_lshlrev_b64 v[10:11], s13, v[10:11]
	v_cvt_pk_bf16_f32 v21, v12, v13
	global_store_dwordx4 v[34:35], v[18:21], off offset:256 sc1
	s_nop 1
	v_lshl_add_u64 v[18:19], v[10:11], 1, v[146:147]
	v_cvt_pk_bf16_f32 v10, v22, v23
	v_cvt_pk_bf16_f32 v11, v24, v25
	v_cvt_pk_bf16_f32 v12, v14, v15
	v_cvt_pk_bf16_f32 v13, v16, v17
	global_store_dwordx4 v[18:19], v[10:13], off sc1
	v_cvt_pk_bf16_f32 v6, v6, v7
	v_cvt_pk_bf16_f32 v7, v8, v9
	v_cvt_pk_bf16_f32 v8, v2, v3
	v_cvt_pk_bf16_f32 v9, v4, v5
	global_store_dwordx4 v[18:19], v[6:9], off offset:256 sc1
	s_cbranch_vccnz .LBB0_384
	s_andn2_b64 vcc, exec, s[8:9]
	s_cbranch_vccnz .LBB0_383
	s_barrier
	s_branch .LBB0_383

.LBB0_415:
	s_ashr_i32 s6, s16, 31
	s_lshr_b32 s6, s6, 26
	s_add_i32 s6, s16, s6
	s_lshl_b32 s7, s6, 5
	s_and_b32 s8, s6, 0xffffffc0
	s_and_b32 s6, s7, 0xfffff800
	v_or_b32_e32 v24, s8, v6
	s_sub_i32 s6, s13, s6
	v_or_b32_e32 v26, 8, v24
	v_or_b32_e32 v28, 16, v24
	v_or_b32_e32 v30, 24, v24
	v_or_b32_e32 v32, 32, v24
	v_or_b32_e32 v34, 40, v24
	v_or_b32_e32 v36, 48, v24
	v_or_b32_e32 v38, 56, v24
	v_ashrrev_i32_e32 v25, 31, v24
	s_ashr_i32 s7, s6, 31
	v_ashrrev_i32_e32 v27, 31, v26
	v_ashrrev_i32_e32 v29, 31, v28
	v_ashrrev_i32_e32 v31, 31, v30
	v_ashrrev_i32_e32 v33, 31, v32
	v_ashrrev_i32_e32 v35, 31, v34
	v_ashrrev_i32_e32 v37, 31, v36
	v_ashrrev_i32_e32 v39, 31, v38
	v_lshlrev_b64 v[24:25], 13, v[24:25]
	v_lshl_add_u64 v[40:41], s[6:7], 2, v[2:3]
	v_lshlrev_b64 v[26:27], 13, v[26:27]
	v_lshlrev_b64 v[28:29], 13, v[28:29]
	v_lshlrev_b64 v[30:31], 13, v[30:31]
	v_lshlrev_b64 v[32:33], 13, v[32:33]
	v_lshlrev_b64 v[34:35], 13, v[34:35]
	v_lshlrev_b64 v[36:37], 13, v[36:37]
	v_lshlrev_b64 v[38:39], 13, v[38:39]
	v_lshl_add_u64 v[24:25], v[40:41], 0, v[24:25]
	v_lshl_add_u64 v[42:43], v[40:41], 0, v[26:27]
	v_lshl_add_u64 v[44:45], v[40:41], 0, v[28:29]
	v_lshl_add_u64 v[46:47], v[40:41], 0, v[30:31]
	v_lshl_add_u64 v[48:49], v[40:41], 0, v[32:33]
	v_lshl_add_u64 v[50:51], v[40:41], 0, v[34:35]
	v_lshl_add_u64 v[52:53], v[40:41], 0, v[36:37]
	v_lshl_add_u64 v[54:55], v[40:41], 0, v[38:39]
	global_load_dwordx4 v[24:27], v[24:25], off nt
	s_nop 0
	global_load_dwordx4 v[28:31], v[42:43], off nt
	global_load_dwordx4 v[32:35], v[44:45], off nt
	global_load_dwordx4 v[36:39], v[46:47], off nt
	s_nop 0
	global_load_dwordx4 v[40:43], v[48:49], off nt
	global_load_dwordx4 v[44:47], v[50:51], off nt
	s_nop 0
	global_load_dwordx4 v[48:51], v[52:53], off nt
	s_nop 0
	global_load_dwordx4 v[52:55], v[54:55], off nt
	v_add_u32_e32 v58, s6, v6
	s_ashr_i32 s9, s8, 31
	v_ashrrev_i32_e32 v59, 31, v58
	v_lshl_add_u64 v[56:57], s[8:9], 1, v[4:5]
	v_lshlrev_b64 v[64:65], 12, v[58:59]
	v_add_u32_e32 v60, 8, v58
	v_lshl_add_u64 v[64:65], v[56:57], 0, v[64:65]
	v_ashrrev_i32_e32 v61, 31, v60
	v_lshlrev_b64 v[60:61], 12, v[60:61]
	v_add_u32_e32 v62, 16, v58
	v_lshl_add_u64 v[60:61], v[56:57], 0, v[60:61]
	v_ashrrev_i32_e32 v63, 31, v62
	v_lshlrev_b64 v[62:63], 12, v[62:63]
	v_lshl_add_u64 v[62:63], v[56:57], 0, v[62:63]
	s_add_i32 s16, s16, s11
	s_add_i32 s13, s13, s15
	s_cmpk_lt_i32 s16, 0x800
	s_waitcnt vmcnt(0)
	ds_write2_b32 v8, v24, v25 offset1:1
	ds_write2_b32 v8, v26, v27 offset0:2 offset1:3
	ds_write2_b32 v9, v28, v29 offset1:1
	ds_write2_b32 v10, v30, v31 offset1:1
	ds_write2_b32 v11, v32, v33 offset1:1
	ds_write2_b32 v12, v34, v35 offset1:1
	ds_write2_b32 v13, v36, v37 offset1:1
	ds_write2_b32 v14, v38, v39 offset1:1
	ds_write2_b32 v15, v40, v41 offset1:1
	ds_write2_b32 v16, v42, v43 offset1:1
	ds_write2_b32 v17, v44, v45 offset1:1
	ds_write2_b32 v18, v46, v47 offset1:1
	ds_write2_b32 v19, v48, v49 offset1:1
	ds_write2_b32 v20, v50, v51 offset1:1
	ds_write2_b32 v21, v52, v53 offset1:1
	ds_write2_b32 v22, v54, v55 offset1:1
	s_waitcnt lgkmcnt(0)
	ds_read2_b32 v[24:25], v7 offset1:33
	s_waitcnt lgkmcnt(0)
	v_cvt_pk_bf16_f32 v24, v24, v25
	ds_read2_b32 v[26:27], v7 offset0:66 offset1:99
	s_waitcnt lgkmcnt(0)
	v_cvt_pk_bf16_f32 v25, v26, v27
	ds_read2_b32 v[26:27], v7 offset0:132 offset1:165
	s_waitcnt lgkmcnt(0)
	v_cvt_pk_bf16_f32 v26, v26, v27
	ds_read2_b32 v[28:29], v7 offset0:198 offset1:231
	s_waitcnt lgkmcnt(0)
	v_cvt_pk_bf16_f32 v27, v28, v29
	ds_read2_b32 v[28:29], v7 offset0:8 offset1:41
	global_store_dwordx4 v[64:65], v[24:27], off sc1
	v_add_u32_e32 v30, 24, v58
	v_ashrrev_i32_e32 v31, 31, v30
	s_waitcnt lgkmcnt(0)
	v_cvt_pk_bf16_f32 v24, v28, v29
	ds_read2_b32 v[26:27], v7 offset0:74 offset1:107
	s_waitcnt lgkmcnt(0)
	v_cvt_pk_bf16_f32 v25, v26, v27
	ds_read2_b32 v[26:27], v7 offset0:140 offset1:173
	s_waitcnt lgkmcnt(0)
	v_cvt_pk_bf16_f32 v26, v26, v27
	ds_read2_b32 v[28:29], v7 offset0:206 offset1:239
	s_waitcnt lgkmcnt(0)
	v_cvt_pk_bf16_f32 v27, v28, v29
	ds_read2_b32 v[28:29], v7 offset0:16 offset1:49
	global_store_dwordx4 v[60:61], v[24:27], off sc1
	v_lshlrev_b64 v[30:31], 12, v[30:31]
	v_lshl_add_u64 v[30:31], v[56:57], 0, v[30:31]
	s_waitcnt lgkmcnt(0)
	v_cvt_pk_bf16_f32 v24, v28, v29
	ds_read2_b32 v[26:27], v7 offset0:82 offset1:115
	s_waitcnt lgkmcnt(0)
	v_cvt_pk_bf16_f32 v25, v26, v27
	ds_read2_b32 v[26:27], v7 offset0:148 offset1:181
	s_waitcnt lgkmcnt(0)
	v_cvt_pk_bf16_f32 v26, v26, v27
	ds_read2_b32 v[28:29], v7 offset0:214 offset1:247
	s_waitcnt lgkmcnt(0)
	v_cvt_pk_bf16_f32 v27, v28, v29
	ds_read2_b32 v[28:29], v7 offset0:24 offset1:57
	global_store_dwordx4 v[62:63], v[24:27], off sc1
	s_waitcnt lgkmcnt(0)
	s_nop 0
	v_cvt_pk_bf16_f32 v24, v28, v29
	ds_read2_b32 v[26:27], v7 offset0:90 offset1:123
	s_waitcnt lgkmcnt(0)
	v_cvt_pk_bf16_f32 v25, v26, v27
	ds_read2_b32 v[26:27], v7 offset0:156 offset1:189
	s_waitcnt lgkmcnt(0)
	v_cvt_pk_bf16_f32 v26, v26, v27
	ds_read2_b32 v[28:29], v7 offset0:222 offset1:255
	s_waitcnt lgkmcnt(0)
	v_cvt_pk_bf16_f32 v27, v28, v29
	global_store_dwordx4 v[30:31], v[24:27], off sc1
	s_waitcnt lgkmcnt(0)
	s_cbranch_scc1 .LBB0_415

.LBB0_418:
	s_lshl_b32 s18, s7, 6
	v_or_b32_e32 v56, s18, v6
	s_ashr_i32 s7, s6, 31
	v_lshl_add_u64 v[54:55], s[6:7], 2, v[2:3]
	v_or_b32_e32 v28, 8, v56
	v_or_b32_e32 v34, 16, v56
	v_or_b32_e32 v36, 24, v56
	v_or_b32_e32 v42, 32, v56
	v_or_b32_e32 v44, 40, v56
	v_mad_i64_i32 v[26:27], s[6:7], v56, s13, v[54:55]
	v_mad_i64_i32 v[30:31], s[6:7], v28, s13, v[54:55]
	v_mad_i64_i32 v[34:35], s[6:7], v34, s13, v[54:55]
	v_mad_i64_i32 v[38:39], s[6:7], v36, s13, v[54:55]
	v_mad_i64_i32 v[42:43], s[6:7], v42, s13, v[54:55]
	v_mad_i64_i32 v[46:47], s[6:7], v44, s13, v[54:55]
	global_load_dwordx4 v[26:29], v[26:27], off nt
	s_nop 0
	global_load_dwordx4 v[30:33], v[30:31], off nt
	s_nop 0
	global_load_dwordx4 v[34:37], v[34:35], off nt
	s_nop 0
	global_load_dwordx4 v[38:41], v[38:39], off nt
	s_nop 0
	global_load_dwordx4 v[42:45], v[42:43], off nt
	s_nop 0
	global_load_dwordx4 v[46:49], v[46:47], off nt
	v_or_b32_e32 v50, 48, v56
	v_mad_i64_i32 v[50:51], s[6:7], v50, s13, v[54:55]
	global_load_dwordx4 v[50:53], v[50:51], off nt
	v_or_b32_e32 v56, 56, v56
	v_mad_i64_i32 v[54:55], s[6:7], v56, s13, v[54:55]
	global_load_dwordx4 v[54:57], v[54:55], off nt
	s_ashr_i32 s19, s18, 31
	s_add_i32 s15, s15, s11
	s_add_i32 s8, s8, s9
	s_cmpk_lt_i32 s15, 0x1800
	s_waitcnt vmcnt(0)
	ds_write2_b32 v11, v26, v27 offset1:1
	ds_write2_b32 v11, v28, v29 offset0:2 offset1:3
	ds_write2_b32 v12, v30, v31 offset1:1
	ds_write2_b32 v13, v32, v33 offset1:1
	ds_write2_b32 v14, v34, v35 offset1:1
	ds_write2_b32 v15, v36, v37 offset1:1
	ds_write2_b32 v16, v38, v39 offset1:1
	ds_write2_b32 v17, v40, v41 offset1:1
	ds_write2_b32 v18, v42, v43 offset1:1
	ds_write2_b32 v19, v44, v45 offset1:1
	ds_write2_b32 v20, v46, v47 offset1:1
	ds_write2_b32 v21, v48, v49 offset1:1
	ds_write2_b32 v22, v50, v51 offset1:1
	ds_write2_b32 v23, v52, v53 offset1:1
	ds_write2_b32 v24, v54, v55 offset1:1
	ds_write2_b32 v25, v56, v57 offset1:1
	s_waitcnt lgkmcnt(0)
	v_add_u32_e32 v32, s16, v6
	ds_read2_b32 v[26:27], v10 offset1:33
	v_ashrrev_i32_e32 v33, 31, v32
	s_waitcnt lgkmcnt(0)
	v_cvt_pk_bf16_f32 v26, v26, v27
	ds_read2_b32 v[28:29], v10 offset0:66 offset1:99
	v_lshl_add_u64 v[34:35], s[18:19], 1, v[4:5]
	v_lshlrev_b64 v[32:33], 12, v[32:33]
	s_waitcnt lgkmcnt(0)
	v_cvt_pk_bf16_f32 v27, v28, v29
	ds_read2_b32 v[28:29], v10 offset0:132 offset1:165
	v_lshl_add_u64 v[32:33], v[34:35], 0, v[32:33]
	s_waitcnt lgkmcnt(0)
	v_cvt_pk_bf16_f32 v28, v28, v29
	ds_read2_b32 v[30:31], v10 offset0:198 offset1:231
	s_waitcnt lgkmcnt(0)
	v_cvt_pk_bf16_f32 v29, v30, v31
	global_store_dwordx4 v[32:33], v[26:29], off sc1
	v_add_u32_e32 v32, s16, v7
	ds_read2_b32 v[30:31], v10 offset0:8 offset1:41
	s_waitcnt lgkmcnt(0)
	v_cvt_pk_bf16_f32 v26, v30, v31
	ds_read2_b32 v[28:29], v10 offset0:74 offset1:107
	v_ashrrev_i32_e32 v33, 31, v32
	s_waitcnt lgkmcnt(0)
	v_cvt_pk_bf16_f32 v27, v28, v29
	ds_read2_b32 v[28:29], v10 offset0:140 offset1:173
	v_lshlrev_b64 v[32:33], 12, v[32:33]
	s_waitcnt lgkmcnt(0)
	v_cvt_pk_bf16_f32 v28, v28, v29
	ds_read2_b32 v[30:31], v10 offset0:206 offset1:239
	s_waitcnt lgkmcnt(0)
	v_cvt_pk_bf16_f32 v29, v30, v31
	v_lshl_add_u64 v[32:33], v[34:35], 0, v[32:33]
	ds_read2_b32 v[30:31], v10 offset0:16 offset1:49
	global_store_dwordx4 v[32:33], v[26:29], off sc1
	v_add_u32_e32 v32, s16, v8
	v_ashrrev_i32_e32 v33, 31, v32
	s_waitcnt lgkmcnt(0)
	v_cvt_pk_bf16_f32 v26, v30, v31
	ds_read2_b32 v[28:29], v10 offset0:82 offset1:115
	s_waitcnt lgkmcnt(0)
	v_cvt_pk_bf16_f32 v27, v28, v29
	ds_read2_b32 v[28:29], v10 offset0:148 offset1:181
	s_waitcnt lgkmcnt(0)
	v_cvt_pk_bf16_f32 v28, v28, v29
	ds_read2_b32 v[30:31], v10 offset0:214 offset1:247
	v_lshlrev_b64 v[32:33], 12, v[32:33]
	s_waitcnt lgkmcnt(0)
	v_cvt_pk_bf16_f32 v29, v30, v31
	ds_read2_b32 v[30:31], v10 offset0:24 offset1:57
	v_lshl_add_u64 v[32:33], v[34:35], 0, v[32:33]
	global_store_dwordx4 v[32:33], v[26:29], off sc1
	s_waitcnt lgkmcnt(0)
	s_nop 0
	v_cvt_pk_bf16_f32 v26, v30, v31
	v_add_u32_e32 v30, s16, v9
	v_ashrrev_i32_e32 v31, 31, v30
	ds_read2_b32 v[28:29], v10 offset0:90 offset1:123
	v_lshlrev_b64 v[30:31], 12, v[30:31]
	s_waitcnt lgkmcnt(0)
	v_cvt_pk_bf16_f32 v27, v28, v29
	ds_read2_b32 v[28:29], v10 offset0:156 offset1:189
	v_lshl_add_u64 v[30:31], v[34:35], 0, v[30:31]
	s_waitcnt lgkmcnt(0)
	v_cvt_pk_bf16_f32 v28, v28, v29
	ds_read2_b32 v[32:33], v10 offset0:222 offset1:255
	s_waitcnt lgkmcnt(0)
	v_cvt_pk_bf16_f32 v29, v32, v33
	global_store_dwordx4 v[30:31], v[26:29], off sc1
	s_waitcnt lgkmcnt(0)
	s_cbranch_scc0 .LBB0_421

.LBB0_423:
	s_ashr_i32 s4, s10, 31
	s_lshr_b32 s4, s4, 26
	s_add_i32 s4, s10, s4
	s_lshl_b32 s5, s4, 5
	s_and_b32 s6, s4, 0xffffffc0
	s_and_b32 s4, s5, 0xfffff800
	v_or_b32_e32 v22, s6, v6
	s_sub_i32 s4, s8, s4
	v_or_b32_e32 v24, 8, v22
	v_or_b32_e32 v26, 16, v22
	v_or_b32_e32 v28, 24, v22
	v_or_b32_e32 v30, 32, v22
	v_or_b32_e32 v32, 40, v22
	v_or_b32_e32 v34, 48, v22
	v_or_b32_e32 v36, 56, v22
	v_ashrrev_i32_e32 v23, 31, v22
	s_ashr_i32 s5, s4, 31
	v_ashrrev_i32_e32 v25, 31, v24
	v_ashrrev_i32_e32 v27, 31, v26
	v_ashrrev_i32_e32 v29, 31, v28
	v_ashrrev_i32_e32 v31, 31, v30
	v_ashrrev_i32_e32 v33, 31, v32
	v_ashrrev_i32_e32 v35, 31, v34
	v_ashrrev_i32_e32 v37, 31, v36
	v_lshlrev_b64 v[22:23], 13, v[22:23]
	v_lshl_add_u64 v[38:39], s[4:5], 2, v[2:3]
	v_lshlrev_b64 v[24:25], 13, v[24:25]
	v_lshlrev_b64 v[26:27], 13, v[26:27]
	v_lshlrev_b64 v[28:29], 13, v[28:29]
	v_lshlrev_b64 v[30:31], 13, v[30:31]
	v_lshlrev_b64 v[32:33], 13, v[32:33]
	v_lshlrev_b64 v[34:35], 13, v[34:35]
	v_lshlrev_b64 v[36:37], 13, v[36:37]
	v_lshl_add_u64 v[22:23], v[38:39], 0, v[22:23]
	v_lshl_add_u64 v[40:41], v[38:39], 0, v[24:25]
	v_lshl_add_u64 v[42:43], v[38:39], 0, v[26:27]
	v_lshl_add_u64 v[44:45], v[38:39], 0, v[28:29]
	v_lshl_add_u64 v[46:47], v[38:39], 0, v[30:31]
	v_lshl_add_u64 v[48:49], v[38:39], 0, v[32:33]
	v_lshl_add_u64 v[50:51], v[38:39], 0, v[34:35]
	v_lshl_add_u64 v[52:53], v[38:39], 0, v[36:37]
	global_load_dwordx4 v[22:25], v[22:23], off nt
	s_nop 0
	global_load_dwordx4 v[26:29], v[40:41], off nt
	global_load_dwordx4 v[30:33], v[42:43], off nt
	global_load_dwordx4 v[34:37], v[44:45], off nt
	s_nop 0
	global_load_dwordx4 v[38:41], v[46:47], off nt
	global_load_dwordx4 v[42:45], v[48:49], off nt
	s_nop 0
	global_load_dwordx4 v[46:49], v[50:51], off nt
	s_nop 0
	global_load_dwordx4 v[50:53], v[52:53], off nt
	v_add_u32_e32 v56, s4, v6
	s_ashr_i32 s7, s6, 31
	v_ashrrev_i32_e32 v57, 31, v56
	v_lshl_add_u64 v[54:55], s[6:7], 1, v[4:5]
	v_lshlrev_b64 v[62:63], 12, v[56:57]
	v_add_u32_e32 v58, 8, v56
	v_lshl_add_u64 v[62:63], v[54:55], 0, v[62:63]
	v_ashrrev_i32_e32 v59, 31, v58
	v_lshlrev_b64 v[58:59], 12, v[58:59]
	v_add_u32_e32 v60, 16, v56
	v_lshl_add_u64 v[58:59], v[54:55], 0, v[58:59]
	v_ashrrev_i32_e32 v61, 31, v60
	v_lshlrev_b64 v[60:61], 12, v[60:61]
	v_lshl_add_u64 v[60:61], v[54:55], 0, v[60:61]
	s_add_i32 s10, s10, s11
	s_add_i32 s8, s8, s9
	s_cmpk_lt_i32 s10, 0x800
	s_waitcnt vmcnt(0)
	ds_write2_b32 v7, v22, v23 offset1:1
	ds_write2_b32 v7, v24, v25 offset0:2 offset1:3
	ds_write2_b32 v8, v26, v27 offset1:1
	ds_write2_b32 v9, v28, v29 offset1:1
	ds_write2_b32 v10, v30, v31 offset1:1
	ds_write2_b32 v11, v32, v33 offset1:1
	ds_write2_b32 v12, v34, v35 offset1:1
	ds_write2_b32 v13, v36, v37 offset1:1
	ds_write2_b32 v14, v38, v39 offset1:1
	ds_write2_b32 v15, v40, v41 offset1:1
	ds_write2_b32 v16, v42, v43 offset1:1
	ds_write2_b32 v17, v44, v45 offset1:1
	ds_write2_b32 v18, v46, v47 offset1:1
	ds_write2_b32 v19, v48, v49 offset1:1
	ds_write2_b32 v20, v50, v51 offset1:1
	ds_write2_b32 v21, v52, v53 offset1:1
	s_waitcnt lgkmcnt(0)
	ds_read2_b32 v[22:23], v1 offset1:33
	s_waitcnt lgkmcnt(0)
	v_cvt_pk_bf16_f32 v22, v22, v23
	ds_read2_b32 v[24:25], v1 offset0:66 offset1:99
	s_waitcnt lgkmcnt(0)
	v_cvt_pk_bf16_f32 v23, v24, v25
	ds_read2_b32 v[24:25], v1 offset0:132 offset1:165
	s_waitcnt lgkmcnt(0)
	v_cvt_pk_bf16_f32 v24, v24, v25
	ds_read2_b32 v[26:27], v1 offset0:198 offset1:231
	s_waitcnt lgkmcnt(0)
	v_cvt_pk_bf16_f32 v25, v26, v27
	ds_read2_b32 v[26:27], v1 offset0:8 offset1:41
	global_store_dwordx4 v[62:63], v[22:25], off sc1
	v_add_u32_e32 v28, 24, v56
	v_ashrrev_i32_e32 v29, 31, v28
	s_waitcnt lgkmcnt(0)
	v_cvt_pk_bf16_f32 v22, v26, v27
	ds_read2_b32 v[24:25], v1 offset0:74 offset1:107
	s_waitcnt lgkmcnt(0)
	v_cvt_pk_bf16_f32 v23, v24, v25
	ds_read2_b32 v[24:25], v1 offset0:140 offset1:173
	s_waitcnt lgkmcnt(0)
	v_cvt_pk_bf16_f32 v24, v24, v25
	ds_read2_b32 v[26:27], v1 offset0:206 offset1:239
	s_waitcnt lgkmcnt(0)
	v_cvt_pk_bf16_f32 v25, v26, v27
	ds_read2_b32 v[26:27], v1 offset0:16 offset1:49
	global_store_dwordx4 v[58:59], v[22:25], off sc1
	v_lshlrev_b64 v[28:29], 12, v[28:29]
	v_lshl_add_u64 v[28:29], v[54:55], 0, v[28:29]
	s_waitcnt lgkmcnt(0)
	v_cvt_pk_bf16_f32 v22, v26, v27
	ds_read2_b32 v[24:25], v1 offset0:82 offset1:115
	s_waitcnt lgkmcnt(0)
	v_cvt_pk_bf16_f32 v23, v24, v25
	ds_read2_b32 v[24:25], v1 offset0:148 offset1:181
	s_waitcnt lgkmcnt(0)
	v_cvt_pk_bf16_f32 v24, v24, v25
	ds_read2_b32 v[26:27], v1 offset0:214 offset1:247
	s_waitcnt lgkmcnt(0)
	v_cvt_pk_bf16_f32 v25, v26, v27
	ds_read2_b32 v[26:27], v1 offset0:24 offset1:57
	global_store_dwordx4 v[60:61], v[22:25], off sc1
	s_waitcnt lgkmcnt(0)
	s_nop 0
	v_cvt_pk_bf16_f32 v22, v26, v27
	ds_read2_b32 v[24:25], v1 offset0:90 offset1:123
	s_waitcnt lgkmcnt(0)
	v_cvt_pk_bf16_f32 v23, v24, v25
	ds_read2_b32 v[24:25], v1 offset0:156 offset1:189
	s_waitcnt lgkmcnt(0)
	v_cvt_pk_bf16_f32 v24, v24, v25
	ds_read2_b32 v[26:27], v1 offset0:222 offset1:255
	s_waitcnt lgkmcnt(0)
	v_cvt_pk_bf16_f32 v25, v26, v27
	global_store_dwordx4 v[28:29], v[22:25], off sc1
	s_waitcnt lgkmcnt(0)
	s_cbranch_scc1 .LBB0_423

.LBB0_486:
	s_or_b64 exec, exec, s[40:41]
	s_add_i32 s40, s48, s73
	s_waitcnt vmcnt(1)
	ds_write_b128 v171, v[6:9]
	s_waitcnt vmcnt(0)
	ds_write_b16 v172, v2 offset:36864
	ds_write_b16_d16_hi v172, v2 offset:37384
	ds_write_b16 v172, v3 offset:37904
	ds_write_b16_d16_hi v172, v3 offset:38424
	ds_write_b16 v172, v4 offset:38944
	ds_write_b16_d16_hi v172, v4 offset:39464
	ds_write_b16 v172, v5 offset:39984
	ds_write_b16_d16_hi v172, v5 offset:40504
	v_add_u32_e32 v2, s40, v161
	v_ashrrev_i32_e32 v3, 31, v2
	v_lshlrev_b64 v[2:3], 8, v[2:3]
	v_or3_b32 v3, v3, 0, 0
	v_or3_b32 v2, v2, v146, s63
	v_lshlrev_b64 v[2:3], 1, v[2:3]
	v_lshl_add_u64 v[6:7], s[44:45], 0, v[2:3]
	v_lshl_add_u64 v[2:3], s[42:43], 0, v[2:3]
	global_load_dwordx4 v[2:5], v[2:3], off
	s_lshl_b32 s46, s46, 1
	v_lshl_add_u64 v[150:151], v[144:145], 0, s[46:47]
	s_waitcnt vmcnt(0)
	ds_write_b128 v173, v[2:5]
	global_load_dwordx4 v[2:5], v[6:7], off
	s_waitcnt vmcnt(0)
	ds_write_b16 v170, v2 offset:37120
	ds_write_b16_d16_hi v170, v2 offset:37640
	ds_write_b16 v170, v3 offset:38160
	ds_write_b16_d16_hi v170, v3 offset:38680
	ds_write_b16 v170, v4 offset:39200
	ds_write_b16_d16_hi v170, v4 offset:39720
	ds_write_b16 v170, v5 offset:40240
	ds_write_b16_d16_hi v170, v5 offset:40760
	v_add_u32_e32 v2, s40, v162
	v_ashrrev_i32_e32 v3, 31, v2
	v_lshlrev_b64 v[2:3], 8, v[2:3]
	v_or3_b32 v3, v3, 0, 0
	v_or3_b32 v2, v2, v146, s63
	v_lshlrev_b64 v[2:3], 1, v[2:3]
	v_lshl_add_u64 v[6:7], s[44:45], 0, v[2:3]
	v_lshl_add_u64 v[2:3], s[42:43], 0, v[2:3]
	global_load_dwordx4 v[2:5], v[2:3], off
	s_lshl_b32 s40, s72, 2
	s_load_dwordx16 s[64:79], s[0:1], 0x40
	s_waitcnt vmcnt(0)
	ds_write_b128 v174, v[2:5]
	global_load_dwordx4 v[2:5], v[6:7], off
	s_waitcnt vmcnt(0)
	ds_write_b16 v175, v2 offset:36864
	ds_write_b16_d16_hi v175, v2 offset:37384
	ds_write_b16 v175, v3 offset:37904
	ds_write_b16_d16_hi v175, v3 offset:38424
	ds_write_b16 v175, v4 offset:38944
	ds_write_b16_d16_hi v175, v4 offset:39464
	ds_write_b16 v175, v5 offset:39984
	ds_write_b16_d16_hi v175, v5 offset:40504
	v_mov_b32_e32 v2, s40
	s_waitcnt lgkmcnt(0)
	s_barrier
	global_load_dword v178, v2, s[72:73]
	ds_read_b128 v[2:5], v176
	ds_read_b128 v[6:9], v176 offset:32
	s_waitcnt lgkmcnt(1)
	v_mfma_f32_32x32x16_bf16 v[66:81], v[2:5], v[50:53], 0
	ds_read_b128 v[2:5], v176 offset:64
	ds_read_b128 v[18:21], v176 offset:4640
	ds_read_b128 v[34:37], v176 offset:9248
	s_or_b64 s[40:41], s[38:39], s[6:7]
	s_cmp_lg_u32 s49, 31
	ds_read_b128 v[54:57], v176 offset:13856
	ds_read_b128 v[180:183], v176 offset:18464
	s_waitcnt lgkmcnt(5)
	v_mfma_f32_32x32x16_bf16 v[66:81], v[6:9], v[138:141], v[66:81]
	s_waitcnt vmcnt(0)
	v_mul_f32_e32 v179, 0x3fb8aa3b, v178
	s_waitcnt lgkmcnt(4)
	v_mfma_f32_32x32x16_bf16 v[66:81], v[2:5], v[134:137], v[66:81]
	ds_read_b128 v[2:5], v176 offset:96
	s_waitcnt lgkmcnt(0)
	v_mfma_f32_32x32x16_bf16 v[66:81], v[2:5], v[130:133], v[66:81]
	ds_read_b128 v[2:5], v176 offset:4608
	s_waitcnt lgkmcnt(0)
	v_mfma_f32_32x32x16_bf16 v[2:17], v[2:5], v[50:53], 0
	s_nop 8
	v_cndmask_b32_e64 v68, v177, v68, s[8:9]
	v_cndmask_b32_e64 v66, v177, v66, s[4:5]
	v_cndmask_b32_e64 v66, v66, v177, s[38:39]
	v_cndmask_b32_e64 v67, v67, v177, s[40:41]
	v_mfma_f32_32x32x16_bf16 v[2:17], v[18:21], v[138:141], v[2:17]
	ds_read_b128 v[18:21], v176 offset:4672
	s_waitcnt lgkmcnt(0)
	v_mfma_f32_32x32x16_bf16 v[2:17], v[18:21], v[134:137], v[2:17]
	ds_read_b128 v[18:21], v176 offset:4704
	s_waitcnt lgkmcnt(0)
	v_mfma_f32_32x32x16_bf16 v[2:17], v[18:21], v[130:133], v[2:17]
	ds_read_b128 v[18:21], v176 offset:9216
	s_waitcnt lgkmcnt(0)
	v_mfma_f32_32x32x16_bf16 v[18:33], v[18:21], v[50:53], 0
	s_nop 8
	v_cndmask_b32_e64 v185, v11, v177, s[38:39]
	v_cndmask_b32_e64 v186, v12, v177, s[38:39]
	v_cndmask_b32_e64 v188, v13, v177, s[38:39]
	v_cndmask_b32_e64 v189, v14, v177, s[38:39]
	v_cndmask_b32_e64 v190, v15, v177, s[38:39]
	v_cndmask_b32_e64 v191, v16, v177, s[38:39]
	v_cndmask_b32_e64 v192, v17, v177, s[38:39]
	v_mfma_f32_32x32x16_bf16 v[18:33], v[34:37], v[138:141], v[18:33]
	ds_read_b128 v[34:37], v176 offset:9280
	s_waitcnt lgkmcnt(0)
	v_mfma_f32_32x32x16_bf16 v[18:33], v[34:37], v[134:137], v[18:33]
	ds_read_b128 v[34:37], v176 offset:9312
	s_waitcnt lgkmcnt(0)
	v_mfma_f32_32x32x16_bf16 v[18:33], v[34:37], v[130:133], v[18:33]
	ds_read_b128 v[34:37], v176 offset:13824
	s_waitcnt lgkmcnt(0)
	v_mfma_f32_32x32x16_bf16 v[34:49], v[34:37], v[50:53], 0
	s_nop 8
	v_cndmask_b32_e64 v193, v18, v177, s[38:39]
	v_cndmask_b32_e64 v194, v19, v177, s[38:39]
	v_cndmask_b32_e64 v195, v20, v177, s[38:39]
	v_cndmask_b32_e64 v196, v21, v177, s[38:39]
	v_cndmask_b32_e64 v197, v22, v177, s[38:39]
	v_cndmask_b32_e64 v198, v23, v177, s[38:39]
	v_cndmask_b32_e64 v199, v24, v177, s[38:39]
	v_mfma_f32_32x32x16_bf16 v[34:49], v[54:57], v[138:141], v[34:49]
	ds_read_b128 v[54:57], v176 offset:13888
	v_cndmask_b32_e64 v200, v25, v177, s[38:39]
	v_cndmask_b32_e64 v201, v26, v177, s[38:39]
	v_cndmask_b32_e64 v202, v27, v177, s[38:39]
	v_cndmask_b32_e64 v203, v28, v177, s[38:39]
	v_cndmask_b32_e64 v204, v29, v177, s[38:39]
	v_cndmask_b32_e64 v205, v30, v177, s[38:39]
	s_waitcnt lgkmcnt(0)
	v_mfma_f32_32x32x16_bf16 v[34:49], v[54:57], v[134:137], v[34:49]
	ds_read_b128 v[54:57], v176 offset:13920
	v_cndmask_b32_e64 v206, v31, v177, s[38:39]
	s_waitcnt lgkmcnt(0)
	v_mfma_f32_32x32x16_bf16 v[34:49], v[54:57], v[130:133], v[34:49]
	ds_read_b128 v[54:57], v176 offset:18432
	s_waitcnt lgkmcnt(0)
	v_mfma_f32_32x32x16_bf16 v[50:65], v[54:57], v[50:53], 0
	s_nop 8
	v_cndmask_b32_e64 v38, v38, v177, s[38:39]
	v_cndmask_b32_e64 v31, v45, v177, s[38:39]
	v_cndmask_b32_e64 v30, v46, v177, s[38:39]
	v_cndmask_b32_e64 v29, v47, v177, s[38:39]
	v_cndmask_b32_e64 v28, v48, v177, s[38:39]
	v_cndmask_b32_e64 v27, v49, v177, s[38:39]
	v_mfma_f32_32x32x16_bf16 v[50:65], v[180:183], v[138:141], v[50:65]
	ds_read_b128 v[138:141], v176 offset:18496
	v_cndmask_b32_e64 v180, v7, v177, s[38:39]
	v_cndmask_b32_e64 v181, v8, v177, s[38:39]
	v_cndmask_b32_e64 v182, v9, v177, s[38:39]
	v_cndmask_b32_e64 v183, v10, v177, s[38:39]
	s_waitcnt lgkmcnt(0)
	v_mfma_f32_32x32x16_bf16 v[50:65], v[138:141], v[134:137], v[50:65]
	ds_read_b128 v[134:137], v176 offset:18528
	v_cndmask_b32_e64 v138, v3, v177, s[38:39]
	v_cndmask_b32_e64 v139, v4, v177, s[38:39]
	v_cndmask_b32_e64 v140, v5, v177, s[38:39]
	v_cndmask_b32_e64 v141, v6, v177, s[38:39]
	s_waitcnt lgkmcnt(0)
	v_mfma_f32_32x32x16_bf16 v[50:65], v[134:137], v[130:133], v[50:65]
	v_cndmask_b32_e64 v131, v68, v177, s[38:39]
	v_cndmask_b32_e64 v68, v177, v69, s[10:11]
	v_cndmask_b32_e64 v69, v177, v70, s[12:13]
	v_cndmask_b32_e64 v70, v69, v177, s[38:39]
	v_cndmask_b32_e64 v69, v177, v71, s[14:15]
	v_max3_f32 v130, v66, s89, v67
	v_cndmask_b32_e64 v132, v68, v177, s[38:39]
	v_cndmask_b32_e64 v71, v69, v177, s[38:39]
	v_cndmask_b32_e64 v69, v177, v72, s[16:17]
	v_max3_f32 v68, v130, v131, v132
	v_cndmask_b32_e64 v130, v69, v177, s[38:39]
	v_cndmask_b32_e64 v69, v177, v73, s[18:19]
	v_cndmask_b32_e64 v73, v69, v177, s[38:39]
	v_cndmask_b32_e64 v69, v177, v74, s[20:21]
	v_cndmask_b32_e64 v133, v69, v177, s[38:39]
	v_cndmask_b32_e64 v69, v177, v75, s[22:23]
	v_cndmask_b32_e64 v134, v69, v177, s[38:39]
	v_cndmask_b32_e64 v69, v177, v76, s[24:25]
	v_cndmask_b32_e64 v76, v69, v177, s[38:39]
	v_cndmask_b32_e64 v69, v177, v77, s[26:27]
	v_max3_f32 v68, v68, v70, v71
	v_cndmask_b32_e64 v77, v69, v177, s[38:39]
	v_cndmask_b32_e64 v69, v177, v78, s[28:29]
	v_max3_f32 v68, v68, v130, v73
	v_cndmask_b32_e64 v135, v69, v177, s[38:39]
	v_cndmask_b32_e64 v69, v177, v79, s[30:31]
	v_max3_f32 v68, v68, v133, v134
	v_cndmask_b32_e64 v79, v69, v177, s[38:39]
	v_cndmask_b32_e64 v69, v177, v80, s[34:35]
	v_max3_f32 v68, v68, v76, v77
	v_cndmask_b32_e64 v136, v69, v177, s[38:39]
	v_cndmask_b32_e64 v69, v177, v81, s[36:37]
	v_max3_f32 v68, v68, v135, v79
	v_cndmask_b32_e64 v81, v69, v177, s[38:39]
	v_max3_f32 v68, v68, v136, v81
	v_cndmask_b32_e64 v137, v2, v177, s[38:39]
	v_max3_f32 v2, v68, v137, v138
	v_max3_f32 v2, v2, v139, v140
	v_max3_f32 v2, v2, v141, v180
	v_max3_f32 v2, v2, v181, v182
	v_max3_f32 v2, v2, v183, v185
	v_max3_f32 v2, v2, v186, v188
	v_max3_f32 v2, v2, v189, v190
	v_max3_f32 v2, v2, v191, v192
	v_max3_f32 v2, v2, v193, v194
	v_max3_f32 v2, v2, v195, v196
	v_max3_f32 v2, v2, v197, v198
	v_max3_f32 v2, v2, v199, v200
	v_max3_f32 v2, v2, v201, v202
	v_max3_f32 v2, v2, v203, v204
	v_max3_f32 v2, v2, v205, v206
	v_cndmask_b32_e64 v78, v32, v177, s[38:39]
	v_cndmask_b32_e64 v75, v33, v177, s[38:39]
	v_max3_f32 v2, v2, v78, v75
	v_cndmask_b32_e64 v74, v34, v177, s[38:39]
	v_cndmask_b32_e64 v72, v35, v177, s[38:39]
	v_max3_f32 v2, v2, v74, v72
	v_cndmask_b32_e64 v69, v36, v177, s[38:39]
	v_cndmask_b32_e64 v68, v37, v177, s[38:39]
	v_max3_f32 v2, v2, v69, v68
	v_cndmask_b32_e64 v37, v39, v177, s[38:39]
	v_max3_f32 v2, v2, v38, v37
	v_cndmask_b32_e64 v36, v40, v177, s[38:39]
	v_cndmask_b32_e64 v35, v41, v177, s[38:39]
	v_max3_f32 v2, v2, v36, v35
	v_cndmask_b32_e64 v34, v42, v177, s[38:39]
	v_cndmask_b32_e64 v33, v43, v177, s[38:39]
	v_max3_f32 v2, v2, v34, v33
	v_cndmask_b32_e64 v32, v44, v177, s[38:39]
	v_max3_f32 v2, v2, v32, v31
	v_max3_f32 v2, v2, v30, v29
	v_max3_f32 v2, v2, v28, v27
	v_cndmask_b32_e64 v26, v50, v177, s[4:5]
	v_cndmask_b32_e64 v25, v177, v51, s[6:7]
	v_max3_f32 v2, v2, v26, v25
	v_cndmask_b32_e64 v24, v52, v177, s[8:9]
	v_cndmask_b32_e64 v23, v53, v177, s[10:11]
	v_max3_f32 v2, v2, v24, v23
	v_cndmask_b32_e64 v22, v54, v177, s[12:13]
	v_cndmask_b32_e64 v21, v55, v177, s[14:15]
	v_max3_f32 v2, v2, v22, v21
	v_cndmask_b32_e64 v20, v56, v177, s[16:17]
	v_cndmask_b32_e64 v19, v57, v177, s[18:19]
	v_max3_f32 v2, v2, v20, v19
	v_cndmask_b32_e64 v18, v58, v177, s[20:21]
	v_cndmask_b32_e64 v17, v59, v177, s[22:23]
	v_max3_f32 v2, v2, v18, v17
	v_cndmask_b32_e64 v16, v60, v177, s[24:25]
	v_cndmask_b32_e64 v15, v61, v177, s[26:27]
	v_max3_f32 v2, v2, v16, v15
	v_cndmask_b32_e64 v13, v62, v177, s[28:29]
	v_cndmask_b32_e64 v12, v63, v177, s[30:31]
	v_max3_f32 v2, v2, v13, v12
	v_cndmask_b32_e64 v11, v64, v177, s[34:35]
	v_cndmask_b32_e64 v10, v65, v177, s[36:37]
	v_max3_f32 v2, v2, v11, v10
	ds_bpermute_b32 v3, v165, v2
	s_waitcnt lgkmcnt(0)
	v_max_f32_e32 v3, v3, v3
	v_max_f32_e32 v2, v2, v3
	v_mul_f32_e32 v2, 0x3e38aa3b, v2
	v_max_f32_e32 v14, v2, v179
	v_fma_f32 v2, v66, s97, -v14
	v_exp_f32_e32 v2, v2
	v_fma_f32 v3, v67, s97, -v14
	v_exp_f32_e32 v3, v3
	v_fma_f32 v40, v133, s97, -v14
	v_add_f32_e32 v4, 0, v2
	v_exp_f32_e32 v51, v40
	v_add_f32_e32 v5, v3, v4
	v_fma_f32 v4, v131, s97, -v14
	v_exp_f32_e32 v4, v4
	v_fma_f32 v40, v134, s97, -v14
	v_exp_f32_e32 v53, v40
	v_fma_f32 v40, v76, s97, -v14
	v_add_f32_e32 v6, v4, v5
	v_fma_f32 v5, v132, s97, -v14
	v_exp_f32_e32 v5, v5
	v_exp_f32_e32 v56, v40
	v_fma_f32 v40, v77, s97, -v14
	v_exp_f32_e32 v64, v40
	v_add_f32_e32 v7, v5, v6
	v_fma_f32 v6, v70, s97, -v14
	v_exp_f32_e32 v6, v6
	v_fma_f32 v40, v135, s97, -v14
	v_fma_f32 v38, v38, s97, -v14
	v_fma_f32 v37, v37, s97, -v14
	v_add_f32_e32 v8, v6, v7
	v_fma_f32 v7, v71, s97, -v14
	v_exp_f32_e32 v7, v7
	v_exp_f32_e32 v71, v40
	v_fma_f32 v40, v79, s97, -v14
	v_exp_f32_e32 v80, v40
	v_add_f32_e32 v9, v7, v8
	v_fma_f32 v8, v130, s97, -v14
	v_exp_f32_e32 v8, v8
	v_fma_f32 v40, v136, s97, -v14
	v_exp_f32_e32 v136, v40
	v_fma_f32 v40, v81, s97, -v14
	v_add_f32_e32 v39, v8, v9
	v_fma_f32 v9, v73, s97, -v14
	v_exp_f32_e32 v9, v9
	v_exp_f32_e32 v184, v40
	v_fma_f32 v40, v137, s97, -v14
	v_exp_f32_e32 v52, v40
	v_add_f32_e32 v39, v9, v39
	v_add_f32_e32 v39, v51, v39
	v_add_f32_e32 v39, v53, v39
	v_add_f32_e32 v39, v56, v39
	v_add_f32_e32 v39, v64, v39
	v_add_f32_e32 v39, v71, v39
	v_fma_f32 v40, v138, s97, -v14
	v_add_f32_e32 v39, v80, v39
	v_exp_f32_e32 v55, v40
	v_fma_f32 v40, v139, s97, -v14
	v_add_f32_e32 v39, v136, v39
	v_exp_f32_e32 v59, v40
	v_fma_f32 v40, v140, s97, -v14
	v_add_f32_e32 v39, v184, v39
	v_exp_f32_e32 v70, v40
	v_fma_f32 v40, v141, s97, -v14
	v_add_f32_e32 v39, v52, v39
	v_exp_f32_e32 v77, v40
	v_fma_f32 v40, v180, s97, -v14
	v_add_f32_e32 v39, v55, v39
	v_exp_f32_e32 v135, v40
	v_fma_f32 v40, v181, s97, -v14
	v_add_f32_e32 v39, v59, v39
	v_exp_f32_e32 v140, v40
	v_fma_f32 v40, v182, s97, -v14
	v_add_f32_e32 v39, v70, v39
	v_exp_f32_e32 v187, v40
	v_fma_f32 v40, v183, s97, -v14
	v_add_f32_e32 v39, v77, v39
	v_exp_f32_e32 v54, v40
	v_fma_f32 v40, v185, s97, -v14
	v_add_f32_e32 v39, v135, v39
	v_exp_f32_e32 v58, v40
	v_fma_f32 v40, v186, s97, -v14
	v_add_f32_e32 v39, v140, v39
	v_exp_f32_e32 v62, v40
	v_fma_f32 v40, v188, s97, -v14
	v_add_f32_e32 v39, v187, v39
	v_exp_f32_e32 v76, v40
	v_fma_f32 v40, v189, s97, -v14
	v_add_f32_e32 v39, v54, v39
	v_exp_f32_e32 v134, v40
	v_fma_f32 v40, v190, s97, -v14
	v_add_f32_e32 v39, v58, v39
	v_exp_f32_e32 v139, v40
	v_fma_f32 v40, v191, s97, -v14
	v_add_f32_e32 v39, v62, v39
	v_exp_f32_e32 v182, v40
	v_fma_f32 v40, v192, s97, -v14
	v_add_f32_e32 v39, v76, v39
	v_exp_f32_e32 v190, v40
	v_fma_f32 v40, v193, s97, -v14
	v_add_f32_e32 v39, v134, v39
	v_exp_f32_e32 v57, v40
	v_fma_f32 v40, v194, s97, -v14
	v_add_f32_e32 v39, v139, v39
	v_exp_f32_e32 v61, v40
	v_fma_f32 v40, v195, s97, -v14
	v_add_f32_e32 v39, v182, v39
	v_exp_f32_e32 v67, v40
	v_fma_f32 v40, v196, s97, -v14
	v_add_f32_e32 v39, v190, v39
	v_exp_f32_e32 v132, v40
	v_fma_f32 v40, v197, s97, -v14
	v_add_f32_e32 v39, v57, v39
	v_exp_f32_e32 v138, v40
	v_fma_f32 v40, v198, s97, -v14
	v_add_f32_e32 v39, v61, v39
	v_exp_f32_e32 v181, v40
	v_fma_f32 v40, v199, s97, -v14
	v_add_f32_e32 v39, v67, v39
	v_exp_f32_e32 v186, v40
	v_fma_f32 v40, v200, s97, -v14
	v_add_f32_e32 v39, v132, v39
	v_exp_f32_e32 v192, v40
	v_fma_f32 v40, v201, s97, -v14
	v_add_f32_e32 v39, v138, v39
	v_exp_f32_e32 v60, v40
	v_fma_f32 v40, v202, s97, -v14
	v_add_f32_e32 v39, v181, v39
	v_exp_f32_e32 v66, v40
	v_fma_f32 v40, v203, s97, -v14
	v_add_f32_e32 v39, v186, v39
	v_exp_f32_e32 v73, v40
	v_fma_f32 v40, v204, s97, -v14
	v_add_f32_e32 v39, v192, v39
	v_exp_f32_e32 v137, v40
	v_fma_f32 v40, v205, s97, -v14
	v_add_f32_e32 v39, v60, v39
	v_exp_f32_e32 v180, v40
	v_fma_f32 v40, v206, s97, -v14
	v_add_f32_e32 v39, v66, v39
	v_exp_f32_e32 v185, v40
	v_fma_f32 v40, v78, s97, -v14
	v_add_f32_e32 v39, v73, v39
	v_exp_f32_e32 v189, v40
	v_fma_f32 v40, v75, s97, -v14
	v_add_f32_e32 v39, v137, v39
	v_exp_f32_e32 v193, v40
	v_fma_f32 v40, v74, s97, -v14
	v_add_f32_e32 v39, v180, v39
	v_exp_f32_e32 v63, v40
	v_fma_f32 v40, v72, s97, -v14
	v_add_f32_e32 v39, v185, v39
	v_exp_f32_e32 v72, v40
	v_fma_f32 v40, v69, s97, -v14
	v_add_f32_e32 v39, v189, v39
	v_exp_f32_e32 v79, v40
	v_fma_f32 v40, v68, s97, -v14
	v_add_f32_e32 v39, v193, v39
	v_exp_f32_e32 v141, v40
	v_add_f32_e32 v39, v63, v39
	v_exp_f32_e32 v183, v38
	v_add_f32_e32 v39, v72, v39
	v_exp_f32_e32 v188, v37
	v_fma_f32 v36, v36, s97, -v14
	v_add_f32_e32 v39, v79, v39
	v_exp_f32_e32 v191, v36
	v_fma_f32 v35, v35, s97, -v14
	v_add_f32_e32 v39, v141, v39
	v_exp_f32_e32 v194, v35
	v_fma_f32 v34, v34, s97, -v14
	v_add_f32_e32 v38, v183, v39
	v_exp_f32_e32 v65, v34
	v_fma_f32 v33, v33, s97, -v14
	v_add_f32_e32 v37, v188, v38
	v_exp_f32_e32 v68, v33
	v_fma_f32 v32, v32, s97, -v14
	v_add_f32_e32 v36, v191, v37
	v_exp_f32_e32 v69, v32
	v_fma_f32 v31, v31, s97, -v14
	v_add_f32_e32 v35, v194, v36
	v_exp_f32_e32 v74, v31
	v_fma_f32 v30, v30, s97, -v14
	v_add_f32_e32 v34, v65, v35
	v_exp_f32_e32 v75, v30
	v_fma_f32 v29, v29, s97, -v14
	v_add_f32_e32 v33, v68, v34
	v_exp_f32_e32 v78, v29
	v_fma_f32 v28, v28, s97, -v14
	v_add_f32_e32 v32, v69, v33
	v_exp_f32_e32 v81, v28
	v_fma_f32 v27, v27, s97, -v14
	v_add_f32_e32 v31, v74, v32
	v_exp_f32_e32 v133, v27
	v_fma_f32 v26, v26, s97, -v14
	v_add_f32_e32 v30, v75, v31
	v_exp_f32_e32 v43, v26
	v_fma_f32 v25, v25, s97, -v14
	v_add_f32_e32 v29, v78, v30
	v_exp_f32_e32 v44, v25
	v_fma_f32 v24, v24, s97, -v14
	v_add_f32_e32 v28, v81, v29
	v_exp_f32_e32 v45, v24
	v_fma_f32 v23, v23, s97, -v14
	v_add_f32_e32 v27, v133, v28
	v_exp_f32_e32 v46, v23
	v_fma_f32 v22, v22, s97, -v14
	v_add_f32_e32 v26, v43, v27
	v_exp_f32_e32 v47, v22
	v_fma_f32 v21, v21, s97, -v14
	v_add_f32_e32 v25, v44, v26
	v_exp_f32_e32 v48, v21
	v_fma_f32 v20, v20, s97, -v14
	v_add_f32_e32 v24, v45, v25
	v_exp_f32_e32 v49, v20
	v_fma_f32 v19, v19, s97, -v14
	v_add_f32_e32 v23, v46, v24
	v_exp_f32_e32 v50, v19
	v_fma_f32 v18, v18, s97, -v14
	v_add_f32_e32 v22, v47, v23
	v_exp_f32_e32 v35, v18
	v_fma_f32 v17, v17, s97, -v14
	v_add_f32_e32 v21, v48, v22
	v_exp_f32_e32 v36, v17
	v_fma_f32 v16, v16, s97, -v14
	v_add_f32_e32 v20, v49, v21
	v_exp_f32_e32 v37, v16
	v_fma_f32 v15, v15, s97, -v14
	v_add_f32_e32 v19, v50, v20
	v_exp_f32_e32 v38, v15
	v_fma_f32 v13, v13, s97, -v14
	v_add_f32_e32 v18, v35, v19
	v_exp_f32_e32 v39, v13
	v_fma_f32 v12, v12, s97, -v14
	v_add_f32_e32 v17, v36, v18
	v_exp_f32_e32 v40, v12
	v_fma_f32 v11, v11, s97, -v14
	v_add_f32_e32 v16, v37, v17
	v_exp_f32_e32 v41, v11
	v_fma_f32 v10, v10, s97, -v14
	v_add_f32_e32 v15, v38, v16
	v_exp_f32_e32 v42, v10
	v_add_f32_e32 v13, v39, v15
	v_add_f32_e32 v12, v40, v13
	v_add_f32_e32 v11, v41, v12
	v_add_f32_e32 v10, v42, v11
	ds_bpermute_b32 v11, v165, v10
	v_add_u32_e32 v131, 0x9000, v163
	v_cvt_pk_bf16_f32 v18, v2, v3
	v_cvt_pk_bf16_f32 v19, v4, v5
	v_cvt_pk_bf16_f32 v20, v6, v7
	v_cvt_pk_bf16_f32 v21, v8, v9
	ds_read2_b64 v[2:5], v131 offset1:2
	s_waitcnt lgkmcnt(1)
	v_add_f32_e32 v10, v10, v11
	v_fma_f32 v11, v178, s88, -v14
	v_exp_f32_e32 v11, v11
	v_add_u32_e32 v130, 0x9000, v164
	ds_read2_b64 v[22:25], v130 offset1:2
	v_cvt_pk_bf16_f32 v196, v51, v53
	v_cvt_pk_bf16_f32 v197, v56, v64
	v_cvt_pk_bf16_f32 v198, v71, v80
	v_cvt_pk_bf16_f32 v199, v136, v184
	ds_read2_b64 v[200:203], v131 offset0:4 offset1:6
	v_add_f32_e32 v34, v11, v10
	s_waitcnt lgkmcnt(2)
	v_mfma_f32_32x32x16_bf16 v[2:17], v[2:5], v[18:21], 0
	s_waitcnt lgkmcnt(0)
	v_mfma_f32_32x32x16_bf16 v[2:17], v[200:203], v[196:199], v[2:17]
	ds_read2_b64 v[200:203], v130 offset0:4 offset1:6
	v_mfma_f32_32x32x16_bf16 v[18:33], v[22:25], v[18:21], 0
	s_waitcnt lgkmcnt(0)
	v_mfma_f32_32x32x16_bf16 v[18:33], v[200:203], v[196:199], v[18:33]
	v_cvt_pk_bf16_f32 v196, v52, v55
	v_cvt_pk_bf16_f32 v197, v59, v70
	v_cvt_pk_bf16_f32 v198, v77, v135
	v_cvt_pk_bf16_f32 v199, v140, v187
	ds_read2_b64 v[200:203], v131 offset0:8 offset1:10
	s_waitcnt lgkmcnt(0)
	v_mfma_f32_32x32x16_bf16 v[2:17], v[200:203], v[196:199], v[2:17]
	ds_read2_b64 v[200:203], v130 offset0:8 offset1:10
	v_cvt_pk_bf16_f32 v52, v54, v58
	v_cvt_pk_bf16_f32 v53, v62, v76
	v_cvt_pk_bf16_f32 v54, v134, v139
	v_cvt_pk_bf16_f32 v55, v182, v190
	s_waitcnt lgkmcnt(0)
	v_mfma_f32_32x32x16_bf16 v[18:33], v[200:203], v[196:199], v[18:33]
	ds_read2_b64 v[196:199], v131 offset0:12 offset1:14
	s_waitcnt lgkmcnt(0)
	v_mfma_f32_32x32x16_bf16 v[2:17], v[196:199], v[52:55], v[2:17]
	ds_read2_b64 v[196:199], v130 offset0:12 offset1:14
	s_waitcnt lgkmcnt(0)
	v_mfma_f32_32x32x16_bf16 v[18:33], v[196:199], v[52:55], v[18:33]
	v_cvt_pk_bf16_f32 v52, v57, v61
	v_cvt_pk_bf16_f32 v53, v67, v132
	v_cvt_pk_bf16_f32 v54, v138, v181
	v_cvt_pk_bf16_f32 v55, v186, v192
	ds_read2_b64 v[56:59], v131 offset0:16 offset1:18
	s_waitcnt lgkmcnt(0)
	v_mfma_f32_32x32x16_bf16 v[2:17], v[56:59], v[52:55], v[2:17]
	ds_read2_b64 v[56:59], v130 offset0:16 offset1:18
	s_waitcnt lgkmcnt(0)
	v_mfma_f32_32x32x16_bf16 v[18:33], v[56:59], v[52:55], v[18:33]
	v_cvt_pk_bf16_f32 v52, v60, v66
	v_cvt_pk_bf16_f32 v53, v73, v137
	v_cvt_pk_bf16_f32 v54, v180, v185
	v_cvt_pk_bf16_f32 v55, v189, v193
	ds_read2_b64 v[56:59], v131 offset0:20 offset1:22
	s_waitcnt lgkmcnt(0)
	v_mfma_f32_32x32x16_bf16 v[2:17], v[56:59], v[52:55], v[2:17]
	ds_read2_b64 v[56:59], v130 offset0:20 offset1:22
	s_waitcnt lgkmcnt(0)
	v_mfma_f32_32x32x16_bf16 v[18:33], v[56:59], v[52:55], v[18:33]
	v_cvt_pk_bf16_f32 v52, v63, v72
	v_cvt_pk_bf16_f32 v53, v79, v141
	v_cvt_pk_bf16_f32 v54, v183, v188
	v_cvt_pk_bf16_f32 v55, v191, v194
	ds_read2_b64 v[56:59], v131 offset0:24 offset1:26
	s_waitcnt lgkmcnt(0)
	v_mfma_f32_32x32x16_bf16 v[2:17], v[56:59], v[52:55], v[2:17]
	ds_read2_b64 v[56:59], v130 offset0:24 offset1:26
	s_waitcnt lgkmcnt(0)
	v_mfma_f32_32x32x16_bf16 v[18:33], v[56:59], v[52:55], v[18:33]
	v_cvt_pk_bf16_f32 v52, v65, v68
	v_cvt_pk_bf16_f32 v53, v69, v74
	v_cvt_pk_bf16_f32 v54, v75, v78
	v_cvt_pk_bf16_f32 v55, v81, v133
	ds_read2_b64 v[56:59], v131 offset0:28 offset1:30
	s_waitcnt lgkmcnt(0)
	v_mfma_f32_32x32x16_bf16 v[2:17], v[56:59], v[52:55], v[2:17]
	ds_read2_b64 v[56:59], v130 offset0:28 offset1:30
	v_cvt_pk_bf16_f32 v44, v43, v44
	v_cvt_pk_bf16_f32 v45, v45, v46
	v_cvt_pk_bf16_f32 v46, v47, v48
	v_cvt_pk_bf16_f32 v47, v49, v50
	ds_read2_b64 v[48:51], v131 offset0:32 offset1:34
	s_waitcnt lgkmcnt(0)
	v_mfma_f32_32x32x16_bf16 v[2:17], v[48:51], v[44:47], v[2:17]
	ds_read2_b64 v[48:51], v130 offset0:32 offset1:34
	v_cvt_pk_bf16_f32 v36, v35, v36
	v_cvt_pk_bf16_f32 v37, v37, v38
	v_cvt_pk_bf16_f32 v38, v39, v40
	v_cvt_pk_bf16_f32 v39, v41, v42
	ds_read2_b64 v[40:43], v131 offset0:36 offset1:38
	v_div_scale_f32 v35, s[72:73], v34, v34, 1.0
	v_mfma_f32_32x32x16_bf16 v[18:33], v[56:59], v[52:55], v[18:33]
	s_waitcnt lgkmcnt(0)
	v_mfma_f32_32x32x16_bf16 v[2:17], v[40:43], v[36:39], v[2:17]
	ds_read2_b64 v[40:43], v130 offset0:36 offset1:38
	v_mfma_f32_32x32x16_bf16 v[18:33], v[48:51], v[44:47], v[18:33]
	s_waitcnt lgkmcnt(0)
	v_mfma_f32_32x32x16_bf16 v[18:33], v[40:43], v[36:39], v[18:33]
	v_rcp_f32_e32 v36, v35
	s_nop 0
	v_fma_f32 v37, -v35, v36, 1.0
	v_fmac_f32_e32 v36, v37, v36
	v_div_scale_f32 v37, vcc, 1.0, v34, 1.0
	v_mul_f32_e32 v38, v37, v36
	v_fma_f32 v39, -v35, v38, v37
	v_fmac_f32_e32 v38, v39, v36
	v_fma_f32 v35, -v35, v38, v37
	v_div_fmas_f32 v35, v35, v36, v38
	v_div_fixup_f32 v36, v35, v34, 1.0
	v_mul_f32_e32 v2, v2, v36
	v_mul_f32_e32 v3, v3, v36
	v_cvt_pk_bf16_f32 v2, v2, v3
	v_mul_f32_e32 v3, v4, v36
	v_lshl_add_u64 v[34:35], v[150:151], 0, v[156:157]
	v_mul_f32_e32 v4, v5, v36
	v_cvt_pk_bf16_f32 v3, v3, v4
	global_store_dwordx2 v[34:35], v[2:3], off sc1
	v_mul_f32_e32 v2, v6, v36
	v_mul_f32_e32 v3, v7, v36
	v_cvt_pk_bf16_f32 v2, v2, v3
	v_mul_f32_e32 v3, v8, v36
	v_mul_f32_e32 v4, v9, v36
	v_cvt_pk_bf16_f32 v3, v3, v4
	global_store_dwordx2 v[34:35], v[2:3], off offset:16 sc1
	v_mul_f32_e32 v2, v10, v36
	v_mul_f32_e32 v3, v11, v36
	v_cvt_pk_bf16_f32 v2, v2, v3
	v_mul_f32_e32 v3, v12, v36
	v_mul_f32_e32 v4, v13, v36
	v_cvt_pk_bf16_f32 v3, v3, v4
	global_store_dwordx2 v[34:35], v[2:3], off offset:32 sc1
	v_mul_f32_e32 v2, v14, v36
	v_mul_f32_e32 v3, v15, v36
	v_cvt_pk_bf16_f32 v2, v2, v3
	v_mul_f32_e32 v3, v16, v36
	v_mul_f32_e32 v4, v17, v36
	v_cvt_pk_bf16_f32 v3, v3, v4
	global_store_dwordx2 v[34:35], v[2:3], off offset:48 sc1
	v_mul_f32_e32 v2, v18, v36
	v_mul_f32_e32 v3, v19, v36
	v_cvt_pk_bf16_f32 v2, v2, v3
	v_mul_f32_e32 v3, v20, v36
	v_mul_f32_e32 v4, v21, v36
	v_cvt_pk_bf16_f32 v3, v3, v4
	global_store_dwordx2 v[34:35], v[2:3], off offset:64 sc1
	v_mul_f32_e32 v2, v22, v36
	v_mul_f32_e32 v3, v23, v36
	v_cvt_pk_bf16_f32 v2, v2, v3
	v_mul_f32_e32 v3, v24, v36
	v_mul_f32_e32 v4, v25, v36
	v_cvt_pk_bf16_f32 v3, v3, v4
	global_store_dwordx2 v[34:35], v[2:3], off offset:80 sc1
	v_mul_f32_e32 v2, v26, v36
	v_mul_f32_e32 v3, v27, v36
	v_cvt_pk_bf16_f32 v2, v2, v3
	v_mul_f32_e32 v3, v28, v36
	v_mul_f32_e32 v4, v29, v36
	v_cvt_pk_bf16_f32 v3, v3, v4
	global_store_dwordx2 v[34:35], v[2:3], off offset:96 sc1
	v_mul_f32_e32 v2, v30, v36
	v_mul_f32_e32 v3, v31, v36
	v_cvt_pk_bf16_f32 v2, v2, v3
	v_mul_f32_e32 v3, v32, v36
	v_mul_f32_e32 v4, v33, v36
	v_cvt_pk_bf16_f32 v3, v3, v4
	global_store_dwordx2 v[34:35], v[2:3], off offset:112 sc1
	ds_read_b128 v[2:5], v176 offset:4608
	ds_read_b128 v[6:9], v176 offset:4640
	s_waitcnt lgkmcnt(1)
	v_mfma_f32_32x32x16_bf16 v[50:65], v[2:5], v[126:129], 0
	ds_read_b128 v[2:5], v176 offset:4672
	ds_read_b128 v[66:69], v176 offset:18464
	s_waitcnt lgkmcnt(2)
	v_mfma_f32_32x32x16_bf16 v[50:65], v[6:9], v[122:125], v[50:65]
	s_waitcnt lgkmcnt(1)
	v_mfma_f32_32x32x16_bf16 v[50:65], v[2:5], v[118:121], v[50:65]
	ds_read_b128 v[2:5], v176 offset:4704
	s_waitcnt lgkmcnt(0)
	v_mfma_f32_32x32x16_bf16 v[50:65], v[2:5], v[114:117], v[50:65]
	ds_read_b128 v[2:5], v176 offset:9216
	s_waitcnt lgkmcnt(0)
	v_mfma_f32_32x32x16_bf16 v[34:49], v[2:5], v[126:129], 0
	ds_read_b128 v[2:5], v176 offset:9248
	s_nop 7
	v_cndmask_b32_e64 v50, v177, v50, s[4:5]
	v_cndmask_b32_e64 v50, v50, v177, s[38:39]
	v_cndmask_b32_e64 v51, v51, v177, s[40:41]
	v_cndmask_b32_e64 v52, v177, v52, s[8:9]
	v_cndmask_b32_e64 v53, v177, v53, s[10:11]
	v_cndmask_b32_e64 v52, v52, v177, s[38:39]
	s_waitcnt lgkmcnt(0)
	v_mfma_f32_32x32x16_bf16 v[34:49], v[2:5], v[122:125], v[34:49]
	ds_read_b128 v[2:5], v176 offset:9280
	v_cndmask_b32_e64 v53, v53, v177, s[38:39]
	v_cndmask_b32_e64 v54, v177, v54, s[12:13]
	v_cndmask_b32_e64 v55, v177, v55, s[14:15]
	v_cndmask_b32_e64 v54, v54, v177, s[38:39]
	v_cndmask_b32_e64 v55, v55, v177, s[38:39]
	v_cndmask_b32_e64 v56, v177, v56, s[16:17]
	s_waitcnt lgkmcnt(0)
	v_mfma_f32_32x32x16_bf16 v[34:49], v[2:5], v[118:121], v[34:49]
	ds_read_b128 v[2:5], v176 offset:9312
	v_cndmask_b32_e64 v57, v177, v57, s[18:19]
	v_cndmask_b32_e64 v56, v56, v177, s[38:39]
	v_cndmask_b32_e64 v57, v57, v177, s[38:39]
	v_cndmask_b32_e64 v58, v177, v58, s[20:21]
	v_cndmask_b32_e64 v59, v177, v59, s[22:23]
	v_cndmask_b32_e64 v58, v58, v177, s[38:39]
	s_waitcnt lgkmcnt(0)
	v_mfma_f32_32x32x16_bf16 v[34:49], v[2:5], v[114:117], v[34:49]
	ds_read_b128 v[2:5], v176 offset:13824
	v_cndmask_b32_e64 v59, v59, v177, s[38:39]
	v_cndmask_b32_e64 v60, v177, v60, s[24:25]
	v_cndmask_b32_e64 v61, v177, v61, s[26:27]
	v_cndmask_b32_e64 v60, v60, v177, s[38:39]
	v_cndmask_b32_e64 v61, v61, v177, s[38:39]
	v_cndmask_b32_e64 v62, v177, v62, s[28:29]
	s_waitcnt lgkmcnt(0)
	v_mfma_f32_32x32x16_bf16 v[18:33], v[2:5], v[126:129], 0
	ds_read_b128 v[2:5], v176 offset:13856
	v_cndmask_b32_e64 v63, v177, v63, s[30:31]
	v_cndmask_b32_e64 v62, v62, v177, s[38:39]
	v_cndmask_b32_e64 v63, v63, v177, s[38:39]
	v_cndmask_b32_e64 v64, v177, v64, s[34:35]
	v_cndmask_b32_e64 v65, v177, v65, s[36:37]
	v_cndmask_b32_e64 v64, v64, v177, s[38:39]
	s_waitcnt lgkmcnt(0)
	v_mfma_f32_32x32x16_bf16 v[18:33], v[2:5], v[122:125], v[18:33]
	ds_read_b128 v[2:5], v176 offset:13888
	v_cndmask_b32_e64 v43, v43, v177, s[38:39]
	v_cndmask_b32_e64 v44, v44, v177, s[38:39]
	v_cndmask_b32_e64 v45, v45, v177, s[38:39]
	v_cndmask_b32_e64 v46, v46, v177, s[38:39]
	v_cndmask_b32_e64 v47, v47, v177, s[38:39]
	v_cndmask_b32_e64 v48, v48, v177, s[38:39]
	s_waitcnt lgkmcnt(0)
	v_mfma_f32_32x32x16_bf16 v[18:33], v[2:5], v[118:121], v[18:33]
	ds_read_b128 v[2:5], v176 offset:13920
	v_cndmask_b32_e64 v49, v49, v177, s[38:39]
	s_waitcnt lgkmcnt(0)
	v_mfma_f32_32x32x16_bf16 v[18:33], v[2:5], v[114:117], v[18:33]
	ds_read_b128 v[2:5], v176 offset:18432
	s_waitcnt lgkmcnt(0)
	v_mfma_f32_32x32x16_bf16 v[2:17], v[2:5], v[126:129], 0
	s_nop 8
	v_cndmask_b32_e64 v133, v20, v177, s[38:39]
	v_cndmask_b32_e64 v134, v21, v177, s[38:39]
	v_cndmask_b32_e64 v136, v22, v177, s[38:39]
	v_cndmask_b32_e64 v137, v23, v177, s[38:39]
	v_cndmask_b32_e64 v138, v24, v177, s[38:39]
	v_cndmask_b32_e64 v139, v25, v177, s[38:39]
	v_cndmask_b32_e64 v140, v26, v177, s[38:39]
	v_mfma_f32_32x32x16_bf16 v[2:17], v[66:69], v[122:125], v[2:17]
	ds_read_b128 v[66:69], v176 offset:18496
	v_cndmask_b32_e64 v141, v27, v177, s[38:39]
	v_cndmask_b32_e64 v156, v28, v177, s[38:39]
	v_cndmask_b32_e64 v157, v29, v177, s[38:39]
	v_cndmask_b32_e64 v180, v30, v177, s[38:39]
	v_cndmask_b32_e64 v181, v31, v177, s[38:39]
	v_cndmask_b32_e64 v182, v32, v177, s[38:39]
	s_waitcnt lgkmcnt(0)
	v_mfma_f32_32x32x16_bf16 v[2:17], v[66:69], v[118:121], v[2:17]
	ds_read_b128 v[66:69], v176 offset:18528
	v_cndmask_b32_e64 v183, v33, v177, s[38:39]
	s_waitcnt lgkmcnt(0)
	v_mfma_f32_32x32x16_bf16 v[2:17], v[66:69], v[114:117], v[2:17]
	ds_read_b128 v[66:69], v176 offset:23040
	s_waitcnt lgkmcnt(0)
	v_mfma_f32_32x32x16_bf16 v[66:81], v[66:69], v[126:129], 0
	ds_read_b128 v[126:129], v176 offset:23072
	s_waitcnt lgkmcnt(0)
	v_mfma_f32_32x32x16_bf16 v[66:81], v[126:129], v[122:125], v[66:81]
	ds_read_b128 v[122:125], v176 offset:23104
	v_cndmask_b32_e64 v126, v18, v177, s[38:39]
	v_cndmask_b32_e64 v128, v19, v177, s[38:39]
	s_waitcnt lgkmcnt(0)
	v_mfma_f32_32x32x16_bf16 v[66:81], v[122:125], v[118:121], v[66:81]
	ds_read_b128 v[118:121], v176 offset:23136
	v_cndmask_b32_e64 v122, v40, v177, s[38:39]
	v_cndmask_b32_e64 v123, v41, v177, s[38:39]
	v_cndmask_b32_e64 v124, v42, v177, s[38:39]
	s_waitcnt lgkmcnt(0)
	v_mfma_f32_32x32x16_bf16 v[66:81], v[118:121], v[114:117], v[66:81]
	v_max3_f32 v114, v50, s89, v51
	v_max3_f32 v114, v114, v52, v53
	v_max3_f32 v114, v114, v54, v55
	v_max3_f32 v114, v114, v56, v57
	v_max3_f32 v114, v114, v58, v59
	v_max3_f32 v114, v114, v60, v61
	v_max3_f32 v114, v114, v62, v63
	v_cndmask_b32_e64 v115, v65, v177, s[38:39]
	v_max3_f32 v65, v114, v64, v115
	v_cndmask_b32_e64 v114, v34, v177, s[38:39]
	v_cndmask_b32_e64 v116, v35, v177, s[38:39]
	v_max3_f32 v34, v65, v114, v116
	v_cndmask_b32_e64 v117, v36, v177, s[38:39]
	v_cndmask_b32_e64 v118, v37, v177, s[38:39]
	v_max3_f32 v34, v34, v117, v118
	v_cndmask_b32_e64 v119, v38, v177, s[38:39]
	v_cndmask_b32_e64 v120, v39, v177, s[38:39]
	v_max3_f32 v34, v34, v119, v120
	v_max3_f32 v34, v34, v122, v123
	v_max3_f32 v34, v34, v124, v43
	v_max3_f32 v34, v34, v44, v45
	v_max3_f32 v34, v34, v46, v47
	v_max3_f32 v34, v34, v48, v49
	v_max3_f32 v18, v34, v126, v128
	v_max3_f32 v18, v18, v133, v134
	v_max3_f32 v18, v18, v136, v137
	v_max3_f32 v18, v18, v138, v139
	v_max3_f32 v18, v18, v140, v141
	v_max3_f32 v18, v18, v156, v157
	v_max3_f32 v18, v18, v180, v181
	v_max3_f32 v18, v18, v182, v183
	v_max3_f32 v18, v18, v2, v3
	v_max3_f32 v18, v18, v4, v5
	v_max3_f32 v18, v18, v6, v7
	v_max3_f32 v18, v18, v8, v9
	v_max3_f32 v18, v18, v10, v11
	v_max3_f32 v18, v18, v12, v13
	v_max3_f32 v18, v18, v14, v15
	v_max3_f32 v18, v18, v16, v17
	v_cndmask_b32_e64 v42, v66, v177, s[4:5]
	v_cndmask_b32_e64 v41, v177, v67, s[6:7]
	v_max3_f32 v18, v18, v42, v41
	v_cndmask_b32_e64 v40, v68, v177, s[8:9]
	v_cndmask_b32_e64 v39, v69, v177, s[10:11]
	v_max3_f32 v18, v18, v40, v39
	v_cndmask_b32_e64 v38, v70, v177, s[12:13]
	v_cndmask_b32_e64 v37, v71, v177, s[14:15]
	v_max3_f32 v18, v18, v38, v37
	v_cndmask_b32_e64 v36, v72, v177, s[16:17]
	v_cndmask_b32_e64 v35, v73, v177, s[18:19]
	v_max3_f32 v18, v18, v36, v35
	v_cndmask_b32_e64 v34, v74, v177, s[20:21]
	v_cndmask_b32_e64 v33, v75, v177, s[22:23]
	v_max3_f32 v18, v18, v34, v33
	v_cndmask_b32_e64 v32, v76, v177, s[24:25]
	v_cndmask_b32_e64 v31, v77, v177, s[26:27]
	v_max3_f32 v18, v18, v32, v31
	v_cndmask_b32_e64 v30, v78, v177, s[28:29]
	v_cndmask_b32_e64 v29, v79, v177, s[30:31]
	v_max3_f32 v18, v18, v30, v29
	v_cndmask_b32_e64 v28, v80, v177, s[34:35]
	v_cndmask_b32_e64 v26, v81, v177, s[36:37]
	v_max3_f32 v18, v18, v28, v26
	ds_bpermute_b32 v19, v165, v18
	s_waitcnt lgkmcnt(0)
	v_max_f32_e32 v19, v19, v19
	v_max_f32_e32 v18, v18, v19
	v_mul_f32_e32 v18, 0x3e38aa3b, v18
	v_max_f32_e32 v27, v18, v179
	v_fma_f32 v18, v50, s97, -v27
	v_exp_f32_e32 v18, v18
	v_fma_f32 v19, v51, s97, -v27
	v_exp_f32_e32 v19, v19
	v_fma_f32 v51, v58, s97, -v27
	v_add_f32_e32 v20, 0, v18
	v_exp_f32_e32 v51, v51
	v_add_f32_e32 v21, v19, v20
	v_fma_f32 v20, v52, s97, -v27
	v_exp_f32_e32 v20, v20
	v_fma_f32 v52, v59, s97, -v27
	v_fma_f32 v43, v43, s97, -v27
	v_fma_f32 v44, v44, s97, -v27
	v_add_f32_e32 v22, v20, v21
	v_fma_f32 v21, v53, s97, -v27
	v_exp_f32_e32 v21, v21
	v_exp_f32_e32 v53, v52
	v_fma_f32 v52, v60, s97, -v27
	v_exp_f32_e32 v58, v52
	v_add_f32_e32 v23, v21, v22
	v_fma_f32 v22, v54, s97, -v27
	v_exp_f32_e32 v22, v22
	v_fma_f32 v52, v61, s97, -v27
	v_exp_f32_e32 v65, v52
	v_fma_f32 v52, v62, s97, -v27
	v_add_f32_e32 v24, v22, v23
	v_fma_f32 v23, v55, s97, -v27
	v_exp_f32_e32 v23, v23
	v_exp_f32_e32 v72, v52
	v_fma_f32 v52, v63, s97, -v27
	v_exp_f32_e32 v80, v52
	v_add_f32_e32 v25, v23, v24
	v_fma_f32 v24, v56, s97, -v27
	v_exp_f32_e32 v24, v24
	v_fma_f32 v52, v64, s97, -v27
	v_exp_f32_e32 v121, v52
	v_fma_f32 v52, v115, s97, -v27
	v_add_f32_e32 v50, v24, v25
	v_fma_f32 v25, v57, s97, -v27
	v_exp_f32_e32 v25, v25
	v_exp_f32_e32 v127, v52
	v_fma_f32 v52, v114, s97, -v27
	v_exp_f32_e32 v52, v52
	v_add_f32_e32 v50, v25, v50
	v_add_f32_e32 v50, v51, v50
	v_add_f32_e32 v50, v53, v50
	v_add_f32_e32 v50, v58, v50
	v_add_f32_e32 v50, v65, v50
	v_add_f32_e32 v50, v72, v50
	v_fma_f32 v54, v116, s97, -v27
	v_add_f32_e32 v50, v80, v50
	v_exp_f32_e32 v55, v54
	v_fma_f32 v54, v117, s97, -v27
	v_add_f32_e32 v50, v121, v50
	v_exp_f32_e32 v62, v54
	v_fma_f32 v54, v118, s97, -v27
	v_add_f32_e32 v50, v127, v50
	v_exp_f32_e32 v71, v54
	v_fma_f32 v54, v119, s97, -v27
	v_add_f32_e32 v50, v52, v50
	v_exp_f32_e32 v78, v54
	v_fma_f32 v54, v120, s97, -v27
	v_add_f32_e32 v50, v55, v50
	v_exp_f32_e32 v116, v54
	v_fma_f32 v54, v122, s97, -v27
	v_add_f32_e32 v50, v62, v50
	v_exp_f32_e32 v125, v54
	v_fma_f32 v54, v123, s97, -v27
	v_add_f32_e32 v50, v71, v50
	v_exp_f32_e32 v132, v54
	v_fma_f32 v54, v124, s97, -v27
	v_add_f32_e32 v50, v78, v50
	v_exp_f32_e32 v54, v54
	v_add_f32_e32 v50, v116, v50
	v_exp_f32_e32 v57, v43
	v_add_f32_e32 v50, v125, v50
	v_exp_f32_e32 v69, v44
	v_fma_f32 v44, v45, s97, -v27
	v_add_f32_e32 v50, v132, v50
	v_exp_f32_e32 v77, v44
	v_fma_f32 v44, v46, s97, -v27
	v_add_f32_e32 v50, v54, v50
	v_exp_f32_e32 v115, v44
	v_fma_f32 v44, v47, s97, -v27
	v_add_f32_e32 v43, v57, v50
	v_exp_f32_e32 v120, v44
	v_fma_f32 v44, v48, s97, -v27
	v_add_f32_e32 v43, v69, v43
	v_exp_f32_e32 v129, v44
	v_fma_f32 v44, v49, s97, -v27
	v_add_f32_e32 v43, v77, v43
	v_exp_f32_e32 v135, v44
	v_fma_f32 v44, v126, s97, -v27
	v_add_f32_e32 v43, v115, v43
	v_exp_f32_e32 v56, v44
	v_fma_f32 v44, v128, s97, -v27
	v_add_f32_e32 v43, v120, v43
	v_exp_f32_e32 v60, v44
	v_fma_f32 v44, v133, s97, -v27
	v_add_f32_e32 v43, v129, v43
	v_exp_f32_e32 v75, v44
	v_fma_f32 v44, v134, s97, -v27
	v_add_f32_e32 v43, v135, v43
	v_exp_f32_e32 v114, v44
	v_fma_f32 v44, v136, s97, -v27
	v_add_f32_e32 v43, v56, v43
	v_exp_f32_e32 v119, v44
	v_fma_f32 v44, v137, s97, -v27
	v_add_f32_e32 v43, v60, v43
	v_exp_f32_e32 v124, v44
	v_fma_f32 v44, v138, s97, -v27
	v_add_f32_e32 v43, v75, v43
	v_exp_f32_e32 v134, v44
	v_fma_f32 v44, v139, s97, -v27
	v_add_f32_e32 v43, v114, v43
	v_exp_f32_e32 v137, v44
	v_fma_f32 v44, v140, s97, -v27
	v_add_f32_e32 v43, v119, v43
	v_exp_f32_e32 v59, v44
	v_fma_f32 v44, v141, s97, -v27
	v_add_f32_e32 v43, v124, v43
	v_exp_f32_e32 v67, v44
	v_fma_f32 v44, v156, s97, -v27
	v_add_f32_e32 v43, v134, v43
	v_exp_f32_e32 v81, v44
	v_fma_f32 v44, v157, s97, -v27
	v_add_f32_e32 v43, v137, v43
	v_exp_f32_e32 v118, v44
	v_fma_f32 v44, v180, s97, -v27
	v_add_f32_e32 v43, v59, v43
	v_exp_f32_e32 v123, v44
	v_fma_f32 v44, v181, s97, -v27
	v_add_f32_e32 v43, v67, v43
	v_exp_f32_e32 v128, v44
	v_fma_f32 v44, v182, s97, -v27
	v_add_f32_e32 v43, v81, v43
	v_exp_f32_e32 v136, v44
	v_fma_f32 v44, v183, s97, -v27
	v_add_f32_e32 v43, v118, v43
	v_exp_f32_e32 v139, v44
	v_fma_f32 v2, v2, s97, -v27
	v_add_f32_e32 v43, v123, v43
	v_exp_f32_e32 v64, v2
	v_fma_f32 v3, v3, s97, -v27
	v_add_f32_e32 v43, v128, v43
	v_exp_f32_e32 v73, v3
	v_fma_f32 v3, v4, s97, -v27
	v_add_f32_e32 v43, v136, v43
	v_exp_f32_e32 v117, v3
	v_fma_f32 v3, v5, s97, -v27
	v_add_f32_e32 v43, v139, v43
	v_exp_f32_e32 v122, v3
	v_fma_f32 v3, v6, s97, -v27
	v_add_f32_e32 v2, v64, v43
	v_exp_f32_e32 v126, v3
	v_fma_f32 v3, v7, s97, -v27
	v_add_f32_e32 v2, v73, v2
	v_exp_f32_e32 v133, v3
	v_fma_f32 v3, v8, s97, -v27
	v_add_f32_e32 v2, v117, v2
	v_exp_f32_e32 v138, v3
	v_fma_f32 v3, v9, s97, -v27
	v_add_f32_e32 v2, v122, v2
	v_exp_f32_e32 v140, v3
	v_fma_f32 v3, v10, s97, -v27
	v_add_f32_e32 v2, v126, v2
	v_exp_f32_e32 v61, v3
	v_fma_f32 v3, v11, s97, -v27
	v_add_f32_e32 v2, v133, v2
	v_exp_f32_e32 v63, v3
	v_fma_f32 v3, v12, s97, -v27
	v_add_f32_e32 v2, v138, v2
	v_exp_f32_e32 v66, v3
	v_fma_f32 v3, v13, s97, -v27
	v_add_f32_e32 v2, v140, v2
	v_exp_f32_e32 v68, v3
	v_fma_f32 v3, v14, s97, -v27
	v_add_f32_e32 v2, v61, v2
	v_exp_f32_e32 v70, v3
	v_fma_f32 v3, v15, s97, -v27
	v_add_f32_e32 v2, v63, v2
	v_exp_f32_e32 v74, v3
	v_fma_f32 v3, v16, s97, -v27
	v_add_f32_e32 v2, v66, v2
	v_exp_f32_e32 v76, v3
	v_fma_f32 v3, v17, s97, -v27
	v_add_f32_e32 v2, v68, v2
	v_exp_f32_e32 v79, v3
	v_fma_f32 v3, v42, s97, -v27
	v_add_f32_e32 v2, v70, v2
	v_exp_f32_e32 v43, v3
	v_fma_f32 v3, v41, s97, -v27
	v_add_f32_e32 v2, v74, v2
	v_exp_f32_e32 v44, v3
	v_fma_f32 v3, v40, s97, -v27
	v_add_f32_e32 v2, v76, v2
	v_exp_f32_e32 v45, v3
	v_fma_f32 v3, v39, s97, -v27
	v_add_f32_e32 v2, v79, v2
	v_exp_f32_e32 v46, v3
	v_fma_f32 v3, v38, s97, -v27
	v_add_f32_e32 v2, v43, v2
	v_exp_f32_e32 v47, v3
	v_fma_f32 v3, v37, s97, -v27
	v_add_f32_e32 v2, v44, v2
	v_exp_f32_e32 v48, v3
	v_fma_f32 v3, v36, s97, -v27
	v_add_f32_e32 v2, v45, v2
	v_exp_f32_e32 v49, v3
	v_fma_f32 v3, v35, s97, -v27
	v_add_f32_e32 v2, v46, v2
	v_exp_f32_e32 v50, v3
	v_fma_f32 v3, v34, s97, -v27
	v_add_f32_e32 v2, v47, v2
	v_exp_f32_e32 v35, v3
	v_fma_f32 v3, v33, s97, -v27
	v_add_f32_e32 v2, v48, v2
	v_exp_f32_e32 v36, v3
	v_fma_f32 v3, v32, s97, -v27
	v_add_f32_e32 v2, v49, v2
	v_exp_f32_e32 v37, v3
	v_fma_f32 v3, v31, s97, -v27
	v_add_f32_e32 v2, v50, v2
	v_exp_f32_e32 v38, v3
	v_fma_f32 v3, v30, s97, -v27
	v_add_f32_e32 v2, v35, v2
	v_exp_f32_e32 v39, v3
	v_fma_f32 v3, v29, s97, -v27
	v_add_f32_e32 v2, v36, v2
	v_exp_f32_e32 v40, v3
	v_fma_f32 v3, v28, s97, -v27
	v_add_f32_e32 v2, v37, v2
	v_exp_f32_e32 v41, v3
	v_fma_f32 v3, v26, s97, -v27
	v_add_f32_e32 v2, v38, v2
	v_exp_f32_e32 v42, v3
	v_add_f32_e32 v2, v39, v2
	v_add_f32_e32 v2, v40, v2
	v_add_f32_e32 v2, v41, v2
	v_add_f32_e32 v2, v42, v2
	ds_bpermute_b32 v3, v165, v2
	v_cvt_pk_bf16_f32 v18, v18, v19
	v_cvt_pk_bf16_f32 v19, v20, v21
	v_cvt_pk_bf16_f32 v20, v22, v23
	v_cvt_pk_bf16_f32 v21, v24, v25
	s_waitcnt lgkmcnt(0)
	v_add_f32_e32 v2, v2, v3
	v_fma_f32 v3, v178, s88, -v27
	v_exp_f32_e32 v3, v3
	ds_read2_b64 v[22:25], v130 offset0:8 offset1:10
	v_add_f32_e32 v34, v3, v2
	ds_read2_b64 v[2:5], v131 offset0:8 offset1:10
	v_cvt_pk_bf16_f32 v180, v51, v53
	v_cvt_pk_bf16_f32 v181, v58, v65
	v_cvt_pk_bf16_f32 v182, v72, v80
	v_cvt_pk_bf16_f32 v183, v121, v127
	ds_read2_b64 v[184:187], v131 offset0:12 offset1:14
	s_waitcnt lgkmcnt(1)
	v_mfma_f32_32x32x16_bf16 v[2:17], v[2:5], v[18:21], 0
	s_waitcnt lgkmcnt(0)
	v_mfma_f32_32x32x16_bf16 v[2:17], v[184:187], v[180:183], v[2:17]
	ds_read2_b64 v[184:187], v130 offset0:12 offset1:14
	v_mfma_f32_32x32x16_bf16 v[18:33], v[22:25], v[18:21], 0
	s_waitcnt lgkmcnt(0)
	v_mfma_f32_32x32x16_bf16 v[18:33], v[184:187], v[180:183], v[18:33]
	v_cvt_pk_bf16_f32 v180, v52, v55
	v_cvt_pk_bf16_f32 v181, v62, v71
	v_cvt_pk_bf16_f32 v182, v78, v116
	v_cvt_pk_bf16_f32 v183, v125, v132
	ds_read2_b64 v[184:187], v131 offset0:16 offset1:18
	s_waitcnt lgkmcnt(0)
	v_mfma_f32_32x32x16_bf16 v[2:17], v[184:187], v[180:183], v[2:17]
	ds_read2_b64 v[184:187], v130 offset0:16 offset1:18
	v_cvt_pk_bf16_f32 v52, v54, v57
	v_cvt_pk_bf16_f32 v53, v69, v77
	v_cvt_pk_bf16_f32 v54, v115, v120
	v_cvt_pk_bf16_f32 v55, v129, v135
	s_waitcnt lgkmcnt(0)
	v_mfma_f32_32x32x16_bf16 v[18:33], v[184:187], v[180:183], v[18:33]
	ds_read2_b64 v[180:183], v131 offset0:20 offset1:22
	s_waitcnt lgkmcnt(0)
	v_mfma_f32_32x32x16_bf16 v[2:17], v[180:183], v[52:55], v[2:17]
	ds_read2_b64 v[180:183], v130 offset0:20 offset1:22
	s_waitcnt lgkmcnt(0)
	v_mfma_f32_32x32x16_bf16 v[18:33], v[180:183], v[52:55], v[18:33]
	v_cvt_pk_bf16_f32 v52, v56, v60
	v_cvt_pk_bf16_f32 v53, v75, v114
	v_cvt_pk_bf16_f32 v54, v119, v124
	v_cvt_pk_bf16_f32 v55, v134, v137
	ds_read2_b64 v[180:183], v131 offset0:24 offset1:26
	s_waitcnt lgkmcnt(0)
	v_mfma_f32_32x32x16_bf16 v[2:17], v[180:183], v[52:55], v[2:17]
	ds_read2_b64 v[180:183], v130 offset0:24 offset1:26
	s_waitcnt lgkmcnt(0)
	v_mfma_f32_32x32x16_bf16 v[18:33], v[180:183], v[52:55], v[18:33]
	v_cvt_pk_bf16_f32 v52, v59, v67
	v_cvt_pk_bf16_f32 v53, v81, v118
	v_cvt_pk_bf16_f32 v54, v123, v128
	v_cvt_pk_bf16_f32 v55, v136, v139
	ds_read2_b64 v[56:59], v131 offset0:28 offset1:30
	s_waitcnt lgkmcnt(0)
	v_mfma_f32_32x32x16_bf16 v[2:17], v[56:59], v[52:55], v[2:17]
	ds_read2_b64 v[56:59], v130 offset0:28 offset1:30
	s_waitcnt lgkmcnt(0)
	v_mfma_f32_32x32x16_bf16 v[18:33], v[56:59], v[52:55], v[18:33]
	v_cvt_pk_bf16_f32 v52, v64, v73
	v_cvt_pk_bf16_f32 v53, v117, v122
	v_cvt_pk_bf16_f32 v54, v126, v133
	v_cvt_pk_bf16_f32 v55, v138, v140
	ds_read2_b64 v[56:59], v131 offset0:32 offset1:34
	s_waitcnt lgkmcnt(0)
	v_mfma_f32_32x32x16_bf16 v[2:17], v[56:59], v[52:55], v[2:17]
	ds_read2_b64 v[56:59], v130 offset0:32 offset1:34
	s_waitcnt lgkmcnt(0)
	v_mfma_f32_32x32x16_bf16 v[18:33], v[56:59], v[52:55], v[18:33]
	v_cvt_pk_bf16_f32 v52, v61, v63
	v_cvt_pk_bf16_f32 v53, v66, v68
	v_cvt_pk_bf16_f32 v54, v70, v74
	v_cvt_pk_bf16_f32 v55, v76, v79
	ds_read2_b64 v[56:59], v131 offset0:36 offset1:38
	s_waitcnt lgkmcnt(0)
	v_mfma_f32_32x32x16_bf16 v[2:17], v[56:59], v[52:55], v[2:17]
	ds_read2_b64 v[56:59], v130 offset0:36 offset1:38
	v_cvt_pk_bf16_f32 v44, v43, v44
	v_cvt_pk_bf16_f32 v45, v45, v46
	v_cvt_pk_bf16_f32 v46, v47, v48
	v_cvt_pk_bf16_f32 v47, v49, v50
	ds_read2_b64 v[48:51], v131 offset0:40 offset1:42
	s_waitcnt lgkmcnt(0)
	v_mfma_f32_32x32x16_bf16 v[2:17], v[48:51], v[44:47], v[2:17]
	ds_read2_b64 v[48:51], v130 offset0:40 offset1:42
	v_cvt_pk_bf16_f32 v36, v35, v36
	v_cvt_pk_bf16_f32 v37, v37, v38
	v_cvt_pk_bf16_f32 v38, v39, v40
	v_cvt_pk_bf16_f32 v39, v41, v42
	ds_read2_b64 v[40:43], v131 offset0:44 offset1:46
	v_div_scale_f32 v35, s[72:73], v34, v34, 1.0
	v_mfma_f32_32x32x16_bf16 v[18:33], v[56:59], v[52:55], v[18:33]
	s_waitcnt lgkmcnt(0)
	v_mfma_f32_32x32x16_bf16 v[2:17], v[40:43], v[36:39], v[2:17]
	ds_read2_b64 v[40:43], v130 offset0:44 offset1:46
	v_mfma_f32_32x32x16_bf16 v[18:33], v[48:51], v[44:47], v[18:33]
	s_waitcnt lgkmcnt(0)
	v_mfma_f32_32x32x16_bf16 v[18:33], v[40:43], v[36:39], v[18:33]
	v_rcp_f32_e32 v36, v35
	s_nop 0
	v_fma_f32 v37, -v35, v36, 1.0
	v_fmac_f32_e32 v36, v37, v36
	v_div_scale_f32 v37, vcc, 1.0, v34, 1.0
	v_mul_f32_e32 v38, v37, v36
	v_fma_f32 v39, -v35, v38, v37
	v_fmac_f32_e32 v38, v39, v36
	v_fma_f32 v35, -v35, v38, v37
	v_div_fmas_f32 v35, v35, v36, v38
	v_div_fixup_f32 v36, v35, v34, 1.0
	v_mul_f32_e32 v2, v2, v36
	v_mul_f32_e32 v3, v3, v36
	v_cvt_pk_bf16_f32 v2, v2, v3
	v_mul_f32_e32 v3, v4, v36
	v_lshl_add_u64 v[34:35], v[150:151], 0, v[154:155]
	v_mul_f32_e32 v4, v5, v36
	v_cvt_pk_bf16_f32 v3, v3, v4
	global_store_dwordx2 v[34:35], v[2:3], off sc1
	v_mul_f32_e32 v2, v6, v36
	v_mul_f32_e32 v3, v7, v36
	v_cvt_pk_bf16_f32 v2, v2, v3
	v_mul_f32_e32 v3, v8, v36
	v_mul_f32_e32 v4, v9, v36
	v_cvt_pk_bf16_f32 v3, v3, v4
	global_store_dwordx2 v[34:35], v[2:3], off offset:16 sc1
	v_mul_f32_e32 v2, v10, v36
	v_mul_f32_e32 v3, v11, v36
	v_cvt_pk_bf16_f32 v2, v2, v3
	v_mul_f32_e32 v3, v12, v36
	v_mul_f32_e32 v4, v13, v36
	v_cvt_pk_bf16_f32 v3, v3, v4
	global_store_dwordx2 v[34:35], v[2:3], off offset:32 sc1
	v_mul_f32_e32 v2, v14, v36
	v_mul_f32_e32 v3, v15, v36
	v_cvt_pk_bf16_f32 v2, v2, v3
	v_mul_f32_e32 v3, v16, v36
	v_mul_f32_e32 v4, v17, v36
	v_cvt_pk_bf16_f32 v3, v3, v4
	global_store_dwordx2 v[34:35], v[2:3], off offset:48 sc1
	v_mul_f32_e32 v2, v18, v36
	v_mul_f32_e32 v3, v19, v36
	v_cvt_pk_bf16_f32 v2, v2, v3
	v_mul_f32_e32 v3, v20, v36
	v_mul_f32_e32 v4, v21, v36
	v_cvt_pk_bf16_f32 v3, v3, v4
	global_store_dwordx2 v[34:35], v[2:3], off offset:64 sc1
	v_mul_f32_e32 v2, v22, v36
	v_mul_f32_e32 v3, v23, v36
	v_cvt_pk_bf16_f32 v2, v2, v3
	v_mul_f32_e32 v3, v24, v36
	v_mul_f32_e32 v4, v25, v36
	v_cvt_pk_bf16_f32 v3, v3, v4
	global_store_dwordx2 v[34:35], v[2:3], off offset:80 sc1
	v_mul_f32_e32 v2, v26, v36
	v_mul_f32_e32 v3, v27, v36
	v_cvt_pk_bf16_f32 v2, v2, v3
	v_mul_f32_e32 v3, v28, v36
	v_mul_f32_e32 v4, v29, v36
	v_cvt_pk_bf16_f32 v3, v3, v4
	global_store_dwordx2 v[34:35], v[2:3], off offset:96 sc1
	v_mul_f32_e32 v2, v30, v36
	v_mul_f32_e32 v3, v31, v36
	v_cvt_pk_bf16_f32 v2, v2, v3
	v_mul_f32_e32 v3, v32, v36
	v_mul_f32_e32 v4, v33, v36
	v_cvt_pk_bf16_f32 v3, v3, v4
	global_store_dwordx2 v[34:35], v[2:3], off offset:112 sc1
	ds_read_b128 v[2:5], v176 offset:9216
	ds_read_b128 v[6:9], v176 offset:9248
	s_waitcnt lgkmcnt(1)
	v_mfma_f32_32x32x16_bf16 v[50:65], v[2:5], v[110:113], 0
	ds_read_b128 v[2:5], v176 offset:9280
	ds_read_b128 v[66:69], v176 offset:23072
	s_waitcnt lgkmcnt(2)
	v_mfma_f32_32x32x16_bf16 v[50:65], v[6:9], v[106:109], v[50:65]
	s_waitcnt lgkmcnt(1)
	v_mfma_f32_32x32x16_bf16 v[50:65], v[2:5], v[102:105], v[50:65]
	ds_read_b128 v[2:5], v176 offset:9312
	s_waitcnt lgkmcnt(0)
	v_mfma_f32_32x32x16_bf16 v[50:65], v[2:5], v[98:101], v[50:65]
	ds_read_b128 v[2:5], v176 offset:13824
	s_waitcnt lgkmcnt(0)
	v_mfma_f32_32x32x16_bf16 v[34:49], v[2:5], v[110:113], 0
	ds_read_b128 v[2:5], v176 offset:13856
	s_nop 7
	v_cndmask_b32_e64 v53, v177, v53, s[10:11]
	v_cndmask_b32_e64 v50, v177, v50, s[4:5]
	v_cndmask_b32_e64 v50, v50, v177, s[38:39]
	v_cndmask_b32_e64 v52, v177, v52, s[8:9]
	v_cndmask_b32_e64 v52, v52, v177, s[38:39]
	s_waitcnt lgkmcnt(0)
	v_mfma_f32_32x32x16_bf16 v[34:49], v[2:5], v[106:109], v[34:49]
	ds_read_b128 v[2:5], v176 offset:13888
	s_waitcnt lgkmcnt(0)
	v_mfma_f32_32x32x16_bf16 v[34:49], v[2:5], v[102:105], v[34:49]
	ds_read_b128 v[2:5], v176 offset:13920
	s_waitcnt lgkmcnt(0)
	v_mfma_f32_32x32x16_bf16 v[34:49], v[2:5], v[98:101], v[34:49]
	ds_read_b128 v[2:5], v176 offset:18432
	s_waitcnt lgkmcnt(0)
	v_mfma_f32_32x32x16_bf16 v[18:33], v[2:5], v[110:113], 0
	ds_read_b128 v[2:5], v176 offset:18464
	s_nop 7
	v_cndmask_b32_e64 v114, v42, v177, s[38:39]
	v_cndmask_b32_e64 v115, v43, v177, s[38:39]
	v_cndmask_b32_e64 v116, v44, v177, s[38:39]
	v_cndmask_b32_e64 v118, v45, v177, s[38:39]
	v_cndmask_b32_e64 v120, v46, v177, s[38:39]
	v_cndmask_b32_e64 v121, v47, v177, s[38:39]
	s_waitcnt lgkmcnt(0)
	v_mfma_f32_32x32x16_bf16 v[18:33], v[2:5], v[106:109], v[18:33]
	ds_read_b128 v[2:5], v176 offset:18496
	v_cndmask_b32_e64 v123, v48, v177, s[38:39]
	v_cndmask_b32_e64 v124, v49, v177, s[38:39]
	s_waitcnt lgkmcnt(0)
	v_mfma_f32_32x32x16_bf16 v[18:33], v[2:5], v[102:105], v[18:33]
	ds_read_b128 v[2:5], v176 offset:18528
	s_waitcnt lgkmcnt(0)
	v_mfma_f32_32x32x16_bf16 v[18:33], v[2:5], v[98:101], v[18:33]
	ds_read_b128 v[2:5], v176 offset:23040
	s_waitcnt lgkmcnt(0)
	v_mfma_f32_32x32x16_bf16 v[2:17], v[2:5], v[110:113], 0
	v_mfma_f32_32x32x16_bf16 v[2:17], v[66:69], v[106:109], v[2:17]
	ds_read_b128 v[66:69], v176 offset:23104
	s_waitcnt lgkmcnt(0)
	v_mfma_f32_32x32x16_bf16 v[2:17], v[66:69], v[102:105], v[2:17]
	ds_read_b128 v[66:69], v176 offset:23136
	s_waitcnt lgkmcnt(0)
	v_mfma_f32_32x32x16_bf16 v[2:17], v[66:69], v[98:101], v[2:17]
	ds_read_b128 v[66:69], v176 offset:27648
	s_waitcnt lgkmcnt(0)
	v_mfma_f32_32x32x16_bf16 v[66:81], v[66:69], v[110:113], 0
	ds_read_b128 v[110:113], v176 offset:27680
	s_waitcnt lgkmcnt(0)
	v_mfma_f32_32x32x16_bf16 v[66:81], v[110:113], v[106:109], v[66:81]
	ds_read_b128 v[106:109], v176 offset:27712
	v_cndmask_b32_e64 v110, v40, v177, s[38:39]
	v_cndmask_b32_e64 v111, v41, v177, s[38:39]
	s_waitcnt lgkmcnt(0)
	v_mfma_f32_32x32x16_bf16 v[66:81], v[106:109], v[102:105], v[66:81]
	ds_read_b128 v[102:105], v176 offset:27744
	v_cndmask_b32_e64 v106, v37, v177, s[38:39]
	v_cndmask_b32_e64 v108, v38, v177, s[38:39]
	v_cndmask_b32_e64 v109, v39, v177, s[38:39]
	s_waitcnt lgkmcnt(0)
	v_mfma_f32_32x32x16_bf16 v[66:81], v[102:105], v[98:101], v[66:81]
	v_cndmask_b32_e64 v99, v53, v177, s[38:39]
	v_cndmask_b32_e64 v53, v177, v54, s[12:13]
	v_cndmask_b32_e64 v54, v53, v177, s[38:39]
	v_cndmask_b32_e64 v53, v177, v55, s[14:15]
	v_cndmask_b32_e64 v55, v53, v177, s[38:39]
	v_cndmask_b32_e64 v53, v177, v56, s[16:17]
	v_cndmask_b32_e64 v56, v53, v177, s[38:39]
	v_cndmask_b32_e64 v53, v177, v57, s[18:19]
	v_cndmask_b32_e64 v57, v53, v177, s[38:39]
	v_cndmask_b32_e64 v53, v177, v58, s[20:21]
	v_cndmask_b32_e64 v98, v51, v177, s[40:41]
	v_cndmask_b32_e64 v100, v53, v177, s[38:39]
	v_cndmask_b32_e64 v53, v177, v59, s[22:23]
	v_max3_f32 v51, v50, s89, v98
	v_cndmask_b32_e64 v59, v53, v177, s[38:39]
	v_cndmask_b32_e64 v53, v177, v60, s[24:25]
	v_max3_f32 v51, v51, v52, v99
	v_cndmask_b32_e64 v60, v53, v177, s[38:39]
	v_cndmask_b32_e64 v53, v177, v61, s[26:27]
	v_max3_f32 v51, v51, v54, v55
	v_cndmask_b32_e64 v101, v53, v177, s[38:39]
	v_cndmask_b32_e64 v53, v177, v62, s[28:29]
	v_max3_f32 v51, v51, v56, v57
	v_cndmask_b32_e64 v102, v53, v177, s[38:39]
	v_cndmask_b32_e64 v53, v177, v63, s[30:31]
	v_max3_f32 v51, v51, v100, v59
	v_cndmask_b32_e64 v63, v53, v177, s[38:39]
	v_cndmask_b32_e64 v53, v177, v64, s[34:35]
	v_max3_f32 v51, v51, v60, v101
	v_cndmask_b32_e64 v64, v53, v177, s[38:39]
	v_cndmask_b32_e64 v53, v177, v65, s[36:37]
	v_max3_f32 v51, v51, v102, v63
	v_cndmask_b32_e64 v65, v53, v177, s[38:39]
	v_max3_f32 v51, v51, v64, v65
	v_cndmask_b32_e64 v103, v34, v177, s[38:39]
	v_cndmask_b32_e64 v104, v35, v177, s[38:39]
	v_max3_f32 v34, v51, v103, v104
	v_cndmask_b32_e64 v105, v36, v177, s[38:39]
	v_max3_f32 v34, v34, v105, v106
	v_max3_f32 v34, v34, v108, v109
	v_max3_f32 v34, v34, v110, v111
	v_max3_f32 v34, v34, v114, v115
	v_max3_f32 v34, v34, v116, v118
	v_max3_f32 v34, v34, v120, v121
	v_max3_f32 v34, v34, v123, v124
	v_max3_f32 v34, v34, v18, v19
	v_max3_f32 v34, v34, v20, v21
	v_max3_f32 v34, v34, v22, v23
	v_max3_f32 v34, v34, v24, v25
	v_max3_f32 v34, v34, v26, v27
	v_max3_f32 v34, v34, v28, v29
	v_max3_f32 v34, v34, v30, v31
	v_max3_f32 v34, v34, v32, v33
	v_max3_f32 v34, v34, v2, v3
	v_max3_f32 v34, v34, v4, v5
	v_max3_f32 v34, v34, v6, v7
	v_max3_f32 v34, v34, v8, v9
	v_max3_f32 v34, v34, v10, v11
	v_max3_f32 v34, v34, v12, v13
	v_max3_f32 v34, v34, v14, v15
	v_max3_f32 v34, v34, v16, v17
	v_cndmask_b32_e64 v43, v66, v177, s[4:5]
	v_cndmask_b32_e64 v44, v177, v67, s[6:7]
	v_max3_f32 v34, v34, v43, v44
	v_cndmask_b32_e64 v45, v68, v177, s[8:9]
	v_cndmask_b32_e64 v46, v69, v177, s[10:11]
	v_max3_f32 v34, v34, v45, v46
	v_cndmask_b32_e64 v47, v70, v177, s[12:13]
	v_cndmask_b32_e64 v48, v71, v177, s[14:15]
	v_max3_f32 v34, v34, v47, v48
	v_cndmask_b32_e64 v49, v72, v177, s[16:17]
	v_cndmask_b32_e64 v42, v73, v177, s[18:19]
	v_max3_f32 v34, v34, v49, v42
	v_cndmask_b32_e64 v35, v74, v177, s[20:21]
	v_cndmask_b32_e64 v36, v75, v177, s[22:23]
	v_max3_f32 v34, v34, v35, v36
	v_cndmask_b32_e64 v37, v76, v177, s[24:25]
	v_cndmask_b32_e64 v38, v77, v177, s[26:27]
	v_max3_f32 v34, v34, v37, v38
	v_cndmask_b32_e64 v39, v78, v177, s[28:29]
	v_cndmask_b32_e64 v40, v79, v177, s[30:31]
	v_max3_f32 v51, v34, v39, v40
	v_cndmask_b32_e64 v41, v80, v177, s[34:35]
	v_cndmask_b32_e64 v34, v81, v177, s[36:37]
	v_max3_f32 v51, v51, v41, v34
	ds_bpermute_b32 v53, v165, v51
	s_waitcnt lgkmcnt(0)
	v_max_f32_e32 v53, v53, v53
	v_max_f32_e32 v51, v51, v53
	v_mul_f32_e32 v51, 0x3e38aa3b, v51
	v_max_f32_e32 v133, v51, v179
	v_fma_f32 v50, v50, s97, -v133
	v_exp_f32_e32 v51, v50
	v_fma_f32 v53, v98, s97, -v133
	v_exp_f32_e32 v53, v53
	v_fma_f32 v52, v52, s97, -v133
	v_exp_f32_e32 v58, v52
	v_fma_f32 v52, v99, s97, -v133
	v_exp_f32_e32 v61, v52
	v_fma_f32 v52, v54, s97, -v133
	v_add_f32_e32 v50, 0, v51
	v_exp_f32_e32 v68, v52
	v_fma_f32 v52, v55, s97, -v133
	v_add_f32_e32 v50, v53, v50
	v_exp_f32_e32 v77, v52
	v_fma_f32 v52, v56, s97, -v133
	v_add_f32_e32 v50, v58, v50
	v_exp_f32_e32 v107, v52
	v_fma_f32 v52, v57, s97, -v133
	v_add_f32_e32 v50, v61, v50
	v_exp_f32_e32 v112, v52
	v_fma_f32 v52, v100, s97, -v133
	v_add_f32_e32 v50, v68, v50
	v_exp_f32_e32 v52, v52
	v_fma_f32 v54, v59, s97, -v133
	v_add_f32_e32 v50, v77, v50
	v_exp_f32_e32 v55, v54
	v_fma_f32 v54, v60, s97, -v133
	v_add_f32_e32 v50, v107, v50
	v_exp_f32_e32 v62, v54
	v_fma_f32 v54, v101, s97, -v133
	v_add_f32_e32 v50, v112, v50
	v_exp_f32_e32 v70, v54
	v_fma_f32 v54, v102, s97, -v133
	v_add_f32_e32 v50, v52, v50
	v_exp_f32_e32 v78, v54
	v_fma_f32 v54, v63, s97, -v133
	v_add_f32_e32 v50, v55, v50
	v_exp_f32_e32 v102, v54
	v_fma_f32 v54, v64, s97, -v133
	v_add_f32_e32 v50, v62, v50
	v_exp_f32_e32 v113, v54
	v_fma_f32 v54, v65, s97, -v133
	v_add_f32_e32 v50, v70, v50
	v_exp_f32_e32 v119, v54
	v_fma_f32 v54, v103, s97, -v133
	v_add_f32_e32 v50, v78, v50
	v_exp_f32_e32 v54, v54
	v_fma_f32 v56, v104, s97, -v133
	v_add_f32_e32 v50, v102, v50
	v_exp_f32_e32 v57, v56
	v_fma_f32 v56, v105, s97, -v133
	v_add_f32_e32 v50, v113, v50
	v_exp_f32_e32 v66, v56
	v_fma_f32 v56, v106, s97, -v133
	v_add_f32_e32 v50, v119, v50
	v_exp_f32_e32 v76, v56
	v_fma_f32 v56, v108, s97, -v133
	v_add_f32_e32 v50, v54, v50
	v_exp_f32_e32 v100, v56
	v_fma_f32 v56, v109, s97, -v133
	v_add_f32_e32 v50, v57, v50
	v_exp_f32_e32 v106, v56
	v_fma_f32 v56, v110, s97, -v133
	v_add_f32_e32 v50, v66, v50
	v_exp_f32_e32 v117, v56
	v_fma_f32 v56, v111, s97, -v133
	v_add_f32_e32 v50, v76, v50
	v_exp_f32_e32 v122, v56
	v_fma_f32 v56, v114, s97, -v133
	v_add_f32_e32 v50, v100, v50
	v_exp_f32_e32 v56, v56
	v_fma_f32 v59, v115, s97, -v133
	v_add_f32_e32 v50, v106, v50
	v_exp_f32_e32 v60, v59
	v_fma_f32 v59, v116, s97, -v133
	v_add_f32_e32 v50, v117, v50
	v_exp_f32_e32 v74, v59
	v_fma_f32 v59, v118, s97, -v133
	v_add_f32_e32 v50, v122, v50
	v_exp_f32_e32 v99, v59
	v_fma_f32 v59, v120, s97, -v133
	v_add_f32_e32 v50, v56, v50
	v_exp_f32_e32 v105, v59
	v_fma_f32 v59, v121, s97, -v133
	v_add_f32_e32 v50, v60, v50
	v_exp_f32_e32 v111, v59
	v_fma_f32 v59, v123, s97, -v133
	v_add_f32_e32 v50, v74, v50
	v_exp_f32_e32 v121, v59
	v_fma_f32 v59, v124, s97, -v133
	v_add_f32_e32 v50, v99, v50
	v_exp_f32_e32 v125, v59
	v_fma_f32 v18, v18, s97, -v133
	v_add_f32_e32 v50, v105, v50
	v_exp_f32_e32 v59, v18
	v_fma_f32 v19, v19, s97, -v133
	v_add_f32_e32 v50, v111, v50
	v_exp_f32_e32 v64, v19
	v_fma_f32 v19, v20, s97, -v133
	v_add_f32_e32 v50, v121, v50
	v_exp_f32_e32 v81, v19
	v_fma_f32 v19, v21, s97, -v133
	v_add_f32_e32 v50, v125, v50
	v_exp_f32_e32 v104, v19
	v_fma_f32 v19, v22, s97, -v133
	v_add_f32_e32 v18, v59, v50
	v_exp_f32_e32 v110, v19
	v_fma_f32 v19, v23, s97, -v133
	v_add_f32_e32 v18, v64, v18
	v_exp_f32_e32 v116, v19
	v_fma_f32 v19, v24, s97, -v133
	v_add_f32_e32 v18, v81, v18
	v_exp_f32_e32 v124, v19
	v_fma_f32 v19, v25, s97, -v133
	v_add_f32_e32 v18, v104, v18
	v_exp_f32_e32 v127, v19
	v_fma_f32 v19, v26, s97, -v133
	v_add_f32_e32 v18, v110, v18
	v_exp_f32_e32 v63, v19
	v_fma_f32 v19, v27, s97, -v133
	v_add_f32_e32 v18, v116, v18
	v_exp_f32_e32 v72, v19
	v_fma_f32 v19, v28, s97, -v133
	v_add_f32_e32 v18, v124, v18
	v_exp_f32_e32 v103, v19
	v_fma_f32 v19, v29, s97, -v133
	v_add_f32_e32 v18, v127, v18
	v_exp_f32_e32 v109, v19
	v_fma_f32 v19, v30, s97, -v133
	v_add_f32_e32 v18, v63, v18
	v_exp_f32_e32 v115, v19
	v_fma_f32 v19, v31, s97, -v133
	v_add_f32_e32 v18, v72, v18
	v_exp_f32_e32 v120, v19
	v_fma_f32 v19, v32, s97, -v133
	v_add_f32_e32 v18, v103, v18
	v_exp_f32_e32 v126, v19
	v_fma_f32 v19, v33, s97, -v133
	v_add_f32_e32 v18, v109, v18
	v_exp_f32_e32 v129, v19
	v_fma_f32 v2, v2, s97, -v133
	v_add_f32_e32 v18, v115, v18
	v_exp_f32_e32 v69, v2
	v_fma_f32 v3, v3, s97, -v133
	v_add_f32_e32 v18, v120, v18
	v_exp_f32_e32 v79, v3
	v_fma_f32 v3, v4, s97, -v133
	v_add_f32_e32 v18, v126, v18
	v_exp_f32_e32 v108, v3
	v_fma_f32 v3, v5, s97, -v133
	v_add_f32_e32 v18, v129, v18
	v_exp_f32_e32 v114, v3
	v_fma_f32 v3, v6, s97, -v133
	v_add_f32_e32 v2, v69, v18
	v_exp_f32_e32 v118, v3
	v_fma_f32 v3, v7, s97, -v133
	v_add_f32_e32 v2, v79, v2
	v_exp_f32_e32 v123, v3
	v_fma_f32 v3, v8, s97, -v133
	v_add_f32_e32 v2, v108, v2
	v_exp_f32_e32 v128, v3
	v_fma_f32 v3, v9, s97, -v133
	v_add_f32_e32 v2, v114, v2
	v_exp_f32_e32 v132, v3
	v_fma_f32 v3, v10, s97, -v133
	v_add_f32_e32 v2, v118, v2
	v_exp_f32_e32 v65, v3
	v_fma_f32 v3, v11, s97, -v133
	v_add_f32_e32 v2, v123, v2
	v_exp_f32_e32 v67, v3
	v_fma_f32 v3, v12, s97, -v133
	v_add_f32_e32 v2, v128, v2
	v_exp_f32_e32 v71, v3
	v_fma_f32 v3, v13, s97, -v133
	v_add_f32_e32 v2, v132, v2
	v_exp_f32_e32 v73, v3
	v_fma_f32 v3, v14, s97, -v133
	v_add_f32_e32 v2, v65, v2
	v_exp_f32_e32 v75, v3
	v_fma_f32 v3, v15, s97, -v133
	v_add_f32_e32 v2, v67, v2
	v_exp_f32_e32 v80, v3
	v_fma_f32 v3, v16, s97, -v133
	v_add_f32_e32 v2, v71, v2
	v_exp_f32_e32 v98, v3
	v_fma_f32 v3, v17, s97, -v133
	v_add_f32_e32 v2, v73, v2
	v_exp_f32_e32 v101, v3
	v_fma_f32 v3, v43, s97, -v133
	v_add_f32_e32 v2, v75, v2
	v_exp_f32_e32 v43, v3
	v_fma_f32 v3, v44, s97, -v133
	v_add_f32_e32 v2, v80, v2
	v_exp_f32_e32 v44, v3
	v_fma_f32 v3, v45, s97, -v133
	v_add_f32_e32 v2, v98, v2
	v_exp_f32_e32 v45, v3
	v_fma_f32 v3, v46, s97, -v133
	v_add_f32_e32 v2, v101, v2
	v_exp_f32_e32 v46, v3
	v_fma_f32 v3, v47, s97, -v133
	v_add_f32_e32 v2, v43, v2
	v_exp_f32_e32 v47, v3
	v_fma_f32 v3, v48, s97, -v133
	v_add_f32_e32 v2, v44, v2
	v_exp_f32_e32 v48, v3
	v_fma_f32 v3, v49, s97, -v133
	v_add_f32_e32 v2, v45, v2
	v_exp_f32_e32 v49, v3
	v_fma_f32 v3, v42, s97, -v133
	v_add_f32_e32 v2, v46, v2
	v_exp_f32_e32 v50, v3
	v_fma_f32 v3, v35, s97, -v133
	v_add_f32_e32 v2, v47, v2
	v_exp_f32_e32 v35, v3
	v_fma_f32 v3, v36, s97, -v133
	v_add_f32_e32 v2, v48, v2
	v_exp_f32_e32 v36, v3
	v_fma_f32 v3, v37, s97, -v133
	v_add_f32_e32 v2, v49, v2
	v_exp_f32_e32 v37, v3
	v_fma_f32 v3, v38, s97, -v133
	v_add_f32_e32 v2, v50, v2
	v_exp_f32_e32 v38, v3
	v_fma_f32 v3, v39, s97, -v133
	v_add_f32_e32 v2, v35, v2
	v_exp_f32_e32 v39, v3
	v_fma_f32 v3, v40, s97, -v133
	v_add_f32_e32 v2, v36, v2
	v_exp_f32_e32 v40, v3
	v_fma_f32 v3, v41, s97, -v133
	v_add_f32_e32 v2, v37, v2
	v_exp_f32_e32 v41, v3
	v_fma_f32 v3, v34, s97, -v133
	v_add_f32_e32 v2, v38, v2
	v_exp_f32_e32 v42, v3
	v_add_f32_e32 v2, v39, v2
	v_add_f32_e32 v2, v40, v2
	v_add_f32_e32 v2, v41, v2
	v_add_f32_e32 v2, v42, v2
	ds_bpermute_b32 v3, v165, v2
	v_cvt_pk_bf16_f32 v18, v51, v53
	v_cvt_pk_bf16_f32 v19, v58, v61
	v_cvt_pk_bf16_f32 v20, v68, v77
	v_cvt_pk_bf16_f32 v21, v107, v112
	s_waitcnt lgkmcnt(0)
	v_add_f32_e32 v2, v2, v3
	v_fma_f32 v3, v178, s88, -v133
	v_exp_f32_e32 v3, v3
	ds_read2_b64 v[22:25], v130 offset0:16 offset1:18
	v_add_f32_e32 v34, v3, v2
	ds_read2_b64 v[2:5], v131 offset0:16 offset1:18
	v_cvt_pk_bf16_f32 v134, v52, v55
	v_cvt_pk_bf16_f32 v135, v62, v70
	v_cvt_pk_bf16_f32 v136, v78, v102
	v_cvt_pk_bf16_f32 v137, v113, v119
	ds_read2_b64 v[138:141], v131 offset0:20 offset1:22
	s_waitcnt lgkmcnt(1)
	v_mfma_f32_32x32x16_bf16 v[2:17], v[2:5], v[18:21], 0
	s_waitcnt lgkmcnt(0)
	v_mfma_f32_32x32x16_bf16 v[2:17], v[138:141], v[134:137], v[2:17]
	ds_read2_b64 v[138:141], v130 offset0:20 offset1:22
	v_cvt_pk_bf16_f32 v52, v54, v57
	v_cvt_pk_bf16_f32 v53, v66, v76
	v_cvt_pk_bf16_f32 v54, v100, v106
	v_cvt_pk_bf16_f32 v55, v117, v122
	v_mfma_f32_32x32x16_bf16 v[18:33], v[22:25], v[18:21], 0
	s_waitcnt lgkmcnt(0)
	v_mfma_f32_32x32x16_bf16 v[18:33], v[138:141], v[134:137], v[18:33]
	ds_read2_b64 v[134:137], v131 offset0:24 offset1:26
	s_waitcnt lgkmcnt(0)
	v_mfma_f32_32x32x16_bf16 v[2:17], v[134:137], v[52:55], v[2:17]
	ds_read2_b64 v[134:137], v130 offset0:24 offset1:26
	s_waitcnt lgkmcnt(0)
	v_mfma_f32_32x32x16_bf16 v[18:33], v[134:137], v[52:55], v[18:33]
	v_cvt_pk_bf16_f32 v52, v56, v60
	v_cvt_pk_bf16_f32 v53, v74, v99
	v_cvt_pk_bf16_f32 v54, v105, v111
	v_cvt_pk_bf16_f32 v55, v121, v125
	ds_read2_b64 v[134:137], v131 offset0:28 offset1:30
	s_waitcnt lgkmcnt(0)
	v_mfma_f32_32x32x16_bf16 v[2:17], v[134:137], v[52:55], v[2:17]
	ds_read2_b64 v[134:137], v130 offset0:28 offset1:30
	s_waitcnt lgkmcnt(0)
	v_mfma_f32_32x32x16_bf16 v[18:33], v[134:137], v[52:55], v[18:33]
	v_cvt_pk_bf16_f32 v52, v59, v64
	v_cvt_pk_bf16_f32 v53, v81, v104
	v_cvt_pk_bf16_f32 v54, v110, v116
	v_cvt_pk_bf16_f32 v55, v124, v127
	ds_read2_b64 v[56:59], v131 offset0:32 offset1:34
	s_waitcnt lgkmcnt(0)
	v_mfma_f32_32x32x16_bf16 v[2:17], v[56:59], v[52:55], v[2:17]
	ds_read2_b64 v[56:59], v130 offset0:32 offset1:34
	s_waitcnt lgkmcnt(0)
	v_mfma_f32_32x32x16_bf16 v[18:33], v[56:59], v[52:55], v[18:33]
	v_cvt_pk_bf16_f32 v52, v63, v72
	v_cvt_pk_bf16_f32 v53, v103, v109
	v_cvt_pk_bf16_f32 v54, v115, v120
	v_cvt_pk_bf16_f32 v55, v126, v129
	ds_read2_b64 v[56:59], v131 offset0:36 offset1:38
	s_waitcnt lgkmcnt(0)
	v_mfma_f32_32x32x16_bf16 v[2:17], v[56:59], v[52:55], v[2:17]
	ds_read2_b64 v[56:59], v130 offset0:36 offset1:38
	s_waitcnt lgkmcnt(0)
	v_mfma_f32_32x32x16_bf16 v[18:33], v[56:59], v[52:55], v[18:33]
	v_cvt_pk_bf16_f32 v52, v69, v79
	v_cvt_pk_bf16_f32 v53, v108, v114
	v_cvt_pk_bf16_f32 v54, v118, v123
	v_cvt_pk_bf16_f32 v55, v128, v132
	ds_read2_b64 v[56:59], v131 offset0:40 offset1:42
	s_waitcnt lgkmcnt(0)
	v_mfma_f32_32x32x16_bf16 v[2:17], v[56:59], v[52:55], v[2:17]
	ds_read2_b64 v[56:59], v130 offset0:40 offset1:42
	s_waitcnt lgkmcnt(0)
	v_mfma_f32_32x32x16_bf16 v[18:33], v[56:59], v[52:55], v[18:33]
	v_cvt_pk_bf16_f32 v52, v65, v67
	v_cvt_pk_bf16_f32 v53, v71, v73
	v_cvt_pk_bf16_f32 v54, v75, v80
	v_cvt_pk_bf16_f32 v55, v98, v101
	ds_read2_b64 v[56:59], v131 offset0:44 offset1:46
	s_waitcnt lgkmcnt(0)
	v_mfma_f32_32x32x16_bf16 v[2:17], v[56:59], v[52:55], v[2:17]
	ds_read2_b64 v[56:59], v130 offset0:44 offset1:46
	v_cvt_pk_bf16_f32 v44, v43, v44
	v_cvt_pk_bf16_f32 v45, v45, v46
	v_cvt_pk_bf16_f32 v46, v47, v48
	v_cvt_pk_bf16_f32 v47, v49, v50
	ds_read2_b64 v[48:51], v131 offset0:48 offset1:50
	s_waitcnt lgkmcnt(0)
	v_mfma_f32_32x32x16_bf16 v[2:17], v[48:51], v[44:47], v[2:17]
	ds_read2_b64 v[48:51], v130 offset0:48 offset1:50
	v_cvt_pk_bf16_f32 v36, v35, v36
	v_cvt_pk_bf16_f32 v37, v37, v38
	v_cvt_pk_bf16_f32 v38, v39, v40
	v_cvt_pk_bf16_f32 v39, v41, v42
	ds_read2_b64 v[40:43], v131 offset0:52 offset1:54
	v_div_scale_f32 v35, s[72:73], v34, v34, 1.0
	v_mfma_f32_32x32x16_bf16 v[18:33], v[56:59], v[52:55], v[18:33]
	s_waitcnt lgkmcnt(0)
	v_mfma_f32_32x32x16_bf16 v[2:17], v[40:43], v[36:39], v[2:17]
	ds_read2_b64 v[40:43], v130 offset0:52 offset1:54
	v_mfma_f32_32x32x16_bf16 v[18:33], v[48:51], v[44:47], v[18:33]
	s_waitcnt lgkmcnt(0)
	v_mfma_f32_32x32x16_bf16 v[18:33], v[40:43], v[36:39], v[18:33]
	v_rcp_f32_e32 v36, v35
	s_nop 0
	v_fma_f32 v37, -v35, v36, 1.0
	v_fmac_f32_e32 v36, v37, v36
	v_div_scale_f32 v37, vcc, 1.0, v34, 1.0
	v_mul_f32_e32 v38, v37, v36
	v_fma_f32 v39, -v35, v38, v37
	v_fmac_f32_e32 v38, v39, v36
	v_fma_f32 v35, -v35, v38, v37
	v_div_fmas_f32 v35, v35, v36, v38
	v_div_fixup_f32 v36, v35, v34, 1.0
	v_mul_f32_e32 v2, v2, v36
	v_mul_f32_e32 v3, v3, v36
	v_cvt_pk_bf16_f32 v2, v2, v3
	v_mul_f32_e32 v3, v4, v36
	v_lshl_add_u64 v[34:35], v[150:151], 0, v[152:153]
	v_mul_f32_e32 v4, v5, v36
	v_cvt_pk_bf16_f32 v3, v3, v4
	global_store_dwordx2 v[34:35], v[2:3], off sc1
	v_mul_f32_e32 v2, v6, v36
	v_mul_f32_e32 v3, v7, v36
	v_cvt_pk_bf16_f32 v2, v2, v3
	v_mul_f32_e32 v3, v8, v36
	v_mul_f32_e32 v4, v9, v36
	v_cvt_pk_bf16_f32 v3, v3, v4
	global_store_dwordx2 v[34:35], v[2:3], off offset:16 sc1
	v_mul_f32_e32 v2, v10, v36
	v_mul_f32_e32 v3, v11, v36
	v_cvt_pk_bf16_f32 v2, v2, v3
	v_mul_f32_e32 v3, v12, v36
	v_mul_f32_e32 v4, v13, v36
	v_cvt_pk_bf16_f32 v3, v3, v4
	global_store_dwordx2 v[34:35], v[2:3], off offset:32 sc1
	v_mul_f32_e32 v2, v14, v36
	v_mul_f32_e32 v3, v15, v36
	v_cvt_pk_bf16_f32 v2, v2, v3
	v_mul_f32_e32 v3, v16, v36
	v_mul_f32_e32 v4, v17, v36
	v_cvt_pk_bf16_f32 v3, v3, v4
	global_store_dwordx2 v[34:35], v[2:3], off offset:48 sc1
	v_mul_f32_e32 v2, v18, v36
	v_mul_f32_e32 v3, v19, v36
	v_cvt_pk_bf16_f32 v2, v2, v3
	v_mul_f32_e32 v3, v20, v36
	v_mul_f32_e32 v4, v21, v36
	v_cvt_pk_bf16_f32 v3, v3, v4
	global_store_dwordx2 v[34:35], v[2:3], off offset:64 sc1
	v_mul_f32_e32 v2, v22, v36
	v_mul_f32_e32 v3, v23, v36
	v_cvt_pk_bf16_f32 v2, v2, v3
	v_mul_f32_e32 v3, v24, v36
	v_mul_f32_e32 v4, v25, v36
	v_cvt_pk_bf16_f32 v3, v3, v4
	global_store_dwordx2 v[34:35], v[2:3], off offset:80 sc1
	v_mul_f32_e32 v2, v26, v36
	v_mul_f32_e32 v3, v27, v36
	v_cvt_pk_bf16_f32 v2, v2, v3
	v_mul_f32_e32 v3, v28, v36
	v_mul_f32_e32 v4, v29, v36
	v_cvt_pk_bf16_f32 v3, v3, v4
	global_store_dwordx2 v[34:35], v[2:3], off offset:96 sc1
	v_mul_f32_e32 v2, v30, v36
	v_mul_f32_e32 v3, v31, v36
	v_cvt_pk_bf16_f32 v2, v2, v3
	v_mul_f32_e32 v3, v32, v36
	v_mul_f32_e32 v4, v33, v36
	v_cvt_pk_bf16_f32 v3, v3, v4
	global_store_dwordx2 v[34:35], v[2:3], off offset:112 sc1
	ds_read_b128 v[2:5], v176 offset:13824
	ds_read_b128 v[6:9], v176 offset:13856
	s_waitcnt lgkmcnt(1)
	v_mfma_f32_32x32x16_bf16 v[50:65], v[2:5], v[94:97], 0
	ds_read_b128 v[2:5], v176 offset:13888
	ds_read_b128 v[66:69], v176 offset:27680
	s_waitcnt lgkmcnt(2)
	v_mfma_f32_32x32x16_bf16 v[50:65], v[6:9], v[90:93], v[50:65]
	s_waitcnt lgkmcnt(1)
	v_mfma_f32_32x32x16_bf16 v[50:65], v[2:5], v[86:89], v[50:65]
	ds_read_b128 v[2:5], v176 offset:13920
	s_waitcnt lgkmcnt(0)
	v_mfma_f32_32x32x16_bf16 v[50:65], v[2:5], v[82:85], v[50:65]
	ds_read_b128 v[2:5], v176 offset:18432
	s_waitcnt lgkmcnt(0)
	v_mfma_f32_32x32x16_bf16 v[34:49], v[2:5], v[94:97], 0
	ds_read_b128 v[2:5], v176 offset:18464
	s_nop 7
	v_cndmask_b32_e64 v50, v177, v50, s[4:5]
	s_waitcnt lgkmcnt(0)
	v_mfma_f32_32x32x16_bf16 v[34:49], v[2:5], v[90:93], v[34:49]
	ds_read_b128 v[2:5], v176 offset:18496
	s_waitcnt lgkmcnt(0)
	v_mfma_f32_32x32x16_bf16 v[34:49], v[2:5], v[86:89], v[34:49]
	ds_read_b128 v[2:5], v176 offset:18528
	s_waitcnt lgkmcnt(0)
	v_mfma_f32_32x32x16_bf16 v[34:49], v[2:5], v[82:85], v[34:49]
	ds_read_b128 v[2:5], v176 offset:23040
	s_waitcnt lgkmcnt(0)
	v_mfma_f32_32x32x16_bf16 v[18:33], v[2:5], v[94:97], 0
	ds_read_b128 v[2:5], v176 offset:23072
	s_waitcnt lgkmcnt(0)
	v_mfma_f32_32x32x16_bf16 v[18:33], v[2:5], v[90:93], v[18:33]
	ds_read_b128 v[2:5], v176 offset:23104
	s_waitcnt lgkmcnt(0)
	v_mfma_f32_32x32x16_bf16 v[18:33], v[2:5], v[86:89], v[18:33]
	ds_read_b128 v[2:5], v176 offset:23136
	s_waitcnt lgkmcnt(0)
	v_mfma_f32_32x32x16_bf16 v[18:33], v[2:5], v[82:85], v[18:33]
	ds_read_b128 v[2:5], v176 offset:27648
	s_waitcnt lgkmcnt(0)
	v_mfma_f32_32x32x16_bf16 v[2:17], v[2:5], v[94:97], 0
	v_mfma_f32_32x32x16_bf16 v[2:17], v[66:69], v[90:93], v[2:17]
	ds_read_b128 v[66:69], v176 offset:27712
	s_waitcnt lgkmcnt(0)
	v_mfma_f32_32x32x16_bf16 v[2:17], v[66:69], v[86:89], v[2:17]
	ds_read_b128 v[66:69], v176 offset:27744
	s_waitcnt lgkmcnt(0)
	v_mfma_f32_32x32x16_bf16 v[2:17], v[66:69], v[82:85], v[2:17]
	ds_read_b128 v[66:69], v176 offset:32256
	s_waitcnt lgkmcnt(0)
	v_mfma_f32_32x32x16_bf16 v[66:81], v[66:69], v[94:97], 0
	ds_read_b128 v[94:97], v176 offset:32288
	s_waitcnt lgkmcnt(0)
	v_mfma_f32_32x32x16_bf16 v[66:81], v[94:97], v[90:93], v[66:81]
	ds_read_b128 v[90:93], v176 offset:32320
	s_waitcnt lgkmcnt(0)
	v_mfma_f32_32x32x16_bf16 v[66:81], v[90:93], v[86:89], v[66:81]
	ds_read_b128 v[86:89], v176 offset:32352
	s_waitcnt lgkmcnt(0)
	v_mfma_f32_32x32x16_bf16 v[66:81], v[86:89], v[82:85], v[66:81]
	v_cndmask_b32_e64 v83, v51, v177, s[40:41]
	v_cndmask_b32_e64 v51, v177, v52, s[8:9]
	v_cndmask_b32_e64 v52, v51, v177, s[38:39]
	v_cndmask_b32_e64 v51, v177, v53, s[10:11]
	v_cndmask_b32_e64 v84, v51, v177, s[38:39]
	v_cndmask_b32_e64 v51, v177, v54, s[12:13]
	v_cndmask_b32_e64 v54, v51, v177, s[38:39]
	v_cndmask_b32_e64 v51, v177, v55, s[14:15]
	v_cndmask_b32_e64 v55, v51, v177, s[38:39]
	v_cndmask_b32_e64 v51, v177, v56, s[16:17]
	v_cndmask_b32_e64 v56, v51, v177, s[38:39]
	v_cndmask_b32_e64 v51, v177, v57, s[18:19]
	v_cndmask_b32_e64 v57, v51, v177, s[38:39]
	v_cndmask_b32_e64 v51, v177, v58, s[20:21]
	v_cndmask_b32_e64 v82, v50, v177, s[38:39]
	v_cndmask_b32_e64 v85, v51, v177, s[38:39]
	v_cndmask_b32_e64 v51, v177, v59, s[22:23]
	v_max3_f32 v50, v82, s89, v83
	v_cndmask_b32_e64 v59, v51, v177, s[38:39]
	v_cndmask_b32_e64 v51, v177, v60, s[24:25]
	v_max3_f32 v50, v50, v52, v84
	v_cndmask_b32_e64 v60, v51, v177, s[38:39]
	v_cndmask_b32_e64 v51, v177, v61, s[26:27]
	v_max3_f32 v50, v50, v54, v55
	v_cndmask_b32_e64 v86, v51, v177, s[38:39]
	v_cndmask_b32_e64 v51, v177, v62, s[28:29]
	v_max3_f32 v50, v50, v56, v57
	v_cndmask_b32_e64 v87, v51, v177, s[38:39]
	v_cndmask_b32_e64 v51, v177, v63, s[30:31]
	v_max3_f32 v50, v50, v85, v59
	v_cndmask_b32_e64 v63, v51, v177, s[38:39]
	v_cndmask_b32_e64 v51, v177, v64, s[34:35]
	v_max3_f32 v50, v50, v60, v86
	v_cndmask_b32_e64 v64, v51, v177, s[38:39]
	v_cndmask_b32_e64 v51, v177, v65, s[36:37]
	v_max3_f32 v50, v50, v87, v63
	v_cndmask_b32_e64 v65, v51, v177, s[38:39]
	v_max3_f32 v50, v50, v64, v65
	v_max3_f32 v50, v50, v34, v35
	v_max3_f32 v50, v50, v36, v37
	v_max3_f32 v50, v50, v38, v39
	v_max3_f32 v50, v50, v40, v41
	v_max3_f32 v50, v50, v42, v43
	v_max3_f32 v50, v50, v44, v45
	v_max3_f32 v50, v50, v46, v47
	v_max3_f32 v50, v50, v48, v49
	v_max3_f32 v50, v50, v18, v19
	v_max3_f32 v50, v50, v20, v21
	v_max3_f32 v50, v50, v22, v23
	v_max3_f32 v50, v50, v24, v25
	v_max3_f32 v50, v50, v26, v27
	v_max3_f32 v50, v50, v28, v29
	v_max3_f32 v50, v50, v30, v31
	v_max3_f32 v50, v50, v32, v33
	v_max3_f32 v50, v50, v2, v3
	v_max3_f32 v50, v50, v4, v5
	v_max3_f32 v50, v50, v6, v7
	v_max3_f32 v50, v50, v8, v9
	v_max3_f32 v50, v50, v10, v11
	v_max3_f32 v50, v50, v12, v13
	v_max3_f32 v50, v50, v14, v15
	v_max3_f32 v50, v50, v16, v17
	v_cndmask_b32_e64 v132, v66, v177, s[4:5]
	v_cndmask_b32_e64 v129, v177, v67, s[6:7]
	v_max3_f32 v50, v50, v132, v129
	v_cndmask_b32_e64 v128, v68, v177, s[8:9]
	v_cndmask_b32_e64 v127, v69, v177, s[10:11]
	v_max3_f32 v50, v50, v128, v127
	v_cndmask_b32_e64 v126, v70, v177, s[12:13]
	v_cndmask_b32_e64 v125, v71, v177, s[14:15]
	v_max3_f32 v51, v50, v126, v125
	v_cndmask_b32_e64 v124, v72, v177, s[16:17]
	v_cndmask_b32_e64 v50, v73, v177, s[18:19]
	v_max3_f32 v51, v51, v124, v50
	v_cndmask_b32_e64 v123, v74, v177, s[20:21]
	v_cndmask_b32_e64 v122, v75, v177, s[22:23]
	v_max3_f32 v51, v51, v123, v122
	v_cndmask_b32_e64 v121, v76, v177, s[24:25]
	v_cndmask_b32_e64 v120, v77, v177, s[26:27]
	v_max3_f32 v51, v51, v121, v120
	v_cndmask_b32_e64 v119, v78, v177, s[28:29]
	v_cndmask_b32_e64 v118, v79, v177, s[30:31]
	v_max3_f32 v51, v51, v119, v118
	v_cndmask_b32_e64 v117, v80, v177, s[34:35]
	v_cndmask_b32_e64 v115, v81, v177, s[36:37]
	v_max3_f32 v51, v51, v117, v115
	ds_bpermute_b32 v53, v165, v51
	s_waitcnt lgkmcnt(0)
	v_max_f32_e32 v53, v53, v53
	v_max_f32_e32 v51, v51, v53
	v_mul_f32_e32 v51, 0x3e38aa3b, v51
	v_max_f32_e32 v116, v51, v179
	v_fma_f32 v51, v82, s97, -v116
	v_exp_f32_e32 v51, v51
	v_fma_f32 v53, v83, s97, -v116
	v_exp_f32_e32 v53, v53
	v_fma_f32 v52, v52, s97, -v116
	v_add_f32_e32 v58, 0, v51
	v_fma_f32 v54, v54, s97, -v116
	v_add_f32_e32 v61, v53, v58
	v_exp_f32_e32 v58, v52
	v_exp_f32_e32 v68, v54
	v_fma_f32 v54, v55, s97, -v116
	v_exp_f32_e32 v77, v54
	v_add_f32_e32 v52, v58, v61
	v_fma_f32 v61, v84, s97, -v116
	v_exp_f32_e32 v61, v61
	v_fma_f32 v54, v56, s97, -v116
	v_exp_f32_e32 v91, v54
	v_fma_f32 v54, v57, s97, -v116
	v_add_f32_e32 v52, v61, v52
	v_exp_f32_e32 v96, v54
	v_add_f32_e32 v52, v68, v52
	v_add_f32_e32 v52, v77, v52
	v_add_f32_e32 v52, v91, v52
	v_add_f32_e32 v54, v96, v52
	v_fma_f32 v52, v85, s97, -v116
	v_exp_f32_e32 v52, v52
	v_fma_f32 v55, v59, s97, -v116
	v_exp_f32_e32 v55, v55
	v_fma_f32 v56, v60, s97, -v116
	v_exp_f32_e32 v62, v56
	v_fma_f32 v56, v86, s97, -v116
	v_exp_f32_e32 v70, v56
	v_fma_f32 v56, v87, s97, -v116
	v_add_f32_e32 v54, v52, v54
	v_exp_f32_e32 v78, v56
	v_fma_f32 v56, v63, s97, -v116
	v_add_f32_e32 v54, v55, v54
	v_exp_f32_e32 v86, v56
	v_fma_f32 v56, v64, s97, -v116
	v_add_f32_e32 v54, v62, v54
	v_exp_f32_e32 v97, v56
	v_fma_f32 v56, v65, s97, -v116
	v_add_f32_e32 v54, v70, v54
	v_exp_f32_e32 v103, v56
	v_add_f32_e32 v54, v78, v54
	v_add_f32_e32 v54, v86, v54
	v_add_f32_e32 v54, v97, v54
	v_fma_f32 v34, v34, s97, -v116
	v_add_f32_e32 v56, v103, v54
	v_exp_f32_e32 v54, v34
	v_fma_f32 v35, v35, s97, -v116
	v_exp_f32_e32 v57, v35
	v_fma_f32 v35, v36, s97, -v116
	v_exp_f32_e32 v66, v35
	v_fma_f32 v35, v37, s97, -v116
	v_exp_f32_e32 v76, v35
	v_fma_f32 v35, v38, s97, -v116
	v_add_f32_e32 v34, v54, v56
	v_exp_f32_e32 v84, v35
	v_fma_f32 v35, v39, s97, -v116
	v_add_f32_e32 v34, v57, v34
	v_exp_f32_e32 v90, v35
	v_fma_f32 v35, v40, s97, -v116
	v_add_f32_e32 v34, v66, v34
	v_exp_f32_e32 v101, v35
	v_fma_f32 v35, v41, s97, -v116
	v_add_f32_e32 v34, v76, v34
	v_exp_f32_e32 v106, v35
	v_fma_f32 v35, v42, s97, -v116
	v_add_f32_e32 v34, v84, v34
	v_exp_f32_e32 v56, v35
	v_fma_f32 v35, v43, s97, -v116
	v_add_f32_e32 v34, v90, v34
	v_exp_f32_e32 v60, v35
	v_fma_f32 v35, v44, s97, -v116
	v_add_f32_e32 v34, v101, v34
	v_exp_f32_e32 v74, v35
	v_fma_f32 v35, v45, s97, -v116
	v_add_f32_e32 v34, v106, v34
	v_exp_f32_e32 v83, v35
	v_fma_f32 v35, v46, s97, -v116
	v_add_f32_e32 v34, v56, v34
	v_exp_f32_e32 v89, v35
	v_fma_f32 v35, v47, s97, -v116
	v_add_f32_e32 v34, v60, v34
	v_exp_f32_e32 v95, v35
	v_fma_f32 v35, v48, s97, -v116
	v_add_f32_e32 v34, v74, v34
	v_exp_f32_e32 v105, v35
	v_fma_f32 v35, v49, s97, -v116
	v_add_f32_e32 v34, v83, v34
	v_exp_f32_e32 v109, v35
	v_fma_f32 v18, v18, s97, -v116
	v_add_f32_e32 v34, v89, v34
	v_exp_f32_e32 v59, v18
	v_fma_f32 v19, v19, s97, -v116
	v_add_f32_e32 v34, v95, v34
	v_exp_f32_e32 v64, v19
	v_fma_f32 v19, v20, s97, -v116
	v_add_f32_e32 v34, v105, v34
	v_exp_f32_e32 v81, v19
	v_fma_f32 v19, v21, s97, -v116
	v_add_f32_e32 v34, v109, v34
	v_exp_f32_e32 v88, v19
	v_fma_f32 v19, v22, s97, -v116
	v_add_f32_e32 v18, v59, v34
	v_exp_f32_e32 v94, v19
	v_fma_f32 v19, v23, s97, -v116
	v_add_f32_e32 v18, v64, v18
	v_exp_f32_e32 v100, v19
	v_fma_f32 v19, v24, s97, -v116
	v_add_f32_e32 v18, v81, v18
	v_exp_f32_e32 v108, v19
	v_fma_f32 v19, v25, s97, -v116
	v_add_f32_e32 v18, v88, v18
	v_exp_f32_e32 v111, v19
	v_fma_f32 v19, v26, s97, -v116
	v_add_f32_e32 v18, v94, v18
	v_exp_f32_e32 v63, v19
	v_fma_f32 v19, v27, s97, -v116
	v_add_f32_e32 v18, v100, v18
	v_exp_f32_e32 v72, v19
	v_fma_f32 v19, v28, s97, -v116
	v_add_f32_e32 v18, v108, v18
	v_exp_f32_e32 v87, v19
	v_fma_f32 v19, v29, s97, -v116
	v_add_f32_e32 v18, v111, v18
	v_exp_f32_e32 v93, v19
	v_fma_f32 v19, v30, s97, -v116
	v_add_f32_e32 v18, v63, v18
	v_exp_f32_e32 v99, v19
	v_fma_f32 v19, v31, s97, -v116
	v_add_f32_e32 v18, v72, v18
	v_exp_f32_e32 v104, v19
	v_fma_f32 v19, v32, s97, -v116
	v_add_f32_e32 v18, v87, v18
	v_exp_f32_e32 v110, v19
	v_fma_f32 v19, v33, s97, -v116
	v_add_f32_e32 v18, v93, v18
	v_exp_f32_e32 v113, v19
	v_fma_f32 v2, v2, s97, -v116
	v_add_f32_e32 v18, v99, v18
	v_exp_f32_e32 v69, v2
	v_fma_f32 v3, v3, s97, -v116
	v_add_f32_e32 v18, v104, v18
	v_exp_f32_e32 v79, v3
	v_fma_f32 v3, v4, s97, -v116
	v_add_f32_e32 v18, v110, v18
	v_exp_f32_e32 v92, v3
	v_fma_f32 v3, v5, s97, -v116
	v_add_f32_e32 v18, v113, v18
	v_exp_f32_e32 v98, v3
	v_fma_f32 v3, v6, s97, -v116
	v_add_f32_e32 v2, v69, v18
	v_exp_f32_e32 v102, v3
	v_fma_f32 v3, v7, s97, -v116
	v_add_f32_e32 v2, v79, v2
	v_exp_f32_e32 v107, v3
	v_fma_f32 v3, v8, s97, -v116
	v_add_f32_e32 v2, v92, v2
	v_exp_f32_e32 v112, v3
	v_fma_f32 v3, v9, s97, -v116
	v_add_f32_e32 v2, v98, v2
	v_exp_f32_e32 v114, v3
	v_fma_f32 v3, v10, s97, -v116
	v_add_f32_e32 v2, v102, v2
	v_exp_f32_e32 v65, v3
	v_fma_f32 v3, v11, s97, -v116
	v_add_f32_e32 v2, v107, v2
	v_exp_f32_e32 v67, v3
	v_fma_f32 v3, v12, s97, -v116
	v_add_f32_e32 v2, v112, v2
	v_exp_f32_e32 v71, v3
	v_fma_f32 v3, v13, s97, -v116
	v_add_f32_e32 v2, v114, v2
	v_exp_f32_e32 v73, v3
	v_fma_f32 v3, v14, s97, -v116
	v_add_f32_e32 v2, v65, v2
	v_exp_f32_e32 v75, v3
	v_fma_f32 v3, v15, s97, -v116
	v_add_f32_e32 v2, v67, v2
	v_exp_f32_e32 v80, v3
	v_fma_f32 v3, v16, s97, -v116
	v_add_f32_e32 v2, v71, v2
	v_exp_f32_e32 v82, v3
	v_fma_f32 v3, v17, s97, -v116
	v_add_f32_e32 v2, v73, v2
	v_exp_f32_e32 v85, v3
	v_fma_f32 v3, v132, s97, -v116
	v_add_f32_e32 v2, v75, v2
	v_exp_f32_e32 v43, v3
	v_fma_f32 v3, v129, s97, -v116
	v_add_f32_e32 v2, v80, v2
	v_exp_f32_e32 v44, v3
	v_fma_f32 v3, v128, s97, -v116
	v_add_f32_e32 v2, v82, v2
	v_exp_f32_e32 v45, v3
	v_fma_f32 v3, v127, s97, -v116
	v_add_f32_e32 v2, v85, v2
	v_exp_f32_e32 v46, v3
	v_fma_f32 v3, v126, s97, -v116
	v_add_f32_e32 v2, v43, v2
	v_exp_f32_e32 v47, v3
	v_fma_f32 v3, v125, s97, -v116
	v_add_f32_e32 v2, v44, v2
	v_exp_f32_e32 v48, v3
	v_fma_f32 v3, v124, s97, -v116
	v_add_f32_e32 v2, v45, v2
	v_exp_f32_e32 v49, v3
	v_fma_f32 v3, v50, s97, -v116
	v_add_f32_e32 v2, v46, v2
	v_exp_f32_e32 v50, v3
	v_fma_f32 v3, v123, s97, -v116
	v_add_f32_e32 v2, v47, v2
	v_exp_f32_e32 v35, v3
	v_fma_f32 v3, v122, s97, -v116
	v_add_f32_e32 v2, v48, v2
	v_exp_f32_e32 v36, v3
	v_fma_f32 v3, v121, s97, -v116
	v_add_f32_e32 v2, v49, v2
	v_exp_f32_e32 v37, v3
	v_fma_f32 v3, v120, s97, -v116
	v_add_f32_e32 v2, v50, v2
	v_exp_f32_e32 v38, v3
	v_fma_f32 v3, v119, s97, -v116
	v_add_f32_e32 v2, v35, v2
	v_exp_f32_e32 v39, v3
	v_fma_f32 v3, v118, s97, -v116
	v_add_f32_e32 v2, v36, v2
	v_exp_f32_e32 v40, v3
	v_fma_f32 v3, v117, s97, -v116
	v_add_f32_e32 v2, v37, v2
	v_exp_f32_e32 v41, v3
	v_fma_f32 v3, v115, s97, -v116
	v_add_f32_e32 v2, v38, v2
	v_exp_f32_e32 v42, v3
	v_add_f32_e32 v2, v39, v2
	v_add_f32_e32 v2, v40, v2
	v_add_f32_e32 v2, v41, v2
	v_add_f32_e32 v2, v42, v2
	ds_bpermute_b32 v3, v165, v2
	v_cvt_pk_bf16_f32 v18, v51, v53
	v_cvt_pk_bf16_f32 v19, v58, v61
	v_cvt_pk_bf16_f32 v20, v68, v77
	v_cvt_pk_bf16_f32 v21, v91, v96
	s_waitcnt lgkmcnt(0)
	v_add_f32_e32 v2, v2, v3
	v_fma_f32 v3, v178, s88, -v116
	v_exp_f32_e32 v3, v3
	ds_read2_b64 v[22:25], v130 offset0:24 offset1:26
	v_add_f32_e32 v34, v3, v2
	ds_read2_b64 v[2:5], v131 offset0:24 offset1:26
	v_cvt_pk_bf16_f32 v116, v52, v55
	v_cvt_pk_bf16_f32 v117, v62, v70
	v_cvt_pk_bf16_f32 v118, v78, v86
	v_cvt_pk_bf16_f32 v119, v97, v103
	ds_read2_b64 v[120:123], v131 offset0:28 offset1:30
	s_waitcnt lgkmcnt(1)
	v_mfma_f32_32x32x16_bf16 v[2:17], v[2:5], v[18:21], 0
	s_waitcnt lgkmcnt(0)
	v_mfma_f32_32x32x16_bf16 v[2:17], v[120:123], v[116:119], v[2:17]
	ds_read2_b64 v[120:123], v130 offset0:28 offset1:30
	v_cvt_pk_bf16_f32 v52, v54, v57
	v_cvt_pk_bf16_f32 v53, v66, v76
	v_cvt_pk_bf16_f32 v54, v84, v90
	v_cvt_pk_bf16_f32 v55, v101, v106
	v_mfma_f32_32x32x16_bf16 v[18:33], v[22:25], v[18:21], 0
	s_waitcnt lgkmcnt(0)
	v_mfma_f32_32x32x16_bf16 v[18:33], v[120:123], v[116:119], v[18:33]
	ds_read2_b64 v[116:119], v131 offset0:32 offset1:34
	s_waitcnt lgkmcnt(0)
	v_mfma_f32_32x32x16_bf16 v[2:17], v[116:119], v[52:55], v[2:17]
	ds_read2_b64 v[116:119], v130 offset0:32 offset1:34
	s_waitcnt lgkmcnt(0)
	v_mfma_f32_32x32x16_bf16 v[18:33], v[116:119], v[52:55], v[18:33]
	v_cvt_pk_bf16_f32 v52, v56, v60
	v_cvt_pk_bf16_f32 v53, v74, v83
	v_cvt_pk_bf16_f32 v54, v89, v95
	v_cvt_pk_bf16_f32 v55, v105, v109
	ds_read2_b64 v[116:119], v131 offset0:36 offset1:38
	s_waitcnt lgkmcnt(0)
	v_mfma_f32_32x32x16_bf16 v[2:17], v[116:119], v[52:55], v[2:17]
	ds_read2_b64 v[116:119], v130 offset0:36 offset1:38
	s_waitcnt lgkmcnt(0)
	v_mfma_f32_32x32x16_bf16 v[18:33], v[116:119], v[52:55], v[18:33]
	v_cvt_pk_bf16_f32 v52, v59, v64
	v_cvt_pk_bf16_f32 v53, v81, v88
	v_cvt_pk_bf16_f32 v54, v94, v100
	v_cvt_pk_bf16_f32 v55, v108, v111
	ds_read2_b64 v[56:59], v131 offset0:40 offset1:42
	s_waitcnt lgkmcnt(0)
	v_mfma_f32_32x32x16_bf16 v[2:17], v[56:59], v[52:55], v[2:17]
	ds_read2_b64 v[56:59], v130 offset0:40 offset1:42
	s_waitcnt lgkmcnt(0)
	v_mfma_f32_32x32x16_bf16 v[18:33], v[56:59], v[52:55], v[18:33]
	v_cvt_pk_bf16_f32 v52, v63, v72
	v_cvt_pk_bf16_f32 v53, v87, v93
	v_cvt_pk_bf16_f32 v54, v99, v104
	v_cvt_pk_bf16_f32 v55, v110, v113
	ds_read2_b64 v[56:59], v131 offset0:44 offset1:46
	s_waitcnt lgkmcnt(0)
	v_mfma_f32_32x32x16_bf16 v[2:17], v[56:59], v[52:55], v[2:17]
	ds_read2_b64 v[56:59], v130 offset0:44 offset1:46
	s_waitcnt lgkmcnt(0)
	v_mfma_f32_32x32x16_bf16 v[18:33], v[56:59], v[52:55], v[18:33]
	v_cvt_pk_bf16_f32 v52, v69, v79
	v_cvt_pk_bf16_f32 v53, v92, v98
	v_cvt_pk_bf16_f32 v54, v102, v107
	v_cvt_pk_bf16_f32 v55, v112, v114
	ds_read2_b64 v[56:59], v131 offset0:48 offset1:50
	s_waitcnt lgkmcnt(0)
	v_mfma_f32_32x32x16_bf16 v[2:17], v[56:59], v[52:55], v[2:17]
	ds_read2_b64 v[56:59], v130 offset0:48 offset1:50
	s_waitcnt lgkmcnt(0)
	v_mfma_f32_32x32x16_bf16 v[18:33], v[56:59], v[52:55], v[18:33]
	v_cvt_pk_bf16_f32 v52, v65, v67
	v_cvt_pk_bf16_f32 v53, v71, v73
	v_cvt_pk_bf16_f32 v54, v75, v80
	v_cvt_pk_bf16_f32 v55, v82, v85
	ds_read2_b64 v[56:59], v131 offset0:52 offset1:54
	s_waitcnt lgkmcnt(0)
	v_mfma_f32_32x32x16_bf16 v[2:17], v[56:59], v[52:55], v[2:17]
	ds_read2_b64 v[56:59], v130 offset0:52 offset1:54
	v_cvt_pk_bf16_f32 v44, v43, v44
	v_cvt_pk_bf16_f32 v45, v45, v46
	v_cvt_pk_bf16_f32 v46, v47, v48
	v_cvt_pk_bf16_f32 v47, v49, v50
	ds_read2_b64 v[48:51], v131 offset0:56 offset1:58
	s_waitcnt lgkmcnt(0)
	v_mfma_f32_32x32x16_bf16 v[2:17], v[48:51], v[44:47], v[2:17]
	ds_read2_b64 v[48:51], v130 offset0:56 offset1:58
	v_cvt_pk_bf16_f32 v36, v35, v36
	v_cvt_pk_bf16_f32 v37, v37, v38
	v_cvt_pk_bf16_f32 v38, v39, v40
	v_cvt_pk_bf16_f32 v39, v41, v42
	ds_read2_b64 v[40:43], v131 offset0:60 offset1:62
	v_div_scale_f32 v35, s[38:39], v34, v34, 1.0
	v_mfma_f32_32x32x16_bf16 v[18:33], v[56:59], v[52:55], v[18:33]
	s_waitcnt lgkmcnt(0)
	v_mfma_f32_32x32x16_bf16 v[2:17], v[40:43], v[36:39], v[2:17]
	ds_read2_b64 v[40:43], v130 offset0:60 offset1:62
	v_mfma_f32_32x32x16_bf16 v[18:33], v[48:51], v[44:47], v[18:33]
	s_waitcnt lgkmcnt(0)
	v_mfma_f32_32x32x16_bf16 v[18:33], v[40:43], v[36:39], v[18:33]
	v_rcp_f32_e32 v36, v35
	s_nop 0
	v_fma_f32 v37, -v35, v36, 1.0
	v_fmac_f32_e32 v36, v37, v36
	v_div_scale_f32 v37, vcc, 1.0, v34, 1.0
	v_mul_f32_e32 v38, v37, v36
	v_fma_f32 v39, -v35, v38, v37
	v_fmac_f32_e32 v38, v39, v36
	v_fma_f32 v35, -v35, v38, v37
	v_div_fmas_f32 v35, v35, v36, v38
	v_div_fixup_f32 v36, v35, v34, 1.0
	v_mul_f32_e32 v2, v2, v36
	v_mul_f32_e32 v3, v3, v36
	v_cvt_pk_bf16_f32 v2, v2, v3
	v_mul_f32_e32 v3, v4, v36
	v_lshl_add_u64 v[34:35], v[150:151], 0, v[148:149]
	v_mul_f32_e32 v4, v5, v36
	v_cvt_pk_bf16_f32 v3, v3, v4
	global_store_dwordx2 v[34:35], v[2:3], off sc1
	v_mul_f32_e32 v2, v6, v36
	v_mul_f32_e32 v3, v7, v36
	v_cvt_pk_bf16_f32 v2, v2, v3
	v_mul_f32_e32 v3, v8, v36
	v_mul_f32_e32 v4, v9, v36
	v_cvt_pk_bf16_f32 v3, v3, v4
	global_store_dwordx2 v[34:35], v[2:3], off offset:16 sc1
	v_mul_f32_e32 v2, v10, v36
	v_mul_f32_e32 v3, v11, v36
	v_cvt_pk_bf16_f32 v2, v2, v3
	v_mul_f32_e32 v3, v12, v36
	v_mul_f32_e32 v4, v13, v36
	v_cvt_pk_bf16_f32 v3, v3, v4
	global_store_dwordx2 v[34:35], v[2:3], off offset:32 sc1
	v_mul_f32_e32 v2, v14, v36
	v_mul_f32_e32 v3, v15, v36
	v_cvt_pk_bf16_f32 v2, v2, v3
	v_mul_f32_e32 v3, v16, v36
	v_mul_f32_e32 v4, v17, v36
	v_cvt_pk_bf16_f32 v3, v3, v4
	global_store_dwordx2 v[34:35], v[2:3], off offset:48 sc1
	v_mul_f32_e32 v2, v18, v36
	v_mul_f32_e32 v3, v19, v36
	v_cvt_pk_bf16_f32 v2, v2, v3
	v_mul_f32_e32 v3, v20, v36
	v_mul_f32_e32 v4, v21, v36
	v_cvt_pk_bf16_f32 v3, v3, v4
	global_store_dwordx2 v[34:35], v[2:3], off offset:64 sc1
	v_mul_f32_e32 v2, v22, v36
	v_mul_f32_e32 v3, v23, v36
	v_cvt_pk_bf16_f32 v2, v2, v3
	v_mul_f32_e32 v3, v24, v36
	v_mul_f32_e32 v4, v25, v36
	v_cvt_pk_bf16_f32 v3, v3, v4
	global_store_dwordx2 v[34:35], v[2:3], off offset:80 sc1
	v_mul_f32_e32 v2, v26, v36
	v_mul_f32_e32 v3, v27, v36
	v_cvt_pk_bf16_f32 v2, v2, v3
	v_mul_f32_e32 v3, v28, v36
	v_mul_f32_e32 v4, v29, v36
	v_cvt_pk_bf16_f32 v3, v3, v4
	global_store_dwordx2 v[34:35], v[2:3], off offset:96 sc1
	v_mul_f32_e32 v2, v30, v36
	v_mul_f32_e32 v3, v31, v36
	v_cvt_pk_bf16_f32 v2, v2, v3
	v_mul_f32_e32 v3, v32, v36
	v_mul_f32_e32 v4, v33, v36
	v_cvt_pk_bf16_f32 v3, v3, v4
	global_store_dwordx2 v[34:35], v[2:3], off offset:112 sc1
	s_barrier
	s_cbranch_scc1 .LBB0_480
	s_or_b32 s38, s48, 0xf80
	v_or_b32_e32 v2, s38, v159
	v_or_b32_e32 v4, s63, v146
	v_ashrrev_i32_e32 v3, 31, v2
	v_lshlrev_b64 v[6:7], 9, v[2:3]
	v_lshlrev_b32_e32 v12, 1, v4
	v_or_b32_e32 v6, v6, v12
	v_lshl_add_u64 v[2:3], s[42:43], 0, v[6:7]
	global_load_dwordx4 v[2:5], v[2:3], off
	v_lshl_add_u64 v[6:7], s[44:45], 0, v[6:7]
	global_load_dwordx4 v[6:9], v[6:7], off
	v_add_u32_e32 v10, s38, v160
	v_ashrrev_i32_e32 v11, 31, v10
	v_lshlrev_b64 v[14:15], 9, v[10:11]
	v_or_b32_e32 v14, v14, v12
	v_lshl_add_u64 v[10:11], s[42:43], 0, v[14:15]
	v_lshl_add_u64 v[14:15], s[44:45], 0, v[14:15]
	global_load_dwordx4 v[10:13], v[10:11], off
	s_and_b32 s38, s91, 0xffffff80
	global_load_dwordx4 v[14:17], v[14:15], off
	v_or_b32_e32 v18, s38, v159
	v_ashrrev_i32_e32 v19, 31, v18
	v_lshlrev_b64 v[18:19], 8, v[18:19]
	v_or3_b32 v27, v19, 0, 0
	v_or3_b32 v26, v18, v146, s63
	v_lshlrev_b64 v[26:27], 2, v[26:27]
	v_lshl_add_u64 v[28:29], s[50:51], 0, v[26:27]
	s_mov_b32 s39, 0x4040000
	s_waitcnt vmcnt(3)
	v_lshlrev_b32_e32 v18, 16, v2
	v_and_b32_e32 v19, 0xffff0000, v2
	v_lshlrev_b32_e32 v20, 16, v3
	v_and_b32_e32 v21, 0xffff0000, v3
	global_store_dwordx4 v[28:29], v[18:21], off sc1
	v_lshlrev_b32_e32 v2, 16, v4
	v_and_b32_e32 v3, 0xffff0000, v4
	v_lshl_add_u64 v[18:19], s[92:93], 0, v[26:27]
	v_add_co_u32_e32 v20, vcc, s39, v18
	v_lshlrev_b32_e32 v4, 16, v5
	v_and_b32_e32 v5, 0xffff0000, v5
	v_addc_co_u32_e32 v21, vcc, 0, v19, vcc
	s_waitcnt vmcnt(3)
	v_lshlrev_b32_e32 v22, 16, v6
	v_and_b32_e32 v23, 0xffff0000, v6
	v_lshlrev_b32_e32 v24, 16, v7
	v_and_b32_e32 v25, 0xffff0000, v7
	global_store_dwordx4 v[20:21], v[2:5], off offset:16 sc1
	s_mov_b32 s39, 0x4080000
	v_lshlrev_b32_e32 v6, 16, v8
	v_lshl_add_u64 v[2:3], s[52:53], 0, v[26:27]
	global_store_dwordx4 v[2:3], v[22:25], off sc1
	v_add_co_u32_e32 v2, vcc, s39, v18
	v_and_b32_e32 v7, 0xffff0000, v8
	v_lshlrev_b32_e32 v8, 16, v9
	v_and_b32_e32 v9, 0xffff0000, v9
	v_addc_co_u32_e32 v3, vcc, 0, v19, vcc
	global_store_dwordx4 v[2:3], v[6:9], off offset:16 sc1
	v_or_b32_e32 v2, s38, v160
	v_ashrrev_i32_e32 v3, 31, v2
	v_lshlrev_b64 v[2:3], 8, v[2:3]
	v_or3_b32 v23, v3, 0, 0
	v_or3_b32 v22, v2, v146, s63
	s_waitcnt vmcnt(4)
	v_lshlrev_b32_e32 v6, 16, v14
	v_and_b32_e32 v7, 0xffff0000, v14
	v_lshlrev_b32_e32 v8, 16, v15
	v_and_b32_e32 v9, 0xffff0000, v15
	v_lshlrev_b64 v[14:15], 2, v[22:23]
	v_lshlrev_b32_e32 v18, 16, v10
	v_and_b32_e32 v19, 0xffff0000, v10
	v_lshlrev_b32_e32 v20, 16, v11
	v_and_b32_e32 v21, 0xffff0000, v11
	v_lshlrev_b32_e32 v2, 16, v16
	v_and_b32_e32 v3, 0xffff0000, v16
	v_lshlrev_b32_e32 v4, 16, v17
	v_and_b32_e32 v5, 0xffff0000, v17
	v_lshl_add_u64 v[16:17], s[50:51], 0, v[14:15]
	global_store_dwordx4 v[16:17], v[18:21], off sc1
	v_lshl_add_u64 v[16:17], s[92:93], 0, v[14:15]
	v_lshlrev_b32_e32 v10, 16, v12
	v_add_co_u32_e32 v18, vcc, 0x4040000, v16
	v_and_b32_e32 v11, 0xffff0000, v12
	v_lshlrev_b32_e32 v12, 16, v13
	v_and_b32_e32 v13, 0xffff0000, v13
	v_addc_co_u32_e32 v19, vcc, 0, v17, vcc
	global_store_dwordx4 v[18:19], v[10:13], off offset:16 sc1
	s_nop 1
	v_lshl_add_u64 v[10:11], s[52:53], 0, v[14:15]
	global_store_dwordx4 v[10:11], v[6:9], off sc1
	s_nop 1
	v_add_co_u32_e32 v6, vcc, 0x4080000, v16
	s_nop 1
	v_addc_co_u32_e32 v7, vcc, 0, v17, vcc
	global_store_dwordx4 v[6:7], v[2:5], off offset:16 sc1
	s_branch .LBB0_480

.LBB0_498:
	s_or_b64 exec, exec, s[16:17]
	s_lshl_b32 s16, s12, 3
	s_add_i32 s16, s16, s96
	s_lshl_b64 s[14:15], s[14:15], 11
	s_lshl_b32 s12, s16, 6
	v_mov_b32_e32 v35, s15
	v_or_b32_e32 v34, s14, v166
	v_lshl_add_u64 v[70:71], v[34:35], 0, s[12:13]
	v_lshl_add_u64 v[34:35], v[70:71], 1, s[84:85]
	global_load_ushort v50, v[34:35], off
	v_or_b32_e32 v34, s27, v67
	v_or_b32_e32 v36, s27, v72
	v_or_b32_e32 v38, s27, v73
	v_add_u32_e32 v40, s27, v1
	v_ashrrev_i32_e32 v35, 31, v34
	v_ashrrev_i32_e32 v37, 31, v36
	v_ashrrev_i32_e32 v39, 31, v38
	v_ashrrev_i32_e32 v41, 31, v40
	v_lshlrev_b64 v[34:35], 8, v[34:35]
	v_lshlrev_b64 v[36:37], 8, v[36:37]
	v_lshlrev_b64 v[38:39], 8, v[38:39]
	v_lshlrev_b64 v[40:41], 8, v[40:41]
	v_or3_b32 v35, v35, 0, 0
	v_or3_b32 v34, v34, v66, s26
	v_or3_b32 v37, v37, 0, 0
	v_or3_b32 v36, v36, v66, s26
	v_or3_b32 v39, v39, 0, 0
	v_or3_b32 v38, v38, v66, s26
	v_or3_b32 v41, v41, 0, 0
	v_or3_b32 v40, v40, v66, s26
	v_lshlrev_b64 v[34:35], 2, v[34:35]
	v_lshlrev_b64 v[36:37], 2, v[36:37]
	v_lshlrev_b64 v[38:39], 2, v[38:39]
	v_lshlrev_b64 v[40:41], 2, v[40:41]
	v_lshl_add_u64 v[42:43], s[8:9], 0, v[34:35]
	v_lshl_add_u64 v[34:35], s[10:11], 0, v[34:35]
	v_mov_b32_e32 v94, s22
	v_lshl_add_u64 v[44:45], s[8:9], 0, v[36:37]
	v_lshl_add_u64 v[36:37], s[10:11], 0, v[36:37]
	v_lshl_add_u64 v[46:47], s[8:9], 0, v[38:39]
	v_lshl_add_u64 v[38:39], s[10:11], 0, v[38:39]
	v_lshl_add_u64 v[48:49], s[8:9], 0, v[40:41]
	v_lshl_add_u64 v[40:41], s[10:11], 0, v[40:41]
	s_waitcnt vmcnt(3)
	global_store_dwordx4 v[42:43], v[10:13], off sc1
	global_store_dwordx4 v[34:35], v[2:5], off sc1
	s_waitcnt vmcnt(4)
	global_store_dwordx4 v[44:45], v[6:9], off sc1
	s_waitcnt vmcnt(4)
	global_store_dwordx4 v[36:37], v[14:17], off sc1
	global_store_dwordx4 v[46:47], v[18:21], off sc1
	global_store_dwordx4 v[38:39], v[22:25], off sc1
	global_store_dwordx4 v[48:49], v[26:29], off sc1
	global_store_dwordx4 v[40:41], v[30:33], off sc1
	s_load_dwordx16 s[64:79], s[0:1], 0x40
	s_lshl_b32 s12, s16, 2
	s_mov_b32 s14, s23
	s_waitcnt vmcnt(8)
	v_lshlrev_b32_e32 v34, 16, v50
	ds_write_b32 v74, v34
	ds_write2_b32 v75, v10, v11 offset1:1
	ds_write2_b32 v75, v12, v13 offset0:2 offset1:3
	ds_write_b128 v76, v[2:5] offset:33280
	ds_write2_b32 v77, v6, v7 offset1:1
	ds_write2_b32 v77, v8, v9 offset0:2 offset1:3
	ds_write_b128 v78, v[14:17] offset:33280
	ds_write2_b32 v79, v18, v19 offset1:1
	ds_write2_b32 v79, v20, v21 offset0:2 offset1:3
	ds_write_b128 v80, v[22:25] offset:33280
	ds_write2_b32 v81, v26, v27 offset1:1
	ds_write2_b32 v81, v28, v29 offset0:2 offset1:3
	ds_write_b128 v82, v[30:33] offset:33280
	s_waitcnt lgkmcnt(0)
	s_barrier
	ds_read_b128 v[62:65], v94
	ds_read_b128 v[50:53], v94 offset:16
	ds_read_b128 v[26:29], v94 offset:32
	ds_read_b128 v[18:21], v94 offset:48
	ds_read2_b32 v[2:3], v83 offset1:1
	ds_read2_b32 v[4:5], v83 offset0:2 offset1:3
	ds_read2_b32 v[6:7], v83 offset0:4 offset1:5
	ds_read2_b32 v[8:9], v83 offset0:6 offset1:7
	ds_read2_b32 v[10:11], v83 offset0:8 offset1:9
	ds_read2_b32 v[12:13], v83 offset0:10 offset1:11
	ds_read2_b32 v[14:15], v83 offset0:12 offset1:13
	ds_read2_b32 v[16:17], v83 offset0:14 offset1:15
	ds_read2_b32 v[22:23], v83 offset0:16 offset1:17
	ds_read_b128 v[30:33], v94 offset:64
	ds_read_b128 v[34:37], v94 offset:80
	s_waitcnt lgkmcnt(10)
	v_fma_f32 v100, v2, v62, 0
	v_fma_f32 v101, v3, v63, 0
	s_waitcnt lgkmcnt(9)
	v_fmac_f32_e32 v100, v4, v64
	v_fmac_f32_e32 v101, v5, v65
	s_waitcnt lgkmcnt(8)
	v_fmac_f32_e32 v100, v6, v50
	v_fmac_f32_e32 v101, v7, v51
	s_waitcnt lgkmcnt(7)
	v_fmac_f32_e32 v100, v8, v52
	v_fmac_f32_e32 v101, v9, v53
	s_waitcnt lgkmcnt(6)
	v_fmac_f32_e32 v100, v10, v26
	v_fmac_f32_e32 v101, v11, v27
	s_waitcnt lgkmcnt(5)
	v_fmac_f32_e32 v100, v12, v28
	v_fmac_f32_e32 v101, v13, v29
	s_waitcnt lgkmcnt(4)
	v_fmac_f32_e32 v100, v14, v18
	v_fmac_f32_e32 v101, v15, v19
	ds_read2_b32 v[2:3], v83 offset0:18 offset1:19
	ds_read2_b32 v[4:5], v83 offset0:20 offset1:21
	ds_read2_b32 v[6:7], v83 offset0:22 offset1:23
	s_waitcnt lgkmcnt(6)
	v_fmac_f32_e32 v100, v16, v20
	v_fmac_f32_e32 v101, v17, v21
	s_waitcnt lgkmcnt(4)
	v_fmac_f32_e32 v100, v22, v30
	v_fmac_f32_e32 v101, v23, v31
	s_waitcnt lgkmcnt(2)
	v_fmac_f32_e32 v100, v2, v32
	v_fmac_f32_e32 v101, v3, v33
	s_waitcnt lgkmcnt(1)
	v_fmac_f32_e32 v100, v4, v34
	v_fmac_f32_e32 v101, v5, v35
	s_waitcnt lgkmcnt(0)
	v_fmac_f32_e32 v100, v6, v36
	v_fmac_f32_e32 v101, v7, v37
	ds_read2_b32 v[2:3], v83 offset0:24 offset1:25
	ds_read_b128 v[46:49], v94 offset:96
	ds_read_b128 v[58:61], v94 offset:112
	ds_read2_b32 v[4:5], v83 offset0:26 offset1:27
	ds_read2_b32 v[6:7], v83 offset0:28 offset1:29
	ds_read2_b32 v[8:9], v83 offset0:30 offset1:31
	s_waitcnt lgkmcnt(4)
	v_fmac_f32_e32 v100, v2, v46
	v_fmac_f32_e32 v101, v3, v47
	s_waitcnt lgkmcnt(2)
	v_fmac_f32_e32 v100, v4, v48
	v_fmac_f32_e32 v101, v5, v49
	s_waitcnt lgkmcnt(1)
	v_fmac_f32_e32 v100, v6, v58
	v_fmac_f32_e32 v101, v7, v59
	s_waitcnt lgkmcnt(0)
	v_fmac_f32_e32 v100, v8, v60
	v_fmac_f32_e32 v101, v9, v61
	ds_read2_b32 v[2:3], v83 offset0:32 offset1:33
	ds_read_b128 v[42:45], v94 offset:128
	ds_read_b128 v[54:57], v94 offset:144
	ds_read2_b32 v[4:5], v83 offset0:34 offset1:35
	ds_read2_b32 v[6:7], v83 offset0:36 offset1:37
	ds_read2_b32 v[8:9], v83 offset0:38 offset1:39
	s_waitcnt lgkmcnt(4)
	v_fmac_f32_e32 v100, v2, v42
	v_fmac_f32_e32 v101, v3, v43
	s_waitcnt lgkmcnt(2)
	v_fmac_f32_e32 v100, v4, v44
	v_fmac_f32_e32 v101, v5, v45
	s_waitcnt lgkmcnt(1)
	v_fmac_f32_e32 v100, v6, v54
	v_fmac_f32_e32 v101, v7, v55
	s_waitcnt lgkmcnt(0)
	v_fmac_f32_e32 v100, v8, v56
	v_fmac_f32_e32 v101, v9, v57
	ds_read2_b32 v[6:7], v83 offset0:40 offset1:41
	ds_read_b128 v[38:41], v94 offset:160
	ds_read_b128 v[2:5], v94 offset:176
	ds_read2_b32 v[8:9], v83 offset0:42 offset1:43
	ds_read2_b32 v[10:11], v83 offset0:44 offset1:45
	ds_read2_b32 v[12:13], v83 offset0:46 offset1:47
	s_waitcnt lgkmcnt(4)
	v_fmac_f32_e32 v100, v6, v38
	v_fmac_f32_e32 v101, v7, v39
	s_waitcnt lgkmcnt(2)
	v_fmac_f32_e32 v100, v8, v40
	v_fmac_f32_e32 v101, v9, v41
	s_waitcnt lgkmcnt(1)
	v_fmac_f32_e32 v100, v10, v2
	v_fmac_f32_e32 v101, v11, v3
	s_waitcnt lgkmcnt(0)
	v_fmac_f32_e32 v100, v12, v4
	v_fmac_f32_e32 v101, v13, v5
	ds_read2_b32 v[14:15], v83 offset0:48 offset1:49
	ds_read_b128 v[6:9], v94 offset:192
	ds_read_b128 v[10:13], v94 offset:208
	ds_read2_b32 v[16:17], v83 offset0:50 offset1:51
	ds_read2_b32 v[22:23], v83 offset0:52 offset1:53
	ds_read2_b32 v[24:25], v83 offset0:54 offset1:55
	s_waitcnt lgkmcnt(4)
	v_fmac_f32_e32 v100, v14, v6
	v_fmac_f32_e32 v101, v15, v7
	s_waitcnt lgkmcnt(2)
	v_fmac_f32_e32 v100, v16, v8
	v_fmac_f32_e32 v101, v17, v9
	s_waitcnt lgkmcnt(1)
	v_fmac_f32_e32 v100, v22, v10
	v_fmac_f32_e32 v101, v23, v11
	s_waitcnt lgkmcnt(0)
	v_fmac_f32_e32 v100, v24, v12
	v_fmac_f32_e32 v101, v25, v13
	ds_read2_b32 v[92:93], v83 offset0:56 offset1:57
	ds_read_b128 v[14:17], v94 offset:224
	ds_read_b128 v[22:25], v94 offset:240
	ds_read2_b32 v[94:95], v83 offset0:58 offset1:59
	ds_read2_b32 v[96:97], v83 offset0:60 offset1:61
	ds_read2_b32 v[98:99], v83 offset0:62 offset1:63
	s_waitcnt lgkmcnt(4)
	v_fmac_f32_e32 v100, v92, v14
	v_add_u32_e32 v92, 0x4100, v83
	v_fmac_f32_e32 v101, v93, v15
	s_waitcnt lgkmcnt(2)
	v_fmac_f32_e32 v100, v94, v16
	ds_read2_b32 v[92:93], v92 offset1:1
	v_fmac_f32_e32 v101, v95, v17
	s_waitcnt lgkmcnt(2)
	v_fmac_f32_e32 v100, v96, v22
	v_fmac_f32_e32 v101, v97, v23
	s_waitcnt lgkmcnt(1)
	v_fmac_f32_e32 v100, v98, v24
	v_add_u32_e32 v94, 0x4108, v83
	v_add_u32_e32 v96, 0x4110, v83
	v_add_u32_e32 v98, 0x4118, v83
	v_fmac_f32_e32 v101, v99, v25
	ds_read2_b32 v[94:95], v94 offset1:1
	ds_read2_b32 v[96:97], v96 offset1:1
	ds_read2_b32 v[98:99], v98 offset1:1
	s_waitcnt lgkmcnt(3)
	v_fma_f32 v92, v62, v92, 0
	v_fma_f32 v93, v63, v93, 0
	s_waitcnt lgkmcnt(2)
	v_fmac_f32_e32 v92, v64, v94
	v_fmac_f32_e32 v93, v65, v95
	s_waitcnt lgkmcnt(1)
	v_fmac_f32_e32 v92, v50, v96
	v_add_u32_e32 v50, 0x4120, v83
	v_fmac_f32_e32 v93, v51, v97
	ds_read2_b32 v[50:51], v50 offset1:1
	s_waitcnt lgkmcnt(1)
	v_fmac_f32_e32 v92, v52, v98
	v_add_u32_e32 v52, 0x4128, v83
	v_add_u32_e32 v62, 0x4130, v83
	v_add_u32_e32 v64, 0x4138, v83
	v_fmac_f32_e32 v93, v53, v99
	ds_read2_b32 v[52:53], v52 offset1:1
	ds_read2_b32 v[62:63], v62 offset1:1
	ds_read2_b32 v[64:65], v64 offset1:1
	s_waitcnt lgkmcnt(3)
	v_fmac_f32_e32 v92, v26, v50
	v_fmac_f32_e32 v93, v27, v51
	s_waitcnt lgkmcnt(2)
	v_fmac_f32_e32 v92, v28, v52
	v_fmac_f32_e32 v93, v29, v53
	s_waitcnt lgkmcnt(1)
	v_fmac_f32_e32 v92, v18, v62
	v_add_u32_e32 v18, 0x4140, v83
	v_fmac_f32_e32 v93, v19, v63
	ds_read2_b32 v[18:19], v18 offset1:1
	s_waitcnt lgkmcnt(1)
	v_fmac_f32_e32 v92, v20, v64
	v_add_u32_e32 v20, 0x4148, v83
	v_add_u32_e32 v26, 0x4150, v83
	v_add_u32_e32 v28, 0x4158, v83
	v_fmac_f32_e32 v93, v21, v65
	ds_read2_b32 v[20:21], v20 offset1:1
	ds_read2_b32 v[26:27], v26 offset1:1
	ds_read2_b32 v[28:29], v28 offset1:1
	s_waitcnt lgkmcnt(3)
	v_fmac_f32_e32 v92, v30, v18
	v_add_u32_e32 v18, 0x4160, v83
	v_fmac_f32_e32 v93, v31, v19
	ds_read2_b32 v[18:19], v18 offset1:1
	s_waitcnt lgkmcnt(3)
	v_fmac_f32_e32 v92, v32, v20
	v_fmac_f32_e32 v93, v33, v21
	s_waitcnt lgkmcnt(2)
	v_fmac_f32_e32 v92, v34, v26
	v_fmac_f32_e32 v93, v35, v27
	s_waitcnt lgkmcnt(1)
	v_fmac_f32_e32 v92, v36, v28
	v_add_u32_e32 v20, 0x4168, v83
	v_add_u32_e32 v26, 0x4170, v83
	v_add_u32_e32 v28, 0x4178, v83
	v_fmac_f32_e32 v93, v37, v29
	ds_read2_b32 v[20:21], v20 offset1:1
	ds_read2_b32 v[26:27], v26 offset1:1
	ds_read2_b32 v[28:29], v28 offset1:1
	s_waitcnt lgkmcnt(3)
	v_fmac_f32_e32 v92, v46, v18
	v_add_u32_e32 v18, 0x4180, v83
	v_fmac_f32_e32 v93, v47, v19
	ds_read2_b32 v[18:19], v18 offset1:1
	s_waitcnt lgkmcnt(3)
	v_fmac_f32_e32 v92, v48, v20
	v_fmac_f32_e32 v93, v49, v21
	s_waitcnt lgkmcnt(2)
	v_fmac_f32_e32 v92, v58, v26
	v_fmac_f32_e32 v93, v59, v27
	s_waitcnt lgkmcnt(1)
	v_fmac_f32_e32 v92, v60, v28
	v_add_u32_e32 v20, 0x4188, v83
	v_add_u32_e32 v26, 0x4190, v83
	v_add_u32_e32 v28, 0x4198, v83
	v_fmac_f32_e32 v93, v61, v29
	ds_read2_b32 v[20:21], v20 offset1:1
	ds_read2_b32 v[26:27], v26 offset1:1
	ds_read2_b32 v[28:29], v28 offset1:1
	s_waitcnt lgkmcnt(3)
	v_fmac_f32_e32 v92, v42, v18
	v_add_u32_e32 v18, 0x41a0, v83
	v_fmac_f32_e32 v93, v43, v19
	ds_read2_b32 v[18:19], v18 offset1:1
	s_waitcnt lgkmcnt(3)
	v_fmac_f32_e32 v92, v44, v20
	s_waitcnt lgkmcnt(2)
	v_fmac_f32_e32 v92, v54, v26
	v_fmac_f32_e32 v93, v45, v21
	s_waitcnt lgkmcnt(1)
	v_fmac_f32_e32 v92, v56, v28
	v_fmac_f32_e32 v93, v55, v27
	v_add_u32_e32 v20, 0x41a8, v83
	v_add_u32_e32 v26, 0x41b0, v83
	v_add_u32_e32 v28, 0x41b8, v83
	s_waitcnt lgkmcnt(0)
	v_fmac_f32_e32 v92, v38, v18
	v_mov_b32_e32 v18, s12
	v_fmac_f32_e32 v93, v57, v29
	ds_read2_b32 v[20:21], v20 offset1:1
	ds_read2_b32 v[26:27], v26 offset1:1
	ds_read2_b32 v[28:29], v28 offset1:1
	global_load_dword v18, v18, s[72:73]
	v_fmac_f32_e32 v93, v39, v19
	s_waitcnt lgkmcnt(2)
	v_fmac_f32_e32 v92, v40, v20
	v_fmac_f32_e32 v93, v41, v21
	s_waitcnt lgkmcnt(1)
	v_fmac_f32_e32 v92, v2, v26
	v_add_u32_e32 v2, 0x41c0, v83
	v_fmac_f32_e32 v93, v3, v27
	ds_read2_b32 v[2:3], v2 offset1:1
	s_waitcnt lgkmcnt(1)
	v_fmac_f32_e32 v92, v4, v28
	v_add_u32_e32 v4, 0x41c8, v83
	v_add_u32_e32 v26, 0x41d8, v83
	v_fmac_f32_e32 v93, v5, v29
	v_add_u32_e32 v19, 0x41d0, v83
	ds_read2_b32 v[4:5], v4 offset1:1
	ds_read2_b32 v[20:21], v19 offset1:1
	ds_read2_b32 v[26:27], v26 offset1:1
	s_waitcnt lgkmcnt(3)
	v_fmac_f32_e32 v92, v6, v2
	v_add_u32_e32 v2, 0x41e0, v83
	v_fmac_f32_e32 v93, v7, v3
	ds_read2_b32 v[2:3], v2 offset1:1
	s_waitcnt lgkmcnt(3)
	v_fmac_f32_e32 v92, v8, v4
	v_fmac_f32_e32 v93, v9, v5
	v_add_u32_e32 v4, 0x41e8, v83
	v_add_u32_e32 v6, 0x41f0, v83
	v_add_u32_e32 v8, 0x41f8, v83
	s_waitcnt lgkmcnt(2)
	v_fmac_f32_e32 v92, v10, v20
	v_fmac_f32_e32 v93, v11, v21
	ds_read2_b32 v[4:5], v4 offset1:1
	ds_read2_b32 v[6:7], v6 offset1:1
	ds_read2_b32 v[8:9], v8 offset1:1
	s_waitcnt lgkmcnt(4)
	v_fmac_f32_e32 v92, v12, v26
	v_fmac_f32_e32 v93, v13, v27
	s_waitcnt lgkmcnt(3)
	v_fmac_f32_e32 v92, v14, v2
	v_fmac_f32_e32 v93, v15, v3
	s_waitcnt lgkmcnt(2)
	v_fmac_f32_e32 v92, v16, v4
	v_fmac_f32_e32 v93, v17, v5
	s_waitcnt lgkmcnt(1)
	v_fmac_f32_e32 v92, v22, v6
	v_fmac_f32_e32 v93, v23, v7
	s_waitcnt lgkmcnt(0)
	v_fmac_f32_e32 v92, v24, v8
	v_fmac_f32_e32 v93, v25, v9
	v_add_f32_e32 v100, v100, v101
	v_add_f32_e32 v2, v92, v93
	v_mul_f32_e32 v101, 0x3e000000, v100
	v_mul_f32_e32 v3, 0x3e000000, v2
	v_max_f32_e32 v3, v101, v3
	ds_bpermute_b32 v4, v85, v3
	s_mov_b32 s12, -2
	s_waitcnt lgkmcnt(0)
	v_max_f32_e32 v4, v4, v4
	v_max_f32_e32 v3, v3, v4
	ds_bpermute_b32 v4, v86, v3
	s_waitcnt lgkmcnt(0)
	v_max_f32_e32 v4, v4, v4
	v_max_f32_e32 v3, v3, v4
	ds_bpermute_b32 v4, v87, v3
	s_waitcnt lgkmcnt(0)
	v_max_f32_e32 v4, v4, v4
	v_max_f32_e32 v3, v3, v4
	ds_bpermute_b32 v4, v88, v3
	s_waitcnt lgkmcnt(0)
	v_max_f32_e32 v4, v4, v4
	v_max_f32_e32 v3, v3, v4
	ds_bpermute_b32 v4, v89, v3
	s_waitcnt lgkmcnt(0)
	v_max_f32_e32 v4, v4, v4
	v_max_f32_e32 v3, v3, v4
	ds_bpermute_b32 v4, v90, v3
	s_waitcnt vmcnt(0) lgkmcnt(0)
	v_max3_f32 v4, v3, v4, v18
	v_fma_f32 v3, v100, s24, -v4
	v_fma_f32 v2, v2, s24, -v4
	v_mul_f32_e32 v3, 0x3fb8aa3b, v3
	v_mul_f32_e32 v2, 0x3fb8aa3b, v2
	v_exp_f32_e32 v3, v3
	v_exp_f32_e32 v7, v2
	ds_write2st64_b32 v84, v3, v7 offset1:1
	v_add_f32_e32 v2, v3, v7
	ds_bpermute_b32 v5, v85, v2
	s_waitcnt lgkmcnt(0)
	v_mov_b32_e32 v7, v91
	s_waitcnt lgkmcnt(0)
	v_add_f32_e32 v2, v2, v5
	ds_bpermute_b32 v5, v86, v2
	s_waitcnt lgkmcnt(0)
	v_add_f32_e32 v5, v2, v5
	ds_bpermute_b32 v6, v87, v5
	v_mov_b32_e32 v2, 0
	v_mov_b32_e32 v3, v2
	s_waitcnt lgkmcnt(0)
	v_add_f32_e32 v5, v5, v6
	ds_bpermute_b32 v6, v88, v5

.LBB0_2139:
	s_or_b64 exec, exec, s[68:69]
	v_xor_b32_e32 v70, 0x80000000, v70
	v_cvt_pk_bf16_f32 v38, v38, v70
	v_xor_b32_e32 v70, 0x80000000, v71
	v_cvt_pk_bf16_f32 v39, v39, v70
	v_xor_b32_e32 v70, 0x80000000, v72
	v_xor_b32_e32 v66, 0x80000000, v66
	v_cvt_pk_bf16_f32 v40, v40, v70
	v_xor_b32_e32 v70, 0x80000000, v73
	v_cvt_pk_bf16_f32 v41, v41, v70
	v_cvt_pk_bf16_f32 v42, v42, v66
	v_xor_b32_e32 v66, 0x80000000, v67
	v_cvt_pk_bf16_f32 v43, v43, v66
	v_xor_b32_e32 v66, 0x80000000, v68
	v_xor_b32_e32 v62, 0x80000000, v62
	v_cvt_pk_bf16_f32 v44, v44, v66
	v_xor_b32_e32 v66, 0x80000000, v69
	v_cvt_pk_bf16_f32 v45, v45, v66
	v_cvt_pk_bf16_f32 v46, v46, v62
	v_xor_b32_e32 v62, 0x80000000, v63
	v_cvt_pk_bf16_f32 v47, v47, v62
	v_xor_b32_e32 v62, 0x80000000, v64
	v_xor_b32_e32 v58, 0x80000000, v58
	v_cvt_pk_bf16_f32 v48, v48, v62
	v_xor_b32_e32 v62, 0x80000000, v65
	v_cvt_pk_bf16_f32 v49, v49, v62
	v_cvt_pk_bf16_f32 v50, v50, v58
	v_xor_b32_e32 v58, 0x80000000, v59
	v_cvt_pk_bf16_f32 v51, v51, v58
	v_xor_b32_e32 v58, 0x80000000, v60
	v_cvt_pk_bf16_f32 v52, v52, v58
	v_xor_b32_e32 v58, 0x80000000, v61
	v_cvt_pk_bf16_f32 v53, v53, v58
	v_mfma_f32_16x16x32_bf16 v[58:61], v[2:5], v[54:57], 0
	ds_read_b64 v[146:147], v201
	s_lshl_b32 s74, s53, 8
	s_add_u32 s16, s92, s16
	s_addc_u32 s17, s93, s17
	s_add_u32 s16, s16, s74
	s_nop 2
	ds_write_b128 v202, v[58:61]
	v_mfma_f32_16x16x32_bf16 v[58:61], v[6:9], v[54:57], 0
	s_addc_u32 s17, s17, 0
	v_lshlrev_b32_e32 v148, 2, v166
	v_mov_b32_e32 v149, v122
	s_add_u32 s14, s92, s14
	s_addc_u32 s15, s93, s15
	s_nop 2
	ds_write_b128 v202, v[58:61] offset:64
	v_mfma_f32_16x16x32_bf16 v[58:61], v[10:13], v[54:57], 0
	s_add_u32 s14, s14, s74
	s_addc_u32 s15, s15, 0
	s_nop 5
	ds_write_b128 v202, v[58:61] offset:128
	v_mfma_f32_16x16x32_bf16 v[58:61], v[14:17], v[54:57], 0
	s_nop 7
	ds_write_b128 v202, v[58:61] offset:192
	v_mfma_f32_16x16x32_bf16 v[58:61], v[18:21], v[54:57], 0
	s_nop 7
	ds_write_b128 v202, v[58:61] offset:256
	v_mfma_f32_16x16x32_bf16 v[58:61], v[22:25], v[54:57], 0
	s_nop 7
	ds_write_b128 v202, v[58:61] offset:320
	v_mfma_f32_16x16x32_bf16 v[58:61], v[26:29], v[54:57], 0
	s_nop 7
	ds_write_b128 v202, v[58:61] offset:384
	v_mfma_f32_16x16x32_bf16 v[58:61], v[30:33], v[54:57], 0
	v_mfma_f32_16x16x32_bf16 v[54:57], v[34:37], v[54:57], 0
	s_nop 6
	ds_write_b128 v202, v[58:61] offset:448
	s_waitcnt lgkmcnt(0)
	ds_read_b64 v[58:59], v203
	s_waitcnt lgkmcnt(9)
	v_mul_f32_e32 v60, v79, v147
	v_fma_f32 v60, v78, v146, -v60
	s_waitcnt lgkmcnt(0)
	v_add_f32_e32 v62, v60, v58
	v_mul_f32_e32 v58, v78, v147
	v_fmac_f32_e32 v58, v79, v146
	v_add_f32_e32 v63, v58, v59
	v_lshl_add_u64 v[58:59], s[16:17], 0, v[148:149]
	v_add_co_u32_e32 v60, vcc, s47, v58
	s_nop 1
	v_addc_co_u32_e32 v61, vcc, 0, v59, vcc
	v_add_co_u32_e32 v58, vcc, s49, v58
	global_store_dword v[60:61], v62, off
	s_nop 0
	v_addc_co_u32_e32 v59, vcc, 0, v59, vcc
	global_store_dword v[58:59], v63, off
	v_cvt_pk_bf16_f32 v58, v62, v63
	ds_write_b32 v223, v58 offset:8448
	ds_read_b64 v[58:59], v203 offset:528
	v_mul_f32_e32 v60, v77, v147
	v_fma_f32 v60, v76, v146, -v60
	s_waitcnt lgkmcnt(0)
	v_add_f32_e32 v62, v60, v58
	v_mul_f32_e32 v58, v76, v147
	v_fmac_f32_e32 v58, v77, v146
	v_add_f32_e32 v63, v58, v59
	v_lshl_add_u64 v[58:59], s[14:15], 0, v[148:149]
	v_add_co_u32_e32 v60, vcc, s47, v58
	s_nop 1
	v_addc_co_u32_e32 v61, vcc, 0, v59, vcc
	v_add_co_u32_e32 v58, vcc, s49, v58
	global_store_dword v[60:61], v62, off
	s_nop 0
	v_addc_co_u32_e32 v59, vcc, 0, v59, vcc
	global_store_dword v[58:59], v63, off
	v_cvt_pk_bf16_f32 v58, v62, v63
	ds_write_b32 v223, v58 offset:8720
	s_waitcnt lgkmcnt(0)
	ds_read_b128 v[58:61], v224 offset:8448
	s_waitcnt lgkmcnt(0)
	v_mfma_f32_16x16x32_bf16 v[54:57], v[38:41], v[58:61], v[54:57]
	ds_read_b128 v[58:61], v224 offset:8512
	s_waitcnt lgkmcnt(0)
	v_mfma_f32_16x16x32_bf16 v[54:57], v[42:45], v[58:61], v[54:57]
	ds_read_b128 v[58:61], v224 offset:8576
	s_waitcnt lgkmcnt(0)
	v_mfma_f32_16x16x32_bf16 v[54:57], v[46:49], v[58:61], v[54:57]
	ds_read_b128 v[58:61], v224 offset:8640
	s_waitcnt lgkmcnt(0)
	v_mfma_f32_16x16x32_bf16 v[54:57], v[50:53], v[58:61], v[54:57]
	s_and_saveexec_b64 s[14:15], s[0:1]
	s_xor_b64 s[14:15], exec, s[14:15]
	s_lshl_b32 s20, s53, 4
	s_or_saveexec_b64 s[14:15], s[14:15]
	v_mov_b64_e32 v[58:59], s[20:21]
	s_xor_b64 exec, exec, s[14:15]
	s_cbranch_execz .LBB0_2143
	s_nop 0
	v_mul_f32_e32 v58, 0x3d372713, v54
	v_fma_f32 v58, v54, v58, 1.0
	v_mul_f32_e32 v58, v54, v58
	v_mul_f32_e32 v58, 0x3fcc422a, v58
	v_mul_f32_e32 v58, 0xbfb8aa3b, v58
	v_exp_f32_e32 v58, v58
	s_lshl_b32 s16, s53, 5
	s_mov_b32 s17, s21
	s_lshl_b32 s20, s53, 4
	v_add_f32_e32 v58, 1.0, v58
	v_rcp_f32_e32 v58, v58
	v_mov_b32_e32 v141, v122
	v_mul_f32_e32 v54, v54, v58
	v_mul_f32_e32 v58, 0x3d372713, v55
	v_fma_f32 v58, v55, v58, 1.0
	v_mul_f32_e32 v58, v55, v58
	v_mul_f32_e32 v58, 0x3fcc422a, v58
	v_mul_f32_e32 v58, 0xbfb8aa3b, v58
	v_exp_f32_e32 v58, v58
	s_nop 0
	v_add_f32_e32 v58, 1.0, v58
	v_rcp_f32_e32 v58, v58
	s_nop 0
	v_mul_f32_e32 v55, v55, v58
	v_mul_f32_e32 v58, 0x3d372713, v56
	v_fma_f32 v58, v56, v58, 1.0
	v_mul_f32_e32 v58, v56, v58
	v_mul_f32_e32 v58, 0x3fcc422a, v58
	v_mul_f32_e32 v58, 0xbfb8aa3b, v58
	v_exp_f32_e32 v58, v58
	v_cvt_pk_bf16_f32 v54, v54, v55
	s_nop 0
	v_add_f32_e32 v58, 1.0, v58
	v_rcp_f32_e32 v58, v58
	s_nop 0
	v_mul_f32_e32 v56, v56, v58
	v_mul_f32_e32 v58, 0x3d372713, v57
	v_fma_f32 v58, v57, v58, 1.0
	v_mul_f32_e32 v58, v57, v58
	v_mul_f32_e32 v58, 0x3fcc422a, v58
	v_mul_f32_e32 v58, 0xbfb8aa3b, v58
	v_exp_f32_e32 v58, v58
	s_nop 0
	v_add_f32_e32 v58, 1.0, v58
	v_rcp_f32_e32 v58, v58
	s_nop 0
	v_mul_f32_e32 v57, v57, v58
	v_cvt_pk_bf16_f32 v55, v56, v57
	v_lshlrev_b64 v[56:57], 12, v[74:75]
	v_lshl_add_u64 v[56:57], s[84:85], 0, v[56:57]
	v_lshl_add_u64 v[56:57], v[56:57], 0, s[16:17]
	v_lshl_add_u64 v[56:57], v[56:57], 0, v[140:141]
	v_mov_b64_e32 v[58:59], s[20:21]
	global_store_dwordx2 v[56:57], v[54:55], off sc1

.LBB0_2152:
	v_cndmask_b32_e64 v118, 0, v62, s[4:5]
	v_cndmask_b32_e64 v119, 0, v63, s[4:5]
	v_cndmask_b32_e64 v120, 0, v64, s[4:5]
	v_cndmask_b32_e64 v121, 0, v65, s[4:5]
	v_add_u32_e32 v227, 0x800, v203
	v_add_u32_e32 v228, 0x1000, v203
	v_mfma_f32_16x16x32_bf16 v[90:93], v[2:5], v[118:121], 0
	v_add_u32_e32 v229, 0x1800, v203
	s_mov_b64 s[14:15], -1
	s_and_b64 vcc, exec, s[68:69]
	v_mfma_f32_16x16x32_bf16 v[94:97], v[6:9], v[118:121], 0
	v_add_u32_e32 v123, 0x2000, v204
	s_nop 2
	ds_write_b128 v202, v[90:93]
	v_add_u32_e32 v137, 0x2200, v204
	v_mfma_f32_16x16x32_bf16 v[98:101], v[10:13], v[118:121], 0
	v_add_u32_e32 v139, 0x2400, v204
	v_add_u32_e32 v141, 0x2600, v204
	v_add_u32_e32 v143, 0x2800, v204
	v_mfma_f32_16x16x32_bf16 v[102:105], v[14:17], v[118:121], 0
	ds_write_b128 v202, v[94:97] offset:64
	s_nop 2
	ds_write_b128 v202, v[98:101] offset:128
	s_nop 2
	ds_write_b128 v202, v[102:105] offset:192
	v_add_u32_e32 v149, 0x2a00, v204
	v_mfma_f32_16x16x32_bf16 v[106:109], v[18:21], v[118:121], 0
	v_add_u32_e32 v225, 0x2c00, v204
	v_add_u32_e32 v226, 0x2e00, v204
	v_mfma_f32_16x16x32_bf16 v[90:93], v[22:25], v[118:121], 0
	v_mfma_f32_16x16x32_bf16 v[94:97], v[26:29], v[118:121], 0
	s_nop 3
	ds_write_b128 v202, v[106:109] offset:256
	s_nop 1
	ds_write_b128 v202, v[90:93] offset:320
	ds_write_b128 v202, v[94:97] offset:384
	v_mfma_f32_16x16x32_bf16 v[90:93], v[30:33], v[118:121], 0
	s_nop 7
	ds_write_b128 v202, v[90:93] offset:448
	s_waitcnt lgkmcnt(0)
	ds_read2_b64 v[230:233], v203 offset1:66
	ds_read2_b64 v[114:117], v203 offset0:132 offset1:198
	ds_read2_b64 v[110:113], v227 offset0:8 offset1:74
	ds_read2_b64 v[106:109], v227 offset0:140 offset1:206
	ds_read2_b64 v[102:105], v228 offset0:16 offset1:82
	ds_read2_b64 v[98:101], v228 offset0:148 offset1:214
	ds_read2_b64 v[94:97], v229 offset0:24 offset1:90
	ds_read2_b64 v[90:93], v229 offset0:156 offset1:222
	s_waitcnt lgkmcnt(0)
	s_waitcnt lgkmcnt(7)
	v_pk_fma_f32 v[192:193], v[146:147], v[190:191], v[230:231] op_sel:[0,1,0] op_sel_hi:[1,0,1]
	s_nop 0
	v_pk_fma_f32 v[194:195], v[150:151], v[190:191], v[192:193]
	s_nop 0
	v_pk_fma_f32 v[190:191], v[146:147], v[194:195], v[232:233] op_sel:[0,1,0] op_sel_hi:[1,0,1]
	s_nop 0
	v_pk_fma_f32 v[190:191], v[150:151], v[194:195], v[190:191]
	s_cbranch_vccz .LBB0_2154
	s_waitcnt lgkmcnt(6)
	v_pk_fma_f32 v[192:193], v[146:147], v[190:191], v[114:115] op_sel:[0,1,0] op_sel_hi:[1,0,1]
	v_cvt_pk_bf16_f32 v230, v194, v195
	v_cvt_pk_bf16_f32 v231, v190, v191
	v_mfma_f32_16x16x32_bf16 v[118:121], v[34:37], v[118:121], 0
	v_fma_f32 v192, v150, v190, v192
	v_fma_f32 v193, v151, v191, v193
	s_mov_b64 s[14:15], 0
	v_pk_fma_f32 v[194:195], v[146:147], v[192:193], v[116:117] op_sel:[0,1,0] op_sel_hi:[1,0,1]
	v_cvt_pk_bf16_f32 v232, v192, v193
	s_nop 0
	v_pk_fma_f32 v[192:193], v[150:151], v[192:193], v[194:195]
	s_waitcnt lgkmcnt(5)
	v_pk_fma_f32 v[194:195], v[146:147], v[192:193], v[110:111] op_sel:[0,1,0] op_sel_hi:[1,0,1]
	v_cvt_pk_bf16_f32 v233, v192, v193
	s_nop 0
	v_pk_fma_f32 v[192:193], v[150:151], v[192:193], v[194:195]
	s_nop 0
	v_pk_fma_f32 v[194:195], v[146:147], v[192:193], v[112:113] op_sel:[0,1,0] op_sel_hi:[1,0,1]
	v_cvt_pk_bf16_f32 v234, v192, v193
	s_nop 0
	v_pk_fma_f32 v[192:193], v[150:151], v[192:193], v[194:195]
	s_waitcnt lgkmcnt(4)
	v_pk_fma_f32 v[194:195], v[146:147], v[192:193], v[106:107] op_sel:[0,1,0] op_sel_hi:[1,0,1]
	v_cvt_pk_bf16_f32 v235, v192, v193
	s_nop 0
	v_pk_fma_f32 v[192:193], v[150:151], v[192:193], v[194:195]
	s_nop 0
	v_pk_fma_f32 v[194:195], v[146:147], v[192:193], v[108:109] op_sel:[0,1,0] op_sel_hi:[1,0,1]
	v_cvt_pk_bf16_f32 v236, v192, v193
	s_nop 0
	v_pk_fma_f32 v[192:193], v[150:151], v[192:193], v[194:195]
	s_waitcnt lgkmcnt(3)
	v_pk_fma_f32 v[194:195], v[146:147], v[192:193], v[102:103] op_sel:[0,1,0] op_sel_hi:[1,0,1]
	v_cvt_pk_bf16_f32 v237, v192, v193
	s_nop 0
	v_pk_fma_f32 v[192:193], v[150:151], v[192:193], v[194:195]
	s_nop 0
	v_pk_fma_f32 v[194:195], v[146:147], v[192:193], v[104:105] op_sel:[0,1,0] op_sel_hi:[1,0,1]
	v_cvt_pk_bf16_f32 v238, v192, v193
	s_nop 0
	v_pk_fma_f32 v[192:193], v[150:151], v[192:193], v[194:195]
	s_waitcnt lgkmcnt(2)
	v_pk_fma_f32 v[194:195], v[146:147], v[192:193], v[98:99] op_sel:[0,1,0] op_sel_hi:[1,0,1]
	v_cvt_pk_bf16_f32 v239, v192, v193
	s_nop 0
	v_pk_fma_f32 v[192:193], v[150:151], v[192:193], v[194:195]
	s_nop 0
	v_pk_fma_f32 v[194:195], v[146:147], v[192:193], v[100:101] op_sel:[0,1,0] op_sel_hi:[1,0,1]
	v_cvt_pk_bf16_f32 v240, v192, v193
	s_nop 0
	v_pk_fma_f32 v[192:193], v[150:151], v[192:193], v[194:195]
	s_waitcnt lgkmcnt(1)
	v_pk_fma_f32 v[194:195], v[146:147], v[192:193], v[94:95] op_sel:[0,1,0] op_sel_hi:[1,0,1]
	v_cvt_pk_bf16_f32 v241, v192, v193
	s_nop 0
	v_pk_fma_f32 v[192:193], v[150:151], v[192:193], v[194:195]
	s_nop 0
	v_pk_fma_f32 v[194:195], v[146:147], v[192:193], v[96:97] op_sel:[0,1,0] op_sel_hi:[1,0,1]
	v_cvt_pk_bf16_f32 v242, v192, v193
	s_nop 0
	v_pk_fma_f32 v[192:193], v[150:151], v[192:193], v[194:195]
	s_waitcnt lgkmcnt(0)
	v_pk_fma_f32 v[194:195], v[146:147], v[192:193], v[90:91] op_sel:[0,1,0] op_sel_hi:[1,0,1]
	v_cvt_pk_bf16_f32 v243, v192, v193
	s_nop 0
	v_pk_fma_f32 v[192:193], v[150:151], v[192:193], v[194:195]
	s_nop 0
	v_pk_fma_f32 v[194:195], v[146:147], v[192:193], v[92:93] op_sel:[0,1,0] op_sel_hi:[1,0,1]
	v_cvt_pk_bf16_f32 v244, v192, v193
	s_nop 0
	v_pk_fma_f32 v[192:193], v[150:151], v[192:193], v[194:195]
	s_nop 0
	v_cvt_pk_bf16_f32 v194, v192, v193
	ds_write2_b32 v123, v230, v231 offset0:64 offset1:132
	ds_write2_b32 v137, v232, v233 offset0:72 offset1:140
	ds_write2_b32 v139, v234, v235 offset0:80 offset1:148
	ds_write2_b32 v141, v236, v237 offset0:88 offset1:156
	ds_write2_b32 v143, v238, v239 offset0:96 offset1:164
	ds_write2_b32 v149, v240, v241 offset0:104 offset1:172
	ds_write2_b32 v225, v242, v243 offset0:112 offset1:180
	ds_write2_b32 v226, v244, v194 offset0:120 offset1:188
	s_waitcnt lgkmcnt(0)
	ds_read_b128 v[230:233], v224 offset:8448
	ds_read_b128 v[234:237], v224 offset:8512
	s_waitcnt lgkmcnt(0)
	v_mfma_f32_16x16x32_bf16 v[118:121], v[42:45], v[234:237], v[118:121]
	ds_read_b128 v[234:237], v224 offset:8576
	v_mfma_f32_16x16x32_bf16 v[230:233], v[38:41], v[230:233], 0
	s_waitcnt lgkmcnt(0)
	v_mfma_f32_16x16x32_bf16 v[230:233], v[46:49], v[234:237], v[230:233]
	ds_read_b128 v[234:237], v224 offset:8640
	s_waitcnt lgkmcnt(0)
	v_mfma_f32_16x16x32_bf16 v[118:121], v[50:53], v[234:237], v[118:121]
	s_nop 7
	v_pk_add_f32 v[120:121], v[232:233], v[120:121]
	v_pk_add_f32 v[118:119], v[230:231], v[118:119]
	v_pk_mul_f32 v[194:195], v[120:121], v[120:121]
	v_pk_mul_f32 v[230:231], v[118:119], v[118:119]
	v_mov_b64_e32 v[232:233], s[48:49]
	v_pk_fma_f32 v[230:231], v[230:231], s[46:47], v[232:233] op_sel_hi:[1,0,0] neg_lo:[1,0,0] neg_hi:[1,0,0]
	v_pk_fma_f32 v[194:195], v[194:195], s[46:47], v[232:233] op_sel_hi:[1,0,0] neg_lo:[1,0,0] neg_hi:[1,0,0]
	v_pk_mul_f32 v[230:231], v[118:119], v[230:231]
	v_pk_mul_f32 v[194:195], v[120:121], v[194:195]
	v_exp_f32_e32 v230, v230
	v_exp_f32_e32 v231, v231
	v_exp_f32_e32 v194, v194
	v_exp_f32_e32 v195, v195
	v_pk_add_f32 v[230:231], v[230:231], 1.0 op_sel_hi:[1,0]
	s_nop 0
	v_rcp_f32_e32 v230, v230
	v_pk_add_f32 v[194:195], v[194:195], 1.0 op_sel_hi:[1,0]
	v_rcp_f32_e32 v231, v231
	v_rcp_f32_e32 v194, v194
	v_rcp_f32_e32 v195, v195
	v_pk_mul_f32 v[118:119], v[118:119], v[230:231]
	s_nop 0
	v_cvt_pk_bf16_f32 v118, v118, v119
	v_pk_mul_f32 v[120:121], v[120:121], v[194:195]
	s_nop 0
	v_cvt_pk_bf16_f32 v119, v120, v121
	v_or_b32_e32 v120, s86, v167
	v_or_b32_e32 v120, s20, v120
	v_mov_b32_e32 v121, s75
	v_lshlrev_b64 v[120:121], 12, v[120:121]
	v_lshl_add_u64 v[120:121], v[154:155], 0, v[120:121]
	global_store_dwordx2 v[120:121], v[118:119], off sc1

.LBB0_2156:
	s_waitcnt lgkmcnt(6)
	v_cndmask_b32_e64 v114, v62, 0, s[4:5]
	v_cndmask_b32_e64 v115, v63, 0, s[4:5]
	v_cndmask_b32_e64 v116, v64, 0, s[4:5]
	v_cndmask_b32_e64 v117, v65, 0, s[4:5]
	s_waitcnt lgkmcnt(0)
	s_mov_b64 s[16:17], -1
	s_andn2_b64 vcc, exec, s[68:69]
	v_mfma_f32_16x16x32_bf16 v[62:65], v[2:5], v[114:117], 0
	s_waitcnt lgkmcnt(0)
	v_mfma_f32_16x16x32_bf16 v[90:93], v[6:9], v[114:117], 0
	v_mfma_f32_16x16x32_bf16 v[94:97], v[10:13], v[114:117], 0
	s_nop 4
	ds_write_b128 v202, v[62:65]
	v_mfma_f32_16x16x32_bf16 v[98:101], v[14:17], v[114:117], 0
	ds_write_b128 v202, v[90:93] offset:64
	ds_write_b128 v202, v[94:97] offset:128
	s_nop 5
	ds_write_b128 v202, v[98:101] offset:192
	v_mfma_f32_16x16x32_bf16 v[102:105], v[18:21], v[114:117], 0
	v_mfma_f32_16x16x32_bf16 v[62:65], v[22:25], v[114:117], 0
	v_mfma_f32_16x16x32_bf16 v[90:93], v[26:29], v[114:117], 0
	s_nop 5
	ds_write_b128 v202, v[102:105] offset:256
	ds_write_b128 v202, v[62:65] offset:320
	ds_write_b128 v202, v[90:93] offset:384
	v_mfma_f32_16x16x32_bf16 v[62:65], v[30:33], v[114:117], 0
	s_nop 7
	ds_write_b128 v202, v[62:65] offset:448
	s_waitcnt lgkmcnt(0)
	ds_read2_b64 v[230:233], v203 offset1:66
	ds_read2_b64 v[110:113], v203 offset0:132 offset1:198
	ds_read2_b64 v[106:109], v227 offset0:8 offset1:74
	ds_read2_b64 v[102:105], v227 offset0:140 offset1:206
	ds_read2_b64 v[98:101], v228 offset0:16 offset1:82
	ds_read2_b64 v[94:97], v228 offset0:148 offset1:214
	ds_read2_b64 v[90:93], v229 offset0:24 offset1:90
	ds_read2_b64 v[62:65], v229 offset0:156 offset1:222
	s_waitcnt lgkmcnt(0)
	s_waitcnt lgkmcnt(7)
	v_pk_fma_f32 v[118:119], v[146:147], v[192:193], v[230:231] op_sel:[0,1,0] op_sel_hi:[1,0,1]
	s_nop 0
	v_pk_fma_f32 v[120:121], v[150:151], v[192:193], v[118:119]
	v_cndmask_b32_e64 v118, 0, 1, s[68:69]
	v_cmp_ne_u32_e64 s[14:15], 1, v118
	v_pk_fma_f32 v[118:119], v[146:147], v[120:121], v[232:233] op_sel:[0,1,0] op_sel_hi:[1,0,1]
	s_nop 0
	v_pk_fma_f32 v[118:119], v[150:151], v[120:121], v[118:119]
	s_cbranch_vccnz .LBB0_2158
	v_cvt_pk_bf16_f32 v192, v120, v121
	s_waitcnt lgkmcnt(6)
	v_pk_fma_f32 v[120:121], v[146:147], v[118:119], v[110:111] op_sel:[0,1,0] op_sel_hi:[1,0,1]
	v_cvt_pk_bf16_f32 v193, v118, v119
	v_mfma_f32_16x16x32_bf16 v[114:117], v[34:37], v[114:117], 0
	v_fma_f32 v120, v150, v118, v120
	v_fma_f32 v121, v151, v119, v121
	s_mov_b64 s[16:17], 0
	v_pk_fma_f32 v[190:191], v[146:147], v[120:121], v[112:113] op_sel:[0,1,0] op_sel_hi:[1,0,1]
	v_cvt_pk_bf16_f32 v194, v120, v121
	s_nop 0
	v_pk_fma_f32 v[120:121], v[150:151], v[120:121], v[190:191]
	s_waitcnt lgkmcnt(5)
	v_pk_fma_f32 v[190:191], v[146:147], v[120:121], v[106:107] op_sel:[0,1,0] op_sel_hi:[1,0,1]
	v_cvt_pk_bf16_f32 v195, v120, v121
	s_nop 0
	v_pk_fma_f32 v[120:121], v[150:151], v[120:121], v[190:191]
	s_nop 0
	v_pk_fma_f32 v[190:191], v[146:147], v[120:121], v[108:109] op_sel:[0,1,0] op_sel_hi:[1,0,1]
	v_cvt_pk_bf16_f32 v230, v120, v121
	s_nop 0
	v_pk_fma_f32 v[120:121], v[150:151], v[120:121], v[190:191]
	s_waitcnt lgkmcnt(4)
	v_pk_fma_f32 v[190:191], v[146:147], v[120:121], v[102:103] op_sel:[0,1,0] op_sel_hi:[1,0,1]
	v_cvt_pk_bf16_f32 v231, v120, v121
	s_nop 0
	v_pk_fma_f32 v[120:121], v[150:151], v[120:121], v[190:191]
	s_nop 0
	v_pk_fma_f32 v[190:191], v[146:147], v[120:121], v[104:105] op_sel:[0,1,0] op_sel_hi:[1,0,1]
	v_cvt_pk_bf16_f32 v232, v120, v121
	s_nop 0
	v_pk_fma_f32 v[120:121], v[150:151], v[120:121], v[190:191]
	s_waitcnt lgkmcnt(3)
	v_pk_fma_f32 v[190:191], v[146:147], v[120:121], v[98:99] op_sel:[0,1,0] op_sel_hi:[1,0,1]
	v_cvt_pk_bf16_f32 v233, v120, v121
	s_nop 0
	v_pk_fma_f32 v[120:121], v[150:151], v[120:121], v[190:191]
	s_nop 0
	v_pk_fma_f32 v[190:191], v[146:147], v[120:121], v[100:101] op_sel:[0,1,0] op_sel_hi:[1,0,1]
	v_cvt_pk_bf16_f32 v234, v120, v121
	s_nop 0
	v_pk_fma_f32 v[120:121], v[150:151], v[120:121], v[190:191]
	s_waitcnt lgkmcnt(2)
	v_pk_fma_f32 v[190:191], v[146:147], v[120:121], v[94:95] op_sel:[0,1,0] op_sel_hi:[1,0,1]
	v_cvt_pk_bf16_f32 v235, v120, v121
	s_nop 0
	v_pk_fma_f32 v[120:121], v[150:151], v[120:121], v[190:191]
	s_nop 0
	v_pk_fma_f32 v[190:191], v[146:147], v[120:121], v[96:97] op_sel:[0,1,0] op_sel_hi:[1,0,1]
	v_cvt_pk_bf16_f32 v236, v120, v121
	s_nop 0
	v_pk_fma_f32 v[120:121], v[150:151], v[120:121], v[190:191]
	s_waitcnt lgkmcnt(1)
	v_pk_fma_f32 v[190:191], v[146:147], v[120:121], v[90:91] op_sel:[0,1,0] op_sel_hi:[1,0,1]
	v_cvt_pk_bf16_f32 v237, v120, v121
	s_nop 0
	v_pk_fma_f32 v[120:121], v[150:151], v[120:121], v[190:191]
	s_nop 0
	v_pk_fma_f32 v[190:191], v[146:147], v[120:121], v[92:93] op_sel:[0,1,0] op_sel_hi:[1,0,1]
	v_cvt_pk_bf16_f32 v238, v120, v121
	s_nop 0
	v_pk_fma_f32 v[120:121], v[150:151], v[120:121], v[190:191]
	s_waitcnt lgkmcnt(0)
	v_pk_fma_f32 v[190:191], v[146:147], v[120:121], v[62:63] op_sel:[0,1,0] op_sel_hi:[1,0,1]
	v_cvt_pk_bf16_f32 v239, v120, v121
	s_nop 0
	v_pk_fma_f32 v[120:121], v[150:151], v[120:121], v[190:191]
	s_nop 0
	v_pk_fma_f32 v[190:191], v[146:147], v[120:121], v[64:65] op_sel:[0,1,0] op_sel_hi:[1,0,1]
	v_cvt_pk_bf16_f32 v240, v120, v121
	s_nop 0
	v_pk_fma_f32 v[190:191], v[150:151], v[120:121], v[190:191]
	s_nop 0
	v_cvt_pk_bf16_f32 v120, v190, v191
	ds_write2_b32 v123, v192, v193 offset0:64 offset1:132
	ds_write2_b32 v137, v194, v195 offset0:72 offset1:140
	ds_write2_b32 v139, v230, v231 offset0:80 offset1:148
	ds_write2_b32 v141, v232, v233 offset0:88 offset1:156
	ds_write2_b32 v143, v234, v235 offset0:96 offset1:164
	ds_write2_b32 v149, v236, v237 offset0:104 offset1:172
	ds_write2_b32 v225, v238, v239 offset0:112 offset1:180
	ds_write2_b32 v226, v240, v120 offset0:120 offset1:188
	s_waitcnt lgkmcnt(0)
	ds_read_b128 v[192:195], v224 offset:8448
	ds_read_b128 v[230:233], v224 offset:8512
	s_waitcnt lgkmcnt(0)
	v_mfma_f32_16x16x32_bf16 v[114:117], v[42:45], v[230:233], v[114:117]
	ds_read_b128 v[230:233], v224 offset:8576
	v_mfma_f32_16x16x32_bf16 v[192:195], v[38:41], v[192:195], 0
	s_waitcnt lgkmcnt(0)
	v_mfma_f32_16x16x32_bf16 v[192:195], v[46:49], v[230:233], v[192:195]
	ds_read_b128 v[230:233], v224 offset:8640
	s_waitcnt lgkmcnt(0)
	v_mfma_f32_16x16x32_bf16 v[114:117], v[50:53], v[230:233], v[114:117]
	s_nop 7
	v_pk_add_f32 v[116:117], v[194:195], v[116:117]
	v_pk_add_f32 v[114:115], v[192:193], v[114:115]
	v_pk_mul_f32 v[120:121], v[116:117], v[116:117]
	v_pk_mul_f32 v[192:193], v[114:115], v[114:115]
	v_mov_b64_e32 v[194:195], s[48:49]
	v_pk_fma_f32 v[192:193], v[192:193], s[46:47], v[194:195] op_sel_hi:[1,0,0] neg_lo:[1,0,0] neg_hi:[1,0,0]
	v_pk_fma_f32 v[120:121], v[120:121], s[46:47], v[194:195] op_sel_hi:[1,0,0] neg_lo:[1,0,0] neg_hi:[1,0,0]
	v_pk_mul_f32 v[192:193], v[114:115], v[192:193]
	v_pk_mul_f32 v[120:121], v[116:117], v[120:121]
	v_exp_f32_e32 v192, v192
	v_exp_f32_e32 v193, v193
	v_exp_f32_e32 v120, v120
	v_exp_f32_e32 v121, v121
	v_pk_add_f32 v[192:193], v[192:193], 1.0 op_sel_hi:[1,0]
	s_nop 0
	v_rcp_f32_e32 v192, v192
	v_pk_add_f32 v[120:121], v[120:121], 1.0 op_sel_hi:[1,0]
	v_rcp_f32_e32 v193, v193
	v_rcp_f32_e32 v120, v120
	v_rcp_f32_e32 v121, v121
	v_pk_mul_f32 v[114:115], v[114:115], v[192:193]
	s_nop 0
	v_cvt_pk_bf16_f32 v114, v114, v115
	v_pk_mul_f32 v[116:117], v[116:117], v[120:121]
	s_nop 0
	v_cvt_pk_bf16_f32 v115, v116, v117
	v_or_b32_e32 v116, s86, v206
	v_or_b32_e32 v116, s20, v116
	v_mov_b32_e32 v117, s75
	v_lshlrev_b64 v[116:117], 12, v[116:117]
	v_lshl_add_u64 v[116:117], v[154:155], 0, v[116:117]
	global_store_dwordx2 v[116:117], v[114:115], off sc1

.LBB0_2162:
	v_cndmask_b32_e64 v118, 0, v70, s[4:5]
	v_cndmask_b32_e64 v119, 0, v71, s[4:5]
	v_cndmask_b32_e64 v120, 0, v72, s[4:5]
	v_cndmask_b32_e64 v121, 0, v73, s[4:5]
	s_mov_b64 s[72:73], -1
	s_and_b64 vcc, exec, s[14:15]
	v_mfma_f32_16x16x32_bf16 v[90:93], v[2:5], v[118:121], 0
	v_mfma_f32_16x16x32_bf16 v[94:97], v[6:9], v[118:121], 0
	v_mfma_f32_16x16x32_bf16 v[98:101], v[10:13], v[118:121], 0
	s_nop 5
	ds_write_b128 v202, v[90:93]
	v_mfma_f32_16x16x32_bf16 v[102:105], v[14:17], v[118:121], 0
	ds_write_b128 v202, v[94:97] offset:64
	ds_write_b128 v202, v[98:101] offset:128
	s_nop 5
	ds_write_b128 v202, v[102:105] offset:192
	v_mfma_f32_16x16x32_bf16 v[106:109], v[18:21], v[118:121], 0
	v_mfma_f32_16x16x32_bf16 v[90:93], v[22:25], v[118:121], 0
	v_mfma_f32_16x16x32_bf16 v[94:97], v[26:29], v[118:121], 0
	s_nop 5
	ds_write_b128 v202, v[106:109] offset:256
	ds_write_b128 v202, v[90:93] offset:320
	ds_write_b128 v202, v[94:97] offset:384
	v_mfma_f32_16x16x32_bf16 v[90:93], v[30:33], v[118:121], 0
	s_nop 7
	ds_write_b128 v202, v[90:93] offset:448
	s_waitcnt lgkmcnt(0)
	ds_read2_b64 v[230:233], v203 offset1:66
	ds_read2_b64 v[114:117], v203 offset0:132 offset1:198
	ds_read2_b64 v[110:113], v227 offset0:8 offset1:74
	ds_read2_b64 v[106:109], v227 offset0:140 offset1:206
	ds_read2_b64 v[102:105], v228 offset0:16 offset1:82
	ds_read2_b64 v[98:101], v228 offset0:148 offset1:214
	ds_read2_b64 v[94:97], v229 offset0:24 offset1:90
	ds_read2_b64 v[90:93], v229 offset0:156 offset1:222
	s_waitcnt lgkmcnt(0)
	s_waitcnt lgkmcnt(7)
	v_pk_fma_f32 v[192:193], v[146:147], v[190:191], v[230:231] op_sel:[0,1,0] op_sel_hi:[1,0,1]
	s_nop 0
	v_pk_fma_f32 v[194:195], v[150:151], v[190:191], v[192:193]
	s_nop 0
	v_pk_fma_f32 v[190:191], v[146:147], v[194:195], v[232:233] op_sel:[0,1,0] op_sel_hi:[1,0,1]
	s_nop 0
	v_pk_fma_f32 v[190:191], v[150:151], v[194:195], v[190:191]
	s_cbranch_vccnz .LBB0_2164
	s_waitcnt lgkmcnt(6)
	v_pk_fma_f32 v[192:193], v[146:147], v[190:191], v[114:115] op_sel:[0,1,0] op_sel_hi:[1,0,1]
	v_cvt_pk_bf16_f32 v230, v194, v195
	v_cvt_pk_bf16_f32 v231, v190, v191
	v_mfma_f32_16x16x32_bf16 v[118:121], v[34:37], v[118:121], 0
	v_fma_f32 v192, v150, v190, v192
	v_fma_f32 v193, v151, v191, v193
	s_mov_b64 s[72:73], 0
	v_pk_fma_f32 v[194:195], v[146:147], v[192:193], v[116:117] op_sel:[0,1,0] op_sel_hi:[1,0,1]
	v_cvt_pk_bf16_f32 v232, v192, v193
	s_nop 0
	v_pk_fma_f32 v[192:193], v[150:151], v[192:193], v[194:195]
	s_waitcnt lgkmcnt(5)
	v_pk_fma_f32 v[194:195], v[146:147], v[192:193], v[110:111] op_sel:[0,1,0] op_sel_hi:[1,0,1]
	v_cvt_pk_bf16_f32 v233, v192, v193
	s_nop 0
	v_pk_fma_f32 v[192:193], v[150:151], v[192:193], v[194:195]
	s_nop 0
	v_pk_fma_f32 v[194:195], v[146:147], v[192:193], v[112:113] op_sel:[0,1,0] op_sel_hi:[1,0,1]
	v_cvt_pk_bf16_f32 v234, v192, v193
	s_nop 0
	v_pk_fma_f32 v[192:193], v[150:151], v[192:193], v[194:195]
	s_waitcnt lgkmcnt(4)
	v_pk_fma_f32 v[194:195], v[146:147], v[192:193], v[106:107] op_sel:[0,1,0] op_sel_hi:[1,0,1]
	v_cvt_pk_bf16_f32 v235, v192, v193
	s_nop 0
	v_pk_fma_f32 v[192:193], v[150:151], v[192:193], v[194:195]
	s_nop 0
	v_pk_fma_f32 v[194:195], v[146:147], v[192:193], v[108:109] op_sel:[0,1,0] op_sel_hi:[1,0,1]
	v_cvt_pk_bf16_f32 v236, v192, v193
	s_nop 0
	v_pk_fma_f32 v[192:193], v[150:151], v[192:193], v[194:195]
	s_waitcnt lgkmcnt(3)
	v_pk_fma_f32 v[194:195], v[146:147], v[192:193], v[102:103] op_sel:[0,1,0] op_sel_hi:[1,0,1]
	v_cvt_pk_bf16_f32 v237, v192, v193
	s_nop 0
	v_pk_fma_f32 v[192:193], v[150:151], v[192:193], v[194:195]
	s_nop 0
	v_pk_fma_f32 v[194:195], v[146:147], v[192:193], v[104:105] op_sel:[0,1,0] op_sel_hi:[1,0,1]
	v_cvt_pk_bf16_f32 v238, v192, v193
	s_nop 0
	v_pk_fma_f32 v[192:193], v[150:151], v[192:193], v[194:195]
	s_waitcnt lgkmcnt(2)
	v_pk_fma_f32 v[194:195], v[146:147], v[192:193], v[98:99] op_sel:[0,1,0] op_sel_hi:[1,0,1]
	v_cvt_pk_bf16_f32 v239, v192, v193
	s_nop 0
	v_pk_fma_f32 v[192:193], v[150:151], v[192:193], v[194:195]
	s_nop 0
	v_pk_fma_f32 v[194:195], v[146:147], v[192:193], v[100:101] op_sel:[0,1,0] op_sel_hi:[1,0,1]
	v_cvt_pk_bf16_f32 v240, v192, v193
	s_nop 0
	v_pk_fma_f32 v[192:193], v[150:151], v[192:193], v[194:195]
	s_waitcnt lgkmcnt(1)
	v_pk_fma_f32 v[194:195], v[146:147], v[192:193], v[94:95] op_sel:[0,1,0] op_sel_hi:[1,0,1]
	v_cvt_pk_bf16_f32 v241, v192, v193
	s_nop 0
	v_pk_fma_f32 v[192:193], v[150:151], v[192:193], v[194:195]
	s_nop 0
	v_pk_fma_f32 v[194:195], v[146:147], v[192:193], v[96:97] op_sel:[0,1,0] op_sel_hi:[1,0,1]
	v_cvt_pk_bf16_f32 v242, v192, v193
	s_nop 0
	v_pk_fma_f32 v[192:193], v[150:151], v[192:193], v[194:195]
	s_waitcnt lgkmcnt(0)
	v_pk_fma_f32 v[194:195], v[146:147], v[192:193], v[90:91] op_sel:[0,1,0] op_sel_hi:[1,0,1]
	v_cvt_pk_bf16_f32 v243, v192, v193
	s_nop 0
	v_pk_fma_f32 v[192:193], v[150:151], v[192:193], v[194:195]
	s_nop 0
	v_pk_fma_f32 v[194:195], v[146:147], v[192:193], v[92:93] op_sel:[0,1,0] op_sel_hi:[1,0,1]
	v_cvt_pk_bf16_f32 v244, v192, v193
	s_nop 0
	v_pk_fma_f32 v[192:193], v[150:151], v[192:193], v[194:195]
	s_nop 0
	v_cvt_pk_bf16_f32 v194, v192, v193
	ds_write2_b32 v123, v230, v231 offset0:64 offset1:132
	ds_write2_b32 v137, v232, v233 offset0:72 offset1:140
	ds_write2_b32 v139, v234, v235 offset0:80 offset1:148
	ds_write2_b32 v141, v236, v237 offset0:88 offset1:156
	ds_write2_b32 v143, v238, v239 offset0:96 offset1:164
	ds_write2_b32 v149, v240, v241 offset0:104 offset1:172
	ds_write2_b32 v225, v242, v243 offset0:112 offset1:180
	ds_write2_b32 v226, v244, v194 offset0:120 offset1:188
	s_waitcnt lgkmcnt(0)
	ds_read_b128 v[230:233], v224 offset:8448
	ds_read_b128 v[234:237], v224 offset:8512
	s_waitcnt lgkmcnt(0)
	v_mfma_f32_16x16x32_bf16 v[118:121], v[42:45], v[234:237], v[118:121]
	ds_read_b128 v[234:237], v224 offset:8576
	v_mfma_f32_16x16x32_bf16 v[230:233], v[38:41], v[230:233], 0
	s_waitcnt lgkmcnt(0)
	v_mfma_f32_16x16x32_bf16 v[230:233], v[46:49], v[234:237], v[230:233]
	ds_read_b128 v[234:237], v224 offset:8640
	s_waitcnt lgkmcnt(0)
	v_mfma_f32_16x16x32_bf16 v[118:121], v[50:53], v[234:237], v[118:121]
	s_nop 7
	v_pk_add_f32 v[120:121], v[232:233], v[120:121]
	v_pk_add_f32 v[118:119], v[230:231], v[118:119]
	v_pk_mul_f32 v[194:195], v[120:121], v[120:121]
	v_pk_mul_f32 v[230:231], v[118:119], v[118:119]
	v_mov_b64_e32 v[232:233], s[48:49]
	v_pk_fma_f32 v[230:231], v[230:231], s[46:47], v[232:233] op_sel_hi:[1,0,0] neg_lo:[1,0,0] neg_hi:[1,0,0]
	v_pk_fma_f32 v[194:195], v[194:195], s[46:47], v[232:233] op_sel_hi:[1,0,0] neg_lo:[1,0,0] neg_hi:[1,0,0]
	v_pk_mul_f32 v[230:231], v[118:119], v[230:231]
	v_pk_mul_f32 v[194:195], v[120:121], v[194:195]
	v_exp_f32_e32 v230, v230
	v_exp_f32_e32 v231, v231
	v_exp_f32_e32 v194, v194
	v_exp_f32_e32 v195, v195
	v_pk_add_f32 v[230:231], v[230:231], 1.0 op_sel_hi:[1,0]
	s_nop 0
	v_rcp_f32_e32 v230, v230
	v_pk_add_f32 v[194:195], v[194:195], 1.0 op_sel_hi:[1,0]
	v_rcp_f32_e32 v231, v231
	v_rcp_f32_e32 v194, v194
	v_rcp_f32_e32 v195, v195
	v_pk_mul_f32 v[118:119], v[118:119], v[230:231]
	s_nop 0
	v_cvt_pk_bf16_f32 v118, v118, v119
	v_pk_mul_f32 v[120:121], v[120:121], v[194:195]
	s_nop 0
	v_cvt_pk_bf16_f32 v119, v120, v121
	v_or_b32_e32 v120, s86, v207
	v_or_b32_e32 v120, s20, v120
	v_mov_b32_e32 v121, s75
	v_lshlrev_b64 v[120:121], 12, v[120:121]
	v_lshl_add_u64 v[120:121], v[154:155], 0, v[120:121]
	global_store_dwordx2 v[120:121], v[118:119], off sc1

.LBB0_2166:
	s_waitcnt lgkmcnt(6)
	v_cndmask_b32_e64 v114, v70, 0, s[4:5]
	v_cndmask_b32_e64 v115, v71, 0, s[4:5]
	v_cndmask_b32_e64 v116, v72, 0, s[4:5]
	v_cndmask_b32_e64 v117, v73, 0, s[4:5]
	s_waitcnt lgkmcnt(0)
	s_mov_b64 s[72:73], -1
	s_and_b64 vcc, exec, s[14:15]
	v_mfma_f32_16x16x32_bf16 v[70:73], v[2:5], v[114:117], 0
	s_waitcnt lgkmcnt(0)
	v_mfma_f32_16x16x32_bf16 v[90:93], v[6:9], v[114:117], 0
	v_mfma_f32_16x16x32_bf16 v[94:97], v[10:13], v[114:117], 0
	s_nop 4
	ds_write_b128 v202, v[70:73]
	v_mfma_f32_16x16x32_bf16 v[98:101], v[14:17], v[114:117], 0
	ds_write_b128 v202, v[90:93] offset:64
	ds_write_b128 v202, v[94:97] offset:128
	s_nop 5
	ds_write_b128 v202, v[98:101] offset:192
	v_mfma_f32_16x16x32_bf16 v[102:105], v[18:21], v[114:117], 0
	v_mfma_f32_16x16x32_bf16 v[70:73], v[22:25], v[114:117], 0
	v_mfma_f32_16x16x32_bf16 v[90:93], v[26:29], v[114:117], 0
	s_nop 5
	ds_write_b128 v202, v[102:105] offset:256
	ds_write_b128 v202, v[70:73] offset:320
	ds_write_b128 v202, v[90:93] offset:384
	v_mfma_f32_16x16x32_bf16 v[70:73], v[30:33], v[114:117], 0
	s_nop 7
	ds_write_b128 v202, v[70:73] offset:448
	s_waitcnt lgkmcnt(0)
	ds_read2_b64 v[230:233], v203 offset1:66
	ds_read2_b64 v[110:113], v203 offset0:132 offset1:198
	ds_read2_b64 v[106:109], v227 offset0:8 offset1:74
	ds_read2_b64 v[102:105], v227 offset0:140 offset1:206
	ds_read2_b64 v[98:101], v228 offset0:16 offset1:82
	ds_read2_b64 v[94:97], v228 offset0:148 offset1:214
	ds_read2_b64 v[90:93], v229 offset0:24 offset1:90
	ds_read2_b64 v[70:73], v229 offset0:156 offset1:222
	s_waitcnt lgkmcnt(0)
	s_waitcnt lgkmcnt(7)
	v_pk_fma_f32 v[118:119], v[146:147], v[192:193], v[230:231] op_sel:[0,1,0] op_sel_hi:[1,0,1]
	s_nop 0
	v_pk_fma_f32 v[120:121], v[150:151], v[192:193], v[118:119]
	s_nop 0
	v_pk_fma_f32 v[118:119], v[146:147], v[120:121], v[232:233] op_sel:[0,1,0] op_sel_hi:[1,0,1]
	s_nop 0
	v_pk_fma_f32 v[118:119], v[150:151], v[120:121], v[118:119]
	s_cbranch_vccnz .LBB0_2168
	v_cvt_pk_bf16_f32 v192, v120, v121
	s_waitcnt lgkmcnt(6)
	v_pk_fma_f32 v[120:121], v[146:147], v[118:119], v[110:111] op_sel:[0,1,0] op_sel_hi:[1,0,1]
	v_cvt_pk_bf16_f32 v193, v118, v119
	v_mfma_f32_16x16x32_bf16 v[114:117], v[34:37], v[114:117], 0
	v_fma_f32 v120, v150, v118, v120
	v_fma_f32 v121, v151, v119, v121
	s_mov_b64 s[72:73], 0
	v_pk_fma_f32 v[190:191], v[146:147], v[120:121], v[112:113] op_sel:[0,1,0] op_sel_hi:[1,0,1]
	v_cvt_pk_bf16_f32 v194, v120, v121
	s_nop 0
	v_pk_fma_f32 v[120:121], v[150:151], v[120:121], v[190:191]
	s_waitcnt lgkmcnt(5)
	v_pk_fma_f32 v[190:191], v[146:147], v[120:121], v[106:107] op_sel:[0,1,0] op_sel_hi:[1,0,1]
	v_cvt_pk_bf16_f32 v195, v120, v121
	s_nop 0
	v_pk_fma_f32 v[120:121], v[150:151], v[120:121], v[190:191]
	s_nop 0
	v_pk_fma_f32 v[190:191], v[146:147], v[120:121], v[108:109] op_sel:[0,1,0] op_sel_hi:[1,0,1]
	v_cvt_pk_bf16_f32 v230, v120, v121
	s_nop 0
	v_pk_fma_f32 v[120:121], v[150:151], v[120:121], v[190:191]
	s_waitcnt lgkmcnt(4)
	v_pk_fma_f32 v[190:191], v[146:147], v[120:121], v[102:103] op_sel:[0,1,0] op_sel_hi:[1,0,1]
	v_cvt_pk_bf16_f32 v231, v120, v121
	s_nop 0
	v_pk_fma_f32 v[120:121], v[150:151], v[120:121], v[190:191]
	s_nop 0
	v_pk_fma_f32 v[190:191], v[146:147], v[120:121], v[104:105] op_sel:[0,1,0] op_sel_hi:[1,0,1]
	v_cvt_pk_bf16_f32 v232, v120, v121
	s_nop 0
	v_pk_fma_f32 v[120:121], v[150:151], v[120:121], v[190:191]
	s_waitcnt lgkmcnt(3)
	v_pk_fma_f32 v[190:191], v[146:147], v[120:121], v[98:99] op_sel:[0,1,0] op_sel_hi:[1,0,1]
	v_cvt_pk_bf16_f32 v233, v120, v121
	s_nop 0
	v_pk_fma_f32 v[120:121], v[150:151], v[120:121], v[190:191]
	s_nop 0
	v_pk_fma_f32 v[190:191], v[146:147], v[120:121], v[100:101] op_sel:[0,1,0] op_sel_hi:[1,0,1]
	v_cvt_pk_bf16_f32 v234, v120, v121
	s_nop 0
	v_pk_fma_f32 v[120:121], v[150:151], v[120:121], v[190:191]
	s_waitcnt lgkmcnt(2)
	v_pk_fma_f32 v[190:191], v[146:147], v[120:121], v[94:95] op_sel:[0,1,0] op_sel_hi:[1,0,1]
	v_cvt_pk_bf16_f32 v235, v120, v121
	s_nop 0
	v_pk_fma_f32 v[120:121], v[150:151], v[120:121], v[190:191]
	s_nop 0
	v_pk_fma_f32 v[190:191], v[146:147], v[120:121], v[96:97] op_sel:[0,1,0] op_sel_hi:[1,0,1]
	v_cvt_pk_bf16_f32 v236, v120, v121
	s_nop 0
	v_pk_fma_f32 v[120:121], v[150:151], v[120:121], v[190:191]
	s_waitcnt lgkmcnt(1)
	v_pk_fma_f32 v[190:191], v[146:147], v[120:121], v[90:91] op_sel:[0,1,0] op_sel_hi:[1,0,1]
	v_cvt_pk_bf16_f32 v237, v120, v121
	s_nop 0
	v_pk_fma_f32 v[120:121], v[150:151], v[120:121], v[190:191]
	s_nop 0
	v_pk_fma_f32 v[190:191], v[146:147], v[120:121], v[92:93] op_sel:[0,1,0] op_sel_hi:[1,0,1]
	v_cvt_pk_bf16_f32 v238, v120, v121
	s_nop 0
	v_pk_fma_f32 v[120:121], v[150:151], v[120:121], v[190:191]
	s_waitcnt lgkmcnt(0)
	v_pk_fma_f32 v[190:191], v[146:147], v[120:121], v[70:71] op_sel:[0,1,0] op_sel_hi:[1,0,1]
	v_cvt_pk_bf16_f32 v239, v120, v121
	s_nop 0
	v_pk_fma_f32 v[120:121], v[150:151], v[120:121], v[190:191]
	s_nop 0
	v_pk_fma_f32 v[190:191], v[146:147], v[120:121], v[72:73] op_sel:[0,1,0] op_sel_hi:[1,0,1]
	v_cvt_pk_bf16_f32 v240, v120, v121
	s_nop 0
	v_pk_fma_f32 v[190:191], v[150:151], v[120:121], v[190:191]
	s_nop 0
	v_cvt_pk_bf16_f32 v120, v190, v191
	ds_write2_b32 v123, v192, v193 offset0:64 offset1:132
	ds_write2_b32 v137, v194, v195 offset0:72 offset1:140
	ds_write2_b32 v139, v230, v231 offset0:80 offset1:148
	ds_write2_b32 v141, v232, v233 offset0:88 offset1:156
	ds_write2_b32 v143, v234, v235 offset0:96 offset1:164
	ds_write2_b32 v149, v236, v237 offset0:104 offset1:172
	ds_write2_b32 v225, v238, v239 offset0:112 offset1:180
	ds_write2_b32 v226, v240, v120 offset0:120 offset1:188
	s_waitcnt lgkmcnt(0)
	ds_read_b128 v[192:195], v224 offset:8448
	ds_read_b128 v[230:233], v224 offset:8512
	s_waitcnt lgkmcnt(0)
	v_mfma_f32_16x16x32_bf16 v[114:117], v[42:45], v[230:233], v[114:117]
	ds_read_b128 v[230:233], v224 offset:8576
	v_mfma_f32_16x16x32_bf16 v[192:195], v[38:41], v[192:195], 0
	s_waitcnt lgkmcnt(0)
	v_mfma_f32_16x16x32_bf16 v[192:195], v[46:49], v[230:233], v[192:195]
	ds_read_b128 v[230:233], v224 offset:8640
	s_waitcnt lgkmcnt(0)
	v_mfma_f32_16x16x32_bf16 v[114:117], v[50:53], v[230:233], v[114:117]
	s_nop 7
	v_pk_add_f32 v[116:117], v[194:195], v[116:117]
	v_pk_add_f32 v[114:115], v[192:193], v[114:115]
	v_pk_mul_f32 v[120:121], v[116:117], v[116:117]
	v_pk_mul_f32 v[192:193], v[114:115], v[114:115]
	v_mov_b64_e32 v[194:195], s[48:49]
	v_pk_fma_f32 v[192:193], v[192:193], s[46:47], v[194:195] op_sel_hi:[1,0,0] neg_lo:[1,0,0] neg_hi:[1,0,0]
	v_pk_fma_f32 v[120:121], v[120:121], s[46:47], v[194:195] op_sel_hi:[1,0,0] neg_lo:[1,0,0] neg_hi:[1,0,0]
	v_pk_mul_f32 v[192:193], v[114:115], v[192:193]
	v_pk_mul_f32 v[120:121], v[116:117], v[120:121]
	v_exp_f32_e32 v192, v192
	v_exp_f32_e32 v193, v193
	v_exp_f32_e32 v120, v120
	v_exp_f32_e32 v121, v121
	v_pk_add_f32 v[192:193], v[192:193], 1.0 op_sel_hi:[1,0]
	s_nop 0
	v_rcp_f32_e32 v192, v192
	v_pk_add_f32 v[120:121], v[120:121], 1.0 op_sel_hi:[1,0]
	v_rcp_f32_e32 v193, v193
	v_rcp_f32_e32 v120, v120
	v_rcp_f32_e32 v121, v121
	v_pk_mul_f32 v[114:115], v[114:115], v[192:193]
	s_nop 0
	v_cvt_pk_bf16_f32 v114, v114, v115
	v_pk_mul_f32 v[116:117], v[116:117], v[120:121]
	s_nop 0
	v_cvt_pk_bf16_f32 v115, v116, v117
	v_or_b32_e32 v116, s86, v208
	v_or_b32_e32 v116, s20, v116
	v_mov_b32_e32 v117, s75
	v_lshlrev_b64 v[116:117], 12, v[116:117]
	v_lshl_add_u64 v[116:117], v[154:155], 0, v[116:117]
	global_store_dwordx2 v[116:117], v[114:115], off sc1

.LBB0_2172:
	v_cndmask_b32_e64 v118, 0, v78, s[4:5]
	v_cndmask_b32_e64 v119, 0, v79, s[4:5]
	v_cndmask_b32_e64 v120, 0, v80, s[4:5]
	v_cndmask_b32_e64 v121, 0, v81, s[4:5]
	s_mov_b64 s[72:73], -1
	s_and_b64 vcc, exec, s[14:15]
	v_mfma_f32_16x16x32_bf16 v[90:93], v[2:5], v[118:121], 0
	v_mfma_f32_16x16x32_bf16 v[94:97], v[6:9], v[118:121], 0
	v_mfma_f32_16x16x32_bf16 v[98:101], v[10:13], v[118:121], 0
	s_nop 5
	ds_write_b128 v202, v[90:93]
	v_mfma_f32_16x16x32_bf16 v[102:105], v[14:17], v[118:121], 0
	ds_write_b128 v202, v[94:97] offset:64
	ds_write_b128 v202, v[98:101] offset:128
	s_nop 5
	ds_write_b128 v202, v[102:105] offset:192
	v_mfma_f32_16x16x32_bf16 v[106:109], v[18:21], v[118:121], 0
	v_mfma_f32_16x16x32_bf16 v[90:93], v[22:25], v[118:121], 0
	v_mfma_f32_16x16x32_bf16 v[94:97], v[26:29], v[118:121], 0
	s_nop 5
	ds_write_b128 v202, v[106:109] offset:256
	ds_write_b128 v202, v[90:93] offset:320
	ds_write_b128 v202, v[94:97] offset:384
	v_mfma_f32_16x16x32_bf16 v[90:93], v[30:33], v[118:121], 0
	s_nop 7
	ds_write_b128 v202, v[90:93] offset:448
	s_waitcnt lgkmcnt(0)
	ds_read2_b64 v[230:233], v203 offset1:66
	ds_read2_b64 v[114:117], v203 offset0:132 offset1:198
	ds_read2_b64 v[110:113], v227 offset0:8 offset1:74
	ds_read2_b64 v[106:109], v227 offset0:140 offset1:206
	ds_read2_b64 v[102:105], v228 offset0:16 offset1:82
	ds_read2_b64 v[98:101], v228 offset0:148 offset1:214
	ds_read2_b64 v[94:97], v229 offset0:24 offset1:90
	ds_read2_b64 v[90:93], v229 offset0:156 offset1:222
	s_waitcnt lgkmcnt(0)
	s_waitcnt lgkmcnt(7)
	v_pk_fma_f32 v[192:193], v[146:147], v[190:191], v[230:231] op_sel:[0,1,0] op_sel_hi:[1,0,1]
	s_nop 0
	v_pk_fma_f32 v[194:195], v[150:151], v[190:191], v[192:193]
	s_nop 0
	v_pk_fma_f32 v[190:191], v[146:147], v[194:195], v[232:233] op_sel:[0,1,0] op_sel_hi:[1,0,1]
	s_nop 0
	v_pk_fma_f32 v[190:191], v[150:151], v[194:195], v[190:191]
	s_cbranch_vccnz .LBB0_2174
	s_waitcnt lgkmcnt(6)
	v_pk_fma_f32 v[192:193], v[146:147], v[190:191], v[114:115] op_sel:[0,1,0] op_sel_hi:[1,0,1]
	v_cvt_pk_bf16_f32 v230, v194, v195
	v_cvt_pk_bf16_f32 v231, v190, v191
	v_mfma_f32_16x16x32_bf16 v[118:121], v[34:37], v[118:121], 0
	v_fma_f32 v192, v150, v190, v192
	v_fma_f32 v193, v151, v191, v193
	s_mov_b64 s[72:73], 0
	v_pk_fma_f32 v[194:195], v[146:147], v[192:193], v[116:117] op_sel:[0,1,0] op_sel_hi:[1,0,1]
	v_cvt_pk_bf16_f32 v232, v192, v193
	s_nop 0
	v_pk_fma_f32 v[192:193], v[150:151], v[192:193], v[194:195]
	s_waitcnt lgkmcnt(5)
	v_pk_fma_f32 v[194:195], v[146:147], v[192:193], v[110:111] op_sel:[0,1,0] op_sel_hi:[1,0,1]
	v_cvt_pk_bf16_f32 v233, v192, v193
	s_nop 0
	v_pk_fma_f32 v[192:193], v[150:151], v[192:193], v[194:195]
	s_nop 0
	v_pk_fma_f32 v[194:195], v[146:147], v[192:193], v[112:113] op_sel:[0,1,0] op_sel_hi:[1,0,1]
	v_cvt_pk_bf16_f32 v234, v192, v193
	s_nop 0
	v_pk_fma_f32 v[192:193], v[150:151], v[192:193], v[194:195]
	s_waitcnt lgkmcnt(4)
	v_pk_fma_f32 v[194:195], v[146:147], v[192:193], v[106:107] op_sel:[0,1,0] op_sel_hi:[1,0,1]
	v_cvt_pk_bf16_f32 v235, v192, v193
	s_nop 0
	v_pk_fma_f32 v[192:193], v[150:151], v[192:193], v[194:195]
	s_nop 0
	v_pk_fma_f32 v[194:195], v[146:147], v[192:193], v[108:109] op_sel:[0,1,0] op_sel_hi:[1,0,1]
	v_cvt_pk_bf16_f32 v236, v192, v193
	s_nop 0
	v_pk_fma_f32 v[192:193], v[150:151], v[192:193], v[194:195]
	s_waitcnt lgkmcnt(3)
	v_pk_fma_f32 v[194:195], v[146:147], v[192:193], v[102:103] op_sel:[0,1,0] op_sel_hi:[1,0,1]
	v_cvt_pk_bf16_f32 v237, v192, v193
	s_nop 0
	v_pk_fma_f32 v[192:193], v[150:151], v[192:193], v[194:195]
	s_nop 0
	v_pk_fma_f32 v[194:195], v[146:147], v[192:193], v[104:105] op_sel:[0,1,0] op_sel_hi:[1,0,1]
	v_cvt_pk_bf16_f32 v238, v192, v193
	s_nop 0
	v_pk_fma_f32 v[192:193], v[150:151], v[192:193], v[194:195]
	s_waitcnt lgkmcnt(2)
	v_pk_fma_f32 v[194:195], v[146:147], v[192:193], v[98:99] op_sel:[0,1,0] op_sel_hi:[1,0,1]
	v_cvt_pk_bf16_f32 v239, v192, v193
	s_nop 0
	v_pk_fma_f32 v[192:193], v[150:151], v[192:193], v[194:195]
	s_nop 0
	v_pk_fma_f32 v[194:195], v[146:147], v[192:193], v[100:101] op_sel:[0,1,0] op_sel_hi:[1,0,1]
	v_cvt_pk_bf16_f32 v240, v192, v193
	s_nop 0
	v_pk_fma_f32 v[192:193], v[150:151], v[192:193], v[194:195]
	s_waitcnt lgkmcnt(1)
	v_pk_fma_f32 v[194:195], v[146:147], v[192:193], v[94:95] op_sel:[0,1,0] op_sel_hi:[1,0,1]
	v_cvt_pk_bf16_f32 v241, v192, v193
	s_nop 0
	v_pk_fma_f32 v[192:193], v[150:151], v[192:193], v[194:195]
	s_nop 0
	v_pk_fma_f32 v[194:195], v[146:147], v[192:193], v[96:97] op_sel:[0,1,0] op_sel_hi:[1,0,1]
	v_cvt_pk_bf16_f32 v242, v192, v193
	s_nop 0
	v_pk_fma_f32 v[192:193], v[150:151], v[192:193], v[194:195]
	s_waitcnt lgkmcnt(0)
	v_pk_fma_f32 v[194:195], v[146:147], v[192:193], v[90:91] op_sel:[0,1,0] op_sel_hi:[1,0,1]
	v_cvt_pk_bf16_f32 v243, v192, v193
	s_nop 0
	v_pk_fma_f32 v[192:193], v[150:151], v[192:193], v[194:195]
	s_nop 0
	v_pk_fma_f32 v[194:195], v[146:147], v[192:193], v[92:93] op_sel:[0,1,0] op_sel_hi:[1,0,1]
	v_cvt_pk_bf16_f32 v244, v192, v193
	s_nop 0
	v_pk_fma_f32 v[192:193], v[150:151], v[192:193], v[194:195]
	s_nop 0
	v_cvt_pk_bf16_f32 v194, v192, v193
	ds_write2_b32 v123, v230, v231 offset0:64 offset1:132
	ds_write2_b32 v137, v232, v233 offset0:72 offset1:140
	ds_write2_b32 v139, v234, v235 offset0:80 offset1:148
	ds_write2_b32 v141, v236, v237 offset0:88 offset1:156
	ds_write2_b32 v143, v238, v239 offset0:96 offset1:164
	ds_write2_b32 v149, v240, v241 offset0:104 offset1:172
	ds_write2_b32 v225, v242, v243 offset0:112 offset1:180
	ds_write2_b32 v226, v244, v194 offset0:120 offset1:188
	s_waitcnt lgkmcnt(0)
	ds_read_b128 v[230:233], v224 offset:8448
	ds_read_b128 v[234:237], v224 offset:8512
	s_waitcnt lgkmcnt(0)
	v_mfma_f32_16x16x32_bf16 v[118:121], v[42:45], v[234:237], v[118:121]
	ds_read_b128 v[234:237], v224 offset:8576
	v_mfma_f32_16x16x32_bf16 v[230:233], v[38:41], v[230:233], 0
	s_waitcnt lgkmcnt(0)
	v_mfma_f32_16x16x32_bf16 v[230:233], v[46:49], v[234:237], v[230:233]
	ds_read_b128 v[234:237], v224 offset:8640
	s_waitcnt lgkmcnt(0)
	v_mfma_f32_16x16x32_bf16 v[118:121], v[50:53], v[234:237], v[118:121]
	s_nop 7
	v_pk_add_f32 v[120:121], v[232:233], v[120:121]
	v_pk_add_f32 v[118:119], v[230:231], v[118:119]
	v_pk_mul_f32 v[194:195], v[120:121], v[120:121]
	v_pk_mul_f32 v[230:231], v[118:119], v[118:119]
	v_mov_b64_e32 v[232:233], s[48:49]
	v_pk_fma_f32 v[230:231], v[230:231], s[46:47], v[232:233] op_sel_hi:[1,0,0] neg_lo:[1,0,0] neg_hi:[1,0,0]
	v_pk_fma_f32 v[194:195], v[194:195], s[46:47], v[232:233] op_sel_hi:[1,0,0] neg_lo:[1,0,0] neg_hi:[1,0,0]
	v_pk_mul_f32 v[230:231], v[118:119], v[230:231]
	v_pk_mul_f32 v[194:195], v[120:121], v[194:195]
	v_exp_f32_e32 v230, v230
	v_exp_f32_e32 v231, v231
	v_exp_f32_e32 v194, v194
	v_exp_f32_e32 v195, v195
	v_pk_add_f32 v[230:231], v[230:231], 1.0 op_sel_hi:[1,0]
	s_nop 0
	v_rcp_f32_e32 v230, v230
	v_pk_add_f32 v[194:195], v[194:195], 1.0 op_sel_hi:[1,0]
	v_rcp_f32_e32 v231, v231
	v_rcp_f32_e32 v194, v194
	v_rcp_f32_e32 v195, v195
	v_pk_mul_f32 v[118:119], v[118:119], v[230:231]
	s_nop 0
	v_cvt_pk_bf16_f32 v118, v118, v119
	v_pk_mul_f32 v[120:121], v[120:121], v[194:195]
	s_nop 0
	v_cvt_pk_bf16_f32 v119, v120, v121
	v_or_b32_e32 v120, s86, v209
	v_or_b32_e32 v120, s20, v120
	v_mov_b32_e32 v121, s75
	v_lshlrev_b64 v[120:121], 12, v[120:121]
	v_lshl_add_u64 v[120:121], v[154:155], 0, v[120:121]
	global_store_dwordx2 v[120:121], v[118:119], off sc1

.LBB0_2176:
	s_waitcnt lgkmcnt(6)
	v_cndmask_b32_e64 v114, v78, 0, s[4:5]
	v_cndmask_b32_e64 v115, v79, 0, s[4:5]
	v_cndmask_b32_e64 v116, v80, 0, s[4:5]
	v_cndmask_b32_e64 v117, v81, 0, s[4:5]
	s_waitcnt lgkmcnt(0)
	s_mov_b64 s[72:73], -1
	s_and_b64 vcc, exec, s[14:15]
	v_mfma_f32_16x16x32_bf16 v[78:81], v[2:5], v[114:117], 0
	s_waitcnt lgkmcnt(0)
	v_mfma_f32_16x16x32_bf16 v[90:93], v[6:9], v[114:117], 0
	v_mfma_f32_16x16x32_bf16 v[94:97], v[10:13], v[114:117], 0
	s_nop 4
	ds_write_b128 v202, v[78:81]
	v_mfma_f32_16x16x32_bf16 v[98:101], v[14:17], v[114:117], 0
	ds_write_b128 v202, v[90:93] offset:64
	ds_write_b128 v202, v[94:97] offset:128
	s_nop 5
	ds_write_b128 v202, v[98:101] offset:192
	v_mfma_f32_16x16x32_bf16 v[102:105], v[18:21], v[114:117], 0
	v_mfma_f32_16x16x32_bf16 v[78:81], v[22:25], v[114:117], 0
	v_mfma_f32_16x16x32_bf16 v[90:93], v[26:29], v[114:117], 0
	s_nop 5
	ds_write_b128 v202, v[102:105] offset:256
	ds_write_b128 v202, v[78:81] offset:320
	ds_write_b128 v202, v[90:93] offset:384
	v_mfma_f32_16x16x32_bf16 v[78:81], v[30:33], v[114:117], 0
	s_nop 7
	ds_write_b128 v202, v[78:81] offset:448
	s_waitcnt lgkmcnt(0)
	ds_read2_b64 v[230:233], v203 offset1:66
	ds_read2_b64 v[110:113], v203 offset0:132 offset1:198
	ds_read2_b64 v[106:109], v227 offset0:8 offset1:74
	ds_read2_b64 v[102:105], v227 offset0:140 offset1:206
	ds_read2_b64 v[98:101], v228 offset0:16 offset1:82
	ds_read2_b64 v[94:97], v228 offset0:148 offset1:214
	ds_read2_b64 v[90:93], v229 offset0:24 offset1:90
	ds_read2_b64 v[78:81], v229 offset0:156 offset1:222
	s_waitcnt lgkmcnt(0)
	s_waitcnt lgkmcnt(7)
	v_pk_fma_f32 v[118:119], v[146:147], v[192:193], v[230:231] op_sel:[0,1,0] op_sel_hi:[1,0,1]
	s_nop 0
	v_pk_fma_f32 v[120:121], v[150:151], v[192:193], v[118:119]
	s_nop 0
	v_pk_fma_f32 v[118:119], v[146:147], v[120:121], v[232:233] op_sel:[0,1,0] op_sel_hi:[1,0,1]
	s_nop 0
	v_pk_fma_f32 v[118:119], v[150:151], v[120:121], v[118:119]
	s_cbranch_vccnz .LBB0_2178
	v_cvt_pk_bf16_f32 v192, v120, v121
	s_waitcnt lgkmcnt(6)
	v_pk_fma_f32 v[120:121], v[146:147], v[118:119], v[110:111] op_sel:[0,1,0] op_sel_hi:[1,0,1]
	v_cvt_pk_bf16_f32 v193, v118, v119
	v_mfma_f32_16x16x32_bf16 v[114:117], v[34:37], v[114:117], 0
	v_fma_f32 v120, v150, v118, v120
	v_fma_f32 v121, v151, v119, v121
	s_mov_b64 s[72:73], 0
	v_pk_fma_f32 v[190:191], v[146:147], v[120:121], v[112:113] op_sel:[0,1,0] op_sel_hi:[1,0,1]
	v_cvt_pk_bf16_f32 v194, v120, v121
	s_nop 0
	v_pk_fma_f32 v[120:121], v[150:151], v[120:121], v[190:191]
	s_waitcnt lgkmcnt(5)
	v_pk_fma_f32 v[190:191], v[146:147], v[120:121], v[106:107] op_sel:[0,1,0] op_sel_hi:[1,0,1]
	v_cvt_pk_bf16_f32 v195, v120, v121
	s_nop 0
	v_pk_fma_f32 v[120:121], v[150:151], v[120:121], v[190:191]
	s_nop 0
	v_pk_fma_f32 v[190:191], v[146:147], v[120:121], v[108:109] op_sel:[0,1,0] op_sel_hi:[1,0,1]
	v_cvt_pk_bf16_f32 v230, v120, v121
	s_nop 0
	v_pk_fma_f32 v[120:121], v[150:151], v[120:121], v[190:191]
	s_waitcnt lgkmcnt(4)
	v_pk_fma_f32 v[190:191], v[146:147], v[120:121], v[102:103] op_sel:[0,1,0] op_sel_hi:[1,0,1]
	v_cvt_pk_bf16_f32 v231, v120, v121
	s_nop 0
	v_pk_fma_f32 v[120:121], v[150:151], v[120:121], v[190:191]
	s_nop 0
	v_pk_fma_f32 v[190:191], v[146:147], v[120:121], v[104:105] op_sel:[0,1,0] op_sel_hi:[1,0,1]
	v_cvt_pk_bf16_f32 v232, v120, v121
	s_nop 0
	v_pk_fma_f32 v[120:121], v[150:151], v[120:121], v[190:191]
	s_waitcnt lgkmcnt(3)
	v_pk_fma_f32 v[190:191], v[146:147], v[120:121], v[98:99] op_sel:[0,1,0] op_sel_hi:[1,0,1]
	v_cvt_pk_bf16_f32 v233, v120, v121
	s_nop 0
	v_pk_fma_f32 v[120:121], v[150:151], v[120:121], v[190:191]
	s_nop 0
	v_pk_fma_f32 v[190:191], v[146:147], v[120:121], v[100:101] op_sel:[0,1,0] op_sel_hi:[1,0,1]
	v_cvt_pk_bf16_f32 v234, v120, v121
	s_nop 0
	v_pk_fma_f32 v[120:121], v[150:151], v[120:121], v[190:191]
	s_waitcnt lgkmcnt(2)
	v_pk_fma_f32 v[190:191], v[146:147], v[120:121], v[94:95] op_sel:[0,1,0] op_sel_hi:[1,0,1]
	v_cvt_pk_bf16_f32 v235, v120, v121
	s_nop 0
	v_pk_fma_f32 v[120:121], v[150:151], v[120:121], v[190:191]
	s_nop 0
	v_pk_fma_f32 v[190:191], v[146:147], v[120:121], v[96:97] op_sel:[0,1,0] op_sel_hi:[1,0,1]
	v_cvt_pk_bf16_f32 v236, v120, v121
	s_nop 0
	v_pk_fma_f32 v[120:121], v[150:151], v[120:121], v[190:191]
	s_waitcnt lgkmcnt(1)
	v_pk_fma_f32 v[190:191], v[146:147], v[120:121], v[90:91] op_sel:[0,1,0] op_sel_hi:[1,0,1]
	v_cvt_pk_bf16_f32 v237, v120, v121
	s_nop 0
	v_pk_fma_f32 v[120:121], v[150:151], v[120:121], v[190:191]
	s_nop 0
	v_pk_fma_f32 v[190:191], v[146:147], v[120:121], v[92:93] op_sel:[0,1,0] op_sel_hi:[1,0,1]
	v_cvt_pk_bf16_f32 v238, v120, v121
	s_nop 0
	v_pk_fma_f32 v[120:121], v[150:151], v[120:121], v[190:191]
	s_waitcnt lgkmcnt(0)
	v_pk_fma_f32 v[190:191], v[146:147], v[120:121], v[78:79] op_sel:[0,1,0] op_sel_hi:[1,0,1]
	v_cvt_pk_bf16_f32 v239, v120, v121
	s_nop 0
	v_pk_fma_f32 v[120:121], v[150:151], v[120:121], v[190:191]
	s_nop 0
	v_pk_fma_f32 v[190:191], v[146:147], v[120:121], v[80:81] op_sel:[0,1,0] op_sel_hi:[1,0,1]
	v_cvt_pk_bf16_f32 v240, v120, v121
	s_nop 0
	v_pk_fma_f32 v[190:191], v[150:151], v[120:121], v[190:191]
	s_nop 0
	v_cvt_pk_bf16_f32 v120, v190, v191
	ds_write2_b32 v123, v192, v193 offset0:64 offset1:132
	ds_write2_b32 v137, v194, v195 offset0:72 offset1:140
	ds_write2_b32 v139, v230, v231 offset0:80 offset1:148
	ds_write2_b32 v141, v232, v233 offset0:88 offset1:156
	ds_write2_b32 v143, v234, v235 offset0:96 offset1:164
	ds_write2_b32 v149, v236, v237 offset0:104 offset1:172
	ds_write2_b32 v225, v238, v239 offset0:112 offset1:180
	ds_write2_b32 v226, v240, v120 offset0:120 offset1:188
	s_waitcnt lgkmcnt(0)
	ds_read_b128 v[192:195], v224 offset:8448
	ds_read_b128 v[230:233], v224 offset:8512
	s_waitcnt lgkmcnt(0)
	v_mfma_f32_16x16x32_bf16 v[114:117], v[42:45], v[230:233], v[114:117]
	ds_read_b128 v[230:233], v224 offset:8576
	v_mfma_f32_16x16x32_bf16 v[192:195], v[38:41], v[192:195], 0
	s_waitcnt lgkmcnt(0)
	v_mfma_f32_16x16x32_bf16 v[192:195], v[46:49], v[230:233], v[192:195]
	ds_read_b128 v[230:233], v224 offset:8640
	s_waitcnt lgkmcnt(0)
	v_mfma_f32_16x16x32_bf16 v[114:117], v[50:53], v[230:233], v[114:117]
	s_nop 7
	v_pk_add_f32 v[116:117], v[194:195], v[116:117]
	v_pk_add_f32 v[114:115], v[192:193], v[114:115]
	v_pk_mul_f32 v[120:121], v[116:117], v[116:117]
	v_pk_mul_f32 v[192:193], v[114:115], v[114:115]
	v_mov_b64_e32 v[194:195], s[48:49]
	v_pk_fma_f32 v[192:193], v[192:193], s[46:47], v[194:195] op_sel_hi:[1,0,0] neg_lo:[1,0,0] neg_hi:[1,0,0]
	v_pk_fma_f32 v[120:121], v[120:121], s[46:47], v[194:195] op_sel_hi:[1,0,0] neg_lo:[1,0,0] neg_hi:[1,0,0]
	v_pk_mul_f32 v[192:193], v[114:115], v[192:193]
	v_pk_mul_f32 v[120:121], v[116:117], v[120:121]
	v_exp_f32_e32 v192, v192
	v_exp_f32_e32 v193, v193
	v_exp_f32_e32 v120, v120
	v_exp_f32_e32 v121, v121
	v_pk_add_f32 v[192:193], v[192:193], 1.0 op_sel_hi:[1,0]
	s_nop 0
	v_rcp_f32_e32 v192, v192
	v_pk_add_f32 v[120:121], v[120:121], 1.0 op_sel_hi:[1,0]
	v_rcp_f32_e32 v193, v193
	v_rcp_f32_e32 v120, v120
	v_rcp_f32_e32 v121, v121
	v_pk_mul_f32 v[114:115], v[114:115], v[192:193]
	s_nop 0
	v_cvt_pk_bf16_f32 v114, v114, v115
	v_pk_mul_f32 v[116:117], v[116:117], v[120:121]
	s_nop 0
	v_cvt_pk_bf16_f32 v115, v116, v117
	v_or_b32_e32 v116, s86, v210
	v_or_b32_e32 v116, s20, v116
	v_mov_b32_e32 v117, s75
	v_lshlrev_b64 v[116:117], 12, v[116:117]
	v_lshl_add_u64 v[116:117], v[154:155], 0, v[116:117]
	global_store_dwordx2 v[116:117], v[114:115], off sc1

.LBB0_2182:
	v_cndmask_b32_e64 v118, 0, v86, s[4:5]
	v_cndmask_b32_e64 v119, 0, v87, s[4:5]
	v_cndmask_b32_e64 v120, 0, v88, s[4:5]
	v_cndmask_b32_e64 v121, 0, v89, s[4:5]
	s_mov_b64 s[72:73], -1
	s_and_b64 vcc, exec, s[14:15]
	v_mfma_f32_16x16x32_bf16 v[90:93], v[2:5], v[118:121], 0
	v_mfma_f32_16x16x32_bf16 v[94:97], v[6:9], v[118:121], 0
	v_mfma_f32_16x16x32_bf16 v[98:101], v[10:13], v[118:121], 0
	s_nop 5
	ds_write_b128 v202, v[90:93]
	v_mfma_f32_16x16x32_bf16 v[102:105], v[14:17], v[118:121], 0
	ds_write_b128 v202, v[94:97] offset:64
	ds_write_b128 v202, v[98:101] offset:128
	s_nop 5
	ds_write_b128 v202, v[102:105] offset:192
	v_mfma_f32_16x16x32_bf16 v[106:109], v[18:21], v[118:121], 0
	v_mfma_f32_16x16x32_bf16 v[90:93], v[22:25], v[118:121], 0
	v_mfma_f32_16x16x32_bf16 v[94:97], v[26:29], v[118:121], 0
	s_nop 5
	ds_write_b128 v202, v[106:109] offset:256
	ds_write_b128 v202, v[90:93] offset:320
	ds_write_b128 v202, v[94:97] offset:384
	v_mfma_f32_16x16x32_bf16 v[90:93], v[30:33], v[118:121], 0
	s_nop 7
	ds_write_b128 v202, v[90:93] offset:448
	s_waitcnt lgkmcnt(0)
	ds_read2_b64 v[230:233], v203 offset1:66
	ds_read2_b64 v[114:117], v203 offset0:132 offset1:198
	ds_read2_b64 v[110:113], v227 offset0:8 offset1:74
	ds_read2_b64 v[106:109], v227 offset0:140 offset1:206
	ds_read2_b64 v[102:105], v228 offset0:16 offset1:82
	ds_read2_b64 v[98:101], v228 offset0:148 offset1:214
	ds_read2_b64 v[94:97], v229 offset0:24 offset1:90
	ds_read2_b64 v[90:93], v229 offset0:156 offset1:222
	s_waitcnt lgkmcnt(0)
	s_waitcnt lgkmcnt(7)
	v_pk_fma_f32 v[192:193], v[146:147], v[190:191], v[230:231] op_sel:[0,1,0] op_sel_hi:[1,0,1]
	s_nop 0
	v_pk_fma_f32 v[194:195], v[150:151], v[190:191], v[192:193]
	s_nop 0
	v_pk_fma_f32 v[190:191], v[146:147], v[194:195], v[232:233] op_sel:[0,1,0] op_sel_hi:[1,0,1]
	s_nop 0
	v_pk_fma_f32 v[190:191], v[150:151], v[194:195], v[190:191]
	s_cbranch_vccnz .LBB0_2184
	s_waitcnt lgkmcnt(6)
	v_pk_fma_f32 v[192:193], v[146:147], v[190:191], v[114:115] op_sel:[0,1,0] op_sel_hi:[1,0,1]
	v_cvt_pk_bf16_f32 v230, v194, v195
	v_cvt_pk_bf16_f32 v231, v190, v191
	v_mfma_f32_16x16x32_bf16 v[118:121], v[34:37], v[118:121], 0
	v_fma_f32 v192, v150, v190, v192
	v_fma_f32 v193, v151, v191, v193
	s_mov_b64 s[72:73], 0
	v_pk_fma_f32 v[194:195], v[146:147], v[192:193], v[116:117] op_sel:[0,1,0] op_sel_hi:[1,0,1]
	v_cvt_pk_bf16_f32 v232, v192, v193
	s_nop 0
	v_pk_fma_f32 v[192:193], v[150:151], v[192:193], v[194:195]
	s_waitcnt lgkmcnt(5)
	v_pk_fma_f32 v[194:195], v[146:147], v[192:193], v[110:111] op_sel:[0,1,0] op_sel_hi:[1,0,1]
	v_cvt_pk_bf16_f32 v233, v192, v193
	s_nop 0
	v_pk_fma_f32 v[192:193], v[150:151], v[192:193], v[194:195]
	s_nop 0
	v_pk_fma_f32 v[194:195], v[146:147], v[192:193], v[112:113] op_sel:[0,1,0] op_sel_hi:[1,0,1]
	v_cvt_pk_bf16_f32 v234, v192, v193
	s_nop 0
	v_pk_fma_f32 v[192:193], v[150:151], v[192:193], v[194:195]
	s_waitcnt lgkmcnt(4)
	v_pk_fma_f32 v[194:195], v[146:147], v[192:193], v[106:107] op_sel:[0,1,0] op_sel_hi:[1,0,1]
	v_cvt_pk_bf16_f32 v235, v192, v193
	s_nop 0
	v_pk_fma_f32 v[192:193], v[150:151], v[192:193], v[194:195]
	s_nop 0
	v_pk_fma_f32 v[194:195], v[146:147], v[192:193], v[108:109] op_sel:[0,1,0] op_sel_hi:[1,0,1]
	v_cvt_pk_bf16_f32 v236, v192, v193
	s_nop 0
	v_pk_fma_f32 v[192:193], v[150:151], v[192:193], v[194:195]
	s_waitcnt lgkmcnt(3)
	v_pk_fma_f32 v[194:195], v[146:147], v[192:193], v[102:103] op_sel:[0,1,0] op_sel_hi:[1,0,1]
	v_cvt_pk_bf16_f32 v237, v192, v193
	s_nop 0
	v_pk_fma_f32 v[192:193], v[150:151], v[192:193], v[194:195]
	s_nop 0
	v_pk_fma_f32 v[194:195], v[146:147], v[192:193], v[104:105] op_sel:[0,1,0] op_sel_hi:[1,0,1]
	v_cvt_pk_bf16_f32 v238, v192, v193
	s_nop 0
	v_pk_fma_f32 v[192:193], v[150:151], v[192:193], v[194:195]
	s_waitcnt lgkmcnt(2)
	v_pk_fma_f32 v[194:195], v[146:147], v[192:193], v[98:99] op_sel:[0,1,0] op_sel_hi:[1,0,1]
	v_cvt_pk_bf16_f32 v239, v192, v193
	s_nop 0
	v_pk_fma_f32 v[192:193], v[150:151], v[192:193], v[194:195]
	s_nop 0
	v_pk_fma_f32 v[194:195], v[146:147], v[192:193], v[100:101] op_sel:[0,1,0] op_sel_hi:[1,0,1]
	v_cvt_pk_bf16_f32 v240, v192, v193
	s_nop 0
	v_pk_fma_f32 v[192:193], v[150:151], v[192:193], v[194:195]
	s_waitcnt lgkmcnt(1)
	v_pk_fma_f32 v[194:195], v[146:147], v[192:193], v[94:95] op_sel:[0,1,0] op_sel_hi:[1,0,1]
	v_cvt_pk_bf16_f32 v241, v192, v193
	s_nop 0
	v_pk_fma_f32 v[192:193], v[150:151], v[192:193], v[194:195]
	s_nop 0
	v_pk_fma_f32 v[194:195], v[146:147], v[192:193], v[96:97] op_sel:[0,1,0] op_sel_hi:[1,0,1]
	v_cvt_pk_bf16_f32 v242, v192, v193
	s_nop 0
	v_pk_fma_f32 v[192:193], v[150:151], v[192:193], v[194:195]
	s_waitcnt lgkmcnt(0)
	v_pk_fma_f32 v[194:195], v[146:147], v[192:193], v[90:91] op_sel:[0,1,0] op_sel_hi:[1,0,1]
	v_cvt_pk_bf16_f32 v243, v192, v193
	s_nop 0
	v_pk_fma_f32 v[192:193], v[150:151], v[192:193], v[194:195]
	s_nop 0
	v_pk_fma_f32 v[194:195], v[146:147], v[192:193], v[92:93] op_sel:[0,1,0] op_sel_hi:[1,0,1]
	v_cvt_pk_bf16_f32 v244, v192, v193
	s_nop 0
	v_pk_fma_f32 v[192:193], v[150:151], v[192:193], v[194:195]
	s_nop 0
	v_cvt_pk_bf16_f32 v194, v192, v193
	ds_write2_b32 v123, v230, v231 offset0:64 offset1:132
	ds_write2_b32 v137, v232, v233 offset0:72 offset1:140
	ds_write2_b32 v139, v234, v235 offset0:80 offset1:148
	ds_write2_b32 v141, v236, v237 offset0:88 offset1:156
	ds_write2_b32 v143, v238, v239 offset0:96 offset1:164
	ds_write2_b32 v149, v240, v241 offset0:104 offset1:172
	ds_write2_b32 v225, v242, v243 offset0:112 offset1:180
	ds_write2_b32 v226, v244, v194 offset0:120 offset1:188
	s_waitcnt lgkmcnt(0)
	ds_read_b128 v[230:233], v224 offset:8448
	ds_read_b128 v[234:237], v224 offset:8512
	s_waitcnt lgkmcnt(0)
	v_mfma_f32_16x16x32_bf16 v[118:121], v[42:45], v[234:237], v[118:121]
	ds_read_b128 v[234:237], v224 offset:8576
	v_mfma_f32_16x16x32_bf16 v[230:233], v[38:41], v[230:233], 0
	s_waitcnt lgkmcnt(0)
	v_mfma_f32_16x16x32_bf16 v[230:233], v[46:49], v[234:237], v[230:233]
	ds_read_b128 v[234:237], v224 offset:8640
	s_waitcnt lgkmcnt(0)
	v_mfma_f32_16x16x32_bf16 v[118:121], v[50:53], v[234:237], v[118:121]
	s_nop 7
	v_pk_add_f32 v[120:121], v[232:233], v[120:121]
	v_pk_add_f32 v[118:119], v[230:231], v[118:119]
	v_pk_mul_f32 v[194:195], v[120:121], v[120:121]
	v_pk_mul_f32 v[230:231], v[118:119], v[118:119]
	v_mov_b64_e32 v[232:233], s[48:49]
	v_pk_fma_f32 v[230:231], v[230:231], s[46:47], v[232:233] op_sel_hi:[1,0,0] neg_lo:[1,0,0] neg_hi:[1,0,0]
	v_pk_fma_f32 v[194:195], v[194:195], s[46:47], v[232:233] op_sel_hi:[1,0,0] neg_lo:[1,0,0] neg_hi:[1,0,0]
	v_pk_mul_f32 v[230:231], v[118:119], v[230:231]
	v_pk_mul_f32 v[194:195], v[120:121], v[194:195]
	v_exp_f32_e32 v230, v230
	v_exp_f32_e32 v231, v231
	v_exp_f32_e32 v194, v194
	v_exp_f32_e32 v195, v195
	v_pk_add_f32 v[230:231], v[230:231], 1.0 op_sel_hi:[1,0]
	s_nop 0
	v_rcp_f32_e32 v230, v230
	v_pk_add_f32 v[194:195], v[194:195], 1.0 op_sel_hi:[1,0]
	v_rcp_f32_e32 v231, v231
	v_rcp_f32_e32 v194, v194
	v_rcp_f32_e32 v195, v195
	v_pk_mul_f32 v[118:119], v[118:119], v[230:231]
	s_nop 0
	v_cvt_pk_bf16_f32 v118, v118, v119
	v_pk_mul_f32 v[120:121], v[120:121], v[194:195]
	s_nop 0
	v_cvt_pk_bf16_f32 v119, v120, v121
	v_or_b32_e32 v120, s86, v211
	v_or_b32_e32 v120, s20, v120
	v_mov_b32_e32 v121, s75
	v_lshlrev_b64 v[120:121], 12, v[120:121]
	v_lshl_add_u64 v[120:121], v[154:155], 0, v[120:121]
	global_store_dwordx2 v[120:121], v[118:119], off sc1

.LBB0_2186:
	s_waitcnt lgkmcnt(6)
	v_cndmask_b32_e64 v114, v86, 0, s[4:5]
	v_cndmask_b32_e64 v115, v87, 0, s[4:5]
	v_cndmask_b32_e64 v116, v88, 0, s[4:5]
	v_cndmask_b32_e64 v117, v89, 0, s[4:5]
	s_waitcnt lgkmcnt(0)
	s_mov_b64 s[72:73], -1
	s_and_b64 vcc, exec, s[14:15]
	v_mfma_f32_16x16x32_bf16 v[86:89], v[2:5], v[114:117], 0
	s_waitcnt lgkmcnt(0)
	v_mfma_f32_16x16x32_bf16 v[90:93], v[6:9], v[114:117], 0
	v_mfma_f32_16x16x32_bf16 v[94:97], v[10:13], v[114:117], 0
	s_nop 4
	ds_write_b128 v202, v[86:89]
	v_mfma_f32_16x16x32_bf16 v[98:101], v[14:17], v[114:117], 0
	ds_write_b128 v202, v[90:93] offset:64
	ds_write_b128 v202, v[94:97] offset:128
	s_nop 5
	ds_write_b128 v202, v[98:101] offset:192
	v_mfma_f32_16x16x32_bf16 v[102:105], v[18:21], v[114:117], 0
	v_mfma_f32_16x16x32_bf16 v[86:89], v[22:25], v[114:117], 0
	v_mfma_f32_16x16x32_bf16 v[90:93], v[26:29], v[114:117], 0
	s_nop 5
	ds_write_b128 v202, v[102:105] offset:256
	ds_write_b128 v202, v[86:89] offset:320
	ds_write_b128 v202, v[90:93] offset:384
	v_mfma_f32_16x16x32_bf16 v[86:89], v[30:33], v[114:117], 0
	s_nop 7
	ds_write_b128 v202, v[86:89] offset:448
	s_waitcnt lgkmcnt(0)
	ds_read2_b64 v[230:233], v203 offset1:66
	ds_read2_b64 v[110:113], v203 offset0:132 offset1:198
	ds_read2_b64 v[106:109], v227 offset0:8 offset1:74
	ds_read2_b64 v[102:105], v227 offset0:140 offset1:206
	ds_read2_b64 v[98:101], v228 offset0:16 offset1:82
	ds_read2_b64 v[94:97], v228 offset0:148 offset1:214
	ds_read2_b64 v[90:93], v229 offset0:24 offset1:90
	ds_read2_b64 v[86:89], v229 offset0:156 offset1:222
	s_waitcnt lgkmcnt(0)
	s_waitcnt lgkmcnt(7)
	v_pk_fma_f32 v[118:119], v[146:147], v[192:193], v[230:231] op_sel:[0,1,0] op_sel_hi:[1,0,1]
	s_nop 0
	v_pk_fma_f32 v[120:121], v[150:151], v[192:193], v[118:119]
	s_nop 0
	v_pk_fma_f32 v[118:119], v[146:147], v[120:121], v[232:233] op_sel:[0,1,0] op_sel_hi:[1,0,1]
	s_nop 0
	v_pk_fma_f32 v[118:119], v[150:151], v[120:121], v[118:119]
	s_cbranch_vccnz .LBB0_2188
	v_cvt_pk_bf16_f32 v192, v120, v121
	s_waitcnt lgkmcnt(6)
	v_pk_fma_f32 v[120:121], v[146:147], v[118:119], v[110:111] op_sel:[0,1,0] op_sel_hi:[1,0,1]
	v_cvt_pk_bf16_f32 v193, v118, v119
	v_mfma_f32_16x16x32_bf16 v[114:117], v[34:37], v[114:117], 0
	v_fma_f32 v120, v150, v118, v120
	v_fma_f32 v121, v151, v119, v121
	s_mov_b64 s[72:73], 0
	v_pk_fma_f32 v[190:191], v[146:147], v[120:121], v[112:113] op_sel:[0,1,0] op_sel_hi:[1,0,1]
	v_cvt_pk_bf16_f32 v194, v120, v121
	s_nop 0
	v_pk_fma_f32 v[120:121], v[150:151], v[120:121], v[190:191]
	s_waitcnt lgkmcnt(5)
	v_pk_fma_f32 v[190:191], v[146:147], v[120:121], v[106:107] op_sel:[0,1,0] op_sel_hi:[1,0,1]
	v_cvt_pk_bf16_f32 v195, v120, v121
	s_nop 0
	v_pk_fma_f32 v[120:121], v[150:151], v[120:121], v[190:191]
	s_nop 0
	v_pk_fma_f32 v[190:191], v[146:147], v[120:121], v[108:109] op_sel:[0,1,0] op_sel_hi:[1,0,1]
	v_cvt_pk_bf16_f32 v230, v120, v121
	s_nop 0
	v_pk_fma_f32 v[120:121], v[150:151], v[120:121], v[190:191]
	s_waitcnt lgkmcnt(4)
	v_pk_fma_f32 v[190:191], v[146:147], v[120:121], v[102:103] op_sel:[0,1,0] op_sel_hi:[1,0,1]
	v_cvt_pk_bf16_f32 v231, v120, v121
	s_nop 0
	v_pk_fma_f32 v[120:121], v[150:151], v[120:121], v[190:191]
	s_nop 0
	v_pk_fma_f32 v[190:191], v[146:147], v[120:121], v[104:105] op_sel:[0,1,0] op_sel_hi:[1,0,1]
	v_cvt_pk_bf16_f32 v232, v120, v121
	s_nop 0
	v_pk_fma_f32 v[120:121], v[150:151], v[120:121], v[190:191]
	s_waitcnt lgkmcnt(3)
	v_pk_fma_f32 v[190:191], v[146:147], v[120:121], v[98:99] op_sel:[0,1,0] op_sel_hi:[1,0,1]
	v_cvt_pk_bf16_f32 v233, v120, v121
	s_nop 0
	v_pk_fma_f32 v[120:121], v[150:151], v[120:121], v[190:191]
	s_nop 0
	v_pk_fma_f32 v[190:191], v[146:147], v[120:121], v[100:101] op_sel:[0,1,0] op_sel_hi:[1,0,1]
	v_cvt_pk_bf16_f32 v234, v120, v121
	s_nop 0
	v_pk_fma_f32 v[120:121], v[150:151], v[120:121], v[190:191]
	s_waitcnt lgkmcnt(2)
	v_pk_fma_f32 v[190:191], v[146:147], v[120:121], v[94:95] op_sel:[0,1,0] op_sel_hi:[1,0,1]
	v_cvt_pk_bf16_f32 v235, v120, v121
	s_nop 0
	v_pk_fma_f32 v[120:121], v[150:151], v[120:121], v[190:191]
	s_nop 0
	v_pk_fma_f32 v[190:191], v[146:147], v[120:121], v[96:97] op_sel:[0,1,0] op_sel_hi:[1,0,1]
	v_cvt_pk_bf16_f32 v236, v120, v121
	s_nop 0
	v_pk_fma_f32 v[120:121], v[150:151], v[120:121], v[190:191]
	s_waitcnt lgkmcnt(1)
	v_pk_fma_f32 v[190:191], v[146:147], v[120:121], v[90:91] op_sel:[0,1,0] op_sel_hi:[1,0,1]
	v_cvt_pk_bf16_f32 v237, v120, v121
	s_nop 0
	v_pk_fma_f32 v[120:121], v[150:151], v[120:121], v[190:191]
	s_nop 0
	v_pk_fma_f32 v[190:191], v[146:147], v[120:121], v[92:93] op_sel:[0,1,0] op_sel_hi:[1,0,1]
	v_cvt_pk_bf16_f32 v238, v120, v121
	s_nop 0
	v_pk_fma_f32 v[120:121], v[150:151], v[120:121], v[190:191]
	s_waitcnt lgkmcnt(0)
	v_pk_fma_f32 v[190:191], v[146:147], v[120:121], v[86:87] op_sel:[0,1,0] op_sel_hi:[1,0,1]
	v_cvt_pk_bf16_f32 v239, v120, v121
	s_nop 0
	v_pk_fma_f32 v[120:121], v[150:151], v[120:121], v[190:191]
	s_nop 0
	v_pk_fma_f32 v[190:191], v[146:147], v[120:121], v[88:89] op_sel:[0,1,0] op_sel_hi:[1,0,1]
	v_cvt_pk_bf16_f32 v240, v120, v121
	s_nop 0
	v_pk_fma_f32 v[190:191], v[150:151], v[120:121], v[190:191]
	s_nop 0
	v_cvt_pk_bf16_f32 v120, v190, v191
	ds_write2_b32 v123, v192, v193 offset0:64 offset1:132
	ds_write2_b32 v137, v194, v195 offset0:72 offset1:140
	ds_write2_b32 v139, v230, v231 offset0:80 offset1:148
	ds_write2_b32 v141, v232, v233 offset0:88 offset1:156
	ds_write2_b32 v143, v234, v235 offset0:96 offset1:164
	ds_write2_b32 v149, v236, v237 offset0:104 offset1:172
	ds_write2_b32 v225, v238, v239 offset0:112 offset1:180
	ds_write2_b32 v226, v240, v120 offset0:120 offset1:188
	s_waitcnt lgkmcnt(0)
	ds_read_b128 v[192:195], v224 offset:8448
	ds_read_b128 v[230:233], v224 offset:8512
	s_waitcnt lgkmcnt(0)
	v_mfma_f32_16x16x32_bf16 v[114:117], v[42:45], v[230:233], v[114:117]
	ds_read_b128 v[230:233], v224 offset:8576
	v_mfma_f32_16x16x32_bf16 v[192:195], v[38:41], v[192:195], 0
	s_waitcnt lgkmcnt(0)
	v_mfma_f32_16x16x32_bf16 v[192:195], v[46:49], v[230:233], v[192:195]
	ds_read_b128 v[230:233], v224 offset:8640
	s_waitcnt lgkmcnt(0)
	v_mfma_f32_16x16x32_bf16 v[114:117], v[50:53], v[230:233], v[114:117]
	s_nop 7
	v_pk_add_f32 v[116:117], v[194:195], v[116:117]
	v_pk_add_f32 v[114:115], v[192:193], v[114:115]
	v_pk_mul_f32 v[120:121], v[116:117], v[116:117]
	v_pk_mul_f32 v[192:193], v[114:115], v[114:115]
	v_mov_b64_e32 v[194:195], s[48:49]
	v_pk_fma_f32 v[192:193], v[192:193], s[46:47], v[194:195] op_sel_hi:[1,0,0] neg_lo:[1,0,0] neg_hi:[1,0,0]
	v_pk_fma_f32 v[120:121], v[120:121], s[46:47], v[194:195] op_sel_hi:[1,0,0] neg_lo:[1,0,0] neg_hi:[1,0,0]
	v_pk_mul_f32 v[192:193], v[114:115], v[192:193]
	v_pk_mul_f32 v[120:121], v[116:117], v[120:121]
	v_exp_f32_e32 v192, v192
	v_exp_f32_e32 v193, v193
	v_exp_f32_e32 v120, v120
	v_exp_f32_e32 v121, v121
	v_pk_add_f32 v[192:193], v[192:193], 1.0 op_sel_hi:[1,0]
	s_nop 0
	v_rcp_f32_e32 v192, v192
	v_pk_add_f32 v[120:121], v[120:121], 1.0 op_sel_hi:[1,0]
	v_rcp_f32_e32 v193, v193
	v_rcp_f32_e32 v120, v120
	v_rcp_f32_e32 v121, v121
	v_pk_mul_f32 v[114:115], v[114:115], v[192:193]
	s_nop 0
	v_cvt_pk_bf16_f32 v114, v114, v115
	v_pk_mul_f32 v[116:117], v[116:117], v[120:121]
	s_nop 0
	v_cvt_pk_bf16_f32 v115, v116, v117
	v_or_b32_e32 v116, s86, v212
	v_or_b32_e32 v116, s20, v116
	v_mov_b32_e32 v117, s75
	v_lshlrev_b64 v[116:117], 12, v[116:117]
	v_lshl_add_u64 v[116:117], v[154:155], 0, v[116:117]
	global_store_dwordx2 v[116:117], v[114:115], off sc1

.LBB0_2192:
	v_cndmask_b32_e64 v118, 0, v82, s[4:5]
	v_cndmask_b32_e64 v119, 0, v83, s[4:5]
	v_cndmask_b32_e64 v120, 0, v84, s[4:5]
	v_cndmask_b32_e64 v121, 0, v85, s[4:5]
	s_mov_b64 s[72:73], -1
	s_and_b64 vcc, exec, s[14:15]
	v_mfma_f32_16x16x32_bf16 v[90:93], v[2:5], v[118:121], 0
	v_mfma_f32_16x16x32_bf16 v[94:97], v[6:9], v[118:121], 0
	v_mfma_f32_16x16x32_bf16 v[98:101], v[10:13], v[118:121], 0
	s_nop 5
	ds_write_b128 v202, v[90:93]
	v_mfma_f32_16x16x32_bf16 v[102:105], v[14:17], v[118:121], 0
	ds_write_b128 v202, v[94:97] offset:64
	ds_write_b128 v202, v[98:101] offset:128
	s_nop 5
	ds_write_b128 v202, v[102:105] offset:192
	v_mfma_f32_16x16x32_bf16 v[106:109], v[18:21], v[118:121], 0
	v_mfma_f32_16x16x32_bf16 v[90:93], v[22:25], v[118:121], 0
	v_mfma_f32_16x16x32_bf16 v[94:97], v[26:29], v[118:121], 0
	s_nop 5
	ds_write_b128 v202, v[106:109] offset:256
	ds_write_b128 v202, v[90:93] offset:320
	ds_write_b128 v202, v[94:97] offset:384
	v_mfma_f32_16x16x32_bf16 v[90:93], v[30:33], v[118:121], 0
	s_nop 7
	ds_write_b128 v202, v[90:93] offset:448
	s_waitcnt lgkmcnt(0)
	ds_read2_b64 v[230:233], v203 offset1:66
	ds_read2_b64 v[114:117], v203 offset0:132 offset1:198
	ds_read2_b64 v[110:113], v227 offset0:8 offset1:74
	ds_read2_b64 v[106:109], v227 offset0:140 offset1:206
	ds_read2_b64 v[102:105], v228 offset0:16 offset1:82
	ds_read2_b64 v[98:101], v228 offset0:148 offset1:214
	ds_read2_b64 v[94:97], v229 offset0:24 offset1:90
	ds_read2_b64 v[90:93], v229 offset0:156 offset1:222
	s_waitcnt lgkmcnt(0)
	s_waitcnt lgkmcnt(7)
	v_pk_fma_f32 v[192:193], v[146:147], v[190:191], v[230:231] op_sel:[0,1,0] op_sel_hi:[1,0,1]
	s_nop 0
	v_pk_fma_f32 v[194:195], v[150:151], v[190:191], v[192:193]
	s_nop 0
	v_pk_fma_f32 v[190:191], v[146:147], v[194:195], v[232:233] op_sel:[0,1,0] op_sel_hi:[1,0,1]
	s_nop 0
	v_pk_fma_f32 v[190:191], v[150:151], v[194:195], v[190:191]
	s_cbranch_vccnz .LBB0_2194
	s_waitcnt lgkmcnt(6)
	v_pk_fma_f32 v[192:193], v[146:147], v[190:191], v[114:115] op_sel:[0,1,0] op_sel_hi:[1,0,1]
	v_cvt_pk_bf16_f32 v230, v194, v195
	v_cvt_pk_bf16_f32 v231, v190, v191
	v_mfma_f32_16x16x32_bf16 v[118:121], v[34:37], v[118:121], 0
	v_fma_f32 v192, v150, v190, v192
	v_fma_f32 v193, v151, v191, v193
	s_mov_b64 s[72:73], 0
	v_pk_fma_f32 v[194:195], v[146:147], v[192:193], v[116:117] op_sel:[0,1,0] op_sel_hi:[1,0,1]
	v_cvt_pk_bf16_f32 v232, v192, v193
	s_nop 0
	v_pk_fma_f32 v[192:193], v[150:151], v[192:193], v[194:195]
	s_waitcnt lgkmcnt(5)
	v_pk_fma_f32 v[194:195], v[146:147], v[192:193], v[110:111] op_sel:[0,1,0] op_sel_hi:[1,0,1]
	v_cvt_pk_bf16_f32 v233, v192, v193
	s_nop 0
	v_pk_fma_f32 v[192:193], v[150:151], v[192:193], v[194:195]
	s_nop 0
	v_pk_fma_f32 v[194:195], v[146:147], v[192:193], v[112:113] op_sel:[0,1,0] op_sel_hi:[1,0,1]
	v_cvt_pk_bf16_f32 v234, v192, v193
	s_nop 0
	v_pk_fma_f32 v[192:193], v[150:151], v[192:193], v[194:195]
	s_waitcnt lgkmcnt(4)
	v_pk_fma_f32 v[194:195], v[146:147], v[192:193], v[106:107] op_sel:[0,1,0] op_sel_hi:[1,0,1]
	v_cvt_pk_bf16_f32 v235, v192, v193
	s_nop 0
	v_pk_fma_f32 v[192:193], v[150:151], v[192:193], v[194:195]
	s_nop 0
	v_pk_fma_f32 v[194:195], v[146:147], v[192:193], v[108:109] op_sel:[0,1,0] op_sel_hi:[1,0,1]
	v_cvt_pk_bf16_f32 v236, v192, v193
	s_nop 0
	v_pk_fma_f32 v[192:193], v[150:151], v[192:193], v[194:195]
	s_waitcnt lgkmcnt(3)
	v_pk_fma_f32 v[194:195], v[146:147], v[192:193], v[102:103] op_sel:[0,1,0] op_sel_hi:[1,0,1]
	v_cvt_pk_bf16_f32 v237, v192, v193
	s_nop 0
	v_pk_fma_f32 v[192:193], v[150:151], v[192:193], v[194:195]
	s_nop 0
	v_pk_fma_f32 v[194:195], v[146:147], v[192:193], v[104:105] op_sel:[0,1,0] op_sel_hi:[1,0,1]
	v_cvt_pk_bf16_f32 v238, v192, v193
	s_nop 0
	v_pk_fma_f32 v[192:193], v[150:151], v[192:193], v[194:195]
	s_waitcnt lgkmcnt(2)
	v_pk_fma_f32 v[194:195], v[146:147], v[192:193], v[98:99] op_sel:[0,1,0] op_sel_hi:[1,0,1]
	v_cvt_pk_bf16_f32 v239, v192, v193
	s_nop 0
	v_pk_fma_f32 v[192:193], v[150:151], v[192:193], v[194:195]
	s_nop 0
	v_pk_fma_f32 v[194:195], v[146:147], v[192:193], v[100:101] op_sel:[0,1,0] op_sel_hi:[1,0,1]
	v_cvt_pk_bf16_f32 v240, v192, v193
	s_nop 0
	v_pk_fma_f32 v[192:193], v[150:151], v[192:193], v[194:195]
	s_waitcnt lgkmcnt(1)
	v_pk_fma_f32 v[194:195], v[146:147], v[192:193], v[94:95] op_sel:[0,1,0] op_sel_hi:[1,0,1]
	v_cvt_pk_bf16_f32 v241, v192, v193
	s_nop 0
	v_pk_fma_f32 v[192:193], v[150:151], v[192:193], v[194:195]
	s_nop 0
	v_pk_fma_f32 v[194:195], v[146:147], v[192:193], v[96:97] op_sel:[0,1,0] op_sel_hi:[1,0,1]
	v_cvt_pk_bf16_f32 v242, v192, v193
	s_nop 0
	v_pk_fma_f32 v[192:193], v[150:151], v[192:193], v[194:195]
	s_waitcnt lgkmcnt(0)
	v_pk_fma_f32 v[194:195], v[146:147], v[192:193], v[90:91] op_sel:[0,1,0] op_sel_hi:[1,0,1]
	v_cvt_pk_bf16_f32 v243, v192, v193
	s_nop 0
	v_pk_fma_f32 v[192:193], v[150:151], v[192:193], v[194:195]
	s_nop 0
	v_pk_fma_f32 v[194:195], v[146:147], v[192:193], v[92:93] op_sel:[0,1,0] op_sel_hi:[1,0,1]
	v_cvt_pk_bf16_f32 v244, v192, v193
	s_nop 0
	v_pk_fma_f32 v[192:193], v[150:151], v[192:193], v[194:195]
	s_nop 0
	v_cvt_pk_bf16_f32 v194, v192, v193
	ds_write2_b32 v123, v230, v231 offset0:64 offset1:132
	ds_write2_b32 v137, v232, v233 offset0:72 offset1:140
	ds_write2_b32 v139, v234, v235 offset0:80 offset1:148
	ds_write2_b32 v141, v236, v237 offset0:88 offset1:156
	ds_write2_b32 v143, v238, v239 offset0:96 offset1:164
	ds_write2_b32 v149, v240, v241 offset0:104 offset1:172
	ds_write2_b32 v225, v242, v243 offset0:112 offset1:180
	ds_write2_b32 v226, v244, v194 offset0:120 offset1:188
	s_waitcnt lgkmcnt(0)
	ds_read_b128 v[230:233], v224 offset:8448
	ds_read_b128 v[234:237], v224 offset:8512
	s_waitcnt lgkmcnt(0)
	v_mfma_f32_16x16x32_bf16 v[118:121], v[42:45], v[234:237], v[118:121]
	ds_read_b128 v[234:237], v224 offset:8576
	v_mfma_f32_16x16x32_bf16 v[230:233], v[38:41], v[230:233], 0
	s_waitcnt lgkmcnt(0)
	v_mfma_f32_16x16x32_bf16 v[230:233], v[46:49], v[234:237], v[230:233]
	ds_read_b128 v[234:237], v224 offset:8640
	s_waitcnt lgkmcnt(0)
	v_mfma_f32_16x16x32_bf16 v[118:121], v[50:53], v[234:237], v[118:121]
	s_nop 7
	v_pk_add_f32 v[120:121], v[232:233], v[120:121]
	v_pk_add_f32 v[118:119], v[230:231], v[118:119]
	v_pk_mul_f32 v[194:195], v[120:121], v[120:121]
	v_pk_mul_f32 v[230:231], v[118:119], v[118:119]
	v_mov_b64_e32 v[232:233], s[48:49]
	v_pk_fma_f32 v[230:231], v[230:231], s[46:47], v[232:233] op_sel_hi:[1,0,0] neg_lo:[1,0,0] neg_hi:[1,0,0]
	v_pk_fma_f32 v[194:195], v[194:195], s[46:47], v[232:233] op_sel_hi:[1,0,0] neg_lo:[1,0,0] neg_hi:[1,0,0]
	v_pk_mul_f32 v[230:231], v[118:119], v[230:231]
	v_pk_mul_f32 v[194:195], v[120:121], v[194:195]
	v_exp_f32_e32 v230, v230
	v_exp_f32_e32 v231, v231
	v_exp_f32_e32 v194, v194
	v_exp_f32_e32 v195, v195
	v_pk_add_f32 v[230:231], v[230:231], 1.0 op_sel_hi:[1,0]
	s_nop 0
	v_rcp_f32_e32 v230, v230
	v_pk_add_f32 v[194:195], v[194:195], 1.0 op_sel_hi:[1,0]
	v_rcp_f32_e32 v231, v231
	v_rcp_f32_e32 v194, v194
	v_rcp_f32_e32 v195, v195
	v_pk_mul_f32 v[118:119], v[118:119], v[230:231]
	s_nop 0
	v_cvt_pk_bf16_f32 v118, v118, v119
	v_pk_mul_f32 v[120:121], v[120:121], v[194:195]
	s_nop 0
	v_cvt_pk_bf16_f32 v119, v120, v121
	v_or_b32_e32 v120, s86, v213
	v_or_b32_e32 v120, s20, v120
	v_mov_b32_e32 v121, s75
	v_lshlrev_b64 v[120:121], 12, v[120:121]
	v_lshl_add_u64 v[120:121], v[154:155], 0, v[120:121]
	global_store_dwordx2 v[120:121], v[118:119], off sc1

.LBB0_2196:
	s_waitcnt lgkmcnt(6)
	v_cndmask_b32_e64 v114, v82, 0, s[4:5]
	v_cndmask_b32_e64 v115, v83, 0, s[4:5]
	v_cndmask_b32_e64 v116, v84, 0, s[4:5]
	v_cndmask_b32_e64 v117, v85, 0, s[4:5]
	s_waitcnt lgkmcnt(0)
	s_mov_b64 s[72:73], -1
	s_and_b64 vcc, exec, s[14:15]
	v_mfma_f32_16x16x32_bf16 v[82:85], v[2:5], v[114:117], 0
	s_waitcnt lgkmcnt(0)
	v_mfma_f32_16x16x32_bf16 v[90:93], v[6:9], v[114:117], 0
	v_mfma_f32_16x16x32_bf16 v[94:97], v[10:13], v[114:117], 0
	s_nop 4
	ds_write_b128 v202, v[82:85]
	v_mfma_f32_16x16x32_bf16 v[98:101], v[14:17], v[114:117], 0
	ds_write_b128 v202, v[90:93] offset:64
	ds_write_b128 v202, v[94:97] offset:128
	s_nop 5
	ds_write_b128 v202, v[98:101] offset:192
	v_mfma_f32_16x16x32_bf16 v[102:105], v[18:21], v[114:117], 0
	v_mfma_f32_16x16x32_bf16 v[82:85], v[22:25], v[114:117], 0
	v_mfma_f32_16x16x32_bf16 v[90:93], v[26:29], v[114:117], 0
	s_nop 5
	ds_write_b128 v202, v[102:105] offset:256
	ds_write_b128 v202, v[82:85] offset:320
	ds_write_b128 v202, v[90:93] offset:384
	v_mfma_f32_16x16x32_bf16 v[82:85], v[30:33], v[114:117], 0
	s_nop 7
	ds_write_b128 v202, v[82:85] offset:448
	s_waitcnt lgkmcnt(0)
	ds_read2_b64 v[230:233], v203 offset1:66
	ds_read2_b64 v[110:113], v203 offset0:132 offset1:198
	ds_read2_b64 v[106:109], v227 offset0:8 offset1:74
	ds_read2_b64 v[102:105], v227 offset0:140 offset1:206
	ds_read2_b64 v[98:101], v228 offset0:16 offset1:82
	ds_read2_b64 v[94:97], v228 offset0:148 offset1:214
	ds_read2_b64 v[90:93], v229 offset0:24 offset1:90
	ds_read2_b64 v[82:85], v229 offset0:156 offset1:222
	s_waitcnt lgkmcnt(0)
	s_waitcnt lgkmcnt(7)
	v_pk_fma_f32 v[118:119], v[146:147], v[192:193], v[230:231] op_sel:[0,1,0] op_sel_hi:[1,0,1]
	s_nop 0
	v_pk_fma_f32 v[120:121], v[150:151], v[192:193], v[118:119]
	s_nop 0
	v_pk_fma_f32 v[118:119], v[146:147], v[120:121], v[232:233] op_sel:[0,1,0] op_sel_hi:[1,0,1]
	s_nop 0
	v_pk_fma_f32 v[118:119], v[150:151], v[120:121], v[118:119]
	s_cbranch_vccnz .LBB0_2198
	v_cvt_pk_bf16_f32 v192, v120, v121
	s_waitcnt lgkmcnt(6)
	v_pk_fma_f32 v[120:121], v[146:147], v[118:119], v[110:111] op_sel:[0,1,0] op_sel_hi:[1,0,1]
	v_cvt_pk_bf16_f32 v193, v118, v119
	v_mfma_f32_16x16x32_bf16 v[114:117], v[34:37], v[114:117], 0
	v_fma_f32 v120, v150, v118, v120
	v_fma_f32 v121, v151, v119, v121
	s_mov_b64 s[72:73], 0
	v_pk_fma_f32 v[190:191], v[146:147], v[120:121], v[112:113] op_sel:[0,1,0] op_sel_hi:[1,0,1]
	v_cvt_pk_bf16_f32 v194, v120, v121
	s_nop 0
	v_pk_fma_f32 v[120:121], v[150:151], v[120:121], v[190:191]
	s_waitcnt lgkmcnt(5)
	v_pk_fma_f32 v[190:191], v[146:147], v[120:121], v[106:107] op_sel:[0,1,0] op_sel_hi:[1,0,1]
	v_cvt_pk_bf16_f32 v195, v120, v121
	s_nop 0
	v_pk_fma_f32 v[120:121], v[150:151], v[120:121], v[190:191]
	s_nop 0
	v_pk_fma_f32 v[190:191], v[146:147], v[120:121], v[108:109] op_sel:[0,1,0] op_sel_hi:[1,0,1]
	v_cvt_pk_bf16_f32 v230, v120, v121
	s_nop 0
	v_pk_fma_f32 v[120:121], v[150:151], v[120:121], v[190:191]
	s_waitcnt lgkmcnt(4)
	v_pk_fma_f32 v[190:191], v[146:147], v[120:121], v[102:103] op_sel:[0,1,0] op_sel_hi:[1,0,1]
	v_cvt_pk_bf16_f32 v231, v120, v121
	s_nop 0
	v_pk_fma_f32 v[120:121], v[150:151], v[120:121], v[190:191]
	s_nop 0
	v_pk_fma_f32 v[190:191], v[146:147], v[120:121], v[104:105] op_sel:[0,1,0] op_sel_hi:[1,0,1]
	v_cvt_pk_bf16_f32 v232, v120, v121
	s_nop 0
	v_pk_fma_f32 v[120:121], v[150:151], v[120:121], v[190:191]
	s_waitcnt lgkmcnt(3)
	v_pk_fma_f32 v[190:191], v[146:147], v[120:121], v[98:99] op_sel:[0,1,0] op_sel_hi:[1,0,1]
	v_cvt_pk_bf16_f32 v233, v120, v121
	s_nop 0
	v_pk_fma_f32 v[120:121], v[150:151], v[120:121], v[190:191]
	s_nop 0
	v_pk_fma_f32 v[190:191], v[146:147], v[120:121], v[100:101] op_sel:[0,1,0] op_sel_hi:[1,0,1]
	v_cvt_pk_bf16_f32 v234, v120, v121
	s_nop 0
	v_pk_fma_f32 v[120:121], v[150:151], v[120:121], v[190:191]
	s_waitcnt lgkmcnt(2)
	v_pk_fma_f32 v[190:191], v[146:147], v[120:121], v[94:95] op_sel:[0,1,0] op_sel_hi:[1,0,1]
	v_cvt_pk_bf16_f32 v235, v120, v121
	s_nop 0
	v_pk_fma_f32 v[120:121], v[150:151], v[120:121], v[190:191]
	s_nop 0
	v_pk_fma_f32 v[190:191], v[146:147], v[120:121], v[96:97] op_sel:[0,1,0] op_sel_hi:[1,0,1]
	v_cvt_pk_bf16_f32 v236, v120, v121
	s_nop 0
	v_pk_fma_f32 v[120:121], v[150:151], v[120:121], v[190:191]
	s_waitcnt lgkmcnt(1)
	v_pk_fma_f32 v[190:191], v[146:147], v[120:121], v[90:91] op_sel:[0,1,0] op_sel_hi:[1,0,1]
	v_cvt_pk_bf16_f32 v237, v120, v121
	s_nop 0
	v_pk_fma_f32 v[120:121], v[150:151], v[120:121], v[190:191]
	s_nop 0
	v_pk_fma_f32 v[190:191], v[146:147], v[120:121], v[92:93] op_sel:[0,1,0] op_sel_hi:[1,0,1]
	v_cvt_pk_bf16_f32 v238, v120, v121
	s_nop 0
	v_pk_fma_f32 v[120:121], v[150:151], v[120:121], v[190:191]
	s_waitcnt lgkmcnt(0)
	v_pk_fma_f32 v[190:191], v[146:147], v[120:121], v[82:83] op_sel:[0,1,0] op_sel_hi:[1,0,1]
	v_cvt_pk_bf16_f32 v239, v120, v121
	s_nop 0
	v_pk_fma_f32 v[120:121], v[150:151], v[120:121], v[190:191]
	s_nop 0
	v_pk_fma_f32 v[190:191], v[146:147], v[120:121], v[84:85] op_sel:[0,1,0] op_sel_hi:[1,0,1]
	v_cvt_pk_bf16_f32 v240, v120, v121
	s_nop 0
	v_pk_fma_f32 v[190:191], v[150:151], v[120:121], v[190:191]
	s_nop 0
	v_cvt_pk_bf16_f32 v120, v190, v191
	ds_write2_b32 v123, v192, v193 offset0:64 offset1:132
	ds_write2_b32 v137, v194, v195 offset0:72 offset1:140
	ds_write2_b32 v139, v230, v231 offset0:80 offset1:148
	ds_write2_b32 v141, v232, v233 offset0:88 offset1:156
	ds_write2_b32 v143, v234, v235 offset0:96 offset1:164
	ds_write2_b32 v149, v236, v237 offset0:104 offset1:172
	ds_write2_b32 v225, v238, v239 offset0:112 offset1:180
	ds_write2_b32 v226, v240, v120 offset0:120 offset1:188
	s_waitcnt lgkmcnt(0)
	ds_read_b128 v[192:195], v224 offset:8448
	ds_read_b128 v[230:233], v224 offset:8512
	s_waitcnt lgkmcnt(0)
	v_mfma_f32_16x16x32_bf16 v[114:117], v[42:45], v[230:233], v[114:117]
	ds_read_b128 v[230:233], v224 offset:8576
	v_mfma_f32_16x16x32_bf16 v[192:195], v[38:41], v[192:195], 0
	s_waitcnt lgkmcnt(0)
	v_mfma_f32_16x16x32_bf16 v[192:195], v[46:49], v[230:233], v[192:195]
	ds_read_b128 v[230:233], v224 offset:8640
	s_waitcnt lgkmcnt(0)
	v_mfma_f32_16x16x32_bf16 v[114:117], v[50:53], v[230:233], v[114:117]
	s_nop 7
	v_pk_add_f32 v[116:117], v[194:195], v[116:117]
	v_pk_add_f32 v[114:115], v[192:193], v[114:115]
	v_pk_mul_f32 v[120:121], v[116:117], v[116:117]
	v_pk_mul_f32 v[192:193], v[114:115], v[114:115]
	v_mov_b64_e32 v[194:195], s[48:49]
	v_pk_fma_f32 v[192:193], v[192:193], s[46:47], v[194:195] op_sel_hi:[1,0,0] neg_lo:[1,0,0] neg_hi:[1,0,0]
	v_pk_fma_f32 v[120:121], v[120:121], s[46:47], v[194:195] op_sel_hi:[1,0,0] neg_lo:[1,0,0] neg_hi:[1,0,0]
	v_pk_mul_f32 v[192:193], v[114:115], v[192:193]
	v_pk_mul_f32 v[120:121], v[116:117], v[120:121]
	v_exp_f32_e32 v192, v192
	v_exp_f32_e32 v193, v193
	v_exp_f32_e32 v120, v120
	v_exp_f32_e32 v121, v121
	v_pk_add_f32 v[192:193], v[192:193], 1.0 op_sel_hi:[1,0]
	s_nop 0
	v_rcp_f32_e32 v192, v192
	v_pk_add_f32 v[120:121], v[120:121], 1.0 op_sel_hi:[1,0]
	v_rcp_f32_e32 v193, v193
	v_rcp_f32_e32 v120, v120
	v_rcp_f32_e32 v121, v121
	v_pk_mul_f32 v[114:115], v[114:115], v[192:193]
	s_nop 0
	v_cvt_pk_bf16_f32 v114, v114, v115
	v_pk_mul_f32 v[116:117], v[116:117], v[120:121]
	s_nop 0
	v_cvt_pk_bf16_f32 v115, v116, v117
	v_or_b32_e32 v116, s86, v214
	v_or_b32_e32 v116, s20, v116
	v_mov_b32_e32 v117, s75
	v_lshlrev_b64 v[116:117], 12, v[116:117]
	v_lshl_add_u64 v[116:117], v[154:155], 0, v[116:117]
	global_store_dwordx2 v[116:117], v[114:115], off sc1

.LBB0_2202:
	v_cndmask_b32_e64 v118, 0, v74, s[4:5]
	v_cndmask_b32_e64 v119, 0, v75, s[4:5]
	v_cndmask_b32_e64 v120, 0, v76, s[4:5]
	v_cndmask_b32_e64 v121, 0, v77, s[4:5]
	s_mov_b64 s[72:73], -1
	s_and_b64 vcc, exec, s[14:15]
	v_mfma_f32_16x16x32_bf16 v[90:93], v[2:5], v[118:121], 0
	v_mfma_f32_16x16x32_bf16 v[94:97], v[6:9], v[118:121], 0
	v_mfma_f32_16x16x32_bf16 v[98:101], v[10:13], v[118:121], 0
	s_nop 5
	ds_write_b128 v202, v[90:93]
	v_mfma_f32_16x16x32_bf16 v[102:105], v[14:17], v[118:121], 0
	ds_write_b128 v202, v[94:97] offset:64
	ds_write_b128 v202, v[98:101] offset:128
	s_nop 5
	ds_write_b128 v202, v[102:105] offset:192
	v_mfma_f32_16x16x32_bf16 v[106:109], v[18:21], v[118:121], 0
	v_mfma_f32_16x16x32_bf16 v[90:93], v[22:25], v[118:121], 0
	v_mfma_f32_16x16x32_bf16 v[94:97], v[26:29], v[118:121], 0
	s_nop 5
	ds_write_b128 v202, v[106:109] offset:256
	ds_write_b128 v202, v[90:93] offset:320
	ds_write_b128 v202, v[94:97] offset:384
	v_mfma_f32_16x16x32_bf16 v[90:93], v[30:33], v[118:121], 0
	s_nop 7
	ds_write_b128 v202, v[90:93] offset:448
	s_waitcnt lgkmcnt(0)
	ds_read2_b64 v[230:233], v203 offset1:66
	ds_read2_b64 v[114:117], v203 offset0:132 offset1:198
	ds_read2_b64 v[110:113], v227 offset0:8 offset1:74
	ds_read2_b64 v[106:109], v227 offset0:140 offset1:206
	ds_read2_b64 v[102:105], v228 offset0:16 offset1:82
	ds_read2_b64 v[98:101], v228 offset0:148 offset1:214
	ds_read2_b64 v[94:97], v229 offset0:24 offset1:90
	ds_read2_b64 v[90:93], v229 offset0:156 offset1:222
	s_waitcnt lgkmcnt(0)
	s_waitcnt lgkmcnt(7)
	v_pk_fma_f32 v[192:193], v[146:147], v[190:191], v[230:231] op_sel:[0,1,0] op_sel_hi:[1,0,1]
	s_nop 0
	v_pk_fma_f32 v[194:195], v[150:151], v[190:191], v[192:193]
	s_nop 0
	v_pk_fma_f32 v[190:191], v[146:147], v[194:195], v[232:233] op_sel:[0,1,0] op_sel_hi:[1,0,1]
	s_nop 0
	v_pk_fma_f32 v[190:191], v[150:151], v[194:195], v[190:191]
	s_cbranch_vccnz .LBB0_2204
	s_waitcnt lgkmcnt(6)
	v_pk_fma_f32 v[192:193], v[146:147], v[190:191], v[114:115] op_sel:[0,1,0] op_sel_hi:[1,0,1]
	v_cvt_pk_bf16_f32 v230, v194, v195
	v_cvt_pk_bf16_f32 v231, v190, v191
	v_mfma_f32_16x16x32_bf16 v[118:121], v[34:37], v[118:121], 0
	v_fma_f32 v192, v150, v190, v192
	v_fma_f32 v193, v151, v191, v193
	s_mov_b64 s[72:73], 0
	v_pk_fma_f32 v[194:195], v[146:147], v[192:193], v[116:117] op_sel:[0,1,0] op_sel_hi:[1,0,1]
	v_cvt_pk_bf16_f32 v232, v192, v193
	s_nop 0
	v_pk_fma_f32 v[192:193], v[150:151], v[192:193], v[194:195]
	s_waitcnt lgkmcnt(5)
	v_pk_fma_f32 v[194:195], v[146:147], v[192:193], v[110:111] op_sel:[0,1,0] op_sel_hi:[1,0,1]
	v_cvt_pk_bf16_f32 v233, v192, v193
	s_nop 0
	v_pk_fma_f32 v[192:193], v[150:151], v[192:193], v[194:195]
	s_nop 0
	v_pk_fma_f32 v[194:195], v[146:147], v[192:193], v[112:113] op_sel:[0,1,0] op_sel_hi:[1,0,1]
	v_cvt_pk_bf16_f32 v234, v192, v193
	s_nop 0
	v_pk_fma_f32 v[192:193], v[150:151], v[192:193], v[194:195]
	s_waitcnt lgkmcnt(4)
	v_pk_fma_f32 v[194:195], v[146:147], v[192:193], v[106:107] op_sel:[0,1,0] op_sel_hi:[1,0,1]
	v_cvt_pk_bf16_f32 v235, v192, v193
	s_nop 0
	v_pk_fma_f32 v[192:193], v[150:151], v[192:193], v[194:195]
	s_nop 0
	v_pk_fma_f32 v[194:195], v[146:147], v[192:193], v[108:109] op_sel:[0,1,0] op_sel_hi:[1,0,1]
	v_cvt_pk_bf16_f32 v236, v192, v193
	s_nop 0
	v_pk_fma_f32 v[192:193], v[150:151], v[192:193], v[194:195]
	s_waitcnt lgkmcnt(3)
	v_pk_fma_f32 v[194:195], v[146:147], v[192:193], v[102:103] op_sel:[0,1,0] op_sel_hi:[1,0,1]
	v_cvt_pk_bf16_f32 v237, v192, v193
	s_nop 0
	v_pk_fma_f32 v[192:193], v[150:151], v[192:193], v[194:195]
	s_nop 0
	v_pk_fma_f32 v[194:195], v[146:147], v[192:193], v[104:105] op_sel:[0,1,0] op_sel_hi:[1,0,1]
	v_cvt_pk_bf16_f32 v238, v192, v193
	s_nop 0
	v_pk_fma_f32 v[192:193], v[150:151], v[192:193], v[194:195]
	s_waitcnt lgkmcnt(2)
	v_pk_fma_f32 v[194:195], v[146:147], v[192:193], v[98:99] op_sel:[0,1,0] op_sel_hi:[1,0,1]
	v_cvt_pk_bf16_f32 v239, v192, v193
	s_nop 0
	v_pk_fma_f32 v[192:193], v[150:151], v[192:193], v[194:195]
	s_nop 0
	v_pk_fma_f32 v[194:195], v[146:147], v[192:193], v[100:101] op_sel:[0,1,0] op_sel_hi:[1,0,1]
	v_cvt_pk_bf16_f32 v240, v192, v193
	s_nop 0
	v_pk_fma_f32 v[192:193], v[150:151], v[192:193], v[194:195]
	s_waitcnt lgkmcnt(1)
	v_pk_fma_f32 v[194:195], v[146:147], v[192:193], v[94:95] op_sel:[0,1,0] op_sel_hi:[1,0,1]
	v_cvt_pk_bf16_f32 v241, v192, v193
	s_nop 0
	v_pk_fma_f32 v[192:193], v[150:151], v[192:193], v[194:195]
	s_nop 0
	v_pk_fma_f32 v[194:195], v[146:147], v[192:193], v[96:97] op_sel:[0,1,0] op_sel_hi:[1,0,1]
	v_cvt_pk_bf16_f32 v242, v192, v193
	s_nop 0
	v_pk_fma_f32 v[192:193], v[150:151], v[192:193], v[194:195]
	s_waitcnt lgkmcnt(0)
	v_pk_fma_f32 v[194:195], v[146:147], v[192:193], v[90:91] op_sel:[0,1,0] op_sel_hi:[1,0,1]
	v_cvt_pk_bf16_f32 v243, v192, v193
	s_nop 0
	v_pk_fma_f32 v[192:193], v[150:151], v[192:193], v[194:195]
	s_nop 0
	v_pk_fma_f32 v[194:195], v[146:147], v[192:193], v[92:93] op_sel:[0,1,0] op_sel_hi:[1,0,1]
	v_cvt_pk_bf16_f32 v244, v192, v193
	s_nop 0
	v_pk_fma_f32 v[192:193], v[150:151], v[192:193], v[194:195]
	s_nop 0
	v_cvt_pk_bf16_f32 v194, v192, v193
	ds_write2_b32 v123, v230, v231 offset0:64 offset1:132
	ds_write2_b32 v137, v232, v233 offset0:72 offset1:140
	ds_write2_b32 v139, v234, v235 offset0:80 offset1:148
	ds_write2_b32 v141, v236, v237 offset0:88 offset1:156
	ds_write2_b32 v143, v238, v239 offset0:96 offset1:164
	ds_write2_b32 v149, v240, v241 offset0:104 offset1:172
	ds_write2_b32 v225, v242, v243 offset0:112 offset1:180
	ds_write2_b32 v226, v244, v194 offset0:120 offset1:188
	s_waitcnt lgkmcnt(0)
	ds_read_b128 v[230:233], v224 offset:8448
	ds_read_b128 v[234:237], v224 offset:8512
	s_waitcnt lgkmcnt(0)
	v_mfma_f32_16x16x32_bf16 v[118:121], v[42:45], v[234:237], v[118:121]
	ds_read_b128 v[234:237], v224 offset:8576
	v_mfma_f32_16x16x32_bf16 v[230:233], v[38:41], v[230:233], 0
	s_waitcnt lgkmcnt(0)
	v_mfma_f32_16x16x32_bf16 v[230:233], v[46:49], v[234:237], v[230:233]
	ds_read_b128 v[234:237], v224 offset:8640
	s_waitcnt lgkmcnt(0)
	v_mfma_f32_16x16x32_bf16 v[118:121], v[50:53], v[234:237], v[118:121]
	s_nop 7
	v_pk_add_f32 v[120:121], v[232:233], v[120:121]
	v_pk_add_f32 v[118:119], v[230:231], v[118:119]
	v_pk_mul_f32 v[194:195], v[120:121], v[120:121]
	v_pk_mul_f32 v[230:231], v[118:119], v[118:119]
	v_mov_b64_e32 v[232:233], s[48:49]
	v_pk_fma_f32 v[230:231], v[230:231], s[46:47], v[232:233] op_sel_hi:[1,0,0] neg_lo:[1,0,0] neg_hi:[1,0,0]
	v_pk_fma_f32 v[194:195], v[194:195], s[46:47], v[232:233] op_sel_hi:[1,0,0] neg_lo:[1,0,0] neg_hi:[1,0,0]
	v_pk_mul_f32 v[230:231], v[118:119], v[230:231]
	v_pk_mul_f32 v[194:195], v[120:121], v[194:195]
	v_exp_f32_e32 v230, v230
	v_exp_f32_e32 v231, v231
	v_exp_f32_e32 v194, v194
	v_exp_f32_e32 v195, v195
	v_pk_add_f32 v[230:231], v[230:231], 1.0 op_sel_hi:[1,0]
	s_nop 0
	v_rcp_f32_e32 v230, v230
	v_pk_add_f32 v[194:195], v[194:195], 1.0 op_sel_hi:[1,0]
	v_rcp_f32_e32 v231, v231
	v_rcp_f32_e32 v194, v194
	v_rcp_f32_e32 v195, v195
	v_pk_mul_f32 v[118:119], v[118:119], v[230:231]
	s_nop 0
	v_cvt_pk_bf16_f32 v118, v118, v119
	v_pk_mul_f32 v[120:121], v[120:121], v[194:195]
	s_nop 0
	v_cvt_pk_bf16_f32 v119, v120, v121
	v_or_b32_e32 v120, s86, v215
	v_or_b32_e32 v120, s20, v120
	v_mov_b32_e32 v121, s75
	v_lshlrev_b64 v[120:121], 12, v[120:121]
	v_lshl_add_u64 v[120:121], v[154:155], 0, v[120:121]
	global_store_dwordx2 v[120:121], v[118:119], off sc1

.LBB0_2206:
	s_waitcnt lgkmcnt(6)
	v_cndmask_b32_e64 v114, v74, 0, s[4:5]
	v_cndmask_b32_e64 v115, v75, 0, s[4:5]
	v_cndmask_b32_e64 v116, v76, 0, s[4:5]
	v_cndmask_b32_e64 v117, v77, 0, s[4:5]
	s_waitcnt lgkmcnt(0)
	s_mov_b64 s[72:73], -1
	s_and_b64 vcc, exec, s[14:15]
	v_mfma_f32_16x16x32_bf16 v[74:77], v[2:5], v[114:117], 0
	s_waitcnt lgkmcnt(0)
	v_mfma_f32_16x16x32_bf16 v[90:93], v[6:9], v[114:117], 0
	v_mfma_f32_16x16x32_bf16 v[94:97], v[10:13], v[114:117], 0
	s_nop 4
	ds_write_b128 v202, v[74:77]
	v_mfma_f32_16x16x32_bf16 v[98:101], v[14:17], v[114:117], 0
	ds_write_b128 v202, v[90:93] offset:64
	ds_write_b128 v202, v[94:97] offset:128
	s_nop 5
	ds_write_b128 v202, v[98:101] offset:192
	v_mfma_f32_16x16x32_bf16 v[102:105], v[18:21], v[114:117], 0
	v_mfma_f32_16x16x32_bf16 v[74:77], v[22:25], v[114:117], 0
	v_mfma_f32_16x16x32_bf16 v[90:93], v[26:29], v[114:117], 0
	s_nop 5
	ds_write_b128 v202, v[102:105] offset:256
	ds_write_b128 v202, v[74:77] offset:320
	ds_write_b128 v202, v[90:93] offset:384
	v_mfma_f32_16x16x32_bf16 v[74:77], v[30:33], v[114:117], 0
	s_nop 7
	ds_write_b128 v202, v[74:77] offset:448
	s_waitcnt lgkmcnt(0)
	ds_read2_b64 v[230:233], v203 offset1:66
	ds_read2_b64 v[110:113], v203 offset0:132 offset1:198
	ds_read2_b64 v[106:109], v227 offset0:8 offset1:74
	ds_read2_b64 v[102:105], v227 offset0:140 offset1:206
	ds_read2_b64 v[98:101], v228 offset0:16 offset1:82
	ds_read2_b64 v[94:97], v228 offset0:148 offset1:214
	ds_read2_b64 v[90:93], v229 offset0:24 offset1:90
	ds_read2_b64 v[74:77], v229 offset0:156 offset1:222
	s_waitcnt lgkmcnt(0)
	s_waitcnt lgkmcnt(7)
	v_pk_fma_f32 v[118:119], v[146:147], v[192:193], v[230:231] op_sel:[0,1,0] op_sel_hi:[1,0,1]
	s_nop 0
	v_pk_fma_f32 v[120:121], v[150:151], v[192:193], v[118:119]
	s_nop 0
	v_pk_fma_f32 v[118:119], v[146:147], v[120:121], v[232:233] op_sel:[0,1,0] op_sel_hi:[1,0,1]
	s_nop 0
	v_pk_fma_f32 v[118:119], v[150:151], v[120:121], v[118:119]
	s_cbranch_vccnz .LBB0_2208
	v_cvt_pk_bf16_f32 v192, v120, v121
	s_waitcnt lgkmcnt(6)
	v_pk_fma_f32 v[120:121], v[146:147], v[118:119], v[110:111] op_sel:[0,1,0] op_sel_hi:[1,0,1]
	v_cvt_pk_bf16_f32 v193, v118, v119
	v_mfma_f32_16x16x32_bf16 v[114:117], v[34:37], v[114:117], 0
	v_fma_f32 v120, v150, v118, v120
	v_fma_f32 v121, v151, v119, v121
	s_mov_b64 s[72:73], 0
	v_pk_fma_f32 v[190:191], v[146:147], v[120:121], v[112:113] op_sel:[0,1,0] op_sel_hi:[1,0,1]
	v_cvt_pk_bf16_f32 v194, v120, v121
	s_nop 0
	v_pk_fma_f32 v[120:121], v[150:151], v[120:121], v[190:191]
	s_waitcnt lgkmcnt(5)
	v_pk_fma_f32 v[190:191], v[146:147], v[120:121], v[106:107] op_sel:[0,1,0] op_sel_hi:[1,0,1]
	v_cvt_pk_bf16_f32 v195, v120, v121
	s_nop 0
	v_pk_fma_f32 v[120:121], v[150:151], v[120:121], v[190:191]
	s_nop 0
	v_pk_fma_f32 v[190:191], v[146:147], v[120:121], v[108:109] op_sel:[0,1,0] op_sel_hi:[1,0,1]
	v_cvt_pk_bf16_f32 v230, v120, v121
	s_nop 0
	v_pk_fma_f32 v[120:121], v[150:151], v[120:121], v[190:191]
	s_waitcnt lgkmcnt(4)
	v_pk_fma_f32 v[190:191], v[146:147], v[120:121], v[102:103] op_sel:[0,1,0] op_sel_hi:[1,0,1]
	v_cvt_pk_bf16_f32 v231, v120, v121
	s_nop 0
	v_pk_fma_f32 v[120:121], v[150:151], v[120:121], v[190:191]
	s_nop 0
	v_pk_fma_f32 v[190:191], v[146:147], v[120:121], v[104:105] op_sel:[0,1,0] op_sel_hi:[1,0,1]
	v_cvt_pk_bf16_f32 v232, v120, v121
	s_nop 0
	v_pk_fma_f32 v[120:121], v[150:151], v[120:121], v[190:191]
	s_waitcnt lgkmcnt(3)
	v_pk_fma_f32 v[190:191], v[146:147], v[120:121], v[98:99] op_sel:[0,1,0] op_sel_hi:[1,0,1]
	v_cvt_pk_bf16_f32 v233, v120, v121
	s_nop 0
	v_pk_fma_f32 v[120:121], v[150:151], v[120:121], v[190:191]
	s_nop 0
	v_pk_fma_f32 v[190:191], v[146:147], v[120:121], v[100:101] op_sel:[0,1,0] op_sel_hi:[1,0,1]
	v_cvt_pk_bf16_f32 v234, v120, v121
	s_nop 0
	v_pk_fma_f32 v[120:121], v[150:151], v[120:121], v[190:191]
	s_waitcnt lgkmcnt(2)
	v_pk_fma_f32 v[190:191], v[146:147], v[120:121], v[94:95] op_sel:[0,1,0] op_sel_hi:[1,0,1]
	v_cvt_pk_bf16_f32 v235, v120, v121
	s_nop 0
	v_pk_fma_f32 v[120:121], v[150:151], v[120:121], v[190:191]
	s_nop 0
	v_pk_fma_f32 v[190:191], v[146:147], v[120:121], v[96:97] op_sel:[0,1,0] op_sel_hi:[1,0,1]
	v_cvt_pk_bf16_f32 v236, v120, v121
	s_nop 0
	v_pk_fma_f32 v[120:121], v[150:151], v[120:121], v[190:191]
	s_waitcnt lgkmcnt(1)
	v_pk_fma_f32 v[190:191], v[146:147], v[120:121], v[90:91] op_sel:[0,1,0] op_sel_hi:[1,0,1]
	v_cvt_pk_bf16_f32 v237, v120, v121
	s_nop 0
	v_pk_fma_f32 v[120:121], v[150:151], v[120:121], v[190:191]
	s_nop 0
	v_pk_fma_f32 v[190:191], v[146:147], v[120:121], v[92:93] op_sel:[0,1,0] op_sel_hi:[1,0,1]
	v_cvt_pk_bf16_f32 v238, v120, v121
	s_nop 0
	v_pk_fma_f32 v[120:121], v[150:151], v[120:121], v[190:191]
	s_waitcnt lgkmcnt(0)
	v_pk_fma_f32 v[190:191], v[146:147], v[120:121], v[74:75] op_sel:[0,1,0] op_sel_hi:[1,0,1]
	v_cvt_pk_bf16_f32 v239, v120, v121
	s_nop 0
	v_pk_fma_f32 v[120:121], v[150:151], v[120:121], v[190:191]
	s_nop 0
	v_pk_fma_f32 v[190:191], v[146:147], v[120:121], v[76:77] op_sel:[0,1,0] op_sel_hi:[1,0,1]
	v_cvt_pk_bf16_f32 v240, v120, v121
	s_nop 0
	v_pk_fma_f32 v[190:191], v[150:151], v[120:121], v[190:191]
	s_nop 0
	v_cvt_pk_bf16_f32 v120, v190, v191
	ds_write2_b32 v123, v192, v193 offset0:64 offset1:132
	ds_write2_b32 v137, v194, v195 offset0:72 offset1:140
	ds_write2_b32 v139, v230, v231 offset0:80 offset1:148
	ds_write2_b32 v141, v232, v233 offset0:88 offset1:156
	ds_write2_b32 v143, v234, v235 offset0:96 offset1:164
	ds_write2_b32 v149, v236, v237 offset0:104 offset1:172
	ds_write2_b32 v225, v238, v239 offset0:112 offset1:180
	ds_write2_b32 v226, v240, v120 offset0:120 offset1:188
	s_waitcnt lgkmcnt(0)
	ds_read_b128 v[192:195], v224 offset:8448
	ds_read_b128 v[230:233], v224 offset:8512
	s_waitcnt lgkmcnt(0)
	v_mfma_f32_16x16x32_bf16 v[114:117], v[42:45], v[230:233], v[114:117]
	ds_read_b128 v[230:233], v224 offset:8576
	v_mfma_f32_16x16x32_bf16 v[192:195], v[38:41], v[192:195], 0
	s_waitcnt lgkmcnt(0)
	v_mfma_f32_16x16x32_bf16 v[192:195], v[46:49], v[230:233], v[192:195]
	ds_read_b128 v[230:233], v224 offset:8640
	s_waitcnt lgkmcnt(0)
	v_mfma_f32_16x16x32_bf16 v[114:117], v[50:53], v[230:233], v[114:117]
	s_nop 7
	v_pk_add_f32 v[116:117], v[194:195], v[116:117]
	v_pk_add_f32 v[114:115], v[192:193], v[114:115]
	v_pk_mul_f32 v[120:121], v[116:117], v[116:117]
	v_pk_mul_f32 v[192:193], v[114:115], v[114:115]
	v_mov_b64_e32 v[194:195], s[48:49]
	v_pk_fma_f32 v[192:193], v[192:193], s[46:47], v[194:195] op_sel_hi:[1,0,0] neg_lo:[1,0,0] neg_hi:[1,0,0]
	v_pk_fma_f32 v[120:121], v[120:121], s[46:47], v[194:195] op_sel_hi:[1,0,0] neg_lo:[1,0,0] neg_hi:[1,0,0]
	v_pk_mul_f32 v[192:193], v[114:115], v[192:193]
	v_pk_mul_f32 v[120:121], v[116:117], v[120:121]
	v_exp_f32_e32 v192, v192
	v_exp_f32_e32 v193, v193
	v_exp_f32_e32 v120, v120
	v_exp_f32_e32 v121, v121
	v_pk_add_f32 v[192:193], v[192:193], 1.0 op_sel_hi:[1,0]
	s_nop 0
	v_rcp_f32_e32 v192, v192
	v_pk_add_f32 v[120:121], v[120:121], 1.0 op_sel_hi:[1,0]
	v_rcp_f32_e32 v193, v193
	v_rcp_f32_e32 v120, v120
	v_rcp_f32_e32 v121, v121
	v_pk_mul_f32 v[114:115], v[114:115], v[192:193]
	s_nop 0
	v_cvt_pk_bf16_f32 v114, v114, v115
	v_pk_mul_f32 v[116:117], v[116:117], v[120:121]
	s_nop 0
	v_cvt_pk_bf16_f32 v115, v116, v117
	v_or_b32_e32 v116, s86, v216
	v_or_b32_e32 v116, s20, v116
	v_mov_b32_e32 v117, s75
	v_lshlrev_b64 v[116:117], 12, v[116:117]
	v_lshl_add_u64 v[116:117], v[154:155], 0, v[116:117]
	global_store_dwordx2 v[116:117], v[114:115], off sc1

.LBB0_2212:
	v_cndmask_b32_e64 v118, 0, v66, s[4:5]
	v_cndmask_b32_e64 v119, 0, v67, s[4:5]
	v_cndmask_b32_e64 v120, 0, v68, s[4:5]
	v_cndmask_b32_e64 v121, 0, v69, s[4:5]
	s_mov_b64 s[72:73], -1
	s_and_b64 vcc, exec, s[14:15]
	v_mfma_f32_16x16x32_bf16 v[90:93], v[2:5], v[118:121], 0
	v_mfma_f32_16x16x32_bf16 v[94:97], v[6:9], v[118:121], 0
	v_mfma_f32_16x16x32_bf16 v[98:101], v[10:13], v[118:121], 0
	s_nop 5
	ds_write_b128 v202, v[90:93]
	v_mfma_f32_16x16x32_bf16 v[102:105], v[14:17], v[118:121], 0
	ds_write_b128 v202, v[94:97] offset:64
	ds_write_b128 v202, v[98:101] offset:128
	s_nop 5
	ds_write_b128 v202, v[102:105] offset:192
	v_mfma_f32_16x16x32_bf16 v[106:109], v[18:21], v[118:121], 0
	v_mfma_f32_16x16x32_bf16 v[90:93], v[22:25], v[118:121], 0
	v_mfma_f32_16x16x32_bf16 v[94:97], v[26:29], v[118:121], 0
	s_nop 5
	ds_write_b128 v202, v[106:109] offset:256
	ds_write_b128 v202, v[90:93] offset:320
	ds_write_b128 v202, v[94:97] offset:384
	v_mfma_f32_16x16x32_bf16 v[90:93], v[30:33], v[118:121], 0
	s_nop 7
	ds_write_b128 v202, v[90:93] offset:448
	s_waitcnt lgkmcnt(0)
	ds_read2_b64 v[230:233], v203 offset1:66
	ds_read2_b64 v[114:117], v203 offset0:132 offset1:198
	ds_read2_b64 v[110:113], v227 offset0:8 offset1:74
	ds_read2_b64 v[106:109], v227 offset0:140 offset1:206
	ds_read2_b64 v[102:105], v228 offset0:16 offset1:82
	ds_read2_b64 v[98:101], v228 offset0:148 offset1:214
	ds_read2_b64 v[94:97], v229 offset0:24 offset1:90
	ds_read2_b64 v[90:93], v229 offset0:156 offset1:222
	s_waitcnt lgkmcnt(0)
	s_waitcnt lgkmcnt(7)
	v_pk_fma_f32 v[192:193], v[146:147], v[190:191], v[230:231] op_sel:[0,1,0] op_sel_hi:[1,0,1]
	s_nop 0
	v_pk_fma_f32 v[194:195], v[150:151], v[190:191], v[192:193]
	s_nop 0
	v_pk_fma_f32 v[190:191], v[146:147], v[194:195], v[232:233] op_sel:[0,1,0] op_sel_hi:[1,0,1]
	s_nop 0
	v_pk_fma_f32 v[190:191], v[150:151], v[194:195], v[190:191]
	s_cbranch_vccnz .LBB0_2214
	s_waitcnt lgkmcnt(6)
	v_pk_fma_f32 v[192:193], v[146:147], v[190:191], v[114:115] op_sel:[0,1,0] op_sel_hi:[1,0,1]
	v_cvt_pk_bf16_f32 v230, v194, v195
	v_cvt_pk_bf16_f32 v231, v190, v191
	v_mfma_f32_16x16x32_bf16 v[118:121], v[34:37], v[118:121], 0
	v_fma_f32 v192, v150, v190, v192
	v_fma_f32 v193, v151, v191, v193
	s_mov_b64 s[72:73], 0
	v_pk_fma_f32 v[194:195], v[146:147], v[192:193], v[116:117] op_sel:[0,1,0] op_sel_hi:[1,0,1]
	v_cvt_pk_bf16_f32 v232, v192, v193
	s_nop 0
	v_pk_fma_f32 v[192:193], v[150:151], v[192:193], v[194:195]
	s_waitcnt lgkmcnt(5)
	v_pk_fma_f32 v[194:195], v[146:147], v[192:193], v[110:111] op_sel:[0,1,0] op_sel_hi:[1,0,1]
	v_cvt_pk_bf16_f32 v233, v192, v193
	s_nop 0
	v_pk_fma_f32 v[192:193], v[150:151], v[192:193], v[194:195]
	s_nop 0
	v_pk_fma_f32 v[194:195], v[146:147], v[192:193], v[112:113] op_sel:[0,1,0] op_sel_hi:[1,0,1]
	v_cvt_pk_bf16_f32 v234, v192, v193
	s_nop 0
	v_pk_fma_f32 v[192:193], v[150:151], v[192:193], v[194:195]
	s_waitcnt lgkmcnt(4)
	v_pk_fma_f32 v[194:195], v[146:147], v[192:193], v[106:107] op_sel:[0,1,0] op_sel_hi:[1,0,1]
	v_cvt_pk_bf16_f32 v235, v192, v193
	s_nop 0
	v_pk_fma_f32 v[192:193], v[150:151], v[192:193], v[194:195]
	s_nop 0
	v_pk_fma_f32 v[194:195], v[146:147], v[192:193], v[108:109] op_sel:[0,1,0] op_sel_hi:[1,0,1]
	v_cvt_pk_bf16_f32 v236, v192, v193
	s_nop 0
	v_pk_fma_f32 v[192:193], v[150:151], v[192:193], v[194:195]
	s_waitcnt lgkmcnt(3)
	v_pk_fma_f32 v[194:195], v[146:147], v[192:193], v[102:103] op_sel:[0,1,0] op_sel_hi:[1,0,1]
	v_cvt_pk_bf16_f32 v237, v192, v193
	s_nop 0
	v_pk_fma_f32 v[192:193], v[150:151], v[192:193], v[194:195]
	s_nop 0
	v_pk_fma_f32 v[194:195], v[146:147], v[192:193], v[104:105] op_sel:[0,1,0] op_sel_hi:[1,0,1]
	v_cvt_pk_bf16_f32 v238, v192, v193
	s_nop 0
	v_pk_fma_f32 v[192:193], v[150:151], v[192:193], v[194:195]
	s_waitcnt lgkmcnt(2)
	v_pk_fma_f32 v[194:195], v[146:147], v[192:193], v[98:99] op_sel:[0,1,0] op_sel_hi:[1,0,1]
	v_cvt_pk_bf16_f32 v239, v192, v193
	s_nop 0
	v_pk_fma_f32 v[192:193], v[150:151], v[192:193], v[194:195]
	s_nop 0
	v_pk_fma_f32 v[194:195], v[146:147], v[192:193], v[100:101] op_sel:[0,1,0] op_sel_hi:[1,0,1]
	v_cvt_pk_bf16_f32 v240, v192, v193
	s_nop 0
	v_pk_fma_f32 v[192:193], v[150:151], v[192:193], v[194:195]
	s_waitcnt lgkmcnt(1)
	v_pk_fma_f32 v[194:195], v[146:147], v[192:193], v[94:95] op_sel:[0,1,0] op_sel_hi:[1,0,1]
	v_cvt_pk_bf16_f32 v241, v192, v193
	s_nop 0
	v_pk_fma_f32 v[192:193], v[150:151], v[192:193], v[194:195]
	s_nop 0
	v_pk_fma_f32 v[194:195], v[146:147], v[192:193], v[96:97] op_sel:[0,1,0] op_sel_hi:[1,0,1]
	v_cvt_pk_bf16_f32 v242, v192, v193
	s_nop 0
	v_pk_fma_f32 v[192:193], v[150:151], v[192:193], v[194:195]
	s_waitcnt lgkmcnt(0)
	v_pk_fma_f32 v[194:195], v[146:147], v[192:193], v[90:91] op_sel:[0,1,0] op_sel_hi:[1,0,1]
	v_cvt_pk_bf16_f32 v243, v192, v193
	s_nop 0
	v_pk_fma_f32 v[192:193], v[150:151], v[192:193], v[194:195]
	s_nop 0
	v_pk_fma_f32 v[194:195], v[146:147], v[192:193], v[92:93] op_sel:[0,1,0] op_sel_hi:[1,0,1]
	v_cvt_pk_bf16_f32 v244, v192, v193
	s_nop 0
	v_pk_fma_f32 v[192:193], v[150:151], v[192:193], v[194:195]
	s_nop 0
	v_cvt_pk_bf16_f32 v194, v192, v193
	ds_write2_b32 v123, v230, v231 offset0:64 offset1:132
	ds_write2_b32 v137, v232, v233 offset0:72 offset1:140
	ds_write2_b32 v139, v234, v235 offset0:80 offset1:148
	ds_write2_b32 v141, v236, v237 offset0:88 offset1:156
	ds_write2_b32 v143, v238, v239 offset0:96 offset1:164
	ds_write2_b32 v149, v240, v241 offset0:104 offset1:172
	ds_write2_b32 v225, v242, v243 offset0:112 offset1:180
	ds_write2_b32 v226, v244, v194 offset0:120 offset1:188
	s_waitcnt lgkmcnt(0)
	ds_read_b128 v[230:233], v224 offset:8448
	ds_read_b128 v[234:237], v224 offset:8512
	s_waitcnt lgkmcnt(0)
	v_mfma_f32_16x16x32_bf16 v[118:121], v[42:45], v[234:237], v[118:121]
	ds_read_b128 v[234:237], v224 offset:8576
	v_mfma_f32_16x16x32_bf16 v[230:233], v[38:41], v[230:233], 0
	s_waitcnt lgkmcnt(0)
	v_mfma_f32_16x16x32_bf16 v[230:233], v[46:49], v[234:237], v[230:233]
	ds_read_b128 v[234:237], v224 offset:8640
	s_waitcnt lgkmcnt(0)
	v_mfma_f32_16x16x32_bf16 v[118:121], v[50:53], v[234:237], v[118:121]
	s_nop 7
	v_pk_add_f32 v[120:121], v[232:233], v[120:121]
	v_pk_add_f32 v[118:119], v[230:231], v[118:119]
	v_pk_mul_f32 v[194:195], v[120:121], v[120:121]
	v_pk_mul_f32 v[230:231], v[118:119], v[118:119]
	v_mov_b64_e32 v[232:233], s[48:49]
	v_pk_fma_f32 v[230:231], v[230:231], s[46:47], v[232:233] op_sel_hi:[1,0,0] neg_lo:[1,0,0] neg_hi:[1,0,0]
	v_pk_fma_f32 v[194:195], v[194:195], s[46:47], v[232:233] op_sel_hi:[1,0,0] neg_lo:[1,0,0] neg_hi:[1,0,0]
	v_pk_mul_f32 v[230:231], v[118:119], v[230:231]
	v_pk_mul_f32 v[194:195], v[120:121], v[194:195]
	v_exp_f32_e32 v230, v230
	v_exp_f32_e32 v231, v231
	v_exp_f32_e32 v194, v194
	v_exp_f32_e32 v195, v195
	v_pk_add_f32 v[230:231], v[230:231], 1.0 op_sel_hi:[1,0]
	s_nop 0
	v_rcp_f32_e32 v230, v230
	v_pk_add_f32 v[194:195], v[194:195], 1.0 op_sel_hi:[1,0]
	v_rcp_f32_e32 v231, v231
	v_rcp_f32_e32 v194, v194
	v_rcp_f32_e32 v195, v195
	v_pk_mul_f32 v[118:119], v[118:119], v[230:231]
	s_nop 0
	v_cvt_pk_bf16_f32 v118, v118, v119
	v_pk_mul_f32 v[120:121], v[120:121], v[194:195]
	s_nop 0
	v_cvt_pk_bf16_f32 v119, v120, v121
	v_or_b32_e32 v120, s86, v217
	v_or_b32_e32 v120, s20, v120
	v_mov_b32_e32 v121, s75
	v_lshlrev_b64 v[120:121], 12, v[120:121]
	v_lshl_add_u64 v[120:121], v[154:155], 0, v[120:121]
	global_store_dwordx2 v[120:121], v[118:119], off sc1

.LBB0_2216:
	s_waitcnt lgkmcnt(6)
	v_cndmask_b32_e64 v114, v66, 0, s[4:5]
	v_cndmask_b32_e64 v115, v67, 0, s[4:5]
	v_cndmask_b32_e64 v116, v68, 0, s[4:5]
	v_cndmask_b32_e64 v117, v69, 0, s[4:5]
	s_waitcnt lgkmcnt(0)
	s_mov_b64 s[72:73], -1
	s_and_b64 vcc, exec, s[14:15]
	v_mfma_f32_16x16x32_bf16 v[66:69], v[2:5], v[114:117], 0
	s_waitcnt lgkmcnt(0)
	v_mfma_f32_16x16x32_bf16 v[90:93], v[6:9], v[114:117], 0
	v_mfma_f32_16x16x32_bf16 v[94:97], v[10:13], v[114:117], 0
	s_nop 4
	ds_write_b128 v202, v[66:69]
	v_mfma_f32_16x16x32_bf16 v[98:101], v[14:17], v[114:117], 0
	ds_write_b128 v202, v[90:93] offset:64
	ds_write_b128 v202, v[94:97] offset:128
	s_nop 5
	ds_write_b128 v202, v[98:101] offset:192
	v_mfma_f32_16x16x32_bf16 v[102:105], v[18:21], v[114:117], 0
	v_mfma_f32_16x16x32_bf16 v[66:69], v[22:25], v[114:117], 0
	v_mfma_f32_16x16x32_bf16 v[90:93], v[26:29], v[114:117], 0
	s_nop 5
	ds_write_b128 v202, v[102:105] offset:256
	ds_write_b128 v202, v[66:69] offset:320
	ds_write_b128 v202, v[90:93] offset:384
	v_mfma_f32_16x16x32_bf16 v[66:69], v[30:33], v[114:117], 0
	s_nop 7
	ds_write_b128 v202, v[66:69] offset:448
	s_waitcnt lgkmcnt(0)
	ds_read2_b64 v[230:233], v203 offset1:66
	ds_read2_b64 v[110:113], v203 offset0:132 offset1:198
	ds_read2_b64 v[106:109], v227 offset0:8 offset1:74
	ds_read2_b64 v[102:105], v227 offset0:140 offset1:206
	ds_read2_b64 v[98:101], v228 offset0:16 offset1:82
	ds_read2_b64 v[94:97], v228 offset0:148 offset1:214
	ds_read2_b64 v[90:93], v229 offset0:24 offset1:90
	ds_read2_b64 v[66:69], v229 offset0:156 offset1:222
	s_waitcnt lgkmcnt(0)
	s_waitcnt lgkmcnt(7)
	v_pk_fma_f32 v[118:119], v[146:147], v[192:193], v[230:231] op_sel:[0,1,0] op_sel_hi:[1,0,1]
	s_nop 0
	v_pk_fma_f32 v[120:121], v[150:151], v[192:193], v[118:119]
	s_nop 0
	v_pk_fma_f32 v[118:119], v[146:147], v[120:121], v[232:233] op_sel:[0,1,0] op_sel_hi:[1,0,1]
	s_nop 0
	v_pk_fma_f32 v[118:119], v[150:151], v[120:121], v[118:119]
	s_cbranch_vccnz .LBB0_2218
	v_cvt_pk_bf16_f32 v192, v120, v121
	s_waitcnt lgkmcnt(6)
	v_pk_fma_f32 v[120:121], v[146:147], v[118:119], v[110:111] op_sel:[0,1,0] op_sel_hi:[1,0,1]
	v_cvt_pk_bf16_f32 v193, v118, v119
	v_mfma_f32_16x16x32_bf16 v[114:117], v[34:37], v[114:117], 0
	v_fma_f32 v120, v150, v118, v120
	v_fma_f32 v121, v151, v119, v121
	s_mov_b64 s[72:73], 0
	v_pk_fma_f32 v[190:191], v[146:147], v[120:121], v[112:113] op_sel:[0,1,0] op_sel_hi:[1,0,1]
	v_cvt_pk_bf16_f32 v194, v120, v121
	s_nop 0
	v_pk_fma_f32 v[120:121], v[150:151], v[120:121], v[190:191]
	s_waitcnt lgkmcnt(5)
	v_pk_fma_f32 v[190:191], v[146:147], v[120:121], v[106:107] op_sel:[0,1,0] op_sel_hi:[1,0,1]
	v_cvt_pk_bf16_f32 v195, v120, v121
	s_nop 0
	v_pk_fma_f32 v[120:121], v[150:151], v[120:121], v[190:191]
	s_nop 0
	v_pk_fma_f32 v[190:191], v[146:147], v[120:121], v[108:109] op_sel:[0,1,0] op_sel_hi:[1,0,1]
	v_cvt_pk_bf16_f32 v230, v120, v121
	s_nop 0
	v_pk_fma_f32 v[120:121], v[150:151], v[120:121], v[190:191]
	s_waitcnt lgkmcnt(4)
	v_pk_fma_f32 v[190:191], v[146:147], v[120:121], v[102:103] op_sel:[0,1,0] op_sel_hi:[1,0,1]
	v_cvt_pk_bf16_f32 v231, v120, v121
	s_nop 0
	v_pk_fma_f32 v[120:121], v[150:151], v[120:121], v[190:191]
	s_nop 0
	v_pk_fma_f32 v[190:191], v[146:147], v[120:121], v[104:105] op_sel:[0,1,0] op_sel_hi:[1,0,1]
	v_cvt_pk_bf16_f32 v232, v120, v121
	s_nop 0
	v_pk_fma_f32 v[120:121], v[150:151], v[120:121], v[190:191]
	s_waitcnt lgkmcnt(3)
	v_pk_fma_f32 v[190:191], v[146:147], v[120:121], v[98:99] op_sel:[0,1,0] op_sel_hi:[1,0,1]
	v_cvt_pk_bf16_f32 v233, v120, v121
	s_nop 0
	v_pk_fma_f32 v[120:121], v[150:151], v[120:121], v[190:191]
	s_nop 0
	v_pk_fma_f32 v[190:191], v[146:147], v[120:121], v[100:101] op_sel:[0,1,0] op_sel_hi:[1,0,1]
	v_cvt_pk_bf16_f32 v234, v120, v121
	s_nop 0
	v_pk_fma_f32 v[120:121], v[150:151], v[120:121], v[190:191]
	s_waitcnt lgkmcnt(2)
	v_pk_fma_f32 v[190:191], v[146:147], v[120:121], v[94:95] op_sel:[0,1,0] op_sel_hi:[1,0,1]
	v_cvt_pk_bf16_f32 v235, v120, v121
	s_nop 0
	v_pk_fma_f32 v[120:121], v[150:151], v[120:121], v[190:191]
	s_nop 0
	v_pk_fma_f32 v[190:191], v[146:147], v[120:121], v[96:97] op_sel:[0,1,0] op_sel_hi:[1,0,1]
	v_cvt_pk_bf16_f32 v236, v120, v121
	s_nop 0
	v_pk_fma_f32 v[120:121], v[150:151], v[120:121], v[190:191]
	s_waitcnt lgkmcnt(1)
	v_pk_fma_f32 v[190:191], v[146:147], v[120:121], v[90:91] op_sel:[0,1,0] op_sel_hi:[1,0,1]
	v_cvt_pk_bf16_f32 v237, v120, v121
	s_nop 0
	v_pk_fma_f32 v[120:121], v[150:151], v[120:121], v[190:191]
	s_nop 0
	v_pk_fma_f32 v[190:191], v[146:147], v[120:121], v[92:93] op_sel:[0,1,0] op_sel_hi:[1,0,1]
	v_cvt_pk_bf16_f32 v238, v120, v121
	s_nop 0
	v_pk_fma_f32 v[120:121], v[150:151], v[120:121], v[190:191]
	s_waitcnt lgkmcnt(0)
	v_pk_fma_f32 v[190:191], v[146:147], v[120:121], v[66:67] op_sel:[0,1,0] op_sel_hi:[1,0,1]
	v_cvt_pk_bf16_f32 v239, v120, v121
	s_nop 0
	v_pk_fma_f32 v[120:121], v[150:151], v[120:121], v[190:191]
	s_nop 0
	v_pk_fma_f32 v[190:191], v[146:147], v[120:121], v[68:69] op_sel:[0,1,0] op_sel_hi:[1,0,1]
	v_cvt_pk_bf16_f32 v240, v120, v121
	s_nop 0
	v_pk_fma_f32 v[190:191], v[150:151], v[120:121], v[190:191]
	s_nop 0
	v_cvt_pk_bf16_f32 v120, v190, v191
	ds_write2_b32 v123, v192, v193 offset0:64 offset1:132
	ds_write2_b32 v137, v194, v195 offset0:72 offset1:140
	ds_write2_b32 v139, v230, v231 offset0:80 offset1:148
	ds_write2_b32 v141, v232, v233 offset0:88 offset1:156
	ds_write2_b32 v143, v234, v235 offset0:96 offset1:164
	ds_write2_b32 v149, v236, v237 offset0:104 offset1:172
	ds_write2_b32 v225, v238, v239 offset0:112 offset1:180
	ds_write2_b32 v226, v240, v120 offset0:120 offset1:188
	s_waitcnt lgkmcnt(0)
	ds_read_b128 v[192:195], v224 offset:8448
	ds_read_b128 v[230:233], v224 offset:8512
	s_waitcnt lgkmcnt(0)
	v_mfma_f32_16x16x32_bf16 v[114:117], v[42:45], v[230:233], v[114:117]
	ds_read_b128 v[230:233], v224 offset:8576
	v_mfma_f32_16x16x32_bf16 v[192:195], v[38:41], v[192:195], 0
	s_waitcnt lgkmcnt(0)
	v_mfma_f32_16x16x32_bf16 v[192:195], v[46:49], v[230:233], v[192:195]
	ds_read_b128 v[230:233], v224 offset:8640
	s_waitcnt lgkmcnt(0)
	v_mfma_f32_16x16x32_bf16 v[114:117], v[50:53], v[230:233], v[114:117]
	s_nop 7
	v_pk_add_f32 v[116:117], v[194:195], v[116:117]
	v_pk_add_f32 v[114:115], v[192:193], v[114:115]
	v_pk_mul_f32 v[120:121], v[116:117], v[116:117]
	v_pk_mul_f32 v[192:193], v[114:115], v[114:115]
	v_mov_b64_e32 v[194:195], s[48:49]
	v_pk_fma_f32 v[192:193], v[192:193], s[46:47], v[194:195] op_sel_hi:[1,0,0] neg_lo:[1,0,0] neg_hi:[1,0,0]
	v_pk_fma_f32 v[120:121], v[120:121], s[46:47], v[194:195] op_sel_hi:[1,0,0] neg_lo:[1,0,0] neg_hi:[1,0,0]
	v_pk_mul_f32 v[192:193], v[114:115], v[192:193]
	v_pk_mul_f32 v[120:121], v[116:117], v[120:121]
	v_exp_f32_e32 v192, v192
	v_exp_f32_e32 v193, v193
	v_exp_f32_e32 v120, v120
	v_exp_f32_e32 v121, v121
	v_pk_add_f32 v[192:193], v[192:193], 1.0 op_sel_hi:[1,0]
	s_nop 0
	v_rcp_f32_e32 v192, v192
	v_pk_add_f32 v[120:121], v[120:121], 1.0 op_sel_hi:[1,0]
	v_rcp_f32_e32 v193, v193
	v_rcp_f32_e32 v120, v120
	v_rcp_f32_e32 v121, v121
	v_pk_mul_f32 v[114:115], v[114:115], v[192:193]
	s_nop 0
	v_cvt_pk_bf16_f32 v114, v114, v115
	v_pk_mul_f32 v[116:117], v[116:117], v[120:121]
	s_nop 0
	v_cvt_pk_bf16_f32 v115, v116, v117
	v_or_b32_e32 v116, s86, v218
	v_or_b32_e32 v116, s20, v116
	v_mov_b32_e32 v117, s75
	v_lshlrev_b64 v[116:117], 12, v[116:117]
	v_lshl_add_u64 v[116:117], v[154:155], 0, v[116:117]
	global_store_dwordx2 v[116:117], v[114:115], off sc1

.LBB0_2222:
	v_cndmask_b32_e64 v118, 0, v58, s[4:5]
	v_cndmask_b32_e64 v119, 0, v59, s[4:5]
	v_cndmask_b32_e64 v120, 0, v60, s[4:5]
	v_cndmask_b32_e64 v121, 0, v61, s[4:5]
	s_mov_b64 s[16:17], -1
	s_and_b64 vcc, exec, s[14:15]
	v_mfma_f32_16x16x32_bf16 v[90:93], v[2:5], v[118:121], 0
	v_mfma_f32_16x16x32_bf16 v[94:97], v[6:9], v[118:121], 0
	v_mfma_f32_16x16x32_bf16 v[98:101], v[10:13], v[118:121], 0
	s_nop 5
	ds_write_b128 v202, v[90:93]
	v_mfma_f32_16x16x32_bf16 v[102:105], v[14:17], v[118:121], 0
	ds_write_b128 v202, v[94:97] offset:64
	ds_write_b128 v202, v[98:101] offset:128
	s_nop 5
	ds_write_b128 v202, v[102:105] offset:192
	v_mfma_f32_16x16x32_bf16 v[106:109], v[18:21], v[118:121], 0
	v_mfma_f32_16x16x32_bf16 v[90:93], v[22:25], v[118:121], 0
	v_mfma_f32_16x16x32_bf16 v[94:97], v[26:29], v[118:121], 0
	s_nop 5
	ds_write_b128 v202, v[106:109] offset:256
	ds_write_b128 v202, v[90:93] offset:320
	ds_write_b128 v202, v[94:97] offset:384
	v_mfma_f32_16x16x32_bf16 v[90:93], v[30:33], v[118:121], 0
	s_nop 7
	ds_write_b128 v202, v[90:93] offset:448
	s_waitcnt lgkmcnt(0)
	ds_read2_b64 v[230:233], v203 offset1:66
	ds_read2_b64 v[114:117], v203 offset0:132 offset1:198
	ds_read2_b64 v[110:113], v227 offset0:8 offset1:74
	ds_read2_b64 v[106:109], v227 offset0:140 offset1:206
	ds_read2_b64 v[102:105], v228 offset0:16 offset1:82
	ds_read2_b64 v[98:101], v228 offset0:148 offset1:214
	ds_read2_b64 v[94:97], v229 offset0:24 offset1:90
	ds_read2_b64 v[90:93], v229 offset0:156 offset1:222
	s_waitcnt lgkmcnt(0)
	s_waitcnt lgkmcnt(7)
	v_pk_fma_f32 v[192:193], v[146:147], v[190:191], v[230:231] op_sel:[0,1,0] op_sel_hi:[1,0,1]
	s_nop 0
	v_pk_fma_f32 v[194:195], v[150:151], v[190:191], v[192:193]
	s_nop 0
	v_pk_fma_f32 v[190:191], v[146:147], v[194:195], v[232:233] op_sel:[0,1,0] op_sel_hi:[1,0,1]
	s_nop 0
	v_pk_fma_f32 v[190:191], v[150:151], v[194:195], v[190:191]
	s_cbranch_vccnz .LBB0_2224
	s_waitcnt lgkmcnt(6)
	v_pk_fma_f32 v[192:193], v[146:147], v[190:191], v[114:115] op_sel:[0,1,0] op_sel_hi:[1,0,1]
	v_cvt_pk_bf16_f32 v230, v194, v195
	v_cvt_pk_bf16_f32 v231, v190, v191
	v_mfma_f32_16x16x32_bf16 v[118:121], v[34:37], v[118:121], 0
	v_fma_f32 v192, v150, v190, v192
	v_fma_f32 v193, v151, v191, v193
	s_mov_b64 s[16:17], 0
	v_pk_fma_f32 v[194:195], v[146:147], v[192:193], v[116:117] op_sel:[0,1,0] op_sel_hi:[1,0,1]
	v_cvt_pk_bf16_f32 v232, v192, v193
	s_nop 0
	v_pk_fma_f32 v[192:193], v[150:151], v[192:193], v[194:195]
	s_waitcnt lgkmcnt(5)
	v_pk_fma_f32 v[194:195], v[146:147], v[192:193], v[110:111] op_sel:[0,1,0] op_sel_hi:[1,0,1]
	v_cvt_pk_bf16_f32 v233, v192, v193
	s_nop 0
	v_pk_fma_f32 v[192:193], v[150:151], v[192:193], v[194:195]
	s_nop 0
	v_pk_fma_f32 v[194:195], v[146:147], v[192:193], v[112:113] op_sel:[0,1,0] op_sel_hi:[1,0,1]
	v_cvt_pk_bf16_f32 v234, v192, v193
	s_nop 0
	v_pk_fma_f32 v[192:193], v[150:151], v[192:193], v[194:195]
	s_waitcnt lgkmcnt(4)
	v_pk_fma_f32 v[194:195], v[146:147], v[192:193], v[106:107] op_sel:[0,1,0] op_sel_hi:[1,0,1]
	v_cvt_pk_bf16_f32 v235, v192, v193
	s_nop 0
	v_pk_fma_f32 v[192:193], v[150:151], v[192:193], v[194:195]
	s_nop 0
	v_pk_fma_f32 v[194:195], v[146:147], v[192:193], v[108:109] op_sel:[0,1,0] op_sel_hi:[1,0,1]
	v_cvt_pk_bf16_f32 v236, v192, v193
	s_nop 0
	v_pk_fma_f32 v[192:193], v[150:151], v[192:193], v[194:195]
	s_waitcnt lgkmcnt(3)
	v_pk_fma_f32 v[194:195], v[146:147], v[192:193], v[102:103] op_sel:[0,1,0] op_sel_hi:[1,0,1]
	v_cvt_pk_bf16_f32 v237, v192, v193
	s_nop 0
	v_pk_fma_f32 v[192:193], v[150:151], v[192:193], v[194:195]
	s_nop 0
	v_pk_fma_f32 v[194:195], v[146:147], v[192:193], v[104:105] op_sel:[0,1,0] op_sel_hi:[1,0,1]
	v_cvt_pk_bf16_f32 v238, v192, v193
	s_nop 0
	v_pk_fma_f32 v[192:193], v[150:151], v[192:193], v[194:195]
	s_waitcnt lgkmcnt(2)
	v_pk_fma_f32 v[194:195], v[146:147], v[192:193], v[98:99] op_sel:[0,1,0] op_sel_hi:[1,0,1]
	v_cvt_pk_bf16_f32 v239, v192, v193
	s_nop 0
	v_pk_fma_f32 v[192:193], v[150:151], v[192:193], v[194:195]
	s_nop 0
	v_pk_fma_f32 v[194:195], v[146:147], v[192:193], v[100:101] op_sel:[0,1,0] op_sel_hi:[1,0,1]
	v_cvt_pk_bf16_f32 v240, v192, v193
	s_nop 0
	v_pk_fma_f32 v[192:193], v[150:151], v[192:193], v[194:195]
	s_waitcnt lgkmcnt(1)
	v_pk_fma_f32 v[194:195], v[146:147], v[192:193], v[94:95] op_sel:[0,1,0] op_sel_hi:[1,0,1]
	v_cvt_pk_bf16_f32 v241, v192, v193
	s_nop 0
	v_pk_fma_f32 v[192:193], v[150:151], v[192:193], v[194:195]
	s_nop 0
	v_pk_fma_f32 v[194:195], v[146:147], v[192:193], v[96:97] op_sel:[0,1,0] op_sel_hi:[1,0,1]
	v_cvt_pk_bf16_f32 v242, v192, v193
	s_nop 0
	v_pk_fma_f32 v[192:193], v[150:151], v[192:193], v[194:195]
	s_waitcnt lgkmcnt(0)
	v_pk_fma_f32 v[194:195], v[146:147], v[192:193], v[90:91] op_sel:[0,1,0] op_sel_hi:[1,0,1]
	v_cvt_pk_bf16_f32 v243, v192, v193
	s_nop 0
	v_pk_fma_f32 v[192:193], v[150:151], v[192:193], v[194:195]
	s_nop 0
	v_pk_fma_f32 v[194:195], v[146:147], v[192:193], v[92:93] op_sel:[0,1,0] op_sel_hi:[1,0,1]
	v_cvt_pk_bf16_f32 v244, v192, v193
	s_nop 0
	v_pk_fma_f32 v[192:193], v[150:151], v[192:193], v[194:195]
	s_nop 0
	v_cvt_pk_bf16_f32 v194, v192, v193
	ds_write2_b32 v123, v230, v231 offset0:64 offset1:132
	ds_write2_b32 v137, v232, v233 offset0:72 offset1:140
	ds_write2_b32 v139, v234, v235 offset0:80 offset1:148
	ds_write2_b32 v141, v236, v237 offset0:88 offset1:156
	ds_write2_b32 v143, v238, v239 offset0:96 offset1:164
	ds_write2_b32 v149, v240, v241 offset0:104 offset1:172
	ds_write2_b32 v225, v242, v243 offset0:112 offset1:180
	ds_write2_b32 v226, v244, v194 offset0:120 offset1:188
	s_waitcnt lgkmcnt(0)
	ds_read_b128 v[230:233], v224 offset:8448
	ds_read_b128 v[234:237], v224 offset:8512
	s_waitcnt lgkmcnt(0)
	v_mfma_f32_16x16x32_bf16 v[118:121], v[42:45], v[234:237], v[118:121]
	ds_read_b128 v[234:237], v224 offset:8576
	v_mfma_f32_16x16x32_bf16 v[230:233], v[38:41], v[230:233], 0
	s_waitcnt lgkmcnt(0)
	v_mfma_f32_16x16x32_bf16 v[230:233], v[46:49], v[234:237], v[230:233]
	ds_read_b128 v[234:237], v224 offset:8640
	s_waitcnt lgkmcnt(0)
	v_mfma_f32_16x16x32_bf16 v[118:121], v[50:53], v[234:237], v[118:121]
	s_nop 7
	v_pk_add_f32 v[120:121], v[232:233], v[120:121]
	v_pk_add_f32 v[118:119], v[230:231], v[118:119]
	v_pk_mul_f32 v[194:195], v[120:121], v[120:121]
	v_pk_mul_f32 v[230:231], v[118:119], v[118:119]
	v_mov_b64_e32 v[232:233], s[48:49]
	v_pk_fma_f32 v[230:231], v[230:231], s[46:47], v[232:233] op_sel_hi:[1,0,0] neg_lo:[1,0,0] neg_hi:[1,0,0]
	v_pk_fma_f32 v[194:195], v[194:195], s[46:47], v[232:233] op_sel_hi:[1,0,0] neg_lo:[1,0,0] neg_hi:[1,0,0]
	v_pk_mul_f32 v[230:231], v[118:119], v[230:231]
	v_pk_mul_f32 v[194:195], v[120:121], v[194:195]
	v_exp_f32_e32 v230, v230
	v_exp_f32_e32 v231, v231
	v_exp_f32_e32 v194, v194
	v_exp_f32_e32 v195, v195
	v_pk_add_f32 v[230:231], v[230:231], 1.0 op_sel_hi:[1,0]
	s_nop 0
	v_rcp_f32_e32 v230, v230
	v_pk_add_f32 v[194:195], v[194:195], 1.0 op_sel_hi:[1,0]
	v_rcp_f32_e32 v231, v231
	v_rcp_f32_e32 v194, v194
	v_rcp_f32_e32 v195, v195
	v_pk_mul_f32 v[118:119], v[118:119], v[230:231]
	s_nop 0
	v_cvt_pk_bf16_f32 v118, v118, v119
	v_pk_mul_f32 v[120:121], v[120:121], v[194:195]
	s_nop 0
	v_cvt_pk_bf16_f32 v119, v120, v121
	v_or_b32_e32 v120, s86, v219
	v_or_b32_e32 v120, s20, v120
	v_mov_b32_e32 v121, s75
	v_lshlrev_b64 v[120:121], 12, v[120:121]
	v_lshl_add_u64 v[120:121], v[154:155], 0, v[120:121]
	global_store_dwordx2 v[120:121], v[118:119], off sc1

.LBB0_2226:
	s_waitcnt lgkmcnt(6)
	v_cndmask_b32_e64 v114, v58, 0, s[4:5]
	v_cndmask_b32_e64 v115, v59, 0, s[4:5]
	v_cndmask_b32_e64 v116, v60, 0, s[4:5]
	v_cndmask_b32_e64 v117, v61, 0, s[4:5]
	s_waitcnt lgkmcnt(0)
	s_mov_b64 s[16:17], -1
	s_and_b64 vcc, exec, s[14:15]
	v_mfma_f32_16x16x32_bf16 v[58:61], v[2:5], v[114:117], 0
	s_waitcnt lgkmcnt(0)
	v_mfma_f32_16x16x32_bf16 v[90:93], v[6:9], v[114:117], 0
	v_mfma_f32_16x16x32_bf16 v[94:97], v[10:13], v[114:117], 0
	s_nop 4
	ds_write_b128 v202, v[58:61]
	v_mfma_f32_16x16x32_bf16 v[98:101], v[14:17], v[114:117], 0
	ds_write_b128 v202, v[90:93] offset:64
	ds_write_b128 v202, v[94:97] offset:128
	s_nop 5
	ds_write_b128 v202, v[98:101] offset:192
	v_mfma_f32_16x16x32_bf16 v[102:105], v[18:21], v[114:117], 0
	v_mfma_f32_16x16x32_bf16 v[58:61], v[22:25], v[114:117], 0
	v_mfma_f32_16x16x32_bf16 v[90:93], v[26:29], v[114:117], 0
	s_nop 5
	ds_write_b128 v202, v[102:105] offset:256
	ds_write_b128 v202, v[58:61] offset:320
	ds_write_b128 v202, v[90:93] offset:384
	v_mfma_f32_16x16x32_bf16 v[58:61], v[30:33], v[114:117], 0
	s_nop 7
	ds_write_b128 v202, v[58:61] offset:448
	s_waitcnt lgkmcnt(0)
	ds_read2_b64 v[230:233], v203 offset1:66
	ds_read2_b64 v[110:113], v203 offset0:132 offset1:198
	ds_read2_b64 v[106:109], v227 offset0:8 offset1:74
	ds_read2_b64 v[102:105], v227 offset0:140 offset1:206
	ds_read2_b64 v[98:101], v228 offset0:16 offset1:82
	ds_read2_b64 v[94:97], v228 offset0:148 offset1:214
	ds_read2_b64 v[90:93], v229 offset0:24 offset1:90
	ds_read2_b64 v[58:61], v229 offset0:156 offset1:222
	s_waitcnt lgkmcnt(0)
	s_waitcnt lgkmcnt(7)
	v_pk_fma_f32 v[118:119], v[146:147], v[192:193], v[230:231] op_sel:[0,1,0] op_sel_hi:[1,0,1]
	s_nop 0
	v_pk_fma_f32 v[120:121], v[150:151], v[192:193], v[118:119]
	s_nop 0
	v_pk_fma_f32 v[118:119], v[146:147], v[120:121], v[232:233] op_sel:[0,1,0] op_sel_hi:[1,0,1]
	s_nop 0
	v_pk_fma_f32 v[118:119], v[150:151], v[120:121], v[118:119]
	s_cbranch_vccnz .LBB0_2228
	v_cvt_pk_bf16_f32 v192, v120, v121
	s_waitcnt lgkmcnt(6)
	v_pk_fma_f32 v[120:121], v[146:147], v[118:119], v[110:111] op_sel:[0,1,0] op_sel_hi:[1,0,1]
	v_cvt_pk_bf16_f32 v193, v118, v119
	v_mfma_f32_16x16x32_bf16 v[114:117], v[34:37], v[114:117], 0
	v_fma_f32 v120, v150, v118, v120
	v_fma_f32 v121, v151, v119, v121
	s_mov_b64 s[16:17], 0
	v_pk_fma_f32 v[190:191], v[146:147], v[120:121], v[112:113] op_sel:[0,1,0] op_sel_hi:[1,0,1]
	v_cvt_pk_bf16_f32 v194, v120, v121
	s_nop 0
	v_pk_fma_f32 v[120:121], v[150:151], v[120:121], v[190:191]
	s_waitcnt lgkmcnt(5)
	v_pk_fma_f32 v[190:191], v[146:147], v[120:121], v[106:107] op_sel:[0,1,0] op_sel_hi:[1,0,1]
	v_cvt_pk_bf16_f32 v195, v120, v121
	s_nop 0
	v_pk_fma_f32 v[120:121], v[150:151], v[120:121], v[190:191]
	s_nop 0
	v_pk_fma_f32 v[190:191], v[146:147], v[120:121], v[108:109] op_sel:[0,1,0] op_sel_hi:[1,0,1]
	v_cvt_pk_bf16_f32 v227, v120, v121
	s_nop 0
	v_pk_fma_f32 v[120:121], v[150:151], v[120:121], v[190:191]
	s_waitcnt lgkmcnt(4)
	v_pk_fma_f32 v[190:191], v[146:147], v[120:121], v[102:103] op_sel:[0,1,0] op_sel_hi:[1,0,1]
	v_cvt_pk_bf16_f32 v228, v120, v121
	s_nop 0
	v_pk_fma_f32 v[120:121], v[150:151], v[120:121], v[190:191]
	s_nop 0
	v_pk_fma_f32 v[190:191], v[146:147], v[120:121], v[104:105] op_sel:[0,1,0] op_sel_hi:[1,0,1]
	v_cvt_pk_bf16_f32 v229, v120, v121
	s_nop 0
	v_pk_fma_f32 v[120:121], v[150:151], v[120:121], v[190:191]
	s_waitcnt lgkmcnt(3)
	v_pk_fma_f32 v[190:191], v[146:147], v[120:121], v[98:99] op_sel:[0,1,0] op_sel_hi:[1,0,1]
	v_cvt_pk_bf16_f32 v230, v120, v121
	s_nop 0
	v_pk_fma_f32 v[120:121], v[150:151], v[120:121], v[190:191]
	s_nop 0
	v_pk_fma_f32 v[190:191], v[146:147], v[120:121], v[100:101] op_sel:[0,1,0] op_sel_hi:[1,0,1]
	v_cvt_pk_bf16_f32 v231, v120, v121
	s_nop 0
	v_pk_fma_f32 v[120:121], v[150:151], v[120:121], v[190:191]
	s_waitcnt lgkmcnt(2)
	v_pk_fma_f32 v[190:191], v[146:147], v[120:121], v[94:95] op_sel:[0,1,0] op_sel_hi:[1,0,1]
	v_cvt_pk_bf16_f32 v232, v120, v121
	s_nop 0
	v_pk_fma_f32 v[120:121], v[150:151], v[120:121], v[190:191]
	s_nop 0
	v_pk_fma_f32 v[190:191], v[146:147], v[120:121], v[96:97] op_sel:[0,1,0] op_sel_hi:[1,0,1]
	v_cvt_pk_bf16_f32 v233, v120, v121
	s_nop 0
	v_pk_fma_f32 v[120:121], v[150:151], v[120:121], v[190:191]
	s_waitcnt lgkmcnt(1)
	v_pk_fma_f32 v[190:191], v[146:147], v[120:121], v[90:91] op_sel:[0,1,0] op_sel_hi:[1,0,1]
	v_cvt_pk_bf16_f32 v234, v120, v121
	s_nop 0
	v_pk_fma_f32 v[120:121], v[150:151], v[120:121], v[190:191]
	s_nop 0
	v_pk_fma_f32 v[190:191], v[146:147], v[120:121], v[92:93] op_sel:[0,1,0] op_sel_hi:[1,0,1]
	v_cvt_pk_bf16_f32 v235, v120, v121
	s_nop 0
	v_pk_fma_f32 v[120:121], v[150:151], v[120:121], v[190:191]
	s_waitcnt lgkmcnt(0)
	v_pk_fma_f32 v[190:191], v[146:147], v[120:121], v[58:59] op_sel:[0,1,0] op_sel_hi:[1,0,1]
	v_cvt_pk_bf16_f32 v236, v120, v121
	s_nop 0
	v_pk_fma_f32 v[120:121], v[150:151], v[120:121], v[190:191]
	s_nop 0
	v_pk_fma_f32 v[190:191], v[146:147], v[120:121], v[60:61] op_sel:[0,1,0] op_sel_hi:[1,0,1]
	v_cvt_pk_bf16_f32 v237, v120, v121
	s_nop 0
	v_pk_fma_f32 v[190:191], v[150:151], v[120:121], v[190:191]
	s_nop 0
	v_cvt_pk_bf16_f32 v120, v190, v191
	ds_write2_b32 v123, v192, v193 offset0:64 offset1:132
	ds_write2_b32 v137, v194, v195 offset0:72 offset1:140
	ds_write2_b32 v139, v227, v228 offset0:80 offset1:148
	ds_write2_b32 v141, v229, v230 offset0:88 offset1:156
	ds_write2_b32 v143, v231, v232 offset0:96 offset1:164
	ds_write2_b32 v149, v233, v234 offset0:104 offset1:172
	ds_write2_b32 v225, v235, v236 offset0:112 offset1:180
	ds_write2_b32 v226, v237, v120 offset0:120 offset1:188
	s_waitcnt lgkmcnt(0)
	ds_read_b128 v[192:195], v224 offset:8448
	ds_read_b128 v[226:229], v224 offset:8512
	s_waitcnt lgkmcnt(0)
	v_mfma_f32_16x16x32_bf16 v[114:117], v[42:45], v[226:229], v[114:117]
	ds_read_b128 v[226:229], v224 offset:8576
	v_mfma_f32_16x16x32_bf16 v[192:195], v[38:41], v[192:195], 0
	s_waitcnt lgkmcnt(0)
	v_mfma_f32_16x16x32_bf16 v[192:195], v[46:49], v[226:229], v[192:195]
	ds_read_b128 v[226:229], v224 offset:8640
	s_waitcnt lgkmcnt(0)
	v_mfma_f32_16x16x32_bf16 v[114:117], v[50:53], v[226:229], v[114:117]
	s_nop 7
	v_pk_add_f32 v[116:117], v[194:195], v[116:117]
	v_pk_add_f32 v[114:115], v[192:193], v[114:115]
	v_pk_mul_f32 v[120:121], v[116:117], v[116:117]
	v_pk_mul_f32 v[192:193], v[114:115], v[114:115]
	v_mov_b64_e32 v[194:195], s[48:49]
	v_pk_fma_f32 v[192:193], v[192:193], s[46:47], v[194:195] op_sel_hi:[1,0,0] neg_lo:[1,0,0] neg_hi:[1,0,0]
	v_pk_fma_f32 v[120:121], v[120:121], s[46:47], v[194:195] op_sel_hi:[1,0,0] neg_lo:[1,0,0] neg_hi:[1,0,0]
	v_pk_mul_f32 v[192:193], v[114:115], v[192:193]
	v_pk_mul_f32 v[120:121], v[116:117], v[120:121]
	v_exp_f32_e32 v192, v192
	v_exp_f32_e32 v193, v193
	v_exp_f32_e32 v120, v120
	v_exp_f32_e32 v121, v121
	v_pk_add_f32 v[192:193], v[192:193], 1.0 op_sel_hi:[1,0]
	s_nop 0
	v_rcp_f32_e32 v192, v192
	v_pk_add_f32 v[120:121], v[120:121], 1.0 op_sel_hi:[1,0]
	v_rcp_f32_e32 v193, v193
	v_rcp_f32_e32 v120, v120
	v_rcp_f32_e32 v121, v121
	v_pk_mul_f32 v[114:115], v[114:115], v[192:193]
	s_nop 0
	v_cvt_pk_bf16_f32 v114, v114, v115
	v_pk_mul_f32 v[116:117], v[116:117], v[120:121]
	s_nop 0
	v_cvt_pk_bf16_f32 v115, v116, v117
	v_or_b32_e32 v116, s86, v220
	v_or_b32_e32 v116, s20, v116
	v_mov_b32_e32 v117, s75
	v_lshlrev_b64 v[116:117], 12, v[116:117]
	v_lshl_add_u64 v[116:117], v[154:155], 0, v[116:117]
	global_store_dwordx2 v[116:117], v[114:115], off sc1

.LBB0_3146:
	s_waitcnt lgkmcnt(0)
	s_barrier
	ds_read_b128 v[2:5], v92
	v_add_u32_e32 v66, v91, v93
	ds_read_b128 v[6:9], v66 offset:34816
	ds_read_b128 v[108:111], v92 offset:32
	ds_read_b128 v[112:115], v66 offset:34848
	s_and_b32 s0, s10, 0xffffff80
	s_lshl_b32 s6, s14, 1
	v_readlane_b32 s14, v254, 60
	s_waitcnt lgkmcnt(2)
	v_mfma_f32_32x32x16_bf16 v[2:17], v[2:5], v[6:9], 0
	v_or_b32_e32 v124, s0, v70
	v_or_b32_e32 v126, s0, v72
	v_readlane_b32 s15, v254, 61
	s_add_u32 s6, s14, s6
	v_ashrrev_i32_e32 v125, 31, v124
	v_ashrrev_i32_e32 v127, 31, v126
	s_addc_u32 s7, s15, 0
	s_waitcnt lgkmcnt(0)
	v_mfma_f32_32x32x16_bf16 v[2:17], v[108:111], v[112:115], v[2:17]
	ds_read_b128 v[108:111], v92 offset:64
	ds_read_b128 v[112:115], v66 offset:34880
	ds_read_b128 v[116:119], v92 offset:96
	ds_read_b128 v[120:123], v66 offset:34912
	s_andn2_b64 vcc, exec, s[4:5]
	s_mov_b32 s15, s13
	s_mov_b32 s10, s12
	s_waitcnt lgkmcnt(2)
	v_mfma_f32_32x32x16_bf16 v[2:17], v[108:111], v[112:115], v[2:17]
	s_waitcnt lgkmcnt(0)
	v_mfma_f32_32x32x16_bf16 v[2:17], v[116:119], v[120:123], v[2:17]
	ds_read_b128 v[108:111], v92 offset:128
	ds_read_b128 v[112:115], v66 offset:34944
	ds_read_b128 v[116:119], v92 offset:160
	ds_read_b128 v[120:123], v66 offset:34976
	s_waitcnt lgkmcnt(2)
	v_mfma_f32_32x32x16_bf16 v[2:17], v[108:111], v[112:115], v[2:17]
	s_waitcnt lgkmcnt(0)
	v_mfma_f32_32x32x16_bf16 v[2:17], v[116:119], v[120:123], v[2:17]
	ds_read_b128 v[108:111], v92 offset:192
	ds_read_b128 v[112:115], v66 offset:35008
	ds_read_b128 v[116:119], v92 offset:224
	ds_read_b128 v[120:123], v66 offset:35040
	s_waitcnt lgkmcnt(2)
	v_mfma_f32_32x32x16_bf16 v[2:17], v[108:111], v[112:115], v[2:17]
	ds_read_b64 v[108:109], v102
	s_waitcnt lgkmcnt(0)
	v_lshlrev_b32_e32 v79, 16, v108
	v_and_b32_e32 v81, 0xffff0000, v108
	v_mfma_f32_32x32x16_bf16 v[2:17], v[116:119], v[120:123], v[2:17]
	v_lshlrev_b32_e32 v83, 16, v109
	v_and_b32_e32 v85, 0xffff0000, v109
	s_waitcnt vmcnt(1)
	s_nop 8
	v_add_f32_e32 v2, v87, v2
	v_add_f32_e32 v3, v87, v3
	v_add_f32_e32 v4, v87, v4
	v_add_f32_e32 v5, v87, v5
	v_mul_f32_e32 v2, v2, v79
	v_mul_f32_e32 v3, v3, v81
	v_mul_f32_e32 v4, v4, v83
	v_mul_f32_e32 v5, v5, v85
	v_cvt_pk_bf16_f32 v2, v2, v3
	v_cvt_pk_bf16_f32 v3, v4, v5
	ds_read_b64 v[4:5], v102 offset:16
	v_add_f32_e32 v6, v87, v6
	v_add_f32_e32 v7, v87, v7
	v_add_f32_e32 v8, v87, v8
	v_add_f32_e32 v9, v87, v9
	ds_write_b64 v102, v[2:3]
	s_waitcnt lgkmcnt(1)
	v_lshlrev_b32_e32 v2, 16, v4
	v_and_b32_e32 v3, 0xffff0000, v4
	v_lshlrev_b32_e32 v4, 16, v5
	v_and_b32_e32 v5, 0xffff0000, v5
	v_mul_f32_e32 v2, v6, v2
	v_mul_f32_e32 v3, v7, v3
	v_mul_f32_e32 v4, v8, v4
	v_mul_f32_e32 v5, v9, v5
	v_cvt_pk_bf16_f32 v2, v2, v3
	v_cvt_pk_bf16_f32 v3, v4, v5
	ds_read_b64 v[4:5], v102 offset:32
	v_add_f32_e32 v10, v87, v10
	v_add_f32_e32 v11, v87, v11
	v_add_f32_e32 v6, v87, v12
	v_add_f32_e32 v7, v87, v13
	ds_write_b64 v102, v[2:3] offset:16
	s_waitcnt lgkmcnt(1)
	v_lshlrev_b32_e32 v2, 16, v4
	v_and_b32_e32 v3, 0xffff0000, v4
	v_lshlrev_b32_e32 v4, 16, v5
	v_and_b32_e32 v5, 0xffff0000, v5
	v_mul_f32_e32 v2, v10, v2
	v_mul_f32_e32 v3, v11, v3
	v_mul_f32_e32 v4, v6, v4
	v_mul_f32_e32 v5, v7, v5
	v_cvt_pk_bf16_f32 v2, v2, v3
	v_cvt_pk_bf16_f32 v3, v4, v5
	ds_read_b64 v[4:5], v102 offset:48
	v_add_f32_e32 v8, v87, v14
	v_add_f32_e32 v6, v87, v15
	ds_write_b64 v102, v[2:3] offset:32
	v_add_f32_e32 v7, v87, v16
	s_waitcnt lgkmcnt(1)
	v_lshlrev_b32_e32 v2, 16, v4
	v_and_b32_e32 v3, 0xffff0000, v4
	v_add_f32_e32 v9, v87, v17
	v_lshlrev_b32_e32 v4, 16, v5
	v_and_b32_e32 v5, 0xffff0000, v5
	v_mul_f32_e32 v2, v8, v2
	v_mul_f32_e32 v3, v6, v3
	v_mul_f32_e32 v4, v7, v4
	v_mul_f32_e32 v5, v9, v5
	v_cvt_pk_bf16_f32 v2, v2, v3
	v_cvt_pk_bf16_f32 v3, v4, v5
	ds_write_b64 v102, v[2:3] offset:48
	ds_read_b128 v[2:5], v92
	ds_read_b128 v[6:9], v66 offset:43520
	ds_read_b128 v[108:111], v66 offset:43552
	ds_read_b128 v[112:115], v92 offset:32
	s_waitcnt lgkmcnt(2)
	v_mfma_f32_32x32x16_bf16 v[2:17], v[2:5], v[6:9], 0
	v_mov_b32_e32 v87, v67
	s_waitcnt lgkmcnt(0)
	v_mfma_f32_32x32x16_bf16 v[2:17], v[112:115], v[108:111], v[2:17]
	ds_read_b128 v[108:111], v92 offset:64
	ds_read_b128 v[112:115], v66 offset:43584
	ds_read_b128 v[116:119], v66 offset:43616
	ds_read_b128 v[120:123], v92 offset:96
	s_waitcnt lgkmcnt(2)
	v_mfma_f32_32x32x16_bf16 v[2:17], v[108:111], v[112:115], v[2:17]
	s_waitcnt lgkmcnt(0)
	v_mfma_f32_32x32x16_bf16 v[2:17], v[120:123], v[116:119], v[2:17]
	ds_read_b128 v[108:111], v92 offset:128
	ds_read_b128 v[112:115], v66 offset:43648
	ds_read_b128 v[116:119], v66 offset:43680
	ds_read_b128 v[120:123], v92 offset:160
	s_waitcnt lgkmcnt(2)
	v_mfma_f32_32x32x16_bf16 v[2:17], v[108:111], v[112:115], v[2:17]
	ds_read_b128 v[108:111], v92 offset:192
	ds_read_b128 v[112:115], v66 offset:43712
	s_waitcnt lgkmcnt(2)
	v_mfma_f32_32x32x16_bf16 v[2:17], v[120:123], v[116:119], v[2:17]
	ds_read_b128 v[116:119], v66 offset:43744
	ds_read_b64 v[128:129], v102 offset:8704
	ds_read_b128 v[120:123], v92 offset:224
	s_waitcnt lgkmcnt(1)
	v_lshlrev_b32_e32 v66, 16, v128
	v_and_b32_e32 v79, 0xffff0000, v128
	v_lshlrev_b32_e32 v81, 16, v129
	v_mfma_f32_32x32x16_bf16 v[2:17], v[108:111], v[112:115], v[2:17]
	v_and_b32_e32 v83, 0xffff0000, v129
	v_lshlrev_b64 v[108:109], 12, v[124:125]
	v_lshlrev_b64 v[110:111], 12, v[126:127]
	v_lshl_add_u64 v[108:109], s[6:7], 0, v[108:109]
	s_waitcnt lgkmcnt(0)
	v_mfma_f32_32x32x16_bf16 v[2:17], v[120:123], v[116:119], v[2:17]
	s_waitcnt vmcnt(0)
	s_nop 10
	v_add_f32_e32 v2, v106, v2
	v_add_f32_e32 v3, v106, v3
	v_add_f32_e32 v4, v106, v4
	v_add_f32_e32 v5, v106, v5
	v_mul_f32_e32 v2, v2, v66
	v_mul_f32_e32 v3, v3, v79
	v_mul_f32_e32 v4, v4, v81
	v_mul_f32_e32 v5, v5, v83
	v_cvt_pk_bf16_f32 v2, v2, v3
	v_cvt_pk_bf16_f32 v3, v4, v5
	ds_read_b64 v[4:5], v102 offset:8720
	v_add_f32_e32 v6, v106, v6
	v_add_f32_e32 v7, v106, v7
	v_add_f32_e32 v8, v106, v8
	v_add_f32_e32 v9, v106, v9
	ds_write_b64 v102, v[2:3] offset:8704
	s_waitcnt lgkmcnt(1)
	v_lshlrev_b32_e32 v2, 16, v4
	v_and_b32_e32 v3, 0xffff0000, v4
	v_lshlrev_b32_e32 v4, 16, v5
	v_and_b32_e32 v5, 0xffff0000, v5
	v_mul_f32_e32 v2, v6, v2
	v_mul_f32_e32 v3, v7, v3
	v_mul_f32_e32 v4, v8, v4
	v_mul_f32_e32 v5, v9, v5
	v_cvt_pk_bf16_f32 v2, v2, v3
	v_cvt_pk_bf16_f32 v3, v4, v5
	ds_read_b64 v[4:5], v102 offset:8736
	v_add_f32_e32 v10, v106, v10
	v_add_f32_e32 v11, v106, v11
	v_add_f32_e32 v6, v106, v12
	v_add_f32_e32 v7, v106, v13
	ds_write_b64 v102, v[2:3] offset:8720
	s_waitcnt lgkmcnt(1)
	v_lshlrev_b32_e32 v2, 16, v4
	v_and_b32_e32 v3, 0xffff0000, v4
	v_lshlrev_b32_e32 v4, 16, v5
	v_and_b32_e32 v5, 0xffff0000, v5
	v_mul_f32_e32 v2, v10, v2
	v_mul_f32_e32 v3, v11, v3
	v_mul_f32_e32 v4, v6, v4
	v_mul_f32_e32 v5, v7, v5
	v_cvt_pk_bf16_f32 v2, v2, v3
	v_cvt_pk_bf16_f32 v3, v4, v5
	ds_read_b64 v[4:5], v102 offset:8752
	v_add_f32_e32 v8, v106, v14
	v_add_f32_e32 v6, v106, v15
	ds_write_b64 v102, v[2:3] offset:8736
	v_add_f32_e32 v7, v106, v16
	s_waitcnt lgkmcnt(1)
	v_lshlrev_b32_e32 v2, 16, v4
	v_and_b32_e32 v3, 0xffff0000, v4
	v_add_f32_e32 v9, v106, v17
	v_lshlrev_b32_e32 v4, 16, v5
	v_and_b32_e32 v5, 0xffff0000, v5
	v_mul_f32_e32 v2, v8, v2
	v_mul_f32_e32 v3, v6, v3
	v_mul_f32_e32 v4, v7, v4
	v_mul_f32_e32 v5, v9, v5
	v_cvt_pk_bf16_f32 v2, v2, v3
	v_cvt_pk_bf16_f32 v3, v4, v5
	ds_write_b64 v102, v[2:3] offset:8752
	s_waitcnt lgkmcnt(0)
	s_barrier
	ds_read_b128 v[2:5], v103
	ds_read_b128 v[6:9], v104
	ds_read_b128 v[10:13], v103 offset:17408
	v_lshl_add_u64 v[14:15], s[6:7], 0, v[110:111]
	v_lshl_add_u64 v[16:17], v[108:109], 0, v[86:87]
	v_lshl_add_u64 v[14:15], v[14:15], 0, v[86:87]
	s_waitcnt lgkmcnt(2)
	global_store_dwordx4 v[16:17], v[2:5], off sc1
	s_waitcnt lgkmcnt(1)
	global_store_dwordx4 v[14:15], v[6:9], off sc1
	ds_read_b128 v[2:5], v105
	s_nop 0
	v_or_b32_e32 v6, s0, v74
	v_ashrrev_i32_e32 v7, 31, v6
	v_lshlrev_b64 v[6:7], 12, v[6:7]
	v_lshl_add_u64 v[6:7], s[6:7], 0, v[6:7]
	v_lshl_add_u64 v[6:7], v[6:7], 0, v[86:87]
	s_waitcnt lgkmcnt(1)
	global_store_dwordx4 v[6:7], v[10:13], off sc1
	v_or_b32_e32 v6, s0, v1
	v_ashrrev_i32_e32 v7, 31, v6
	v_lshlrev_b64 v[6:7], 12, v[6:7]
	v_lshl_add_u64 v[6:7], s[6:7], 0, v[6:7]
	v_lshl_add_u64 v[6:7], v[6:7], 0, v[86:87]
	s_waitcnt lgkmcnt(0)
	global_store_dwordx4 v[6:7], v[2:5], off sc1
	s_cbranch_vccz .LBB0_3151
